# v23: v16 + GEMM phases: one static s_setprio 1 for waves 4-7 at phase entry, all per-segment priority flips neutralised (s_nop 0)
# speedup vs baseline: 1.0057x; 1.0057x over previous
; #define PG8_BAR __builtin_amdgcn_s_barrier()
; template <class Epi, class Sched, bool ALIGN_EPI = false, bool SP2 = false>
; __device__ __forceinline__ void gemm_phase(PG8_LAS unsigned char* lds, const Gemm g, const Sched& S, const Epi& E) {
;     ...
;     for (int i = 0; i < 2; ++i) { int R, C; stage_rc(tid * 16 + i * 8192, R, C); const int Rb = Epi::PERM ? ((R & ~31) + perm32(R & 31)) : R;
;         voffA[i] = (unsigned)(R * g.lda + C) * 2u; voffB[i] = (unsigned)(Rb * g.ldb + C) * 2u; }
;     const size_t kstep = (size_t)(BK * 2);
;     const size_t hsA = (size_t)HALF * g.lda * 2, hsB = (size_t)HALF * g.ldb * 2;
;     const size_t tsA = 2 * hsA, tsB = 2 * hsB;
;     const unsigned ldsbase = (unsigned)(unsigned long long)lds;
;     const unsigned ldsw = (unsigned)wid * 1024u;
;     const int aoff = lds_byte(wr * 64 + fr, fq * 8), boff = lds_byte(wc * 32 + fr, fq * 8);
;     ...
;     Unit cur, nxt; int ui = 0; bool epi_ran = false;
;     if (!S.next(0, cur)) return;
;     f32x4 acc[2][2][4][2];
; #pragma unroll
;     for (int a = 0; a < 2; ++a)
; #pragma unroll
;         for (int b = 0; b < 2; ++b)
; #pragma unroll
;             for (int m = 0; m < 4; ++m)
; #pragma unroll
;                 for (int n = 0; n < 2; ++n) acc[a][b][m][n] = (f32x4){0.f, 0.f, 0.f, 0.f};
;     bf16x8 At[4][2], B0[2][2], B1[2][2];
;     const char* cA = (const char*)g.A + (size_t)cur.pm * tsA + (size_t)cur.k0 * 2; const char* cB = (const char*)g.Bt + (size_t)cur.pn * tsB + (size_t)cur.k0 * 2;
;     S.a_ready(cur);
;     if constexpr (SP2) {
;         PG8_STAGE(PG8_SB(0, 0), cB, voffB); PG8_STAGE(PG8_SB(0, 1), cB + hsB, voffB); PG8_STAGE(PG8_SA(0, 0), cA, voffA); PG8_STAGE(PG8_SA(0, 1), cA + hsA, voffA);
;         if (wr == 1) PG8_BAR;
;         PG8_WAIT_V(2); PG8_BAR;
;         PG8_STAGE(PG8_SB(1, 0), cB + kstep, voffB); PG8_STAGE(PG8_SA(1, 0), cA + kstep, voffA); PG8_STAGE(PG8_SB(1, 1), cB + hsB + kstep, voffB);
;         PG8_WAIT_V(6); PG8_BAR;
;     } else {
;         PG8_STAGE(PG8_SB(0, 0), cB, voffB); PG8_STAGE(PG8_SA(0, 0), cA, voffA); PG8_STAGE(PG8_SB(0, 1), cB + hsB, voffB); PG8_STAGE(PG8_SA(0, 1), cA + hsA, voffA);
;         if (wr == 1) PG8_BAR;
;         PG8_WAIT_V(4); PG8_BAR;
;         PG8_STAGE(PG8_SB(1, 0), cB + kstep, voffB); PG8_STAGE(PG8_SA(1, 0), cA + kstep, voffA); PG8_STAGE(PG8_SB(1, 1), cB + hsB + kstep, voffB);
;         PG8_WAIT_V(6); PG8_BAR;
;     }
.LBB0_279:
	v_readlane_b32 s16, v255, 14
	v_readlane_b32 s17, v255, 15
	s_lshl_b32 s84, s16, 11
	s_lshl_b64 s[16:17], s[84:85], 2
	s_add_u32 s11, s72, s16
	s_addc_u32 s13, s73, s17
	v_bfe_u32 v163, v0, 4, 2
	s_add_u32 s16, s11, 0x208000
	v_and_b32_e32 v162, 15, v0
	v_lshlrev_b32_e32 v2, 4, v163
	v_lshlrev_b32_e32 v0, 2, v0
	s_addc_u32 s17, s13, 0
	s_lshl_b32 s84, s7, 6
	v_lshl_or_b32 v2, v162, 6, v2
	s_lshl_b32 s7, s7, 13
	v_and_b32_e32 v0, 32, v0
	v_bitop3_b32 v4, v2, s7, v0 bitop3:0xde
	s_lshl_b32 s7, s18, 5
	s_and_b32 s82, s7, 0x60
	s_lshl_b32 s7, s82, 7
	s_add_i32 s91, s40, 0x18000
	s_add_u32 s18, s8, 0x80
	s_waitcnt vmcnt(2)
	s_barrier
	s_addc_u32 s19, s9, 0
	s_mov_b32 m0, s91
	s_nop 0
	global_load_lds_dwordx4 v159, s[18:19]
	s_add_i32 s64, s40, 0x1a000
	s_add_i32 s33, s40, 0x8000
	s_mov_b32 m0, s64
	s_nop 0
	global_load_lds_dwordx4 v161, s[18:19]
	s_add_u32 s18, s30, 0x80
	s_addc_u32 s19, s31, 0
	s_mov_b32 m0, s33
	s_nop 0
	global_load_lds_dwordx4 v158, s[18:19]
	s_add_i32 s69, s40, 0xa000
	s_add_i32 s67, s40, 0x1c000
	s_mov_b32 m0, s69
	s_nop 0
	global_load_lds_dwordx4 v160, s[18:19]
	s_add_u32 s18, s8, 0x80080
	s_addc_u32 s19, s9, 0
	s_mov_b32 m0, s67
	s_nop 0
	global_load_lds_dwordx4 v159, s[18:19]
	s_add_i32 s53, s40, 0x1e000
	s_mov_b32 m0, s53
	s_nop 0
	global_load_lds_dwordx4 v161, s[18:19]
	v_bitop3_b32 v5, v2, s7, v0 bitop3:0xde
	s_waitcnt vmcnt(6)
	s_add_i32 s52, s40, 0xc000
	v_mov_b32_e32 v2, v1
	v_mov_b32_e32 v3, v1
	s_cmpk_lt_u32 s6, 0x100
	v_mov_b32_e32 v0, v1
	v_add_u32_e32 v164, 0, v5
	v_add_u32_e32 v165, 0, v4
	v_mov_b64_e32 v[10:11], v[2:3]
	v_mov_b64_e32 v[6:7], v[2:3]
	v_mov_b64_e32 v[30:31], v[2:3]
	v_mov_b64_e32 v[34:35], v[2:3]
	v_mov_b64_e32 v[54:55], v[2:3]
	v_mov_b64_e32 v[58:59], v[2:3]
	v_mov_b64_e32 v[70:71], v[2:3]
	s_waitcnt vmcnt(0)
	v_mov_b64_e32 v[74:75], v[2:3]
	v_mov_b64_e32 v[18:19], v[2:3]
	v_mov_b64_e32 v[14:15], v[2:3]
	v_mov_b64_e32 v[42:43], v[2:3]
	v_mov_b64_e32 v[46:47], v[2:3]
	v_mov_b64_e32 v[62:63], v[2:3]
	v_mov_b64_e32 v[66:67], v[2:3]
	v_mov_b64_e32 v[78:79], v[2:3]
	v_mov_b64_e32 v[82:83], v[2:3]
	v_mov_b64_e32 v[86:87], v[2:3]
	v_mov_b64_e32 v[90:91], v[2:3]
	v_mov_b64_e32 v[102:103], v[2:3]
	v_mov_b64_e32 v[106:107], v[2:3]
	v_mov_b64_e32 v[118:119], v[2:3]
	v_mov_b64_e32 v[122:123], v[2:3]
	v_mov_b64_e32 v[134:135], v[2:3]
	v_mov_b64_e32 v[138:139], v[2:3]
	v_mov_b64_e32 v[94:95], v[2:3]
	v_mov_b64_e32 v[98:99], v[2:3]
	v_mov_b64_e32 v[110:111], v[2:3]
	v_mov_b64_e32 v[114:115], v[2:3]
	v_mov_b64_e32 v[126:127], v[2:3]
	v_mov_b64_e32 v[130:131], v[2:3]
	v_mov_b64_e32 v[142:143], v[2:3]
	v_mov_b64_e32 v[146:147], v[2:3]
	s_cselect_b64 s[18:19], -1, 0
	s_add_i32 s44, s40, 0xe000
	s_mov_b32 s34, 0
	v_mov_b64_e32 v[8:9], v[0:1]
	v_mov_b64_e32 v[4:5], v[0:1]
	v_mov_b64_e32 v[28:29], v[0:1]
	v_mov_b64_e32 v[32:33], v[0:1]
	v_mov_b64_e32 v[52:53], v[0:1]
	v_mov_b64_e32 v[56:57], v[0:1]
	v_mov_b64_e32 v[68:69], v[0:1]
	v_mov_b64_e32 v[72:73], v[0:1]
	v_mov_b64_e32 v[16:17], v[0:1]
	v_mov_b64_e32 v[12:13], v[0:1]
	v_mov_b64_e32 v[40:41], v[0:1]
	v_mov_b64_e32 v[44:45], v[0:1]
	v_mov_b64_e32 v[60:61], v[0:1]
	v_mov_b64_e32 v[64:65], v[0:1]
	v_mov_b64_e32 v[76:77], v[0:1]
	v_mov_b64_e32 v[80:81], v[0:1]
	v_mov_b64_e32 v[84:85], v[0:1]
	v_mov_b64_e32 v[88:89], v[0:1]
	v_mov_b64_e32 v[100:101], v[0:1]
	v_mov_b64_e32 v[104:105], v[0:1]
	v_mov_b64_e32 v[116:117], v[0:1]
	v_mov_b64_e32 v[120:121], v[0:1]
	v_mov_b64_e32 v[132:133], v[0:1]
	v_mov_b64_e32 v[136:137], v[0:1]
	v_mov_b64_e32 v[92:93], v[0:1]
	v_mov_b64_e32 v[96:97], v[0:1]
	v_mov_b64_e32 v[108:109], v[0:1]
	v_mov_b64_e32 v[112:113], v[0:1]
	v_mov_b64_e32 v[124:125], v[0:1]
	v_mov_b64_e32 v[128:129], v[0:1]
	v_mov_b64_e32 v[140:141], v[0:1]
	v_mov_b64_e32 v[144:145], v[0:1]
	s_mov_b64 s[62:63], s[88:89]
	s_barrier
	s_getreg_b32 s100, hwreg(HW_REG_HW_ID, 0, 6)
	s_lshl_b32 s100, s100, 2
	s_add_i32 s100, s100, 0x20540
	v_mov_b32_e32 v251, s100
	ds_read_b32 v251, v251
	s_waitcnt lgkmcnt(0)
	v_readfirstlane_b32 s100, v251
	s_cmp_ge_u32 s100, 4
	s_cbranch_scc0 statprio_skip0
	s_setprio 1
statprio_skip0:
	s_branch .LBB0_282
.LBB0_280:
	ds_read_b128 v[2:5], v166
	ds_read_b128 v[6:9], v166 offset:1024
	ds_read_b128 v[10:13], v166 offset:2048
	ds_read_b128 v[14:17], v166 offset:3072
	ds_read_b128 v[18:21], v167
	ds_read_b128 v[22:25], v167 offset:1024
	ds_read_b128 v[26:29], v167 offset:2048
	ds_read_b128 v[30:33], v167 offset:3072
	s_add_u32 s10, s24, 0x100
	s_addc_u32 s11, s25, 0
	s_add_u32 s8, s24, 0x180
	s_addc_u32 s9, s25, 0
	s_add_u32 s12, s26, 0x100
	s_addc_u32 s13, s27, 0
	ds_read_b128 v[34:37], v165
	ds_read_b128 v[38:41], v165 offset:1024
	ds_read_b128 v[42:45], v165 offset:2048
	ds_read_b128 v[46:49], v165 offset:3072
	ds_read_b128 v[50:53], v165 offset:4096
	ds_read_b128 v[54:57], v165 offset:5120
	ds_read_b128 v[58:61], v165 offset:6144
	ds_read_b128 v[62:65], v165 offset:7168
	s_waitcnt vmcnt(24)
	s_waitcnt lgkmcnt(0)
	s_barrier
	s_nop 0
	s_waitcnt lgkmcnt(7)
	v_mfma_f32_16x16x32_bf16 v[66:69], v[2:5], v[34:37], 0
	v_mfma_f32_16x16x32_bf16 v[70:73], v[10:13], v[34:37], 0
	s_waitcnt lgkmcnt(5)
	v_mfma_f32_16x16x32_bf16 v[74:77], v[2:5], v[42:45], 0
	v_mfma_f32_16x16x32_bf16 v[78:81], v[10:13], v[42:45], 0
	s_waitcnt lgkmcnt(3)
	v_mfma_f32_16x16x32_bf16 v[82:85], v[2:5], v[50:53], 0
	v_mfma_f32_16x16x32_bf16 v[86:89], v[10:13], v[50:53], 0
	s_waitcnt lgkmcnt(1)
	v_mfma_f32_16x16x32_bf16 v[90:93], v[2:5], v[58:61], 0
	v_mfma_f32_16x16x32_bf16 v[94:97], v[10:13], v[58:61], 0
	v_mfma_f32_16x16x32_bf16 v[66:69], v[6:9], v[38:41], v[66:69]
	v_mfma_f32_16x16x32_bf16 v[70:73], v[14:17], v[38:41], v[70:73]
	v_mfma_f32_16x16x32_bf16 v[74:77], v[6:9], v[46:49], v[74:77]
	v_mfma_f32_16x16x32_bf16 v[78:81], v[14:17], v[46:49], v[78:81]
	v_mfma_f32_16x16x32_bf16 v[82:85], v[6:9], v[54:57], v[82:85]
	v_mfma_f32_16x16x32_bf16 v[86:89], v[14:17], v[54:57], v[86:89]
	s_waitcnt lgkmcnt(0)
	v_mfma_f32_16x16x32_bf16 v[90:93], v[6:9], v[62:65], v[90:93]
	v_mfma_f32_16x16x32_bf16 v[100:103], v[14:17], v[62:65], v[94:97]
	s_nop 0
	s_nop 0
	v_mfma_f32_16x16x32_bf16 v[94:97], v[18:21], v[34:37], 0
	v_mfma_f32_16x16x32_bf16 v[34:37], v[26:29], v[34:37], 0
	v_mfma_f32_16x16x32_bf16 v[104:107], v[22:25], v[38:41], v[94:97]
	v_mfma_f32_16x16x32_bf16 v[34:37], v[30:33], v[38:41], v[34:37]
	v_mfma_f32_16x16x32_bf16 v[38:41], v[18:21], v[42:45], 0
	v_mfma_f32_16x16x32_bf16 v[42:45], v[26:29], v[42:45], 0
	v_mfma_f32_16x16x32_bf16 v[38:41], v[22:25], v[46:49], v[38:41]
	v_mfma_f32_16x16x32_bf16 v[42:45], v[30:33], v[46:49], v[42:45]
	v_mfma_f32_16x16x32_bf16 v[46:49], v[18:21], v[50:53], 0
	v_mfma_f32_16x16x32_bf16 v[50:53], v[26:29], v[50:53], 0
	v_mfma_f32_16x16x32_bf16 v[46:49], v[22:25], v[54:57], v[46:49]
	v_mfma_f32_16x16x32_bf16 v[50:53], v[30:33], v[54:57], v[50:53]
	v_mfma_f32_16x16x32_bf16 v[54:57], v[18:21], v[58:61], 0
	v_mfma_f32_16x16x32_bf16 v[58:61], v[26:29], v[58:61], 0
	v_mfma_f32_16x16x32_bf16 v[54:57], v[22:25], v[62:65], v[54:57]
	v_mfma_f32_16x16x32_bf16 v[58:61], v[30:33], v[62:65], v[58:61]
	s_nop 0
	s_barrier
	ds_read_b128 v[62:65], v165 offset:16384
	ds_read_b128 v[94:97], v165 offset:17408
	ds_read_b128 v[108:111], v165 offset:18432
	ds_read_b128 v[112:115], v165 offset:19456
	ds_read_b128 v[116:119], v165 offset:20480
	ds_read_b128 v[120:123], v165 offset:21504
	ds_read_b128 v[124:127], v165 offset:22528
	ds_read_b128 v[128:131], v165 offset:23552
	s_mov_b32 m0, s41
	s_nop 0
	global_load_lds_dwordx4 v159, s[12:13]
	s_nop 0
	s_mov_b32 m0, s48
	s_nop 0
	global_load_lds_dwordx4 v161, s[12:13]
	s_add_u32 s12, s26, 0x80100
	s_addc_u32 s13, s27, 0
	s_mov_b32 m0, s49
	s_nop 0
	global_load_lds_dwordx4 v159, s[12:13]
	s_nop 0
	s_mov_b32 m0, s78
	s_nop 0
	global_load_lds_dwordx4 v161, s[12:13]
	s_nop 0
	s_mov_b32 m0, s40
	s_nop 0
	global_load_lds_dwordx4 v158, s[10:11]
	s_nop 0
	s_mov_b32 m0, s79
	s_nop 0
	global_load_lds_dwordx4 v160, s[10:11]
	s_waitcnt vmcnt(24)
	s_waitcnt lgkmcnt(0)
	s_barrier
	s_nop 0
	s_waitcnt lgkmcnt(7)
	v_mfma_f32_16x16x32_bf16 v[132:135], v[2:5], v[62:65], 0
	s_waitcnt lgkmcnt(6)
	v_mfma_f32_16x16x32_bf16 v[148:151], v[6:9], v[94:97], v[132:135]
	v_mfma_f32_16x16x32_bf16 v[132:135], v[10:13], v[62:65], 0
	v_mfma_f32_16x16x32_bf16 v[152:155], v[14:17], v[94:97], v[132:135]
	s_waitcnt lgkmcnt(5)
	v_mfma_f32_16x16x32_bf16 v[132:135], v[2:5], v[108:111], 0
	s_waitcnt lgkmcnt(4)
	v_mfma_f32_16x16x32_bf16 v[170:173], v[6:9], v[112:115], v[132:135]
	v_mfma_f32_16x16x32_bf16 v[132:135], v[10:13], v[108:111], 0
	v_mfma_f32_16x16x32_bf16 v[174:177], v[14:17], v[112:115], v[132:135]
	s_waitcnt lgkmcnt(3)
	v_mfma_f32_16x16x32_bf16 v[132:135], v[2:5], v[116:119], 0
	s_waitcnt lgkmcnt(1)
	v_mfma_f32_16x16x32_bf16 v[2:5], v[2:5], v[124:127], 0
	v_mfma_f32_16x16x32_bf16 v[178:181], v[6:9], v[120:123], v[132:135]
	s_waitcnt lgkmcnt(0)
	v_mfma_f32_16x16x32_bf16 v[2:5], v[6:9], v[128:131], v[2:5]
	v_mfma_f32_16x16x32_bf16 v[6:9], v[10:13], v[124:127], 0
	v_mfma_f32_16x16x32_bf16 v[132:135], v[10:13], v[116:119], 0
	v_mfma_f32_16x16x32_bf16 v[6:9], v[14:17], v[128:131], v[6:9]
	v_mfma_f32_16x16x32_bf16 v[184:187], v[14:17], v[120:123], v[132:135]
	s_nop 0
	s_nop 0
	v_mfma_f32_16x16x32_bf16 v[10:13], v[18:21], v[62:65], 0
	v_mfma_f32_16x16x32_bf16 v[188:191], v[22:25], v[94:97], v[10:13]
	v_mfma_f32_16x16x32_bf16 v[10:13], v[26:29], v[62:65], 0
	v_mfma_f32_16x16x32_bf16 v[192:195], v[30:33], v[94:97], v[10:13]
	v_mfma_f32_16x16x32_bf16 v[10:13], v[18:21], v[108:111], 0
	v_mfma_f32_16x16x32_bf16 v[196:199], v[22:25], v[112:115], v[10:13]
	v_mfma_f32_16x16x32_bf16 v[10:13], v[26:29], v[108:111], 0
	v_mfma_f32_16x16x32_bf16 v[200:203], v[30:33], v[112:115], v[10:13]
	v_mfma_f32_16x16x32_bf16 v[10:13], v[18:21], v[116:119], 0
	v_mfma_f32_16x16x32_bf16 v[204:207], v[22:25], v[120:123], v[10:13]
	v_mfma_f32_16x16x32_bf16 v[10:13], v[26:29], v[116:119], 0
	v_mfma_f32_16x16x32_bf16 v[208:211], v[30:33], v[120:123], v[10:13]
	v_mfma_f32_16x16x32_bf16 v[10:13], v[18:21], v[124:127], 0
	v_mfma_f32_16x16x32_bf16 v[20:23], v[22:25], v[128:131], v[10:13]
	v_mfma_f32_16x16x32_bf16 v[10:13], v[26:29], v[124:127], 0
	v_mfma_f32_16x16x32_bf16 v[24:27], v[30:33], v[128:131], v[10:13]
	s_nop 0
	s_barrier
	s_nop 4
	ds_read_b128 v[10:13], v168
	ds_read_b128 v[14:17], v168 offset:1024
	ds_read_b128 v[28:31], v168 offset:2048
	ds_read_b128 v[212:215], v168 offset:3072
	ds_read_b128 v[216:219], v169
	ds_read_b128 v[224:227], v169 offset:1024
	ds_read_b128 v[228:231], v169 offset:2048
	ds_read_b128 v[166:169], v169 offset:3072
	ds_read_b128 v[62:65], v165 offset:32768
	ds_read_b128 v[116:119], v165 offset:33792
	ds_read_b128 v[232:235], v165 offset:34816
	ds_read_b128 v[236:239], v165 offset:35840
	ds_read_b128 v[240:243], v165 offset:36864
	ds_read_b128 v[244:247], v165 offset:37888
	ds_read_b128 v[248:251], v165 offset:38912
	ds_read_b128 v[220:223], v165 offset:39936
	s_add_u32 s10, s24, 0x80100
	s_addc_u32 s11, s25, 0
	s_mov_b32 m0, s80
	s_nop 0
	global_load_lds_dwordx4 v158, s[10:11]
	s_nop 0
	s_mov_b32 m0, s81
	s_nop 0
	global_load_lds_dwordx4 v160, s[10:11]
	s_waitcnt vmcnt(24)
	s_waitcnt lgkmcnt(0)
	s_barrier
	s_nop 0
	s_waitcnt lgkmcnt(7)
	v_mfma_f32_16x16x32_bf16 v[66:69], v[10:13], v[62:65], v[66:69]
	s_waitcnt lgkmcnt(6)
	v_mfma_f32_16x16x32_bf16 v[144:147], v[14:17], v[116:119], v[66:69]
	v_mfma_f32_16x16x32_bf16 v[66:69], v[28:31], v[62:65], v[70:73]
	v_mfma_f32_16x16x32_bf16 v[140:143], v[212:215], v[116:119], v[66:69]
	s_waitcnt lgkmcnt(5)
	v_mfma_f32_16x16x32_bf16 v[66:69], v[10:13], v[232:235], v[74:77]
	s_waitcnt lgkmcnt(4)
	v_mfma_f32_16x16x32_bf16 v[128:131], v[14:17], v[236:239], v[66:69]
	v_mfma_f32_16x16x32_bf16 v[66:69], v[28:31], v[232:235], v[78:81]
	v_mfma_f32_16x16x32_bf16 v[124:127], v[212:215], v[236:239], v[66:69]
	s_waitcnt lgkmcnt(3)
	v_mfma_f32_16x16x32_bf16 v[66:69], v[10:13], v[240:243], v[82:85]
	s_waitcnt lgkmcnt(2)
	v_mfma_f32_16x16x32_bf16 v[112:115], v[14:17], v[244:247], v[66:69]
	v_mfma_f32_16x16x32_bf16 v[66:69], v[28:31], v[240:243], v[86:89]
	v_mfma_f32_16x16x32_bf16 v[108:111], v[212:215], v[244:247], v[66:69]
	s_waitcnt lgkmcnt(1)
	v_mfma_f32_16x16x32_bf16 v[66:69], v[10:13], v[248:251], v[90:93]
	s_waitcnt lgkmcnt(0)
	v_mfma_f32_16x16x32_bf16 v[96:99], v[14:17], v[220:223], v[66:69]
	v_mfma_f32_16x16x32_bf16 v[66:69], v[28:31], v[248:251], v[100:103]
	v_mfma_f32_16x16x32_bf16 v[92:95], v[212:215], v[220:223], v[66:69]
	s_nop 0
	s_nop 0
	v_mfma_f32_16x16x32_bf16 v[32:35], v[228:231], v[62:65], v[34:37]
	v_mfma_f32_16x16x32_bf16 v[132:135], v[166:169], v[116:119], v[32:35]
	v_mfma_f32_16x16x32_bf16 v[32:35], v[216:219], v[232:235], v[38:41]
	v_mfma_f32_16x16x32_bf16 v[66:69], v[216:219], v[62:65], v[104:107]
	v_mfma_f32_16x16x32_bf16 v[120:123], v[224:227], v[236:239], v[32:35]
	v_mfma_f32_16x16x32_bf16 v[32:35], v[228:231], v[232:235], v[42:45]
	v_mfma_f32_16x16x32_bf16 v[136:139], v[224:227], v[116:119], v[66:69]
	v_mfma_f32_16x16x32_bf16 v[116:119], v[166:169], v[236:239], v[32:35]
	v_mfma_f32_16x16x32_bf16 v[32:35], v[216:219], v[240:243], v[46:49]
	v_mfma_f32_16x16x32_bf16 v[104:107], v[224:227], v[244:247], v[32:35]
	v_mfma_f32_16x16x32_bf16 v[32:35], v[228:231], v[240:243], v[50:53]
	v_mfma_f32_16x16x32_bf16 v[100:103], v[166:169], v[244:247], v[32:35]
	v_mfma_f32_16x16x32_bf16 v[32:35], v[216:219], v[248:251], v[54:57]
	v_mfma_f32_16x16x32_bf16 v[88:91], v[224:227], v[220:223], v[32:35]
	v_mfma_f32_16x16x32_bf16 v[32:35], v[228:231], v[248:251], v[58:61]
	v_mfma_f32_16x16x32_bf16 v[84:87], v[166:169], v[220:223], v[32:35]
	s_nop 0
	s_barrier
	s_nop 4
	ds_read_b128 v[32:35], v165 offset:49152
	ds_read_b128 v[36:39], v165 offset:50176
	ds_read_b128 v[48:51], v165 offset:51200
	ds_read_b128 v[52:55], v165 offset:52224
	ds_read_b128 v[220:223], v165 offset:53248
	ds_read_b128 v[232:235], v165 offset:54272
	ds_read_b128 v[236:239], v165 offset:55296
	ds_read_b128 v[240:243], v165 offset:56320
	s_add_u32 s10, s26, 0x180
	s_addc_u32 s11, s27, 0
	s_mov_b32 m0, s91
	s_nop 0
	global_load_lds_dwordx4 v159, s[10:11]
	s_nop 0
	s_mov_b32 m0, s64
	s_nop 0
	global_load_lds_dwordx4 v161, s[10:11]
	s_add_u32 s10, s26, 0x80180
	s_addc_u32 s11, s27, 0
	s_mov_b32 m0, s67
	s_nop 0
	global_load_lds_dwordx4 v159, s[10:11]
	s_nop 0
	s_mov_b32 m0, s53
	s_nop 0
	global_load_lds_dwordx4 v161, s[10:11]
	s_nop 0
	s_mov_b32 m0, s33
	s_nop 0
	global_load_lds_dwordx4 v158, s[8:9]
	s_nop 0
	s_mov_b32 m0, s69
	s_nop 0
	global_load_lds_dwordx4 v160, s[8:9]
	s_waitcnt vmcnt(8)
	s_waitcnt lgkmcnt(0)
	s_barrier
	s_nop 0
	s_waitcnt lgkmcnt(7)
	v_mfma_f32_16x16x32_bf16 v[40:43], v[10:13], v[32:35], v[148:151]
	s_waitcnt lgkmcnt(6)
	v_mfma_f32_16x16x32_bf16 v[80:83], v[14:17], v[36:39], v[40:43]
	v_mfma_f32_16x16x32_bf16 v[40:43], v[28:31], v[32:35], v[152:155]
	v_mfma_f32_16x16x32_bf16 v[76:79], v[212:215], v[36:39], v[40:43]
	s_waitcnt lgkmcnt(5)
	v_mfma_f32_16x16x32_bf16 v[40:43], v[10:13], v[48:51], v[170:173]
	s_waitcnt lgkmcnt(4)
	v_mfma_f32_16x16x32_bf16 v[64:67], v[14:17], v[52:55], v[40:43]
	v_mfma_f32_16x16x32_bf16 v[40:43], v[28:31], v[48:51], v[174:177]
	v_mfma_f32_16x16x32_bf16 v[60:63], v[212:215], v[52:55], v[40:43]
	s_waitcnt lgkmcnt(3)
	v_mfma_f32_16x16x32_bf16 v[40:43], v[10:13], v[220:223], v[178:181]
	s_waitcnt lgkmcnt(1)
	v_mfma_f32_16x16x32_bf16 v[2:5], v[10:13], v[236:239], v[2:5]
	v_mfma_f32_16x16x32_bf16 v[44:47], v[14:17], v[232:235], v[40:43]
	v_mfma_f32_16x16x32_bf16 v[40:43], v[28:31], v[220:223], v[184:187]
	s_waitcnt lgkmcnt(0)
	v_mfma_f32_16x16x32_bf16 v[12:15], v[14:17], v[240:243], v[2:5]
	v_mfma_f32_16x16x32_bf16 v[2:5], v[28:31], v[236:239], v[6:9]
	v_mfma_f32_16x16x32_bf16 v[40:43], v[212:215], v[232:235], v[40:43]
	v_mfma_f32_16x16x32_bf16 v[16:19], v[212:215], v[240:243], v[2:5]
	s_nop 0
	s_nop 0
	v_mfma_f32_16x16x32_bf16 v[2:5], v[216:219], v[32:35], v[188:191]
	v_mfma_f32_16x16x32_bf16 v[72:75], v[224:227], v[36:39], v[2:5]
	v_mfma_f32_16x16x32_bf16 v[2:5], v[228:231], v[32:35], v[192:195]
	v_mfma_f32_16x16x32_bf16 v[68:71], v[166:169], v[36:39], v[2:5]
	v_mfma_f32_16x16x32_bf16 v[2:5], v[216:219], v[48:51], v[196:199]
	v_mfma_f32_16x16x32_bf16 v[56:59], v[224:227], v[52:55], v[2:5]
	v_mfma_f32_16x16x32_bf16 v[2:5], v[228:231], v[48:51], v[200:203]
	v_mfma_f32_16x16x32_bf16 v[52:55], v[166:169], v[52:55], v[2:5]
	v_mfma_f32_16x16x32_bf16 v[2:5], v[216:219], v[220:223], v[204:207]
	v_mfma_f32_16x16x32_bf16 v[32:35], v[224:227], v[232:235], v[2:5]
	v_mfma_f32_16x16x32_bf16 v[2:5], v[228:231], v[220:223], v[208:211]
	v_mfma_f32_16x16x32_bf16 v[28:31], v[166:169], v[232:235], v[2:5]
	v_mfma_f32_16x16x32_bf16 v[2:5], v[216:219], v[236:239], v[20:23]
	v_mfma_f32_16x16x32_bf16 v[8:11], v[228:231], v[236:239], v[24:27]
	v_mfma_f32_16x16x32_bf16 v[4:7], v[224:227], v[240:243], v[2:5]
	v_mfma_f32_16x16x32_bf16 v[8:11], v[166:169], v[240:243], v[8:11]
	s_nop 0
	s_barrier
	s_mov_b64 s[8:9], 0

; #define PG8_WAIT_V(n) asm volatile("s_waitcnt vmcnt(" #n ")" ::: "memory")
; template <class Epi, class Sched, bool ALIGN_EPI = false, bool SP2 = false>
; __device__ __forceinline__ void gemm_phase(PG8_LAS unsigned char* lds, const Gemm g, const Sched& S, const Epi& E) {
;     ...
;         for (int t = (DRO && ui > 0) ? 2 : 0; t < nt; t += 2) {
;             const bool last = (t == nt - 2);
;             const char* a1 = cA + (size_t)(t + 1) * kstep;
;             const char* a2 = last ? nA : cA + (size_t)(t + 2) * kstep; const char* b2 = last ? nB : cB + (size_t)(t + 2) * kstep;
;             const char* a3 = a2 + kstep; const char* b3 = b2 + kstep;
;             if (last && has_next) S.a_ready(nxt);
;             if constexpr (SP2) {
;             PG8_TRIP(true, PG8_WAIT_V(8));
.LBB0_290:
	v_add_u32_e32 v166, 0x10000, v164
	v_add_u32_e32 v167, 0x14000, v164
	ds_read_b128 v[20:23], v166
	ds_read_b128 v[24:27], v166 offset:1024
	ds_read_b128 v[36:39], v166 offset:2048
	ds_read_b128 v[48:51], v166 offset:3072
	ds_read_b128 v[148:151], v167
	ds_read_b128 v[152:155], v167 offset:1024
	ds_read_b128 v[168:171], v167 offset:2048
	ds_read_b128 v[172:175], v167 offset:3072
	s_add_u32 s30, s8, 0xfff80080
	s_addc_u32 s31, s9, -1
	s_cmp_eq_u32 s23, 28
	s_cselect_b32 s36, s11, s30
	s_cselect_b32 s37, s7, s31
	s_cselect_b32 s34, s21, s51
	s_cselect_b32 s35, s13, s57
	s_add_u32 s30, s36, 0x80
	s_addc_u32 s31, s37, 0
	ds_read_b128 v[176:179], v165
	ds_read_b128 v[184:187], v165 offset:1024
	ds_read_b128 v[188:191], v165 offset:2048
	ds_read_b128 v[192:195], v165 offset:3072
	ds_read_b128 v[196:199], v165 offset:4096
	ds_read_b128 v[200:203], v165 offset:5120
	ds_read_b128 v[204:207], v165 offset:6144
	ds_read_b128 v[208:211], v165 offset:7168
	s_mov_b32 m0, s52
	s_nop 0
	global_load_lds_dwordx4 v158, s[8:9]
	s_nop 0
	s_mov_b32 m0, s44
	s_nop 0
	global_load_lds_dwordx4 v160, s[8:9]
	s_waitcnt vmcnt(8)
	s_waitcnt lgkmcnt(0)
	s_barrier
	s_nop 0
	s_waitcnt lgkmcnt(7)
	v_mfma_f32_16x16x32_bf16 v[144:147], v[20:23], v[176:179], v[144:147]
	v_mfma_f32_16x16x32_bf16 v[140:143], v[36:39], v[176:179], v[140:143]
	s_waitcnt lgkmcnt(5)
	v_mfma_f32_16x16x32_bf16 v[128:131], v[20:23], v[188:191], v[128:131]
	v_mfma_f32_16x16x32_bf16 v[124:127], v[36:39], v[188:191], v[124:127]
	s_waitcnt lgkmcnt(3)
	v_mfma_f32_16x16x32_bf16 v[112:115], v[20:23], v[196:199], v[112:115]
	v_mfma_f32_16x16x32_bf16 v[108:111], v[36:39], v[196:199], v[108:111]
	s_waitcnt lgkmcnt(1)
	v_mfma_f32_16x16x32_bf16 v[96:99], v[20:23], v[204:207], v[96:99]
	v_mfma_f32_16x16x32_bf16 v[92:95], v[36:39], v[204:207], v[92:95]
	v_mfma_f32_16x16x32_bf16 v[144:147], v[24:27], v[184:187], v[144:147]
	v_mfma_f32_16x16x32_bf16 v[140:143], v[48:51], v[184:187], v[140:143]
	v_mfma_f32_16x16x32_bf16 v[128:131], v[24:27], v[192:195], v[128:131]
	v_mfma_f32_16x16x32_bf16 v[124:127], v[48:51], v[192:195], v[124:127]
	v_mfma_f32_16x16x32_bf16 v[112:115], v[24:27], v[200:203], v[112:115]
	v_mfma_f32_16x16x32_bf16 v[108:111], v[48:51], v[200:203], v[108:111]
	s_waitcnt lgkmcnt(0)
	v_mfma_f32_16x16x32_bf16 v[96:99], v[24:27], v[208:211], v[96:99]
	v_mfma_f32_16x16x32_bf16 v[92:95], v[48:51], v[208:211], v[92:95]
	s_nop 0
	s_nop 0
	v_mfma_f32_16x16x32_bf16 v[136:139], v[148:151], v[176:179], v[136:139]
	v_mfma_f32_16x16x32_bf16 v[132:135], v[168:171], v[176:179], v[132:135]
	v_mfma_f32_16x16x32_bf16 v[120:123], v[148:151], v[188:191], v[120:123]
	v_mfma_f32_16x16x32_bf16 v[116:119], v[168:171], v[188:191], v[116:119]
	v_mfma_f32_16x16x32_bf16 v[104:107], v[148:151], v[196:199], v[104:107]
	v_mfma_f32_16x16x32_bf16 v[100:103], v[168:171], v[196:199], v[100:103]
	v_mfma_f32_16x16x32_bf16 v[88:91], v[148:151], v[204:207], v[88:91]
	v_mfma_f32_16x16x32_bf16 v[84:87], v[168:171], v[204:207], v[84:87]
	v_mfma_f32_16x16x32_bf16 v[136:139], v[152:155], v[184:187], v[136:139]
	v_mfma_f32_16x16x32_bf16 v[132:135], v[172:175], v[184:187], v[132:135]
	v_mfma_f32_16x16x32_bf16 v[120:123], v[152:155], v[192:195], v[120:123]
	v_mfma_f32_16x16x32_bf16 v[116:119], v[172:175], v[192:195], v[116:119]
	v_mfma_f32_16x16x32_bf16 v[104:107], v[152:155], v[200:203], v[104:107]
	v_mfma_f32_16x16x32_bf16 v[100:103], v[172:175], v[200:203], v[100:103]
	v_mfma_f32_16x16x32_bf16 v[88:91], v[152:155], v[208:211], v[88:91]
	v_mfma_f32_16x16x32_bf16 v[84:87], v[172:175], v[208:211], v[84:87]
	s_nop 0
	s_barrier
	ds_read_b128 v[176:179], v165 offset:16384
	ds_read_b128 v[184:187], v165 offset:17408
	ds_read_b128 v[188:191], v165 offset:18432
	ds_read_b128 v[192:195], v165 offset:19456
	ds_read_b128 v[196:199], v165 offset:20480
	ds_read_b128 v[200:203], v165 offset:21504
	ds_read_b128 v[204:207], v165 offset:22528
	ds_read_b128 v[208:211], v165 offset:23552
	s_mov_b32 m0, s41
	s_nop 0
	global_load_lds_dwordx4 v159, s[34:35]
	s_add_u32 s88, s34, 0x80000
	s_mov_b32 m0, s48
	s_nop 0
	global_load_lds_dwordx4 v161, s[34:35]
	s_addc_u32 s89, s35, 0
	s_mov_b32 m0, s49
	s_nop 0
	global_load_lds_dwordx4 v159, s[88:89]
	s_nop 0
	s_mov_b32 m0, s78
	s_nop 0
	global_load_lds_dwordx4 v161, s[88:89]
	s_nop 0
	s_mov_b32 m0, s40
	s_nop 0
	global_load_lds_dwordx4 v158, s[36:37]
	s_nop 0
	s_mov_b32 m0, s79
	s_nop 0
	global_load_lds_dwordx4 v160, s[36:37]
	s_waitcnt vmcnt(8)
	s_waitcnt lgkmcnt(0)
	s_barrier
	s_nop 0
	s_waitcnt lgkmcnt(7)
	v_mfma_f32_16x16x32_bf16 v[80:83], v[20:23], v[176:179], v[80:83]
	v_mfma_f32_16x16x32_bf16 v[76:79], v[36:39], v[176:179], v[76:79]
	s_waitcnt lgkmcnt(5)
	v_mfma_f32_16x16x32_bf16 v[64:67], v[20:23], v[188:191], v[64:67]
	v_mfma_f32_16x16x32_bf16 v[60:63], v[36:39], v[188:191], v[60:63]
	s_waitcnt lgkmcnt(3)
	v_mfma_f32_16x16x32_bf16 v[44:47], v[20:23], v[196:199], v[44:47]
	v_mfma_f32_16x16x32_bf16 v[40:43], v[36:39], v[196:199], v[40:43]
	s_waitcnt lgkmcnt(1)
	v_mfma_f32_16x16x32_bf16 v[12:15], v[20:23], v[204:207], v[12:15]
	v_mfma_f32_16x16x32_bf16 v[16:19], v[36:39], v[204:207], v[16:19]
	v_mfma_f32_16x16x32_bf16 v[80:83], v[24:27], v[184:187], v[80:83]
	v_mfma_f32_16x16x32_bf16 v[76:79], v[48:51], v[184:187], v[76:79]
	v_mfma_f32_16x16x32_bf16 v[64:67], v[24:27], v[192:195], v[64:67]
	v_mfma_f32_16x16x32_bf16 v[60:63], v[48:51], v[192:195], v[60:63]
	v_mfma_f32_16x16x32_bf16 v[44:47], v[24:27], v[200:203], v[44:47]
	v_mfma_f32_16x16x32_bf16 v[40:43], v[48:51], v[200:203], v[40:43]
	s_waitcnt lgkmcnt(0)
	v_mfma_f32_16x16x32_bf16 v[12:15], v[24:27], v[208:211], v[12:15]
	v_mfma_f32_16x16x32_bf16 v[16:19], v[48:51], v[208:211], v[16:19]
	s_nop 0
	s_nop 0
	v_mfma_f32_16x16x32_bf16 v[32:35], v[148:151], v[196:199], v[32:35]
	v_mfma_f32_16x16x32_bf16 v[28:31], v[168:171], v[196:199], v[28:31]
	v_mfma_f32_16x16x32_bf16 v[2:5], v[148:151], v[204:207], v[4:7]
	v_mfma_f32_16x16x32_bf16 v[6:9], v[168:171], v[204:207], v[8:11]
	v_mfma_f32_16x16x32_bf16 v[20:23], v[148:151], v[176:179], v[72:75]
	v_mfma_f32_16x16x32_bf16 v[24:27], v[168:171], v[176:179], v[68:71]
	v_mfma_f32_16x16x32_bf16 v[36:39], v[148:151], v[188:191], v[56:59]
	v_mfma_f32_16x16x32_bf16 v[48:51], v[168:171], v[188:191], v[52:55]
	v_mfma_f32_16x16x32_bf16 v[32:35], v[152:155], v[200:203], v[32:35]
	v_mfma_f32_16x16x32_bf16 v[28:31], v[172:175], v[200:203], v[28:31]
	v_mfma_f32_16x16x32_bf16 v[2:5], v[152:155], v[208:211], v[2:5]
	v_mfma_f32_16x16x32_bf16 v[8:11], v[172:175], v[208:211], v[6:9]
	v_mfma_f32_16x16x32_bf16 v[20:23], v[152:155], v[184:187], v[20:23]
	v_mfma_f32_16x16x32_bf16 v[24:27], v[172:175], v[184:187], v[24:27]
	v_mfma_f32_16x16x32_bf16 v[36:39], v[152:155], v[192:195], v[36:39]
	v_mfma_f32_16x16x32_bf16 v[48:51], v[172:175], v[192:195], v[48:51]
	s_nop 0
	s_barrier
	v_add_u32_e32 v168, 0x18000, v164
	v_add_u32_e32 v169, 0x1c000, v164
	ds_read_b128 v[52:55], v168
	ds_read_b128 v[56:59], v168 offset:1024
	ds_read_b128 v[68:71], v168 offset:2048
	ds_read_b128 v[72:75], v168 offset:3072
	ds_read_b128 v[148:151], v169
	ds_read_b128 v[152:155], v169 offset:1024
	ds_read_b128 v[170:173], v169 offset:2048
	ds_read_b128 v[174:177], v169 offset:3072
	ds_read_b128 v[178:181], v165 offset:32768
	ds_read_b128 v[184:187], v165 offset:33792
	ds_read_b128 v[188:191], v165 offset:34816
	ds_read_b128 v[192:195], v165 offset:35840
	ds_read_b128 v[196:199], v165 offset:36864
	ds_read_b128 v[200:203], v165 offset:37888
	ds_read_b128 v[204:207], v165 offset:38912
	ds_read_b128 v[208:211], v165 offset:39936
	s_add_u32 s36, s36, 0x80000
	s_addc_u32 s37, s37, 0
	s_mov_b32 m0, s80
	s_nop 0
	global_load_lds_dwordx4 v158, s[36:37]
	s_nop 0
	s_mov_b32 m0, s81
	s_nop 0
	global_load_lds_dwordx4 v160, s[36:37]
	s_waitcnt vmcnt(8)
	s_waitcnt lgkmcnt(0)
	s_barrier
	s_nop 0
	s_waitcnt lgkmcnt(7)
	v_mfma_f32_16x16x32_bf16 v[144:147], v[52:55], v[178:181], v[144:147]
	v_mfma_f32_16x16x32_bf16 v[140:143], v[68:71], v[178:181], v[140:143]
	s_waitcnt lgkmcnt(5)
	v_mfma_f32_16x16x32_bf16 v[128:131], v[52:55], v[188:191], v[128:131]
	v_mfma_f32_16x16x32_bf16 v[124:127], v[68:71], v[188:191], v[124:127]
	s_waitcnt lgkmcnt(3)
	v_mfma_f32_16x16x32_bf16 v[112:115], v[52:55], v[196:199], v[112:115]
	v_mfma_f32_16x16x32_bf16 v[108:111], v[68:71], v[196:199], v[108:111]
	s_waitcnt lgkmcnt(1)
	v_mfma_f32_16x16x32_bf16 v[96:99], v[52:55], v[204:207], v[96:99]
	v_mfma_f32_16x16x32_bf16 v[92:95], v[68:71], v[204:207], v[92:95]
	v_mfma_f32_16x16x32_bf16 v[144:147], v[56:59], v[184:187], v[144:147]
	v_mfma_f32_16x16x32_bf16 v[140:143], v[72:75], v[184:187], v[140:143]
	v_mfma_f32_16x16x32_bf16 v[128:131], v[56:59], v[192:195], v[128:131]
	v_mfma_f32_16x16x32_bf16 v[124:127], v[72:75], v[192:195], v[124:127]
	v_mfma_f32_16x16x32_bf16 v[112:115], v[56:59], v[200:203], v[112:115]
	v_mfma_f32_16x16x32_bf16 v[108:111], v[72:75], v[200:203], v[108:111]
	s_waitcnt lgkmcnt(0)
	v_mfma_f32_16x16x32_bf16 v[96:99], v[56:59], v[208:211], v[96:99]
	v_mfma_f32_16x16x32_bf16 v[92:95], v[72:75], v[208:211], v[92:95]
	s_nop 0
	s_nop 0
	v_mfma_f32_16x16x32_bf16 v[136:139], v[148:151], v[178:181], v[136:139]
	v_mfma_f32_16x16x32_bf16 v[132:135], v[170:173], v[178:181], v[132:135]
	v_mfma_f32_16x16x32_bf16 v[120:123], v[148:151], v[188:191], v[120:123]
	v_mfma_f32_16x16x32_bf16 v[116:119], v[170:173], v[188:191], v[116:119]
	v_mfma_f32_16x16x32_bf16 v[104:107], v[148:151], v[196:199], v[104:107]
	v_mfma_f32_16x16x32_bf16 v[100:103], v[170:173], v[196:199], v[100:103]
	v_mfma_f32_16x16x32_bf16 v[88:91], v[148:151], v[204:207], v[88:91]
	v_mfma_f32_16x16x32_bf16 v[84:87], v[170:173], v[204:207], v[84:87]
	v_mfma_f32_16x16x32_bf16 v[136:139], v[152:155], v[184:187], v[136:139]
	v_mfma_f32_16x16x32_bf16 v[132:135], v[174:177], v[184:187], v[132:135]
	v_mfma_f32_16x16x32_bf16 v[120:123], v[152:155], v[192:195], v[120:123]
	v_mfma_f32_16x16x32_bf16 v[116:119], v[174:177], v[192:195], v[116:119]
	v_mfma_f32_16x16x32_bf16 v[104:107], v[152:155], v[200:203], v[104:107]
	v_mfma_f32_16x16x32_bf16 v[100:103], v[174:177], v[200:203], v[100:103]
	v_mfma_f32_16x16x32_bf16 v[88:91], v[152:155], v[208:211], v[88:91]
	v_mfma_f32_16x16x32_bf16 v[84:87], v[174:177], v[208:211], v[84:87]
	s_nop 0
	s_barrier
;     __host__ __device__ bool next(int i, Unit& u) const { return StaticOrder::next(i >> 1, u); }
;     __device__ __forceinline__ bool next(int i, Unit& u) const { const int s = i * G + c; if (s >= 128) return false; const int t = s >> 2; u.pm = pm0 + (t & 3); u.pn = t >> 2; u.k0 = (s & 3) * ksub; return true; }
; #define PG8_STAGE(bufoff, gbase, voff) do { _Pragma("unroll") for (int _i = 0; _i < 2; ++_i) { \
;         const unsigned m0_ = ldsbase + (unsigned)(bufoff) + ldsw + (unsigned)_i * 8192u; \
;         asm volatile("s_mov_b32 m0, %2\n\ts_nop 0\n\tglobal_load_lds_dwordx4 %0, %1" :: "v"((voff)[_i]), "s"((const char*)(gbase)), "s"(m0_) : "memory", "m0"); } } while (0)
; template <class Epi, class Sched, bool ALIGN_EPI = false, bool SP2 = false>
; __device__ __forceinline__ void gemm_phase(PG8_LAS unsigned char* lds, const Gemm g, const Sched& S, const Epi& E) {
;     ...
;     for (;;) {
;         const bool has_next = S.next(ui + 1, nxt);
;         const char* nA = has_next ? (const char*)g.A + (size_t)nxt.pm * tsA + (size_t)nxt.k0 * 2 : cA; const char* nB = has_next ? (const char*)g.Bt + (size_t)nxt.pn * tsB + (size_t)nxt.k0 * 2 : cB;
;         for (int t = (DRO && ui > 0) ? 2 : 0; t < nt; t += 2) {
;     ...
;         if constexpr (DRO) { asm volatile("" ::: "memory"); PG8_STAGE(PG8_SA(1, 1), nA + kstep + hsA, voffA); asm volatile("" ::: "memory"); }
	ds_read_b128 v[178:181], v165 offset:49152
	ds_read_b128 v[184:187], v165 offset:50176
	ds_read_b128 v[188:191], v165 offset:51200
	ds_read_b128 v[192:195], v165 offset:52224
	ds_read_b128 v[196:199], v165 offset:53248
	ds_read_b128 v[200:203], v165 offset:54272
	ds_read_b128 v[204:207], v165 offset:55296
	ds_read_b128 v[208:211], v165 offset:56320
	s_add_u32 s36, s34, 0x80
	s_addc_u32 s37, s35, 0
	s_mov_b32 m0, s91
	s_nop 0
	global_load_lds_dwordx4 v159, s[36:37]
	s_add_u32 s34, s34, 0x80080
	s_mov_b32 m0, s64
	s_nop 0
	global_load_lds_dwordx4 v161, s[36:37]
	s_addc_u32 s35, s35, 0
	s_mov_b32 m0, s67
	s_nop 0
	global_load_lds_dwordx4 v159, s[34:35]
	s_nop 0
	s_mov_b32 m0, s53
	s_nop 0
	global_load_lds_dwordx4 v161, s[34:35]
	s_nop 0
	s_mov_b32 m0, s33
	s_nop 0
	global_load_lds_dwordx4 v158, s[30:31]
	s_nop 0
	s_mov_b32 m0, s69
	s_nop 0
	global_load_lds_dwordx4 v160, s[30:31]
	s_waitcnt vmcnt(8)
	s_waitcnt lgkmcnt(0)
	s_barrier
	s_nop 0
	s_waitcnt lgkmcnt(7)
	v_mfma_f32_16x16x32_bf16 v[80:83], v[52:55], v[178:181], v[80:83]
	v_mfma_f32_16x16x32_bf16 v[76:79], v[68:71], v[178:181], v[76:79]
	s_waitcnt lgkmcnt(5)
	v_mfma_f32_16x16x32_bf16 v[64:67], v[52:55], v[188:191], v[64:67]
	v_mfma_f32_16x16x32_bf16 v[60:63], v[68:71], v[188:191], v[60:63]
	s_waitcnt lgkmcnt(3)
	v_mfma_f32_16x16x32_bf16 v[44:47], v[52:55], v[196:199], v[44:47]
	v_mfma_f32_16x16x32_bf16 v[40:43], v[68:71], v[196:199], v[40:43]
	s_waitcnt lgkmcnt(1)
	v_mfma_f32_16x16x32_bf16 v[12:15], v[52:55], v[204:207], v[12:15]
	v_mfma_f32_16x16x32_bf16 v[16:19], v[68:71], v[204:207], v[16:19]
	v_mfma_f32_16x16x32_bf16 v[80:83], v[56:59], v[184:187], v[80:83]
	v_mfma_f32_16x16x32_bf16 v[76:79], v[72:75], v[184:187], v[76:79]
	v_mfma_f32_16x16x32_bf16 v[64:67], v[56:59], v[192:195], v[64:67]
	v_mfma_f32_16x16x32_bf16 v[60:63], v[72:75], v[192:195], v[60:63]
	v_mfma_f32_16x16x32_bf16 v[44:47], v[56:59], v[200:203], v[44:47]
	v_mfma_f32_16x16x32_bf16 v[40:43], v[72:75], v[200:203], v[40:43]
	s_waitcnt lgkmcnt(0)
	v_mfma_f32_16x16x32_bf16 v[12:15], v[56:59], v[208:211], v[12:15]
	v_mfma_f32_16x16x32_bf16 v[16:19], v[72:75], v[208:211], v[16:19]
	s_nop 0
	s_nop 0
	v_mfma_f32_16x16x32_bf16 v[20:23], v[148:151], v[178:181], v[20:23]
	v_mfma_f32_16x16x32_bf16 v[72:75], v[152:155], v[184:187], v[20:23]
	v_mfma_f32_16x16x32_bf16 v[20:23], v[170:173], v[178:181], v[24:27]
	v_mfma_f32_16x16x32_bf16 v[68:71], v[174:177], v[184:187], v[20:23]
	v_mfma_f32_16x16x32_bf16 v[20:23], v[148:151], v[188:191], v[36:39]
	v_mfma_f32_16x16x32_bf16 v[56:59], v[152:155], v[192:195], v[20:23]
	v_mfma_f32_16x16x32_bf16 v[20:23], v[170:173], v[188:191], v[48:51]
	v_mfma_f32_16x16x32_bf16 v[52:55], v[174:177], v[192:195], v[20:23]
	v_mfma_f32_16x16x32_bf16 v[20:23], v[148:151], v[196:199], v[32:35]
	v_mfma_f32_16x16x32_bf16 v[32:35], v[152:155], v[200:203], v[20:23]
	v_mfma_f32_16x16x32_bf16 v[20:23], v[170:173], v[196:199], v[28:31]
	v_mfma_f32_16x16x32_bf16 v[2:5], v[148:151], v[204:207], v[2:5]
	v_mfma_f32_16x16x32_bf16 v[8:11], v[170:173], v[204:207], v[8:11]
	v_mfma_f32_16x16x32_bf16 v[28:31], v[174:177], v[200:203], v[20:23]
	v_mfma_f32_16x16x32_bf16 v[4:7], v[152:155], v[208:211], v[2:5]
	v_mfma_f32_16x16x32_bf16 v[8:11], v[174:177], v[208:211], v[8:11]
	s_nop 0
	s_barrier
	s_add_i32 s23, s23, 2
	s_add_u32 s51, s51, 0x100
	s_addc_u32 s57, s57, 0
	s_add_u32 s8, s8, 0x100
	s_addc_u32 s9, s9, 0
	s_cmp_gt_u32 s23, 29
	s_cbranch_scc0 .LBB0_290
	s_add_u32 s8, s11, 0x80080
	s_addc_u32 s9, s7, 0
	s_mov_b32 m0, s52
	s_nop 0
	global_load_lds_dwordx4 v158, s[8:9]
	s_and_b64 vcc, exec, s[18:19]
	s_mov_b32 m0, s44
	s_nop 0
	global_load_lds_dwordx4 v160, s[8:9]
	s_cbranch_vccz .LBB0_293
	s_barrier

; #define PG8_BAR __builtin_amdgcn_s_barrier()
; template <class Epi, class Sched, bool ALIGN_EPI = false, bool SP2 = false>
; __device__ __forceinline__ void gemm_phase(PG8_LAS unsigned char* lds, const Gemm g, const Sched& S, const Epi& E) {
;     ...
;     for (int i = 0; i < 2; ++i) { int R, C; stage_rc(tid * 16 + i * 8192, R, C); const int Rb = Epi::PERM ? ((R & ~31) + perm32(R & 31)) : R;
;         voffA[i] = (unsigned)(R * g.lda + C) * 2u; voffB[i] = (unsigned)(Rb * g.ldb + C) * 2u; }
;     const size_t kstep = (size_t)(BK * 2);
;     const size_t hsA = (size_t)HALF * g.lda * 2, hsB = (size_t)HALF * g.ldb * 2;
;     const size_t tsA = 2 * hsA, tsB = 2 * hsB;
;     const unsigned ldsbase = (unsigned)(unsigned long long)lds;
;     const unsigned ldsw = (unsigned)wid * 1024u;
;     const int aoff = lds_byte(wr * 64 + fr, fq * 8), boff = lds_byte(wc * 32 + fr, fq * 8);
;     ...
;     Unit cur, nxt; int ui = 0; bool epi_ran = false;
;     if (!S.next(0, cur)) return;
;     f32x4 acc[2][2][4][2];
; #pragma unroll
;     for (int a = 0; a < 2; ++a)
; #pragma unroll
;         for (int b = 0; b < 2; ++b)
; #pragma unroll
;             for (int m = 0; m < 4; ++m)
; #pragma unroll
;                 for (int n = 0; n < 2; ++n) acc[a][b][m][n] = (f32x4){0.f, 0.f, 0.f, 0.f};
;     bf16x8 At[4][2], B0[2][2], B1[2][2];
;     const char* cA = (const char*)g.A + (size_t)cur.pm * tsA + (size_t)cur.k0 * 2; const char* cB = (const char*)g.Bt + (size_t)cur.pn * tsB + (size_t)cur.k0 * 2;
;     S.a_ready(cur);
;     if constexpr (SP2) {
;         PG8_STAGE(PG8_SB(0, 0), cB, voffB); PG8_STAGE(PG8_SB(0, 1), cB + hsB, voffB); PG8_STAGE(PG8_SA(0, 0), cA, voffA); PG8_STAGE(PG8_SA(0, 1), cA + hsA, voffA);
;         if (wr == 1) PG8_BAR;
;         PG8_WAIT_V(2); PG8_BAR;
;         PG8_STAGE(PG8_SB(1, 0), cB + kstep, voffB); PG8_STAGE(PG8_SA(1, 0), cA + kstep, voffA); PG8_STAGE(PG8_SB(1, 1), cB + hsB + kstep, voffB);
;         PG8_WAIT_V(6); PG8_BAR;
;     } else {
;         PG8_STAGE(PG8_SB(0, 0), cB, voffB); PG8_STAGE(PG8_SA(0, 0), cA, voffA); PG8_STAGE(PG8_SB(0, 1), cB + hsB, voffB); PG8_STAGE(PG8_SA(0, 1), cA + hsA, voffA);
;         if (wr == 1) PG8_BAR;
;         PG8_WAIT_V(4); PG8_BAR;
;         PG8_STAGE(PG8_SB(1, 0), cB + kstep, voffB); PG8_STAGE(PG8_SA(1, 0), cA + kstep, voffA); PG8_STAGE(PG8_SB(1, 1), cB + hsB + kstep, voffB);
;         PG8_WAIT_V(6); PG8_BAR;
;     }
.LBB0_638:
	v_bfe_u32 v175, v0, 4, 2
	s_add_u32 s12, s72, 0x204000
	v_and_b32_e32 v174, 15, v0
	v_lshlrev_b32_e32 v2, 4, v175
	v_lshlrev_b32_e32 v0, 2, v0
	s_addc_u32 s13, s73, 0
	s_and_b32 s9, s14, 3
	v_lshl_or_b32 v2, v174, 6, v2
	s_lshl_b32 s14, s15, 13
	v_and_b32_e32 v0, 32, v0
	s_lshl_b32 s69, s15, 6
	v_bitop3_b32 v4, v2, s14, v0 bitop3:0xde
	s_lshl_b32 s78, s9, 5
	s_lshl_b32 s14, s9, 12
	v_bitop3_b32 v5, v2, s14, v0 bitop3:0xde
	s_add_u32 s14, s72, 0x200000
	s_addc_u32 s15, s73, 0
	s_add_i32 s79, s33, 0x18000
	s_add_u32 s18, s6, 0x80
	s_waitcnt vmcnt(2)
	s_barrier
	s_addc_u32 s19, s7, 0
	s_mov_b32 m0, s79
	s_nop 0
	global_load_lds_dwordx4 v171, s[18:19]
	s_add_i32 s82, s33, 0x1a000
	s_add_i32 s84, s33, 0x8000
	s_mov_b32 m0, s82
	s_nop 0
	global_load_lds_dwordx4 v173, s[18:19]
	s_add_u32 s18, s30, 0x80
	s_addc_u32 s19, s31, 0
	s_mov_b32 m0, s84
	s_nop 0
	global_load_lds_dwordx4 v170, s[18:19]
	s_add_i32 s91, s33, 0xa000
	s_add_i32 s80, s33, 0x1c000
	s_mov_b32 m0, s91
	s_nop 0
	global_load_lds_dwordx4 v172, s[18:19]
	s_add_u32 s18, s6, 0x80080
	s_addc_u32 s19, s7, 0
	s_mov_b32 m0, s80
	s_nop 0
	global_load_lds_dwordx4 v171, s[18:19]
	s_add_i32 s81, s33, 0x1e000
	s_add_i32 s83, s33, 0xc000
	s_mov_b32 m0, s81
	s_nop 0
	global_load_lds_dwordx4 v173, s[18:19]
	s_cmpk_lt_u32 s16, 0x100
	s_waitcnt vmcnt(6)
	s_cselect_b64 s[16:17], -1, 0
	s_and_b32 s51, s78, 32
	v_mov_b32_e32 v2, v1
	v_mov_b32_e32 v3, v1
	s_cmp_gt_u32 s9, 1
	v_mov_b32_e32 v0, v1
	v_add_u32_e32 v176, 0, v5
	v_add_u32_e32 v177, 0, v4
	v_mov_b64_e32 v[14:15], v[2:3]
	v_mov_b64_e32 v[18:19], v[2:3]
	v_mov_b64_e32 v[30:31], v[2:3]
	v_mov_b64_e32 v[34:35], v[2:3]
	v_mov_b64_e32 v[46:47], v[2:3]
	v_mov_b64_e32 v[50:51], v[2:3]
	v_mov_b64_e32 v[62:63], v[2:3]
	v_mov_b64_e32 v[66:67], v[2:3]
	v_mov_b64_e32 v[6:7], v[2:3]
	v_mov_b64_e32 v[10:11], v[2:3]
	v_mov_b64_e32 v[22:23], v[2:3]
	v_mov_b64_e32 v[26:27], v[2:3]
	v_mov_b64_e32 v[38:39], v[2:3]
	v_mov_b64_e32 v[42:43], v[2:3]
	v_mov_b64_e32 v[54:55], v[2:3]
	v_mov_b64_e32 v[58:59], v[2:3]
	v_mov_b64_e32 v[78:79], v[2:3]
	v_mov_b64_e32 v[82:83], v[2:3]
	v_mov_b64_e32 v[94:95], v[2:3]
	v_mov_b64_e32 v[98:99], v[2:3]
	v_mov_b64_e32 v[110:111], v[2:3]
	v_mov_b64_e32 v[114:115], v[2:3]
	v_mov_b64_e32 v[126:127], v[2:3]
	v_mov_b64_e32 v[130:131], v[2:3]
	v_mov_b64_e32 v[70:71], v[2:3]
	v_mov_b64_e32 v[74:75], v[2:3]
	v_mov_b64_e32 v[86:87], v[2:3]
	v_mov_b64_e32 v[90:91], v[2:3]
	v_mov_b64_e32 v[102:103], v[2:3]
	v_mov_b64_e32 v[106:107], v[2:3]
	v_mov_b64_e32 v[118:119], v[2:3]
	v_mov_b64_e32 v[122:123], v[2:3]
	s_cselect_b64 s[18:19], -1, 0
	s_add_i32 s57, s33, 0xe000
	s_mov_b32 s36, 0
	v_mov_b64_e32 v[12:13], v[0:1]
	v_mov_b64_e32 v[16:17], v[0:1]
	v_mov_b64_e32 v[28:29], v[0:1]
	v_mov_b64_e32 v[32:33], v[0:1]
	v_mov_b64_e32 v[44:45], v[0:1]
	v_mov_b64_e32 v[48:49], v[0:1]
	v_mov_b64_e32 v[60:61], v[0:1]
	v_mov_b64_e32 v[64:65], v[0:1]
	v_mov_b64_e32 v[4:5], v[0:1]
	v_mov_b64_e32 v[8:9], v[0:1]
	v_mov_b64_e32 v[20:21], v[0:1]
	v_mov_b64_e32 v[24:25], v[0:1]
	v_mov_b64_e32 v[36:37], v[0:1]
	v_mov_b64_e32 v[40:41], v[0:1]
	v_mov_b64_e32 v[52:53], v[0:1]
	v_mov_b64_e32 v[56:57], v[0:1]
	v_mov_b64_e32 v[76:77], v[0:1]
	v_mov_b64_e32 v[80:81], v[0:1]
	v_mov_b64_e32 v[92:93], v[0:1]
	v_mov_b64_e32 v[96:97], v[0:1]
	v_mov_b64_e32 v[108:109], v[0:1]
	v_mov_b64_e32 v[112:113], v[0:1]
	v_mov_b64_e32 v[124:125], v[0:1]
	v_mov_b64_e32 v[128:129], v[0:1]
	v_mov_b64_e32 v[68:69], v[0:1]
	v_mov_b64_e32 v[72:73], v[0:1]
	v_mov_b64_e32 v[84:85], v[0:1]
	v_mov_b64_e32 v[88:89], v[0:1]
	v_mov_b64_e32 v[100:101], v[0:1]
	v_mov_b64_e32 v[104:105], v[0:1]
	v_mov_b64_e32 v[116:117], v[0:1]
	v_mov_b64_e32 v[120:121], v[0:1]
	s_barrier
	s_getreg_b32 s100, hwreg(HW_REG_HW_ID, 0, 6)
	s_lshl_b32 s100, s100, 2
	s_add_i32 s100, s100, 0x20540
	v_mov_b32_e32 v251, s100
	ds_read_b32 v251, v251
	s_waitcnt lgkmcnt(0)
	v_readfirstlane_b32 s100, v251
	s_cmp_ge_u32 s100, 4
	s_cbranch_scc0 statprio_skip1
	s_setprio 1
statprio_skip1:
	s_branch .LBB0_641
.LBB0_639:
	ds_read_b128 v[2:5], v184
	ds_read_b128 v[6:9], v184 offset:1024
	ds_read_b128 v[10:13], v184 offset:2048
	ds_read_b128 v[14:17], v184 offset:3072
	ds_read_b128 v[18:21], v185
	ds_read_b128 v[22:25], v185 offset:1024
	ds_read_b128 v[26:29], v185 offset:2048
	ds_read_b128 v[30:33], v185 offset:3072
	s_add_u32 s8, s24, 0x100
	s_addc_u32 s9, s25, 0
	s_add_u32 s6, s24, 0x180
	s_addc_u32 s7, s25, 0
	s_add_u32 s28, s26, 0x100
	s_addc_u32 s29, s27, 0
	ds_read_b128 v[34:37], v177
	ds_read_b128 v[38:41], v177 offset:1024
	ds_read_b128 v[42:45], v177 offset:2048
	ds_read_b128 v[46:49], v177 offset:3072
	ds_read_b128 v[50:53], v177 offset:4096
	ds_read_b128 v[54:57], v177 offset:5120
	ds_read_b128 v[58:61], v177 offset:6144
	ds_read_b128 v[62:65], v177 offset:7168
	s_waitcnt vmcnt(24)
	s_waitcnt lgkmcnt(0)
	s_barrier
	s_nop 0
	s_waitcnt lgkmcnt(3)
	v_mfma_f32_16x16x32_bf16 v[86:89], v[10:13], v[50:53], 0
	s_waitcnt lgkmcnt(2)
	v_mfma_f32_16x16x32_bf16 v[92:95], v[14:17], v[54:57], v[86:89]
	s_waitcnt lgkmcnt(1)
	v_mfma_f32_16x16x32_bf16 v[86:89], v[2:5], v[58:61], 0
	v_mfma_f32_16x16x32_bf16 v[66:69], v[2:5], v[34:37], 0
	v_mfma_f32_16x16x32_bf16 v[70:73], v[10:13], v[34:37], 0
	v_mfma_f32_16x16x32_bf16 v[74:77], v[2:5], v[42:45], 0
	v_mfma_f32_16x16x32_bf16 v[78:81], v[10:13], v[42:45], 0
	v_mfma_f32_16x16x32_bf16 v[82:85], v[2:5], v[50:53], 0
	s_waitcnt lgkmcnt(0)
	v_mfma_f32_16x16x32_bf16 v[96:99], v[6:9], v[62:65], v[86:89]
	v_mfma_f32_16x16x32_bf16 v[86:89], v[10:13], v[58:61], 0
	v_mfma_f32_16x16x32_bf16 v[66:69], v[6:9], v[38:41], v[66:69]
	v_mfma_f32_16x16x32_bf16 v[70:73], v[14:17], v[38:41], v[70:73]
	v_mfma_f32_16x16x32_bf16 v[74:77], v[6:9], v[46:49], v[74:77]
	v_mfma_f32_16x16x32_bf16 v[78:81], v[14:17], v[46:49], v[78:81]
	v_mfma_f32_16x16x32_bf16 v[82:85], v[6:9], v[54:57], v[82:85]
	v_mfma_f32_16x16x32_bf16 v[108:111], v[14:17], v[62:65], v[86:89]
	s_nop 0
	s_nop 0
	v_mfma_f32_16x16x32_bf16 v[86:89], v[18:21], v[34:37], 0
	v_mfma_f32_16x16x32_bf16 v[34:37], v[26:29], v[34:37], 0
	v_mfma_f32_16x16x32_bf16 v[112:115], v[22:25], v[38:41], v[86:89]
	v_mfma_f32_16x16x32_bf16 v[34:37], v[30:33], v[38:41], v[34:37]
	v_mfma_f32_16x16x32_bf16 v[38:41], v[18:21], v[42:45], 0
	v_mfma_f32_16x16x32_bf16 v[42:45], v[26:29], v[42:45], 0
	v_mfma_f32_16x16x32_bf16 v[38:41], v[22:25], v[46:49], v[38:41]
	v_mfma_f32_16x16x32_bf16 v[42:45], v[30:33], v[46:49], v[42:45]
	v_mfma_f32_16x16x32_bf16 v[46:49], v[18:21], v[50:53], 0
	v_mfma_f32_16x16x32_bf16 v[50:53], v[26:29], v[50:53], 0
	v_mfma_f32_16x16x32_bf16 v[46:49], v[22:25], v[54:57], v[46:49]
	v_mfma_f32_16x16x32_bf16 v[50:53], v[30:33], v[54:57], v[50:53]
	v_mfma_f32_16x16x32_bf16 v[54:57], v[18:21], v[58:61], 0
	v_mfma_f32_16x16x32_bf16 v[58:61], v[26:29], v[58:61], 0
	v_mfma_f32_16x16x32_bf16 v[54:57], v[22:25], v[62:65], v[54:57]
	v_mfma_f32_16x16x32_bf16 v[58:61], v[30:33], v[62:65], v[58:61]
	s_nop 0
	s_barrier
	ds_read_b128 v[62:65], v177 offset:16384
	ds_read_b128 v[86:89], v177 offset:17408
	ds_read_b128 v[100:103], v177 offset:18432
	ds_read_b128 v[104:107], v177 offset:19456
	ds_read_b128 v[116:119], v177 offset:20480
	ds_read_b128 v[120:123], v177 offset:21504
	ds_read_b128 v[124:127], v177 offset:22528
	ds_read_b128 v[128:131], v177 offset:23552
	s_mov_b32 m0, s44
	s_nop 0
	global_load_lds_dwordx4 v171, s[28:29]
	s_nop 0
	s_mov_b32 m0, s48
	s_nop 0
	global_load_lds_dwordx4 v173, s[28:29]
	s_add_u32 s28, s26, 0x80100
	s_addc_u32 s29, s27, 0
	s_mov_b32 m0, s49
	s_nop 0
	global_load_lds_dwordx4 v171, s[28:29]
	s_nop 0
	s_mov_b32 m0, s52
	s_nop 0
	global_load_lds_dwordx4 v173, s[28:29]
	s_nop 0
	s_mov_b32 m0, s33
	s_nop 0
	global_load_lds_dwordx4 v170, s[8:9]
	s_nop 0
	s_mov_b32 m0, s53
	s_nop 0
	global_load_lds_dwordx4 v172, s[8:9]
	s_waitcnt vmcnt(24)
	s_waitcnt lgkmcnt(0)
	s_barrier
	s_nop 0
	s_waitcnt lgkmcnt(7)
	v_mfma_f32_16x16x32_bf16 v[132:135], v[2:5], v[62:65], 0
	s_waitcnt lgkmcnt(5)
	v_mfma_f32_16x16x32_bf16 v[140:143], v[2:5], v[100:103], 0
	s_waitcnt lgkmcnt(3)
	v_mfma_f32_16x16x32_bf16 v[148:151], v[2:5], v[116:119], 0
	s_waitcnt lgkmcnt(1)
	v_mfma_f32_16x16x32_bf16 v[2:5], v[2:5], v[124:127], 0
	v_mfma_f32_16x16x32_bf16 v[132:135], v[6:9], v[86:89], v[132:135]
	v_mfma_f32_16x16x32_bf16 v[136:139], v[10:13], v[62:65], 0
	v_mfma_f32_16x16x32_bf16 v[140:143], v[6:9], v[104:107], v[140:143]
	v_mfma_f32_16x16x32_bf16 v[144:147], v[10:13], v[100:103], 0
	v_mfma_f32_16x16x32_bf16 v[148:151], v[6:9], v[120:123], v[148:151]
	v_mfma_f32_16x16x32_bf16 v[152:155], v[10:13], v[116:119], 0
	s_waitcnt lgkmcnt(0)
	v_mfma_f32_16x16x32_bf16 v[2:5], v[6:9], v[128:131], v[2:5]
	v_mfma_f32_16x16x32_bf16 v[6:9], v[10:13], v[124:127], 0
	v_mfma_f32_16x16x32_bf16 v[136:139], v[14:17], v[86:89], v[136:139]
	v_mfma_f32_16x16x32_bf16 v[144:147], v[14:17], v[104:107], v[144:147]
	v_mfma_f32_16x16x32_bf16 v[152:155], v[14:17], v[120:123], v[152:155]
	v_mfma_f32_16x16x32_bf16 v[12:15], v[14:17], v[128:131], v[6:9]
	s_nop 0
	s_nop 0
	v_mfma_f32_16x16x32_bf16 v[6:9], v[18:21], v[62:65], 0
	v_mfma_f32_16x16x32_bf16 v[156:159], v[22:25], v[86:89], v[6:9]
	v_mfma_f32_16x16x32_bf16 v[6:9], v[26:29], v[62:65], 0
	v_mfma_f32_16x16x32_bf16 v[160:163], v[30:33], v[86:89], v[6:9]
	v_mfma_f32_16x16x32_bf16 v[6:9], v[18:21], v[100:103], 0
	v_mfma_f32_16x16x32_bf16 v[164:167], v[22:25], v[104:107], v[6:9]
	v_mfma_f32_16x16x32_bf16 v[6:9], v[26:29], v[100:103], 0
	v_mfma_f32_16x16x32_bf16 v[188:191], v[30:33], v[104:107], v[6:9]
	v_mfma_f32_16x16x32_bf16 v[6:9], v[18:21], v[116:119], 0
	v_mfma_f32_16x16x32_bf16 v[192:195], v[22:25], v[120:123], v[6:9]
	v_mfma_f32_16x16x32_bf16 v[6:9], v[26:29], v[116:119], 0
	v_mfma_f32_16x16x32_bf16 v[196:199], v[30:33], v[120:123], v[6:9]
	v_mfma_f32_16x16x32_bf16 v[6:9], v[18:21], v[124:127], 0
	v_mfma_f32_16x16x32_bf16 v[16:19], v[22:25], v[128:131], v[6:9]
	v_mfma_f32_16x16x32_bf16 v[6:9], v[26:29], v[124:127], 0
	v_mfma_f32_16x16x32_bf16 v[200:203], v[30:33], v[128:131], v[6:9]
	s_nop 0
	s_barrier
	s_nop 4
	ds_read_b128 v[6:9], v186
	ds_read_b128 v[28:31], v186 offset:1024
	ds_read_b128 v[62:65], v186 offset:2048
	ds_read_b128 v[204:207], v186 offset:3072
	ds_read_b128 v[208:211], v187
	ds_read_b128 v[212:215], v187 offset:1024
	ds_read_b128 v[216:219], v187 offset:2048
	ds_read_b128 v[184:187], v187 offset:3072
	ds_read_b128 v[20:23], v177 offset:32768
	ds_read_b128 v[24:27], v177 offset:33792
	ds_read_b128 v[228:231], v177 offset:34816
	ds_read_b128 v[232:235], v177 offset:35840
	ds_read_b128 v[236:239], v177 offset:36864
	ds_read_b128 v[240:243], v177 offset:37888
	ds_read_b128 v[244:247], v177 offset:38912
	ds_read_b128 v[248:251], v177 offset:39936
	s_add_u32 s8, s24, 0x80100
	s_addc_u32 s9, s25, 0
	s_mov_b32 m0, s64
	s_nop 0
	global_load_lds_dwordx4 v170, s[8:9]
	s_nop 0
	s_mov_b32 m0, s67
	s_nop 0
	global_load_lds_dwordx4 v172, s[8:9]
	s_waitcnt vmcnt(24)
	s_waitcnt lgkmcnt(0)
	s_barrier
; template <class Epi, class Sched, bool ALIGN_EPI = false, bool SP2 = false>
; __device__ __forceinline__ void gemm_phase(PG8_LAS unsigned char* lds, const Gemm g, const Sched& S, const Epi& E) {
;     ...
;         if constexpr (DRO) {
;             const char* a1 = cA + kstep; const char* a2 = cA + 2 * kstep; const char* b2 = cB + 2 * kstep; const char* a3 = a2 + kstep; const char* b3 = b2 + kstep;
;             PG8_TRIP(false, asm volatile("s_waitcnt vmcnt(%0)" :: "n"(8 + Epi::NVM) : "memory"));
;         }
	s_nop 0
	s_waitcnt lgkmcnt(7)
	v_mfma_f32_16x16x32_bf16 v[66:69], v[6:9], v[20:23], v[66:69]
	s_waitcnt lgkmcnt(6)
	v_mfma_f32_16x16x32_bf16 v[120:123], v[28:31], v[24:27], v[66:69]
	v_mfma_f32_16x16x32_bf16 v[66:69], v[62:65], v[20:23], v[70:73]
	v_mfma_f32_16x16x32_bf16 v[116:119], v[204:207], v[24:27], v[66:69]
	s_waitcnt lgkmcnt(5)
	v_mfma_f32_16x16x32_bf16 v[66:69], v[6:9], v[228:231], v[74:77]
	s_waitcnt lgkmcnt(4)
	v_mfma_f32_16x16x32_bf16 v[104:107], v[28:31], v[232:235], v[66:69]
	v_mfma_f32_16x16x32_bf16 v[66:69], v[62:65], v[228:231], v[78:81]
	v_mfma_f32_16x16x32_bf16 v[100:103], v[204:207], v[232:235], v[66:69]
	s_waitcnt lgkmcnt(3)
	v_mfma_f32_16x16x32_bf16 v[66:69], v[6:9], v[236:239], v[82:85]
	s_waitcnt lgkmcnt(2)
	v_mfma_f32_16x16x32_bf16 v[88:91], v[28:31], v[240:243], v[66:69]
	v_mfma_f32_16x16x32_bf16 v[66:69], v[62:65], v[236:239], v[92:95]
	v_mfma_f32_16x16x32_bf16 v[84:87], v[204:207], v[240:243], v[66:69]
	s_waitcnt lgkmcnt(1)
	v_mfma_f32_16x16x32_bf16 v[66:69], v[6:9], v[244:247], v[96:99]
	s_waitcnt lgkmcnt(0)
	v_mfma_f32_16x16x32_bf16 v[72:75], v[28:31], v[248:251], v[66:69]
	v_mfma_f32_16x16x32_bf16 v[66:69], v[62:65], v[244:247], v[108:111]
	v_mfma_f32_16x16x32_bf16 v[68:71], v[204:207], v[248:251], v[66:69]
	s_nop 0
	s_nop 0
	v_mfma_f32_16x16x32_bf16 v[76:79], v[208:211], v[20:23], v[112:115]
	v_mfma_f32_16x16x32_bf16 v[20:23], v[216:219], v[20:23], v[34:37]
	v_mfma_f32_16x16x32_bf16 v[124:127], v[184:187], v[24:27], v[20:23]
	v_mfma_f32_16x16x32_bf16 v[20:23], v[208:211], v[228:231], v[38:41]
	v_mfma_f32_16x16x32_bf16 v[112:115], v[212:215], v[232:235], v[20:23]
	v_mfma_f32_16x16x32_bf16 v[20:23], v[216:219], v[228:231], v[42:45]
	v_mfma_f32_16x16x32_bf16 v[108:111], v[184:187], v[232:235], v[20:23]
	v_mfma_f32_16x16x32_bf16 v[20:23], v[208:211], v[236:239], v[46:49]
	v_mfma_f32_16x16x32_bf16 v[96:99], v[212:215], v[240:243], v[20:23]
	v_mfma_f32_16x16x32_bf16 v[20:23], v[216:219], v[236:239], v[50:53]
	v_mfma_f32_16x16x32_bf16 v[92:95], v[184:187], v[240:243], v[20:23]
	v_mfma_f32_16x16x32_bf16 v[20:23], v[208:211], v[244:247], v[54:57]
	v_mfma_f32_16x16x32_bf16 v[80:83], v[212:215], v[248:251], v[20:23]
	v_mfma_f32_16x16x32_bf16 v[20:23], v[216:219], v[244:247], v[58:61]
	v_mfma_f32_16x16x32_bf16 v[128:131], v[212:215], v[24:27], v[76:79]
	v_mfma_f32_16x16x32_bf16 v[76:79], v[184:187], v[248:251], v[20:23]
	s_nop 0
	s_barrier
	ds_read_b128 v[32:35], v177 offset:49152
	ds_read_b128 v[44:47], v177 offset:50176
	ds_read_b128 v[228:231], v177 offset:51200
	ds_read_b128 v[232:235], v177 offset:52224
	ds_read_b128 v[236:239], v177 offset:53248
	ds_read_b128 v[240:243], v177 offset:54272
	ds_read_b128 v[244:247], v177 offset:55296
	ds_read_b128 v[248:251], v177 offset:56320
	s_add_u32 s8, s26, 0x180
	s_addc_u32 s9, s27, 0
	s_mov_b32 m0, s79
	s_nop 0
	global_load_lds_dwordx4 v171, s[8:9]
	s_nop 0
	s_mov_b32 m0, s82
	s_nop 0
	global_load_lds_dwordx4 v173, s[8:9]
	s_add_u32 s8, s26, 0x80180
	s_addc_u32 s9, s27, 0
	s_mov_b32 m0, s80
	s_nop 0
	global_load_lds_dwordx4 v171, s[8:9]
	s_nop 0
	s_mov_b32 m0, s81
	s_nop 0
	global_load_lds_dwordx4 v173, s[8:9]
	s_nop 0
	s_mov_b32 m0, s84
	s_nop 0
	global_load_lds_dwordx4 v170, s[6:7]
	s_nop 0
	s_mov_b32 m0, s91
	s_nop 0
	global_load_lds_dwordx4 v172, s[6:7]
	s_waitcnt vmcnt(8)
	s_waitcnt lgkmcnt(0)
	s_barrier
	s_nop 0
	s_waitcnt lgkmcnt(7)
	v_mfma_f32_16x16x32_bf16 v[20:23], v[6:9], v[32:35], v[132:135]
	s_waitcnt lgkmcnt(6)
	v_mfma_f32_16x16x32_bf16 v[56:59], v[28:31], v[44:47], v[20:23]
	v_mfma_f32_16x16x32_bf16 v[20:23], v[62:65], v[32:35], v[136:139]
	v_mfma_f32_16x16x32_bf16 v[52:55], v[204:207], v[44:47], v[20:23]
	s_waitcnt lgkmcnt(5)
	v_mfma_f32_16x16x32_bf16 v[20:23], v[6:9], v[228:231], v[140:143]
	s_waitcnt lgkmcnt(4)
	v_mfma_f32_16x16x32_bf16 v[40:43], v[28:31], v[232:235], v[20:23]
	v_mfma_f32_16x16x32_bf16 v[20:23], v[62:65], v[228:231], v[144:147]
	v_mfma_f32_16x16x32_bf16 v[36:39], v[204:207], v[232:235], v[20:23]
	s_waitcnt lgkmcnt(3)
	v_mfma_f32_16x16x32_bf16 v[20:23], v[6:9], v[236:239], v[148:151]
	s_waitcnt lgkmcnt(1)
	v_mfma_f32_16x16x32_bf16 v[2:5], v[6:9], v[244:247], v[2:5]
	v_mfma_f32_16x16x32_bf16 v[24:27], v[28:31], v[240:243], v[20:23]
	v_mfma_f32_16x16x32_bf16 v[20:23], v[62:65], v[236:239], v[152:155]
	s_waitcnt lgkmcnt(0)
	v_mfma_f32_16x16x32_bf16 v[8:11], v[28:31], v[248:251], v[2:5]
	v_mfma_f32_16x16x32_bf16 v[2:5], v[62:65], v[244:247], v[12:15]
	v_mfma_f32_16x16x32_bf16 v[20:23], v[204:207], v[240:243], v[20:23]
	v_mfma_f32_16x16x32_bf16 v[4:7], v[204:207], v[248:251], v[2:5]
	s_nop 0
	s_nop 0
	v_mfma_f32_16x16x32_bf16 v[12:15], v[208:211], v[32:35], v[156:159]
	v_mfma_f32_16x16x32_bf16 v[64:67], v[212:215], v[44:47], v[12:15]
	v_mfma_f32_16x16x32_bf16 v[12:15], v[216:219], v[32:35], v[160:163]
	v_mfma_f32_16x16x32_bf16 v[60:63], v[184:187], v[44:47], v[12:15]
	v_mfma_f32_16x16x32_bf16 v[12:15], v[208:211], v[228:231], v[164:167]
	v_mfma_f32_16x16x32_bf16 v[48:51], v[212:215], v[232:235], v[12:15]
	v_mfma_f32_16x16x32_bf16 v[12:15], v[216:219], v[228:231], v[188:191]
	v_mfma_f32_16x16x32_bf16 v[44:47], v[184:187], v[232:235], v[12:15]
	v_mfma_f32_16x16x32_bf16 v[12:15], v[208:211], v[236:239], v[192:195]
	v_mfma_f32_16x16x32_bf16 v[32:35], v[212:215], v[240:243], v[12:15]
	v_mfma_f32_16x16x32_bf16 v[12:15], v[216:219], v[236:239], v[196:199]
	v_mfma_f32_16x16x32_bf16 v[28:31], v[184:187], v[240:243], v[12:15]
	v_mfma_f32_16x16x32_bf16 v[12:15], v[208:211], v[244:247], v[16:19]
	v_mfma_f32_16x16x32_bf16 v[16:19], v[212:215], v[248:251], v[12:15]
	v_mfma_f32_16x16x32_bf16 v[12:15], v[216:219], v[244:247], v[200:203]
	v_mfma_f32_16x16x32_bf16 v[12:15], v[184:187], v[248:251], v[12:15]
	s_nop 0
	s_barrier
	s_mov_b64 s[6:7], 0

; template <class Epi, class Sched, bool ALIGN_EPI = false, bool SP2 = false>
; __device__ __forceinline__ void gemm_phase(PG8_LAS unsigned char* lds, const Gemm g, const Sched& S, const Epi& E) {
;     ...
;         for (int t = (DRO && ui > 0) ? 2 : 0; t < nt; t += 2) {
;             const bool last = (t == nt - 2);
;             const char* a1 = cA + (size_t)(t + 1) * kstep;
;             const char* a2 = last ? nA : cA + (size_t)(t + 2) * kstep; const char* b2 = last ? nB : cB + (size_t)(t + 2) * kstep;
;             const char* a3 = a2 + kstep; const char* b3 = b2 + kstep;
.LBB0_649:
	v_add_u32_e32 v184, 0x10000, v176
	v_add_u32_e32 v185, 0x14000, v176
	ds_read_b128 v[132:135], v184
	ds_read_b128 v[136:139], v184 offset:1024
	ds_read_b128 v[140:143], v184 offset:2048
	ds_read_b128 v[144:147], v184 offset:3072
	ds_read_b128 v[148:151], v185
	ds_read_b128 v[152:155], v185 offset:1024
	ds_read_b128 v[156:159], v185 offset:2048
	ds_read_b128 v[160:163], v185 offset:3072
	s_add_u32 s30, s6, 0xfff80080
	s_addc_u32 s31, s7, -1
	s_cmp_eq_u32 vcc_lo, 28
	s_cselect_b32 s40, s23, s30
	s_cselect_b32 s41, s9, s31
	s_cselect_b32 s36, s35, vcc_hi
	s_cselect_b32 s37, s21, s94
	s_add_u32 s30, s40, 0x80
	s_addc_u32 s31, s41, 0
	ds_read_b128 v[164:167], v177
	ds_read_b128 v[186:189], v177 offset:1024
	ds_read_b128 v[190:193], v177 offset:2048
	ds_read_b128 v[194:197], v177 offset:3072
	ds_read_b128 v[198:201], v177 offset:4096
	ds_read_b128 v[202:205], v177 offset:5120
	ds_read_b128 v[206:209], v177 offset:6144
	ds_read_b128 v[210:213], v177 offset:7168
	s_mov_b32 m0, s83
	s_nop 0
	global_load_lds_dwordx4 v170, s[6:7]
	s_nop 0
	s_mov_b32 m0, s57
	s_nop 0
	global_load_lds_dwordx4 v172, s[6:7]
	s_waitcnt vmcnt(8)
	s_waitcnt lgkmcnt(0)
	s_barrier
	s_nop 0
	s_waitcnt lgkmcnt(7)
	v_mfma_f32_16x16x32_bf16 v[120:123], v[132:135], v[164:167], v[120:123]
	v_mfma_f32_16x16x32_bf16 v[116:119], v[140:143], v[164:167], v[116:119]
	s_waitcnt lgkmcnt(5)
	v_mfma_f32_16x16x32_bf16 v[104:107], v[132:135], v[190:193], v[104:107]
	v_mfma_f32_16x16x32_bf16 v[100:103], v[140:143], v[190:193], v[100:103]
	s_waitcnt lgkmcnt(3)
	v_mfma_f32_16x16x32_bf16 v[88:91], v[132:135], v[198:201], v[88:91]
	v_mfma_f32_16x16x32_bf16 v[84:87], v[140:143], v[198:201], v[84:87]
	s_waitcnt lgkmcnt(1)
	v_mfma_f32_16x16x32_bf16 v[72:75], v[132:135], v[206:209], v[72:75]
	v_mfma_f32_16x16x32_bf16 v[68:71], v[140:143], v[206:209], v[68:71]
	v_mfma_f32_16x16x32_bf16 v[120:123], v[136:139], v[186:189], v[120:123]
	v_mfma_f32_16x16x32_bf16 v[116:119], v[144:147], v[186:189], v[116:119]
	v_mfma_f32_16x16x32_bf16 v[104:107], v[136:139], v[194:197], v[104:107]
	v_mfma_f32_16x16x32_bf16 v[100:103], v[144:147], v[194:197], v[100:103]
	v_mfma_f32_16x16x32_bf16 v[88:91], v[136:139], v[202:205], v[88:91]
	v_mfma_f32_16x16x32_bf16 v[84:87], v[144:147], v[202:205], v[84:87]
	s_waitcnt lgkmcnt(0)
	v_mfma_f32_16x16x32_bf16 v[72:75], v[136:139], v[210:213], v[72:75]
	v_mfma_f32_16x16x32_bf16 v[68:71], v[144:147], v[210:213], v[68:71]
	s_nop 0
	s_nop 0
	v_mfma_f32_16x16x32_bf16 v[128:131], v[148:151], v[164:167], v[128:131]
	v_mfma_f32_16x16x32_bf16 v[124:127], v[156:159], v[164:167], v[124:127]
	v_mfma_f32_16x16x32_bf16 v[112:115], v[148:151], v[190:193], v[112:115]
	v_mfma_f32_16x16x32_bf16 v[108:111], v[156:159], v[190:193], v[108:111]
	v_mfma_f32_16x16x32_bf16 v[96:99], v[148:151], v[198:201], v[96:99]
	v_mfma_f32_16x16x32_bf16 v[92:95], v[156:159], v[198:201], v[92:95]
	v_mfma_f32_16x16x32_bf16 v[80:83], v[148:151], v[206:209], v[80:83]
	v_mfma_f32_16x16x32_bf16 v[76:79], v[156:159], v[206:209], v[76:79]
	v_mfma_f32_16x16x32_bf16 v[128:131], v[152:155], v[186:189], v[128:131]
	v_mfma_f32_16x16x32_bf16 v[124:127], v[160:163], v[186:189], v[124:127]
	v_mfma_f32_16x16x32_bf16 v[112:115], v[152:155], v[194:197], v[112:115]
	v_mfma_f32_16x16x32_bf16 v[108:111], v[160:163], v[194:197], v[108:111]
	v_mfma_f32_16x16x32_bf16 v[96:99], v[152:155], v[202:205], v[96:99]
	v_mfma_f32_16x16x32_bf16 v[92:95], v[160:163], v[202:205], v[92:95]
	v_mfma_f32_16x16x32_bf16 v[80:83], v[152:155], v[210:213], v[80:83]
	v_mfma_f32_16x16x32_bf16 v[76:79], v[160:163], v[210:213], v[76:79]
	s_nop 0
	s_barrier
	ds_read_b128 v[164:167], v177 offset:16384
	ds_read_b128 v[186:189], v177 offset:17408
	ds_read_b128 v[190:193], v177 offset:18432
	ds_read_b128 v[194:197], v177 offset:19456
	ds_read_b128 v[198:201], v177 offset:20480
	ds_read_b128 v[202:205], v177 offset:21504
	ds_read_b128 v[206:209], v177 offset:22528
	ds_read_b128 v[210:213], v177 offset:23552
	s_mov_b32 m0, s44
	s_nop 0
	global_load_lds_dwordx4 v171, s[36:37]
	s_add_u32 s88, s36, 0x80000
	s_mov_b32 m0, s48
	s_nop 0
	global_load_lds_dwordx4 v173, s[36:37]
	s_addc_u32 s89, s37, 0
	s_mov_b32 m0, s49
	s_nop 0
	global_load_lds_dwordx4 v171, s[88:89]
	s_nop 0
	s_mov_b32 m0, s52
	s_nop 0
	global_load_lds_dwordx4 v173, s[88:89]
	s_nop 0
	s_mov_b32 m0, s33
	s_nop 0
	global_load_lds_dwordx4 v170, s[40:41]
	s_nop 0
	s_mov_b32 m0, s53
	s_nop 0
	global_load_lds_dwordx4 v172, s[40:41]
	s_waitcnt vmcnt(8)
	s_waitcnt lgkmcnt(0)
	s_barrier
	s_nop 0
	s_waitcnt lgkmcnt(7)
	v_mfma_f32_16x16x32_bf16 v[56:59], v[132:135], v[164:167], v[56:59]
	v_mfma_f32_16x16x32_bf16 v[52:55], v[140:143], v[164:167], v[52:55]
	s_waitcnt lgkmcnt(5)
	v_mfma_f32_16x16x32_bf16 v[40:43], v[132:135], v[190:193], v[40:43]
	v_mfma_f32_16x16x32_bf16 v[36:39], v[140:143], v[190:193], v[36:39]
	s_waitcnt lgkmcnt(3)
	v_mfma_f32_16x16x32_bf16 v[24:27], v[132:135], v[198:201], v[24:27]
	v_mfma_f32_16x16x32_bf16 v[20:23], v[140:143], v[198:201], v[20:23]
	s_waitcnt lgkmcnt(1)
	v_mfma_f32_16x16x32_bf16 v[8:11], v[132:135], v[206:209], v[8:11]
	v_mfma_f32_16x16x32_bf16 v[2:5], v[140:143], v[206:209], v[4:7]
	v_mfma_f32_16x16x32_bf16 v[56:59], v[136:139], v[186:189], v[56:59]
	v_mfma_f32_16x16x32_bf16 v[52:55], v[144:147], v[186:189], v[52:55]
	v_mfma_f32_16x16x32_bf16 v[40:43], v[136:139], v[194:197], v[40:43]
	v_mfma_f32_16x16x32_bf16 v[36:39], v[144:147], v[194:197], v[36:39]
	v_mfma_f32_16x16x32_bf16 v[24:27], v[136:139], v[202:205], v[24:27]
	v_mfma_f32_16x16x32_bf16 v[20:23], v[144:147], v[202:205], v[20:23]
	s_waitcnt lgkmcnt(0)
	v_mfma_f32_16x16x32_bf16 v[8:11], v[136:139], v[210:213], v[8:11]
	v_mfma_f32_16x16x32_bf16 v[2:5], v[144:147], v[210:213], v[2:5]
	s_nop 0
	s_nop 0
	v_mfma_f32_16x16x32_bf16 v[64:67], v[148:151], v[164:167], v[64:67]
	v_mfma_f32_16x16x32_bf16 v[60:63], v[156:159], v[164:167], v[60:63]
	v_mfma_f32_16x16x32_bf16 v[48:51], v[148:151], v[190:193], v[48:51]
	v_mfma_f32_16x16x32_bf16 v[44:47], v[156:159], v[190:193], v[44:47]
	v_mfma_f32_16x16x32_bf16 v[32:35], v[148:151], v[198:201], v[32:35]
	v_mfma_f32_16x16x32_bf16 v[28:31], v[156:159], v[198:201], v[28:31]
	v_mfma_f32_16x16x32_bf16 v[16:19], v[148:151], v[206:209], v[16:19]
	v_mfma_f32_16x16x32_bf16 v[12:15], v[156:159], v[206:209], v[12:15]
	v_mfma_f32_16x16x32_bf16 v[64:67], v[152:155], v[186:189], v[64:67]
	v_mfma_f32_16x16x32_bf16 v[60:63], v[160:163], v[186:189], v[60:63]
	v_mfma_f32_16x16x32_bf16 v[48:51], v[152:155], v[194:197], v[48:51]
	v_mfma_f32_16x16x32_bf16 v[44:47], v[160:163], v[194:197], v[44:47]
	v_mfma_f32_16x16x32_bf16 v[32:35], v[152:155], v[202:205], v[32:35]
	v_mfma_f32_16x16x32_bf16 v[28:31], v[160:163], v[202:205], v[28:31]
	v_mfma_f32_16x16x32_bf16 v[16:19], v[152:155], v[210:213], v[16:19]
	v_mfma_f32_16x16x32_bf16 v[12:15], v[160:163], v[210:213], v[12:15]
	s_nop 0
	s_barrier
	v_add_u32_e32 v186, 0x18000, v176
	v_add_u32_e32 v187, 0x1c000, v176
	ds_read_b128 v[132:135], v186
	ds_read_b128 v[136:139], v186 offset:1024
	ds_read_b128 v[140:143], v186 offset:2048
	ds_read_b128 v[144:147], v186 offset:3072
	ds_read_b128 v[148:151], v187
	ds_read_b128 v[152:155], v187 offset:1024
	ds_read_b128 v[156:159], v187 offset:2048
	ds_read_b128 v[160:163], v187 offset:3072
	ds_read_b128 v[164:167], v177 offset:32768
	ds_read_b128 v[188:191], v177 offset:33792
	ds_read_b128 v[192:195], v177 offset:34816
	ds_read_b128 v[196:199], v177 offset:35840
	ds_read_b128 v[200:203], v177 offset:36864
	ds_read_b128 v[204:207], v177 offset:37888
	ds_read_b128 v[208:211], v177 offset:38912
	ds_read_b128 v[212:215], v177 offset:39936
	s_add_u32 s40, s40, 0x80000
	s_addc_u32 s41, s41, 0
	s_mov_b32 m0, s64
	s_nop 0
	global_load_lds_dwordx4 v170, s[40:41]
	s_nop 0
	s_mov_b32 m0, s67
	s_nop 0
	global_load_lds_dwordx4 v172, s[40:41]
	s_waitcnt vmcnt(8)
	s_waitcnt lgkmcnt(0)
	s_barrier
	s_nop 0
	s_waitcnt lgkmcnt(7)
	v_mfma_f32_16x16x32_bf16 v[120:123], v[132:135], v[164:167], v[120:123]
	v_mfma_f32_16x16x32_bf16 v[116:119], v[140:143], v[164:167], v[116:119]
	s_waitcnt lgkmcnt(5)
	v_mfma_f32_16x16x32_bf16 v[104:107], v[132:135], v[192:195], v[104:107]
	v_mfma_f32_16x16x32_bf16 v[100:103], v[140:143], v[192:195], v[100:103]
	s_waitcnt lgkmcnt(3)
	v_mfma_f32_16x16x32_bf16 v[88:91], v[132:135], v[200:203], v[88:91]
	v_mfma_f32_16x16x32_bf16 v[84:87], v[140:143], v[200:203], v[84:87]
	s_waitcnt lgkmcnt(1)
	v_mfma_f32_16x16x32_bf16 v[72:75], v[132:135], v[208:211], v[72:75]
	v_mfma_f32_16x16x32_bf16 v[68:71], v[140:143], v[208:211], v[68:71]
	v_mfma_f32_16x16x32_bf16 v[120:123], v[136:139], v[188:191], v[120:123]
	v_mfma_f32_16x16x32_bf16 v[116:119], v[144:147], v[188:191], v[116:119]
	v_mfma_f32_16x16x32_bf16 v[104:107], v[136:139], v[196:199], v[104:107]
	v_mfma_f32_16x16x32_bf16 v[100:103], v[144:147], v[196:199], v[100:103]
	v_mfma_f32_16x16x32_bf16 v[88:91], v[136:139], v[204:207], v[88:91]
	v_mfma_f32_16x16x32_bf16 v[84:87], v[144:147], v[204:207], v[84:87]
	s_waitcnt lgkmcnt(0)
	v_mfma_f32_16x16x32_bf16 v[72:75], v[136:139], v[212:215], v[72:75]
	v_mfma_f32_16x16x32_bf16 v[68:71], v[144:147], v[212:215], v[68:71]
	s_nop 0
	s_nop 0
	v_mfma_f32_16x16x32_bf16 v[128:131], v[148:151], v[164:167], v[128:131]
	v_mfma_f32_16x16x32_bf16 v[124:127], v[156:159], v[164:167], v[124:127]
	v_mfma_f32_16x16x32_bf16 v[112:115], v[148:151], v[192:195], v[112:115]
	v_mfma_f32_16x16x32_bf16 v[108:111], v[156:159], v[192:195], v[108:111]
	v_mfma_f32_16x16x32_bf16 v[96:99], v[148:151], v[200:203], v[96:99]
	v_mfma_f32_16x16x32_bf16 v[92:95], v[156:159], v[200:203], v[92:95]
	v_mfma_f32_16x16x32_bf16 v[80:83], v[148:151], v[208:211], v[80:83]
	v_mfma_f32_16x16x32_bf16 v[76:79], v[156:159], v[208:211], v[76:79]
	v_mfma_f32_16x16x32_bf16 v[128:131], v[152:155], v[188:191], v[128:131]
	v_mfma_f32_16x16x32_bf16 v[124:127], v[160:163], v[188:191], v[124:127]
	v_mfma_f32_16x16x32_bf16 v[112:115], v[152:155], v[196:199], v[112:115]
	v_mfma_f32_16x16x32_bf16 v[108:111], v[160:163], v[196:199], v[108:111]
	v_mfma_f32_16x16x32_bf16 v[96:99], v[152:155], v[204:207], v[96:99]
	v_mfma_f32_16x16x32_bf16 v[92:95], v[160:163], v[204:207], v[92:95]
	v_mfma_f32_16x16x32_bf16 v[80:83], v[152:155], v[212:215], v[80:83]
	v_mfma_f32_16x16x32_bf16 v[76:79], v[160:163], v[212:215], v[76:79]
	s_nop 0
	s_barrier
; #define PG8_STAGE(bufoff, gbase, voff) do { _Pragma("unroll") for (int _i = 0; _i < 2; ++_i) { \
;         const unsigned m0_ = ldsbase + (unsigned)(bufoff) + ldsw + (unsigned)_i * 8192u; \
;         asm volatile("s_mov_b32 m0, %2\n\ts_nop 0\n\tglobal_load_lds_dwordx4 %0, %1" :: "v"((voff)[_i]), "s"((const char*)(gbase)), "s"(m0_) : "memory", "m0"); } } while (0)
; template <class Epi, class Sched, bool ALIGN_EPI = false, bool SP2 = false>
; __device__ __forceinline__ void gemm_phase(PG8_LAS unsigned char* lds, const Gemm g, const Sched& S, const Epi& E) {
;     ...
;         if constexpr (DRO) { asm volatile("" ::: "memory"); PG8_STAGE(PG8_SA(1, 1), nA + kstep + hsA, voffA); asm volatile("" ::: "memory"); }
	ds_read_b128 v[164:167], v177 offset:49152
	ds_read_b128 v[188:191], v177 offset:50176
	ds_read_b128 v[192:195], v177 offset:51200
	ds_read_b128 v[196:199], v177 offset:52224
	ds_read_b128 v[200:203], v177 offset:53248
	ds_read_b128 v[204:207], v177 offset:54272
	ds_read_b128 v[208:211], v177 offset:55296
	ds_read_b128 v[212:215], v177 offset:56320
	s_add_u32 s40, s36, 0x80
	s_addc_u32 s41, s37, 0
	s_mov_b32 m0, s79
	s_nop 0
	global_load_lds_dwordx4 v171, s[40:41]
	s_add_u32 s36, s36, 0x80080
	s_mov_b32 m0, s82
	s_nop 0
	global_load_lds_dwordx4 v173, s[40:41]
	s_addc_u32 s37, s37, 0
	s_mov_b32 m0, s80
	s_nop 0
	global_load_lds_dwordx4 v171, s[36:37]
	s_nop 0
	s_mov_b32 m0, s81
	s_nop 0
	global_load_lds_dwordx4 v173, s[36:37]
	s_nop 0
	s_mov_b32 m0, s84
	s_nop 0
	global_load_lds_dwordx4 v170, s[30:31]
	s_nop 0
	s_mov_b32 m0, s91
	s_nop 0
	global_load_lds_dwordx4 v172, s[30:31]
	s_waitcnt vmcnt(8)
	s_waitcnt lgkmcnt(0)
	s_barrier
	s_nop 0
	s_waitcnt lgkmcnt(7)
	v_mfma_f32_16x16x32_bf16 v[56:59], v[132:135], v[164:167], v[56:59]
	v_mfma_f32_16x16x32_bf16 v[52:55], v[140:143], v[164:167], v[52:55]
	s_waitcnt lgkmcnt(5)
	v_mfma_f32_16x16x32_bf16 v[40:43], v[132:135], v[192:195], v[40:43]
	v_mfma_f32_16x16x32_bf16 v[36:39], v[140:143], v[192:195], v[36:39]
	s_waitcnt lgkmcnt(3)
	v_mfma_f32_16x16x32_bf16 v[24:27], v[132:135], v[200:203], v[24:27]
	v_mfma_f32_16x16x32_bf16 v[20:23], v[140:143], v[200:203], v[20:23]
	s_waitcnt lgkmcnt(1)
	v_mfma_f32_16x16x32_bf16 v[6:9], v[132:135], v[208:211], v[8:11]
	v_mfma_f32_16x16x32_bf16 v[2:5], v[140:143], v[208:211], v[2:5]
	v_mfma_f32_16x16x32_bf16 v[56:59], v[136:139], v[188:191], v[56:59]
	v_mfma_f32_16x16x32_bf16 v[52:55], v[144:147], v[188:191], v[52:55]
	v_mfma_f32_16x16x32_bf16 v[40:43], v[136:139], v[196:199], v[40:43]
	v_mfma_f32_16x16x32_bf16 v[36:39], v[144:147], v[196:199], v[36:39]
	v_mfma_f32_16x16x32_bf16 v[24:27], v[136:139], v[204:207], v[24:27]
	v_mfma_f32_16x16x32_bf16 v[20:23], v[144:147], v[204:207], v[20:23]
	s_waitcnt lgkmcnt(0)
	v_mfma_f32_16x16x32_bf16 v[8:11], v[136:139], v[212:215], v[6:9]
	v_mfma_f32_16x16x32_bf16 v[4:7], v[144:147], v[212:215], v[2:5]
	s_nop 0
	s_nop 0
	v_mfma_f32_16x16x32_bf16 v[64:67], v[148:151], v[164:167], v[64:67]
	v_mfma_f32_16x16x32_bf16 v[60:63], v[156:159], v[164:167], v[60:63]
	v_mfma_f32_16x16x32_bf16 v[48:51], v[148:151], v[192:195], v[48:51]
	v_mfma_f32_16x16x32_bf16 v[44:47], v[156:159], v[192:195], v[44:47]
	v_mfma_f32_16x16x32_bf16 v[32:35], v[148:151], v[200:203], v[32:35]
	v_mfma_f32_16x16x32_bf16 v[28:31], v[156:159], v[200:203], v[28:31]
	v_mfma_f32_16x16x32_bf16 v[16:19], v[148:151], v[208:211], v[16:19]
	v_mfma_f32_16x16x32_bf16 v[12:15], v[156:159], v[208:211], v[12:15]
	v_mfma_f32_16x16x32_bf16 v[64:67], v[152:155], v[188:191], v[64:67]
	v_mfma_f32_16x16x32_bf16 v[60:63], v[160:163], v[188:191], v[60:63]
	v_mfma_f32_16x16x32_bf16 v[48:51], v[152:155], v[196:199], v[48:51]
	v_mfma_f32_16x16x32_bf16 v[44:47], v[160:163], v[196:199], v[44:47]
	v_mfma_f32_16x16x32_bf16 v[32:35], v[152:155], v[204:207], v[32:35]
	v_mfma_f32_16x16x32_bf16 v[28:31], v[160:163], v[204:207], v[28:31]
	v_mfma_f32_16x16x32_bf16 v[16:19], v[152:155], v[212:215], v[16:19]
	v_mfma_f32_16x16x32_bf16 v[12:15], v[160:163], v[212:215], v[12:15]
	s_nop 0
	s_barrier
	s_add_i32 vcc_lo, vcc_lo, 2
	s_add_u32 vcc_hi, vcc_hi, 0x100
	s_addc_u32 s94, s94, 0
	s_add_u32 s6, s6, 0x100
	s_addc_u32 s7, s7, 0
	s_cmp_gt_u32 vcc_lo, 29
	s_cbranch_scc0 .LBB0_649
	s_add_u32 s6, s23, 0x80080
	s_addc_u32 s7, s9, 0
	s_mov_b32 m0, s83
	s_nop 0
	global_load_lds_dwordx4 v170, s[6:7]
	s_and_b64 vcc, exec, s[16:17]
	s_mov_b32 m0, s57
	s_nop 0
	global_load_lds_dwordx4 v172, s[6:7]
	s_cbranch_vccz .LBB0_652
	s_barrier

; #define MK_LAS __attribute__((address_space(3)))
; __device__ __forceinline__ unsigned mk_hwkey() { unsigned hw; asm volatile("s_getreg_b32 %0, hwreg(HW_REG_HW_ID, 0, 6)" : "=s"(hw)); return hw; }
; __device__ __forceinline__ int mk_wave() {
;     extern __shared__ __attribute__((aligned(16))) unsigned char lds[];
;     const unsigned hw = mk_hwkey();
;     return __builtin_amdgcn_readfirstlane((int)*(volatile MK_LAS unsigned*)((MK_LAS unsigned char*)lds + TIDTAB_OFF + 4 * hw));
; }
; template <class Epi, class Sched, bool ALIGN_EPI = false, bool SP2 = false>
; __device__ __forceinline__ void gemm_phase(PG8_LAS unsigned char* lds, const Gemm g, const Sched& S, const Epi& E) {
;     ...
;     for (int i = 0; i < 2; ++i) { int R, C; stage_rc(tid * 16 + i * 8192, R, C); const int Rb = Epi::PERM ? ((R & ~31) + perm32(R & 31)) : R;
;         voffA[i] = (unsigned)(R * g.lda + C) * 2u; voffB[i] = (unsigned)(Rb * g.ldb + C) * 2u; }
;     const size_t kstep = (size_t)(BK * 2);
;     const size_t hsA = (size_t)HALF * g.lda * 2, hsB = (size_t)HALF * g.ldb * 2;
;     const size_t tsA = 2 * hsA, tsB = 2 * hsB;
;     const unsigned ldsbase = (unsigned)(unsigned long long)lds;
;     const unsigned ldsw = (unsigned)wid * 1024u;
;     const int aoff = lds_byte(wr * 64 + fr, fq * 8), boff = lds_byte(wc * 32 + fr, fq * 8);
;     ...
;     Unit cur, nxt; int ui = 0; bool epi_ran = false;
;     if (!S.next(0, cur)) return;
;     f32x4 acc[2][2][4][2];
; #pragma unroll
;     for (int a = 0; a < 2; ++a)
; #pragma unroll
;         for (int b = 0; b < 2; ++b)
; #pragma unroll
;             for (int m = 0; m < 4; ++m)
; #pragma unroll
;                 for (int n = 0; n < 2; ++n) acc[a][b][m][n] = (f32x4){0.f, 0.f, 0.f, 0.f};
;     bf16x8 At[4][2], B0[2][2], B1[2][2];
;     const char* cA = (const char*)g.A + (size_t)cur.pm * tsA + (size_t)cur.k0 * 2; const char* cB = (const char*)g.Bt + (size_t)cur.pn * tsB + (size_t)cur.k0 * 2;
;     S.a_ready(cur);
;     if constexpr (SP2) {
;         PG8_STAGE(PG8_SB(0, 0), cB, voffB); PG8_STAGE(PG8_SB(0, 1), cB + hsB, voffB); PG8_STAGE(PG8_SA(0, 0), cA, voffA); PG8_STAGE(PG8_SA(0, 1), cA + hsA, voffA);
;         if (wr == 1) PG8_BAR;
;         PG8_WAIT_V(2); PG8_BAR;
;         PG8_STAGE(PG8_SB(1, 0), cB + kstep, voffB); PG8_STAGE(PG8_SA(1, 0), cA + kstep, voffA); PG8_STAGE(PG8_SB(1, 1), cB + hsB + kstep, voffB);
;         PG8_WAIT_V(6); PG8_BAR;
.LBB0_918:
	s_add_u32 s40, s86, 0x4000
	v_lshrrev_b32_e32 v3, 1, v0
	s_addc_u32 s41, s87, 0
	v_and_b32_e32 v3, 24, v3
	s_lshl_b32 s6, s6, 5
	v_and_b32_e32 v2, 15, v0
	v_lshlrev_b32_e32 v4, 1, v3
	v_lshlrev_b32_e32 v0, 2, v0
	s_and_b32 s8, s6, 0x60
	v_lshl_or_b32 v184, s7, 6, v2
	v_lshl_or_b32 v2, v2, 6, v4
	s_lshl_b32 s7, s7, 13
	v_and_b32_e32 v0, 32, v0
	s_lshl_b32 s6, s8, 7
	s_add_i32 s44, s27, 0x18000
	v_bitop3_b32 v5, v2, s6, v0 bitop3:0xde
	s_add_u32 s6, s18, 0x80
	v_bitop3_b32 v4, v2, s7, v0 bitop3:0xde
	s_waitcnt vmcnt(2)
	s_barrier
	s_addc_u32 s7, s19, 0
	s_mov_b32 m0, s44
	s_nop 0
	global_load_lds_dwordx4 v175, s[6:7]
	s_add_i32 s48, s27, 0x1a000
	s_add_i32 s49, s27, 0x8000
	s_mov_b32 m0, s48
	s_nop 0
	global_load_lds_dwordx4 v177, s[6:7]
	s_add_u32 s6, s20, 0x80
	s_addc_u32 s7, s21, 0
	s_mov_b32 m0, s49
	s_nop 0
	global_load_lds_dwordx4 v174, s[6:7]
	s_add_i32 s51, s27, 0xa000
	s_add_i32 s52, s27, 0x1c000
	s_mov_b32 m0, s51
	s_nop 0
	global_load_lds_dwordx4 v176, s[6:7]
	s_add_u32 s6, s18, 0x80080
	s_addc_u32 s7, s19, 0
	s_mov_b32 m0, s52
	s_nop 0
	global_load_lds_dwordx4 v175, s[6:7]
	s_add_i32 s53, s27, 0x1e000
	s_mov_b32 m0, s53
	s_nop 0
	global_load_lds_dwordx4 v177, s[6:7]
	v_readlane_b32 s6, v255, 8
	s_waitcnt vmcnt(6)
	v_or_b32_e32 v185, s8, v3
	v_mov_b32_e32 v2, v1
	v_mov_b32_e32 v3, v1
	v_readlane_b32 s7, v255, 9
	v_mov_b32_e32 v0, v1
	v_add_u32_e32 v186, 0, v5
	v_add_u32_e32 v187, 0, v4
	v_mov_b64_e32 v[6:7], v[2:3]
	v_mov_b64_e32 v[10:11], v[2:3]
	v_mov_b64_e32 v[22:23], v[2:3]
	v_mov_b64_e32 v[26:27], v[2:3]
	v_mov_b64_e32 v[38:39], v[2:3]
	v_mov_b64_e32 v[42:43], v[2:3]
	v_mov_b64_e32 v[54:55], v[2:3]
	v_mov_b64_e32 v[58:59], v[2:3]
	v_mov_b64_e32 v[14:15], v[2:3]
	v_mov_b64_e32 v[18:19], v[2:3]
	v_mov_b64_e32 v[30:31], v[2:3]
	v_mov_b64_e32 v[34:35], v[2:3]
	v_mov_b64_e32 v[46:47], v[2:3]
	v_mov_b64_e32 v[50:51], v[2:3]
	v_mov_b64_e32 v[62:63], v[2:3]
	v_mov_b64_e32 v[66:67], v[2:3]
	v_mov_b64_e32 v[70:71], v[2:3]
	v_mov_b64_e32 v[74:75], v[2:3]
	v_mov_b64_e32 v[86:87], v[2:3]
	v_mov_b64_e32 v[90:91], v[2:3]
	v_mov_b64_e32 v[102:103], v[2:3]
	v_mov_b64_e32 v[106:107], v[2:3]
	v_mov_b64_e32 v[134:135], v[2:3]
	v_mov_b64_e32 v[138:139], v[2:3]
	v_mov_b64_e32 v[78:79], v[2:3]
	v_mov_b64_e32 v[82:83], v[2:3]
	v_mov_b64_e32 v[94:95], v[2:3]
	v_mov_b64_e32 v[98:99], v[2:3]
	v_mov_b64_e32 v[110:111], v[2:3]
	v_mov_b64_e32 v[118:119], v[2:3]
	v_mov_b64_e32 v[142:143], v[2:3]
	v_mov_b64_e32 v[146:147], v[2:3]
	s_mov_b32 s67, s6
	v_readlane_b32 s6, v255, 4
	s_add_i32 s57, s27, 0xc000
	s_add_i32 s63, s27, 0xe000
	s_mov_b32 s22, 0
	v_mov_b64_e32 v[4:5], v[0:1]
	v_mov_b64_e32 v[8:9], v[0:1]
	v_mov_b64_e32 v[20:21], v[0:1]
	v_mov_b64_e32 v[24:25], v[0:1]
	v_mov_b64_e32 v[36:37], v[0:1]
	v_mov_b64_e32 v[40:41], v[0:1]
	v_mov_b64_e32 v[52:53], v[0:1]
	v_mov_b64_e32 v[56:57], v[0:1]
	v_mov_b64_e32 v[12:13], v[0:1]
	v_mov_b64_e32 v[16:17], v[0:1]
	v_mov_b64_e32 v[28:29], v[0:1]
	v_mov_b64_e32 v[32:33], v[0:1]
	v_mov_b64_e32 v[44:45], v[0:1]
	v_mov_b64_e32 v[48:49], v[0:1]
	v_mov_b64_e32 v[60:61], v[0:1]
	v_mov_b64_e32 v[64:65], v[0:1]
	v_mov_b64_e32 v[68:69], v[0:1]
	v_mov_b64_e32 v[72:73], v[0:1]
	v_mov_b64_e32 v[84:85], v[0:1]
	v_mov_b64_e32 v[88:89], v[0:1]
	v_mov_b64_e32 v[100:101], v[0:1]
	v_mov_b64_e32 v[104:105], v[0:1]
	v_mov_b64_e32 v[132:133], v[0:1]
	v_mov_b64_e32 v[136:137], v[0:1]
	v_mov_b64_e32 v[76:77], v[0:1]
	v_mov_b64_e32 v[80:81], v[0:1]
	v_mov_b64_e32 v[92:93], v[0:1]
	v_mov_b64_e32 v[96:97], v[0:1]
	v_mov_b64_e32 v[108:109], v[0:1]
	v_mov_b64_e32 v[116:117], v[0:1]
	v_mov_b64_e32 v[140:141], v[0:1]
	v_mov_b64_e32 v[144:145], v[0:1]
	s_mov_b32 s69, s6
	s_barrier
	v_readlane_b32 s7, v255, 5
	s_getreg_b32 s100, hwreg(HW_REG_HW_ID, 0, 6)
	s_lshl_b32 s100, s100, 2
	s_add_i32 s100, s100, 0x20540
	v_mov_b32_e32 v251, s100
	ds_read_b32 v251, v251
	s_waitcnt lgkmcnt(0)
	v_readfirstlane_b32 s100, v251
	s_cmp_ge_u32 s100, 4
	s_cbranch_scc0 statprio_skip2
	s_setprio 1
statprio_skip2:
	s_branch .LBB0_920

.LBB0_932:
	v_add_u32_e32 v0, 0x10000, v186
	v_add_u32_e32 v188, 0x14000, v186
	ds_read_b128 v[112:115], v0
	ds_read_b128 v[120:123], v0 offset:1024
	ds_read_b128 v[124:127], v0 offset:2048
	ds_read_b128 v[128:131], v0 offset:3072
	ds_read_b128 v[148:151], v188
	ds_read_b128 v[152:155], v188 offset:1024
	ds_read_b128 v[156:159], v188 offset:2048
	ds_read_b128 v[160:163], v188 offset:3072
	s_add_u32 s20, s18, 0xfff80080
	s_addc_u32 s21, s19, -1
	s_cmp_eq_u32 s78, 28
	s_cselect_b32 s24, s7, s20
	s_cselect_b32 s25, s6, s21
	s_cselect_b32 s22, s11, s79
	s_cselect_b32 s23, s9, s82
	s_add_u32 s20, s24, 0x80
	s_addc_u32 s21, s25, 0
	ds_read_b128 v[164:167], v187
	ds_read_b128 v[168:171], v187 offset:1024
	ds_read_b128 v[178:181], v187 offset:2048
	ds_read_b128 v[190:193], v187 offset:3072
	ds_read_b128 v[194:197], v187 offset:4096
	ds_read_b128 v[198:201], v187 offset:5120
	ds_read_b128 v[202:205], v187 offset:6144
	ds_read_b128 v[206:209], v187 offset:7168
	s_mov_b32 m0, s57
	s_nop 0
	global_load_lds_dwordx4 v174, s[18:19]
	s_nop 0
	s_mov_b32 m0, s63
	s_nop 0
	global_load_lds_dwordx4 v176, s[18:19]
	s_waitcnt vmcnt(8)
	s_waitcnt lgkmcnt(0)
	s_barrier
	s_nop 0
	s_waitcnt lgkmcnt(0)
	v_mfma_f32_16x16x32_bf16 v[144:147], v[112:115], v[164:167], v[144:147]
	v_mfma_f32_16x16x32_bf16 v[140:143], v[124:127], v[164:167], v[140:143]
	s_waitcnt lgkmcnt(5)
	v_mfma_f32_16x16x32_bf16 v[116:119], v[112:115], v[178:181], v[116:119]
	v_mfma_f32_16x16x32_bf16 v[108:111], v[124:127], v[178:181], v[108:111]
	s_waitcnt lgkmcnt(3)
	v_mfma_f32_16x16x32_bf16 v[96:99], v[112:115], v[194:197], v[96:99]
	v_mfma_f32_16x16x32_bf16 v[92:95], v[124:127], v[194:197], v[92:95]
	s_waitcnt lgkmcnt(1)
	v_mfma_f32_16x16x32_bf16 v[80:83], v[112:115], v[202:205], v[80:83]
	v_mfma_f32_16x16x32_bf16 v[76:79], v[124:127], v[202:205], v[76:79]
	v_mfma_f32_16x16x32_bf16 v[144:147], v[120:123], v[168:171], v[144:147]
	v_mfma_f32_16x16x32_bf16 v[140:143], v[128:131], v[168:171], v[140:143]
	v_mfma_f32_16x16x32_bf16 v[116:119], v[120:123], v[190:193], v[116:119]
	v_mfma_f32_16x16x32_bf16 v[108:111], v[128:131], v[190:193], v[108:111]
	v_mfma_f32_16x16x32_bf16 v[96:99], v[120:123], v[198:201], v[96:99]
	v_mfma_f32_16x16x32_bf16 v[92:95], v[128:131], v[198:201], v[92:95]
	s_waitcnt lgkmcnt(0)
	v_mfma_f32_16x16x32_bf16 v[80:83], v[120:123], v[206:209], v[80:83]
	v_mfma_f32_16x16x32_bf16 v[76:79], v[128:131], v[206:209], v[76:79]
	s_nop 0
	s_nop 0
	v_mfma_f32_16x16x32_bf16 v[136:139], v[148:151], v[164:167], v[136:139]
	v_mfma_f32_16x16x32_bf16 v[132:135], v[156:159], v[164:167], v[132:135]
	v_mfma_f32_16x16x32_bf16 v[104:107], v[148:151], v[178:181], v[104:107]
	v_mfma_f32_16x16x32_bf16 v[100:103], v[156:159], v[178:181], v[100:103]
	v_mfma_f32_16x16x32_bf16 v[88:91], v[148:151], v[194:197], v[88:91]
	v_mfma_f32_16x16x32_bf16 v[84:87], v[156:159], v[194:197], v[84:87]
	v_mfma_f32_16x16x32_bf16 v[72:75], v[148:151], v[202:205], v[72:75]
	v_mfma_f32_16x16x32_bf16 v[68:71], v[156:159], v[202:205], v[68:71]
	v_mfma_f32_16x16x32_bf16 v[136:139], v[152:155], v[168:171], v[136:139]
	v_mfma_f32_16x16x32_bf16 v[132:135], v[160:163], v[168:171], v[132:135]
	v_mfma_f32_16x16x32_bf16 v[104:107], v[152:155], v[190:193], v[104:107]
	v_mfma_f32_16x16x32_bf16 v[100:103], v[160:163], v[190:193], v[100:103]
	v_mfma_f32_16x16x32_bf16 v[88:91], v[152:155], v[198:201], v[88:91]
	v_mfma_f32_16x16x32_bf16 v[84:87], v[160:163], v[198:201], v[84:87]
	v_mfma_f32_16x16x32_bf16 v[72:75], v[152:155], v[206:209], v[72:75]
	v_mfma_f32_16x16x32_bf16 v[68:71], v[160:163], v[206:209], v[68:71]
	s_nop 0
	s_barrier
	ds_read_b128 v[164:167], v187 offset:16384
	ds_read_b128 v[168:171], v187 offset:17408
	ds_read_b128 v[178:181], v187 offset:18432
	ds_read_b128 v[190:193], v187 offset:19456
	ds_read_b128 v[194:197], v187 offset:20480
	ds_read_b128 v[198:201], v187 offset:21504
	ds_read_b128 v[202:205], v187 offset:22528
	ds_read_b128 v[206:209], v187 offset:23552
	s_mov_b32 m0, s28
	s_nop 0
	global_load_lds_dwordx4 v175, s[22:23]
	s_add_u32 s88, s22, 0x80000
	s_mov_b32 m0, s29
	s_nop 0
	global_load_lds_dwordx4 v177, s[22:23]
	s_addc_u32 s89, s23, 0
	s_mov_b32 m0, s30
	s_nop 0
	global_load_lds_dwordx4 v175, s[88:89]
	s_nop 0
	s_mov_b32 m0, s31
	s_nop 0
	global_load_lds_dwordx4 v177, s[88:89]
	s_nop 0
	s_mov_b32 m0, s27
	s_nop 0
	global_load_lds_dwordx4 v174, s[24:25]
	s_nop 0
	s_mov_b32 m0, s35
	s_nop 0
	global_load_lds_dwordx4 v176, s[24:25]
	s_waitcnt vmcnt(8)
	s_waitcnt lgkmcnt(0)
	s_barrier
	s_nop 0
	s_waitcnt lgkmcnt(0)
	v_mfma_f32_16x16x32_bf16 v[64:67], v[112:115], v[164:167], v[64:67]
	v_mfma_f32_16x16x32_bf16 v[60:63], v[124:127], v[164:167], v[60:63]
	s_waitcnt lgkmcnt(5)
	v_mfma_f32_16x16x32_bf16 v[48:51], v[112:115], v[178:181], v[48:51]
	v_mfma_f32_16x16x32_bf16 v[44:47], v[124:127], v[178:181], v[44:47]
	s_waitcnt lgkmcnt(3)
	v_mfma_f32_16x16x32_bf16 v[32:35], v[112:115], v[194:197], v[32:35]
	v_mfma_f32_16x16x32_bf16 v[28:31], v[124:127], v[194:197], v[28:31]
	s_waitcnt lgkmcnt(1)
	v_mfma_f32_16x16x32_bf16 v[16:19], v[112:115], v[202:205], v[16:19]
	v_mfma_f32_16x16x32_bf16 v[12:15], v[124:127], v[202:205], v[12:15]
	v_mfma_f32_16x16x32_bf16 v[64:67], v[120:123], v[168:171], v[64:67]
	v_mfma_f32_16x16x32_bf16 v[60:63], v[128:131], v[168:171], v[60:63]
	v_mfma_f32_16x16x32_bf16 v[48:51], v[120:123], v[190:193], v[48:51]
	v_mfma_f32_16x16x32_bf16 v[44:47], v[128:131], v[190:193], v[44:47]
	v_mfma_f32_16x16x32_bf16 v[32:35], v[120:123], v[198:201], v[32:35]
	v_mfma_f32_16x16x32_bf16 v[28:31], v[128:131], v[198:201], v[28:31]
	s_waitcnt lgkmcnt(0)
	v_mfma_f32_16x16x32_bf16 v[16:19], v[120:123], v[206:209], v[16:19]
	v_mfma_f32_16x16x32_bf16 v[12:15], v[128:131], v[206:209], v[12:15]
	s_nop 0
	s_nop 0
	v_mfma_f32_16x16x32_bf16 v[56:59], v[148:151], v[164:167], v[56:59]
	v_mfma_f32_16x16x32_bf16 v[52:55], v[156:159], v[164:167], v[52:55]
	v_mfma_f32_16x16x32_bf16 v[40:43], v[148:151], v[178:181], v[40:43]
	v_mfma_f32_16x16x32_bf16 v[36:39], v[156:159], v[178:181], v[36:39]
	v_mfma_f32_16x16x32_bf16 v[24:27], v[148:151], v[194:197], v[24:27]
	v_mfma_f32_16x16x32_bf16 v[20:23], v[156:159], v[194:197], v[20:23]
	v_mfma_f32_16x16x32_bf16 v[8:11], v[148:151], v[202:205], v[8:11]
	v_mfma_f32_16x16x32_bf16 v[2:5], v[156:159], v[202:205], v[4:7]
	v_mfma_f32_16x16x32_bf16 v[56:59], v[152:155], v[168:171], v[56:59]
	v_mfma_f32_16x16x32_bf16 v[52:55], v[160:163], v[168:171], v[52:55]
	v_mfma_f32_16x16x32_bf16 v[40:43], v[152:155], v[190:193], v[40:43]
	v_mfma_f32_16x16x32_bf16 v[36:39], v[160:163], v[190:193], v[36:39]
	v_mfma_f32_16x16x32_bf16 v[24:27], v[152:155], v[198:201], v[24:27]
	v_mfma_f32_16x16x32_bf16 v[20:23], v[160:163], v[198:201], v[20:23]
	v_mfma_f32_16x16x32_bf16 v[8:11], v[152:155], v[206:209], v[8:11]
	v_mfma_f32_16x16x32_bf16 v[2:5], v[160:163], v[206:209], v[2:5]
	s_nop 0
	s_barrier
	v_add_u32_e32 v189, 0x18000, v186
	v_add_u32_e32 v190, 0x1c000, v186
	ds_read_b128 v[112:115], v189
	ds_read_b128 v[120:123], v189 offset:1024
	ds_read_b128 v[124:127], v189 offset:2048
	ds_read_b128 v[128:131], v189 offset:3072
	ds_read_b128 v[148:151], v190
	ds_read_b128 v[152:155], v190 offset:1024
	ds_read_b128 v[156:159], v190 offset:2048
	ds_read_b128 v[160:163], v190 offset:3072
	ds_read_b128 v[164:167], v187 offset:32768
	ds_read_b128 v[168:171], v187 offset:33792
	ds_read_b128 v[178:181], v187 offset:34816
	ds_read_b128 v[192:195], v187 offset:35840
	ds_read_b128 v[196:199], v187 offset:36864
	ds_read_b128 v[200:203], v187 offset:37888
	ds_read_b128 v[204:207], v187 offset:38912
	ds_read_b128 v[208:211], v187 offset:39936
	s_add_u32 s24, s24, 0x80000
	s_addc_u32 s25, s25, 0
	s_mov_b32 m0, s36
	s_nop 0
	global_load_lds_dwordx4 v174, s[24:25]
	s_nop 0
	s_mov_b32 m0, s37
	s_nop 0
	global_load_lds_dwordx4 v176, s[24:25]
	s_waitcnt vmcnt(8)
	s_waitcnt lgkmcnt(0)
	s_barrier
	s_nop 0
	s_waitcnt lgkmcnt(0)
	v_mfma_f32_16x16x32_bf16 v[144:147], v[112:115], v[164:167], v[144:147]
	v_mfma_f32_16x16x32_bf16 v[140:143], v[124:127], v[164:167], v[140:143]
	s_waitcnt lgkmcnt(5)
	v_mfma_f32_16x16x32_bf16 v[116:119], v[112:115], v[178:181], v[116:119]
	v_mfma_f32_16x16x32_bf16 v[108:111], v[124:127], v[178:181], v[108:111]
	s_waitcnt lgkmcnt(3)
	v_mfma_f32_16x16x32_bf16 v[96:99], v[112:115], v[196:199], v[96:99]
	v_mfma_f32_16x16x32_bf16 v[92:95], v[124:127], v[196:199], v[92:95]
	s_waitcnt lgkmcnt(1)
	v_mfma_f32_16x16x32_bf16 v[80:83], v[112:115], v[204:207], v[80:83]
	v_mfma_f32_16x16x32_bf16 v[76:79], v[124:127], v[204:207], v[76:79]
	v_mfma_f32_16x16x32_bf16 v[144:147], v[120:123], v[168:171], v[144:147]
	v_mfma_f32_16x16x32_bf16 v[140:143], v[128:131], v[168:171], v[140:143]
	v_mfma_f32_16x16x32_bf16 v[116:119], v[120:123], v[192:195], v[116:119]
	v_mfma_f32_16x16x32_bf16 v[108:111], v[128:131], v[192:195], v[108:111]
	v_mfma_f32_16x16x32_bf16 v[96:99], v[120:123], v[200:203], v[96:99]
	v_mfma_f32_16x16x32_bf16 v[92:95], v[128:131], v[200:203], v[92:95]
	s_waitcnt lgkmcnt(0)
	v_mfma_f32_16x16x32_bf16 v[80:83], v[120:123], v[208:211], v[80:83]
	v_mfma_f32_16x16x32_bf16 v[76:79], v[128:131], v[208:211], v[76:79]
	s_nop 0
	s_nop 0
	v_mfma_f32_16x16x32_bf16 v[136:139], v[148:151], v[164:167], v[136:139]
	v_mfma_f32_16x16x32_bf16 v[132:135], v[156:159], v[164:167], v[132:135]
	v_mfma_f32_16x16x32_bf16 v[104:107], v[148:151], v[178:181], v[104:107]
	v_mfma_f32_16x16x32_bf16 v[100:103], v[156:159], v[178:181], v[100:103]
	v_mfma_f32_16x16x32_bf16 v[88:91], v[148:151], v[196:199], v[88:91]
	v_mfma_f32_16x16x32_bf16 v[84:87], v[156:159], v[196:199], v[84:87]
	v_mfma_f32_16x16x32_bf16 v[72:75], v[148:151], v[204:207], v[72:75]
	v_mfma_f32_16x16x32_bf16 v[68:71], v[156:159], v[204:207], v[68:71]
	v_mfma_f32_16x16x32_bf16 v[136:139], v[152:155], v[168:171], v[136:139]
	v_mfma_f32_16x16x32_bf16 v[132:135], v[160:163], v[168:171], v[132:135]
	v_mfma_f32_16x16x32_bf16 v[104:107], v[152:155], v[192:195], v[104:107]
	v_mfma_f32_16x16x32_bf16 v[100:103], v[160:163], v[192:195], v[100:103]
	v_mfma_f32_16x16x32_bf16 v[88:91], v[152:155], v[200:203], v[88:91]
	v_mfma_f32_16x16x32_bf16 v[84:87], v[160:163], v[200:203], v[84:87]
	v_mfma_f32_16x16x32_bf16 v[72:75], v[152:155], v[208:211], v[72:75]
	v_mfma_f32_16x16x32_bf16 v[68:71], v[160:163], v[208:211], v[68:71]
	s_nop 0
	s_barrier
; #define ER_LOAD(dst, ai, mp) do { _Pragma("unroll") for (int mm = 0; mm < 2; ++mm) _Pragma("unroll") for (int bj = 0; bj < 2; ++bj) \
;             dst[mm][bj] = *(const u32x4*)(xb + (size_t)((ai) * HALF + (2 * (mp) + mm) * 16) * 2048 + bj * HALF); } while (0)
;     __device__ __forceinline__ void operator()(const f32x4 (&acc)[2][2][4][2], const Unit& u, int wr, int wc, int fr, int fq) const {
;         const int row0 = u.pm * BM + wr * 64 + fr, col0 = u.pn * BM + wc * 32 + 8 * fq;
;         const int b = (u.pm < n_lat_panels) ? (u.pm >> 4) : 4;
;         const float* g = gate + (size_t)b * gstride + col0;
;         bf16_t* xb = X + (size_t)row0 * 2048 + col0;
;         f32x4 gv[2][2];
; #pragma unroll
;         for (int bj = 0; bj < 2; ++bj)
; #pragma unroll
;             for (int n = 0; n < 2; ++n) gv[bj][n] = *(const f32x4*)(g + bj * HALF + 4 * n);
;         u32x4 xa[2][2], xc[2][2];
;     ...
;         ER_LOAD(xa, 0, 0); ER_LOAD(xc, 0, 1);
	ds_read_b128 v[164:167], v187 offset:49152
	ds_read_b128 v[168:171], v187 offset:50176
	ds_read_b128 v[178:181], v187 offset:51200
	ds_read_b128 v[192:195], v187 offset:52224
	ds_read_b128 v[196:199], v187 offset:53248
	ds_read_b128 v[200:203], v187 offset:54272
	ds_read_b128 v[204:207], v187 offset:55296
	ds_read_b128 v[208:211], v187 offset:56320
	s_add_u32 s24, s22, 0x80
	s_addc_u32 s25, s23, 0
	s_mov_b32 m0, s44
	s_nop 0
	global_load_lds_dwordx4 v175, s[24:25]
	s_add_u32 s22, s22, 0x80080
	s_mov_b32 m0, s48
	s_nop 0
	global_load_lds_dwordx4 v177, s[24:25]
	s_addc_u32 s23, s23, 0
	s_mov_b32 m0, s52
	s_nop 0
	global_load_lds_dwordx4 v175, s[22:23]
	s_nop 0
	s_mov_b32 m0, s53
	s_nop 0
	global_load_lds_dwordx4 v177, s[22:23]
	s_nop 0
	s_mov_b32 m0, s49
	s_nop 0
	global_load_lds_dwordx4 v174, s[20:21]
	s_nop 0
	s_mov_b32 m0, s51
	s_nop 0
	global_load_lds_dwordx4 v176, s[20:21]
	s_waitcnt vmcnt(8)
	s_waitcnt lgkmcnt(0)
	s_barrier
	s_nop 0
	s_waitcnt lgkmcnt(0)
	v_mfma_f32_16x16x32_bf16 v[64:67], v[112:115], v[164:167], v[64:67]
	v_mfma_f32_16x16x32_bf16 v[60:63], v[124:127], v[164:167], v[60:63]
	s_waitcnt lgkmcnt(5)
	v_mfma_f32_16x16x32_bf16 v[48:51], v[112:115], v[178:181], v[48:51]
	v_mfma_f32_16x16x32_bf16 v[44:47], v[124:127], v[178:181], v[44:47]
	s_waitcnt lgkmcnt(3)
	v_mfma_f32_16x16x32_bf16 v[32:35], v[112:115], v[196:199], v[32:35]
	v_mfma_f32_16x16x32_bf16 v[28:31], v[124:127], v[196:199], v[28:31]
	s_waitcnt lgkmcnt(1)
	v_mfma_f32_16x16x32_bf16 v[16:19], v[112:115], v[204:207], v[16:19]
	v_mfma_f32_16x16x32_bf16 v[12:15], v[124:127], v[204:207], v[12:15]
	v_mfma_f32_16x16x32_bf16 v[64:67], v[120:123], v[168:171], v[64:67]
	v_mfma_f32_16x16x32_bf16 v[60:63], v[128:131], v[168:171], v[60:63]
	v_mfma_f32_16x16x32_bf16 v[48:51], v[120:123], v[192:195], v[48:51]
	v_mfma_f32_16x16x32_bf16 v[44:47], v[128:131], v[192:195], v[44:47]
	v_mfma_f32_16x16x32_bf16 v[32:35], v[120:123], v[200:203], v[32:35]
	v_mfma_f32_16x16x32_bf16 v[28:31], v[128:131], v[200:203], v[28:31]
	s_waitcnt lgkmcnt(0)
	v_mfma_f32_16x16x32_bf16 v[16:19], v[120:123], v[208:211], v[16:19]
	v_mfma_f32_16x16x32_bf16 v[12:15], v[128:131], v[208:211], v[12:15]
	s_nop 0
	s_nop 0
	v_mfma_f32_16x16x32_bf16 v[56:59], v[148:151], v[164:167], v[56:59]
	v_mfma_f32_16x16x32_bf16 v[52:55], v[156:159], v[164:167], v[52:55]
	v_mfma_f32_16x16x32_bf16 v[40:43], v[148:151], v[178:181], v[40:43]
	v_mfma_f32_16x16x32_bf16 v[36:39], v[156:159], v[178:181], v[36:39]
	v_mfma_f32_16x16x32_bf16 v[24:27], v[148:151], v[196:199], v[24:27]
	v_mfma_f32_16x16x32_bf16 v[20:23], v[156:159], v[196:199], v[20:23]
	v_mfma_f32_16x16x32_bf16 v[6:9], v[148:151], v[204:207], v[8:11]
	v_mfma_f32_16x16x32_bf16 v[2:5], v[156:159], v[204:207], v[2:5]
	v_mfma_f32_16x16x32_bf16 v[56:59], v[152:155], v[168:171], v[56:59]
	v_mfma_f32_16x16x32_bf16 v[52:55], v[160:163], v[168:171], v[52:55]
	v_mfma_f32_16x16x32_bf16 v[40:43], v[152:155], v[192:195], v[40:43]
	v_mfma_f32_16x16x32_bf16 v[36:39], v[160:163], v[192:195], v[36:39]
	v_mfma_f32_16x16x32_bf16 v[24:27], v[152:155], v[200:203], v[24:27]
	v_mfma_f32_16x16x32_bf16 v[20:23], v[160:163], v[200:203], v[20:23]
	v_mfma_f32_16x16x32_bf16 v[8:11], v[152:155], v[208:211], v[6:9]
	v_mfma_f32_16x16x32_bf16 v[4:7], v[160:163], v[208:211], v[2:5]
	s_nop 0
	s_barrier
	s_add_i32 s78, s78, 2
	s_add_u32 s79, s79, 0x100
	s_addc_u32 s82, s82, 0
	s_add_u32 s18, s18, 0x100
	s_addc_u32 s19, s19, 0
	s_cmp_gt_u32 s78, 29
	s_cbranch_scc0 .LBB0_932
	s_add_u32 s18, s7, 0x80080
	s_addc_u32 s19, s6, 0
	s_min_i32 s6, s69, 64
	v_lshl_add_u32 v2, s69, 8, v184
	s_ashr_i32 s6, s6, 4
	s_mul_hi_i32 s7, s6, 0xc000
	s_mul_i32 s6, s6, 0xc000
	v_ashrrev_i32_e32 v3, 31, v2
	s_mov_b32 m0, s57
	s_nop 0
	global_load_lds_dwordx4 v174, s[18:19]
	v_lshl_or_b32 v148, s67, 8, v185
	s_add_u32 s6, s40, s6
	v_lshlrev_b64 v[2:3], 12, v[2:3]
	s_mov_b32 m0, s63
	s_nop 0
	global_load_lds_dwordx4 v176, s[18:19]
	s_addc_u32 s7, s41, s7
	v_ashrrev_i32_e32 v149, 31, v148
	v_lshl_add_u64 v[2:3], s[80:81], 0, v[2:3]
	v_lshl_add_u64 v[112:113], v[148:149], 2, s[6:7]
	v_lshl_add_u64 v[2:3], v[148:149], 1, v[2:3]
	global_load_dwordx4 v[128:131], v[112:113], off
	global_load_dwordx4 v[124:127], v[112:113], off offset:16
	global_load_dwordx4 v[120:123], v[112:113], off offset:512
	global_load_dwordx4 v[112:115], v[112:113], off offset:528
	global_load_dwordx4 v[178:181], v[2:3], off
	global_load_dwordx4 v[192:195], v[2:3], off offset:256
	v_add_co_u32_e32 v172, vcc, 0x10000, v2
	s_nop 1
	v_addc_co_u32_e32 v173, vcc, 0, v3, vcc
	global_load_dwordx4 v[196:199], v[172:173], off
	global_load_dwordx4 v[164:167], v[172:173], off offset:256
	v_add_co_u32_e32 v170, vcc, 0x20000, v2
	s_nop 1
	v_addc_co_u32_e32 v171, vcc, 0, v3, vcc
	global_load_dwordx4 v[160:163], v[170:171], off
	global_load_dwordx4 v[156:159], v[170:171], off offset:256
	v_add_co_u32_e32 v168, vcc, 0x30000, v2
	s_nop 1
	v_addc_co_u32_e32 v169, vcc, 0, v3, vcc
	global_load_dwordx4 v[152:155], v[168:169], off
	global_load_dwordx4 v[148:151], v[168:169], off offset:256
	v_add_co_u32_e32 v244, vcc, 0x80000, v2
	s_nop 1
	v_addc_co_u32_e32 v245, vcc, 0, v3, vcc
	global_load_dwordx4 v[212:215], v[244:245], off
	global_load_dwordx4 v[216:219], v[244:245], off offset:256
	v_add_co_u32_e32 v246, vcc, 0x90000, v2
	s_nop 1
	v_addc_co_u32_e32 v247, vcc, 0, v3, vcc
	global_load_dwordx4 v[220:223], v[246:247], off
	global_load_dwordx4 v[224:227], v[246:247], off offset:256
	v_add_co_u32_e32 v248, vcc, 0xa0000, v2
	s_nop 1
	v_addc_co_u32_e32 v249, vcc, 0, v3, vcc
	global_load_dwordx4 v[228:231], v[248:249], off
	global_load_dwordx4 v[232:235], v[248:249], off offset:256
	v_add_co_u32_e32 v250, vcc, 0xb0000, v2
	s_nop 1
	v_addc_co_u32_e32 v251, vcc, 0, v3, vcc
	global_load_dwordx4 v[236:239], v[250:251], off
	global_load_dwordx4 v[240:243], v[250:251], off offset:256
	s_nop 0
	s_nop 0
	s_mov_b32 s6, 0x10000
	s_mov_b32 s6, 0x90000
	s_nop 0
	s_mov_b64 s[18:19], -1
	s_nop 0
	s_waitcnt vmcnt(15)
; #define ER_LOAD(dst, ai, mp) do { _Pragma("unroll") for (int mm = 0; mm < 2; ++mm) _Pragma("unroll") for (int bj = 0; bj < 2; ++bj) \
;             dst[mm][bj] = *(const u32x4*)(xb + (size_t)((ai) * HALF + (2 * (mp) + mm) * 16) * 2048 + bj * HALF); } while (0)
;     __device__ __forceinline__ void operator()(const f32x4 (&acc)[2][2][4][2], const Unit& u, int wr, int wc, int fr, int fq) const {
;     ...
;         ER_LOAD(xa, 0, 0); ER_LOAD(xc, 0, 1);
;         ER_STORE(xa, 0, 0); ER_LOAD(xa, 1, 0);
;         ER_STORE(xc, 0, 1); ER_LOAD(xc, 1, 1);
;         ER_STORE(xa, 1, 0); ER_STORE(xc, 1, 1);
	v_cvt_f32_f16_e32 v200, v178
	v_cvt_f32_f16_sdwa v201, v178 dst_sel:DWORD dst_unused:UNUSED_PAD src0_sel:WORD_1
	v_cvt_f32_f16_e32 v178, v179
	v_cvt_f32_f16_sdwa v179, v179 dst_sel:DWORD dst_unused:UNUSED_PAD src0_sel:WORD_1
	v_pk_fma_f32 v[144:145], v[144:145], v[128:129], v[200:201]
	v_pk_fma_f32 v[146:147], v[146:147], v[130:131], v[178:179]
	v_cvt_f32_f16_e32 v178, v180
	v_cvt_f32_f16_sdwa v179, v180 dst_sel:DWORD dst_unused:UNUSED_PAD src0_sel:WORD_1
	v_cvt_f32_f16_e32 v180, v181
	v_cvt_f32_f16_sdwa v181, v181 dst_sel:DWORD dst_unused:UNUSED_PAD src0_sel:WORD_1
	v_pk_fma_f32 v[180:181], v[142:143], v[126:127], v[180:181]
	v_pk_fma_f32 v[142:143], v[140:141], v[124:125], v[178:179]
	v_cvt_pk_f16_f32 v140, v144, v145
	v_cvt_pk_f16_f32 v141, v146, v147
	v_cvt_pk_f16_f32 v142, v142, v143
	v_cvt_pk_f16_f32 v143, v180, v181
	global_store_dwordx4 v[2:3], v[140:143], off
	s_nop 1
	s_waitcnt vmcnt(15)
	v_cvt_f32_f16_e32 v140, v192
	v_cvt_f32_f16_sdwa v141, v192 dst_sel:DWORD dst_unused:UNUSED_PAD src0_sel:WORD_1
	v_cvt_f32_f16_e32 v142, v193
	v_cvt_f32_f16_sdwa v143, v193 dst_sel:DWORD dst_unused:UNUSED_PAD src0_sel:WORD_1
	v_pk_fma_f32 v[136:137], v[136:137], v[120:121], v[140:141]
	v_cvt_f32_f16_e32 v140, v194
	v_pk_fma_f32 v[138:139], v[138:139], v[122:123], v[142:143]
	v_cvt_f32_f16_sdwa v141, v194 dst_sel:DWORD dst_unused:UNUSED_PAD src0_sel:WORD_1
	v_cvt_f32_f16_e32 v142, v195
	v_cvt_f32_f16_sdwa v143, v195 dst_sel:DWORD dst_unused:UNUSED_PAD src0_sel:WORD_1
	v_pk_fma_f32 v[142:143], v[134:135], v[114:115], v[142:143]
	v_pk_fma_f32 v[134:135], v[132:133], v[112:113], v[140:141]
	v_cvt_pk_f16_f32 v132, v136, v137
	v_cvt_pk_f16_f32 v133, v138, v139
	v_cvt_pk_f16_f32 v134, v134, v135
	v_cvt_pk_f16_f32 v135, v142, v143
	global_store_dwordx4 v[2:3], v[132:135], off offset:256
	s_waitcnt vmcnt(13)
	v_cvt_f32_f16_e32 v136, v160
	v_cvt_f32_f16_sdwa v137, v160 dst_sel:DWORD dst_unused:UNUSED_PAD src0_sel:WORD_1
	v_cvt_f32_f16_e32 v132, v196
	v_cvt_f32_f16_sdwa v133, v196 dst_sel:DWORD dst_unused:UNUSED_PAD src0_sel:WORD_1
	v_cvt_f32_f16_e32 v134, v197
	v_cvt_f32_f16_sdwa v135, v197 dst_sel:DWORD dst_unused:UNUSED_PAD src0_sel:WORD_1
	v_cvt_f32_f16_e32 v138, v161
	v_pk_fma_f32 v[116:117], v[116:117], v[128:129], v[132:133]
	v_cvt_f32_f16_e32 v132, v198
	v_pk_fma_f32 v[118:119], v[118:119], v[130:131], v[134:135]
	v_cvt_f32_f16_sdwa v133, v198 dst_sel:DWORD dst_unused:UNUSED_PAD src0_sel:WORD_1
	v_cvt_f32_f16_e32 v134, v199
	v_cvt_f32_f16_sdwa v135, v199 dst_sel:DWORD dst_unused:UNUSED_PAD src0_sel:WORD_1
	v_cvt_f32_f16_sdwa v139, v161 dst_sel:DWORD dst_unused:UNUSED_PAD src0_sel:WORD_1
	v_pk_fma_f32 v[96:97], v[96:97], v[128:129], v[136:137]
	v_cvt_f32_f16_e32 v136, v162
	v_pk_fma_f32 v[134:135], v[110:111], v[126:127], v[134:135]
	v_pk_fma_f32 v[110:111], v[108:109], v[124:125], v[132:133]
	v_cvt_pk_f16_f32 v108, v116, v117
	v_cvt_pk_f16_f32 v109, v118, v119
	v_cvt_pk_f16_f32 v110, v110, v111
	v_cvt_pk_f16_f32 v111, v134, v135
	global_store_dwordx4 v[172:173], v[108:111], off
	v_add_co_u32_e32 v134, vcc, s83, v2
	s_nop 0
	v_cvt_f32_f16_e32 v108, v164
	v_cvt_f32_f16_sdwa v109, v164 dst_sel:DWORD dst_unused:UNUSED_PAD src0_sel:WORD_1
	v_cvt_f32_f16_e32 v110, v165
	v_cvt_f32_f16_sdwa v111, v165 dst_sel:DWORD dst_unused:UNUSED_PAD src0_sel:WORD_1
	v_addc_co_u32_e32 v135, vcc, 0, v3, vcc
	v_pk_fma_f32 v[104:105], v[104:105], v[120:121], v[108:109]
	v_pk_fma_f32 v[106:107], v[106:107], v[122:123], v[110:111]
	v_cvt_f32_f16_e32 v108, v166
	v_cvt_f32_f16_sdwa v109, v166 dst_sel:DWORD dst_unused:UNUSED_PAD src0_sel:WORD_1
	v_cvt_f32_f16_e32 v110, v167
	v_cvt_f32_f16_sdwa v111, v167 dst_sel:DWORD dst_unused:UNUSED_PAD src0_sel:WORD_1
	v_pk_fma_f32 v[98:99], v[98:99], v[130:131], v[138:139]
	v_cvt_f32_f16_sdwa v137, v162 dst_sel:DWORD dst_unused:UNUSED_PAD src0_sel:WORD_1
	v_cvt_f32_f16_e32 v138, v163
	v_pk_fma_f32 v[110:111], v[102:103], v[114:115], v[110:111]
	v_pk_fma_f32 v[102:103], v[100:101], v[112:113], v[108:109]
	v_cvt_pk_f16_f32 v100, v104, v105
	v_cvt_pk_f16_f32 v101, v106, v107
	v_cvt_pk_f16_f32 v102, v102, v103
	v_cvt_pk_f16_f32 v103, v110, v111
	global_store_dwordx4 v[172:173], v[100:103], off offset:256
	v_cvt_f32_f16_sdwa v139, v163 dst_sel:DWORD dst_unused:UNUSED_PAD src0_sel:WORD_1
	v_add_co_u32_e32 v132, vcc, s6, v2
	s_mov_b32 s6, 0xa0000
	v_pk_fma_f32 v[138:139], v[94:95], v[126:127], v[138:139]
	v_pk_fma_f32 v[94:95], v[92:93], v[124:125], v[136:137]
	v_addc_co_u32_e32 v133, vcc, 0, v3, vcc
	v_cvt_pk_f16_f32 v92, v96, v97
	v_cvt_pk_f16_f32 v93, v98, v99
	v_cvt_pk_f16_f32 v94, v94, v95
	v_cvt_pk_f16_f32 v95, v138, v139
	s_nop 0
	global_store_dwordx4 v[170:171], v[92:95], off
	s_nop 1
	s_waitcnt vmcnt(15)
	v_cvt_f32_f16_e32 v92, v156
	v_cvt_f32_f16_sdwa v93, v156 dst_sel:DWORD dst_unused:UNUSED_PAD src0_sel:WORD_1
	v_cvt_f32_f16_e32 v94, v157
	v_cvt_f32_f16_sdwa v95, v157 dst_sel:DWORD dst_unused:UNUSED_PAD src0_sel:WORD_1
	v_pk_fma_f32 v[88:89], v[88:89], v[120:121], v[92:93]
	v_cvt_f32_f16_e32 v92, v158
	v_pk_fma_f32 v[90:91], v[90:91], v[122:123], v[94:95]
	v_cvt_f32_f16_sdwa v93, v158 dst_sel:DWORD dst_unused:UNUSED_PAD src0_sel:WORD_1
	v_cvt_f32_f16_e32 v94, v159
	v_cvt_f32_f16_sdwa v95, v159 dst_sel:DWORD dst_unused:UNUSED_PAD src0_sel:WORD_1
	v_pk_fma_f32 v[94:95], v[86:87], v[114:115], v[94:95]
	v_pk_fma_f32 v[86:87], v[84:85], v[112:113], v[92:93]
	v_cvt_pk_f16_f32 v84, v88, v89
	v_cvt_pk_f16_f32 v85, v90, v91
	v_cvt_pk_f16_f32 v86, v86, v87
	v_cvt_pk_f16_f32 v87, v94, v95
	global_store_dwordx4 v[170:171], v[84:87], off offset:256
	s_waitcnt vmcnt(13)
; #define ER_LOAD(dst, ai, mp) do { _Pragma("unroll") for (int mm = 0; mm < 2; ++mm) _Pragma("unroll") for (int bj = 0; bj < 2; ++bj) \
;             dst[mm][bj] = *(const u32x4*)(xb + (size_t)((ai) * HALF + (2 * (mp) + mm) * 16) * 2048 + bj * HALF); } while (0)
;     __device__ __forceinline__ void operator()(const f32x4 (&acc)[2][2][4][2], const Unit& u, int wr, int wc, int fr, int fq) const {
;     ...
;         ER_LOAD(xa, 0, 0); ER_LOAD(xc, 0, 1);
;         ER_STORE(xa, 0, 0); ER_LOAD(xa, 1, 0);
;         ER_STORE(xc, 0, 1); ER_LOAD(xc, 1, 1);
;         ER_STORE(xa, 1, 0); ER_STORE(xc, 1, 1);
	v_cvt_f32_f16_e32 v88, v213
	v_cvt_f32_f16_e32 v84, v152
	v_cvt_f32_f16_sdwa v85, v152 dst_sel:DWORD dst_unused:UNUSED_PAD src0_sel:WORD_1
	v_cvt_f32_f16_e32 v86, v153
	v_cvt_f32_f16_sdwa v87, v153 dst_sel:DWORD dst_unused:UNUSED_PAD src0_sel:WORD_1
	v_cvt_f32_f16_sdwa v89, v213 dst_sel:DWORD dst_unused:UNUSED_PAD src0_sel:WORD_1
	v_pk_fma_f32 v[80:81], v[80:81], v[128:129], v[84:85]
	v_cvt_f32_f16_e32 v84, v154
	v_pk_fma_f32 v[82:83], v[82:83], v[130:131], v[86:87]
	v_cvt_f32_f16_sdwa v85, v154 dst_sel:DWORD dst_unused:UNUSED_PAD src0_sel:WORD_1
	v_cvt_f32_f16_e32 v86, v155
	v_cvt_f32_f16_sdwa v87, v155 dst_sel:DWORD dst_unused:UNUSED_PAD src0_sel:WORD_1
	v_pk_fma_f32 v[66:67], v[66:67], v[130:131], v[88:89]
	v_cvt_f32_f16_e32 v88, v215
	v_cvt_f32_f16_sdwa v89, v215 dst_sel:DWORD dst_unused:UNUSED_PAD src0_sel:WORD_1
	v_pk_fma_f32 v[86:87], v[78:79], v[126:127], v[86:87]
	v_pk_fma_f32 v[78:79], v[76:77], v[124:125], v[84:85]
	v_cvt_pk_f16_f32 v76, v80, v81
	v_cvt_pk_f16_f32 v77, v82, v83
	v_cvt_pk_f16_f32 v78, v78, v79
	v_cvt_pk_f16_f32 v79, v86, v87
	global_store_dwordx4 v[168:169], v[76:79], off
	v_add_co_u32_e32 v84, vcc, s6, v2
	s_nop 0
	v_cvt_f32_f16_e32 v76, v148
	v_cvt_f32_f16_sdwa v77, v148 dst_sel:DWORD dst_unused:UNUSED_PAD src0_sel:WORD_1
	v_cvt_f32_f16_e32 v78, v149
	v_cvt_f32_f16_sdwa v79, v149 dst_sel:DWORD dst_unused:UNUSED_PAD src0_sel:WORD_1
	v_addc_co_u32_e32 v85, vcc, 0, v3, vcc
	v_pk_fma_f32 v[72:73], v[72:73], v[120:121], v[76:77]
	v_pk_fma_f32 v[74:75], v[74:75], v[122:123], v[78:79]
	v_cvt_f32_f16_e32 v76, v150
	v_cvt_f32_f16_sdwa v77, v150 dst_sel:DWORD dst_unused:UNUSED_PAD src0_sel:WORD_1
	v_cvt_f32_f16_e32 v78, v151
	v_cvt_f32_f16_sdwa v79, v151 dst_sel:DWORD dst_unused:UNUSED_PAD src0_sel:WORD_1
	s_mov_b32 s6, 0xb0000
	v_add_co_u32_e32 v2, vcc, s6, v2
	v_pk_fma_f32 v[78:79], v[70:71], v[114:115], v[78:79]
	v_pk_fma_f32 v[70:71], v[68:69], v[112:113], v[76:77]
	v_cvt_pk_f16_f32 v68, v72, v73
	v_cvt_pk_f16_f32 v69, v74, v75
	v_cvt_pk_f16_f32 v70, v70, v71
	v_cvt_pk_f16_f32 v71, v78, v79
	global_store_dwordx4 v[168:169], v[68:71], off offset:256
	v_addc_co_u32_e32 v3, vcc, 0, v3, vcc
	v_cvt_f32_f16_e32 v86, v212
	v_cvt_f32_f16_sdwa v87, v212 dst_sel:DWORD dst_unused:UNUSED_PAD src0_sel:WORD_1
	v_pk_fma_f32 v[88:89], v[62:63], v[126:127], v[88:89]
	s_and_b64 vcc, s[16:17], exec
	v_pk_fma_f32 v[64:65], v[64:65], v[128:129], v[86:87]
	v_cvt_f32_f16_e32 v86, v214
	v_cvt_f32_f16_sdwa v87, v214 dst_sel:DWORD dst_unused:UNUSED_PAD src0_sel:WORD_1
	v_pk_fma_f32 v[62:63], v[60:61], v[124:125], v[86:87]
	v_cvt_pk_f16_f32 v60, v64, v65
	v_cvt_pk_f16_f32 v61, v66, v67
	v_cvt_pk_f16_f32 v62, v62, v63
	v_cvt_pk_f16_f32 v63, v88, v89
	global_store_dwordx4 v[134:135], v[60:63], off
	s_nop 1
	s_waitcnt vmcnt(15)
	v_cvt_f32_f16_e32 v60, v216
	v_cvt_f32_f16_sdwa v61, v216 dst_sel:DWORD dst_unused:UNUSED_PAD src0_sel:WORD_1
	v_cvt_f32_f16_e32 v62, v217
	v_cvt_f32_f16_sdwa v63, v217 dst_sel:DWORD dst_unused:UNUSED_PAD src0_sel:WORD_1
	v_pk_fma_f32 v[56:57], v[56:57], v[120:121], v[60:61]
	v_cvt_f32_f16_e32 v60, v218
	v_pk_fma_f32 v[58:59], v[58:59], v[122:123], v[62:63]
	v_cvt_f32_f16_sdwa v61, v218 dst_sel:DWORD dst_unused:UNUSED_PAD src0_sel:WORD_1
	v_cvt_f32_f16_e32 v62, v219
	v_cvt_f32_f16_sdwa v63, v219 dst_sel:DWORD dst_unused:UNUSED_PAD src0_sel:WORD_1
	v_pk_fma_f32 v[62:63], v[54:55], v[114:115], v[62:63]
	v_pk_fma_f32 v[54:55], v[52:53], v[112:113], v[60:61]
	v_cvt_pk_f16_f32 v52, v56, v57
	v_cvt_pk_f16_f32 v53, v58, v59
	v_cvt_pk_f16_f32 v54, v54, v55
	v_cvt_pk_f16_f32 v55, v62, v63
	global_store_dwordx4 v[134:135], v[52:55], off offset:256
	s_nop 1
	s_waitcnt vmcnt(15)
	v_cvt_f32_f16_e32 v52, v220
	v_cvt_f32_f16_sdwa v53, v220 dst_sel:DWORD dst_unused:UNUSED_PAD src0_sel:WORD_1
	v_cvt_f32_f16_e32 v54, v221
	v_cvt_f32_f16_sdwa v55, v221 dst_sel:DWORD dst_unused:UNUSED_PAD src0_sel:WORD_1
	v_pk_fma_f32 v[48:49], v[48:49], v[128:129], v[52:53]
	v_cvt_f32_f16_e32 v52, v222
	v_pk_fma_f32 v[50:51], v[50:51], v[130:131], v[54:55]
	v_cvt_f32_f16_sdwa v53, v222 dst_sel:DWORD dst_unused:UNUSED_PAD src0_sel:WORD_1
	v_cvt_f32_f16_e32 v54, v223
	v_cvt_f32_f16_sdwa v55, v223 dst_sel:DWORD dst_unused:UNUSED_PAD src0_sel:WORD_1
	v_pk_fma_f32 v[54:55], v[46:47], v[126:127], v[54:55]
	v_pk_fma_f32 v[46:47], v[44:45], v[124:125], v[52:53]
	v_cvt_pk_f16_f32 v44, v48, v49
	v_cvt_pk_f16_f32 v45, v50, v51
	v_cvt_pk_f16_f32 v46, v46, v47
	v_cvt_pk_f16_f32 v47, v54, v55
	global_store_dwordx4 v[132:133], v[44:47], off
	s_nop 1
	s_waitcnt vmcnt(15)
	v_cvt_f32_f16_e32 v44, v224
	v_cvt_f32_f16_sdwa v45, v224 dst_sel:DWORD dst_unused:UNUSED_PAD src0_sel:WORD_1
	v_cvt_f32_f16_e32 v46, v225
	v_cvt_f32_f16_sdwa v47, v225 dst_sel:DWORD dst_unused:UNUSED_PAD src0_sel:WORD_1
	v_pk_fma_f32 v[40:41], v[40:41], v[120:121], v[44:45]
	v_cvt_f32_f16_e32 v44, v226
	v_pk_fma_f32 v[42:43], v[42:43], v[122:123], v[46:47]
	v_cvt_f32_f16_sdwa v45, v226 dst_sel:DWORD dst_unused:UNUSED_PAD src0_sel:WORD_1
	v_cvt_f32_f16_e32 v46, v227
	v_cvt_f32_f16_sdwa v47, v227 dst_sel:DWORD dst_unused:UNUSED_PAD src0_sel:WORD_1
	v_pk_fma_f32 v[46:47], v[38:39], v[114:115], v[46:47]
	v_pk_fma_f32 v[38:39], v[36:37], v[112:113], v[44:45]
	v_cvt_pk_f16_f32 v36, v40, v41
	v_cvt_pk_f16_f32 v37, v42, v43
	v_cvt_pk_f16_f32 v38, v38, v39
	v_cvt_pk_f16_f32 v39, v46, v47
	global_store_dwordx4 v[132:133], v[36:39], off offset:256
	s_nop 0
	s_waitcnt vmcnt(15)
; #define ER_LOAD(dst, ai, mp) do { _Pragma("unroll") for (int mm = 0; mm < 2; ++mm) _Pragma("unroll") for (int bj = 0; bj < 2; ++bj) \
;             dst[mm][bj] = *(const u32x4*)(xb + (size_t)((ai) * HALF + (2 * (mp) + mm) * 16) * 2048 + bj * HALF); } while (0)
;     __device__ __forceinline__ void operator()(const f32x4 (&acc)[2][2][4][2], const Unit& u, int wr, int wc, int fr, int fq) const {
;     ...
;         ER_LOAD(xa, 0, 0); ER_LOAD(xc, 0, 1);
;         ER_STORE(xa, 0, 0); ER_LOAD(xa, 1, 0);
;         ER_STORE(xc, 0, 1); ER_LOAD(xc, 1, 1);
;         ER_STORE(xa, 1, 0); ER_STORE(xc, 1, 1);
	v_cvt_f32_f16_e32 v36, v228
	v_cvt_f32_f16_sdwa v37, v228 dst_sel:DWORD dst_unused:UNUSED_PAD src0_sel:WORD_1
	v_cvt_f32_f16_e32 v38, v229
	v_cvt_f32_f16_sdwa v39, v229 dst_sel:DWORD dst_unused:UNUSED_PAD src0_sel:WORD_1
	v_pk_fma_f32 v[32:33], v[32:33], v[128:129], v[36:37]
	v_cvt_f32_f16_e32 v36, v230
	v_pk_fma_f32 v[34:35], v[34:35], v[130:131], v[38:39]
	v_cvt_f32_f16_sdwa v37, v230 dst_sel:DWORD dst_unused:UNUSED_PAD src0_sel:WORD_1
	v_cvt_f32_f16_e32 v38, v231
	v_cvt_f32_f16_sdwa v39, v231 dst_sel:DWORD dst_unused:UNUSED_PAD src0_sel:WORD_1
	v_pk_fma_f32 v[38:39], v[30:31], v[126:127], v[38:39]
	v_pk_fma_f32 v[30:31], v[28:29], v[124:125], v[36:37]
	v_cvt_pk_f16_f32 v28, v32, v33
	v_cvt_pk_f16_f32 v29, v34, v35
	v_cvt_pk_f16_f32 v30, v30, v31
	v_cvt_pk_f16_f32 v31, v38, v39
	global_store_dwordx4 v[84:85], v[28:31], off
	s_nop 1
	s_waitcnt vmcnt(15)
	v_cvt_f32_f16_e32 v28, v232
	v_cvt_f32_f16_sdwa v29, v232 dst_sel:DWORD dst_unused:UNUSED_PAD src0_sel:WORD_1
	v_cvt_f32_f16_e32 v30, v233
	v_cvt_f32_f16_sdwa v31, v233 dst_sel:DWORD dst_unused:UNUSED_PAD src0_sel:WORD_1
	v_pk_fma_f32 v[24:25], v[24:25], v[120:121], v[28:29]
	v_cvt_f32_f16_e32 v28, v234
	v_pk_fma_f32 v[26:27], v[26:27], v[122:123], v[30:31]
	v_cvt_f32_f16_sdwa v29, v234 dst_sel:DWORD dst_unused:UNUSED_PAD src0_sel:WORD_1
	v_cvt_f32_f16_e32 v30, v235
	v_cvt_f32_f16_sdwa v31, v235 dst_sel:DWORD dst_unused:UNUSED_PAD src0_sel:WORD_1
	v_pk_fma_f32 v[30:31], v[22:23], v[114:115], v[30:31]
	v_pk_fma_f32 v[22:23], v[20:21], v[112:113], v[28:29]
	v_cvt_pk_f16_f32 v20, v24, v25
	v_cvt_pk_f16_f32 v21, v26, v27
	v_cvt_pk_f16_f32 v22, v22, v23
	v_cvt_pk_f16_f32 v23, v30, v31
	global_store_dwordx4 v[84:85], v[20:23], off offset:256
	s_nop 1
	s_waitcnt vmcnt(15)
	v_cvt_f32_f16_e32 v20, v236
	v_cvt_f32_f16_sdwa v21, v236 dst_sel:DWORD dst_unused:UNUSED_PAD src0_sel:WORD_1
	v_cvt_f32_f16_e32 v22, v237
	v_cvt_f32_f16_sdwa v23, v237 dst_sel:DWORD dst_unused:UNUSED_PAD src0_sel:WORD_1
	v_pk_fma_f32 v[16:17], v[16:17], v[128:129], v[20:21]
	v_cvt_f32_f16_e32 v20, v238
	v_pk_fma_f32 v[18:19], v[18:19], v[130:131], v[22:23]
	v_cvt_f32_f16_sdwa v21, v238 dst_sel:DWORD dst_unused:UNUSED_PAD src0_sel:WORD_1
	v_cvt_f32_f16_e32 v22, v239
	v_cvt_f32_f16_sdwa v23, v239 dst_sel:DWORD dst_unused:UNUSED_PAD src0_sel:WORD_1
	v_pk_fma_f32 v[22:23], v[14:15], v[126:127], v[22:23]
	v_pk_fma_f32 v[14:15], v[12:13], v[124:125], v[20:21]
	v_cvt_pk_f16_f32 v12, v16, v17
	v_cvt_pk_f16_f32 v13, v18, v19
	v_cvt_pk_f16_f32 v14, v14, v15
	v_cvt_pk_f16_f32 v15, v22, v23
	global_store_dwordx4 v[2:3], v[12:15], off
	s_nop 1
	s_waitcnt vmcnt(15)
	v_cvt_f32_f16_e32 v12, v240
	v_cvt_f32_f16_sdwa v13, v240 dst_sel:DWORD dst_unused:UNUSED_PAD src0_sel:WORD_1
	v_cvt_f32_f16_e32 v14, v241
	v_cvt_f32_f16_sdwa v15, v241 dst_sel:DWORD dst_unused:UNUSED_PAD src0_sel:WORD_1
	v_pk_fma_f32 v[8:9], v[8:9], v[120:121], v[12:13]
	v_cvt_f32_f16_e32 v12, v242
	v_pk_fma_f32 v[10:11], v[10:11], v[122:123], v[14:15]
	v_cvt_f32_f16_sdwa v13, v242 dst_sel:DWORD dst_unused:UNUSED_PAD src0_sel:WORD_1
	v_cvt_f32_f16_e32 v14, v243
	v_cvt_f32_f16_sdwa v15, v243 dst_sel:DWORD dst_unused:UNUSED_PAD src0_sel:WORD_1
	v_pk_fma_f32 v[14:15], v[6:7], v[114:115], v[14:15]
	v_pk_fma_f32 v[6:7], v[4:5], v[112:113], v[12:13]
	v_cvt_pk_f16_f32 v4, v8, v9
	v_cvt_pk_f16_f32 v5, v10, v11
	v_cvt_pk_f16_f32 v6, v6, v7
	v_cvt_pk_f16_f32 v7, v14, v15
	global_store_dwordx4 v[2:3], v[4:7], off offset:256
	s_cbranch_vccz .LBB0_919
	ds_read_b128 v[2:5], v0
	ds_read_b128 v[6:9], v0 offset:1024
	ds_read_b128 v[10:13], v0 offset:2048
	ds_read_b128 v[14:17], v0 offset:3072
	ds_read_b128 v[18:21], v188
	ds_read_b128 v[22:25], v188 offset:1024
	ds_read_b128 v[26:29], v188 offset:2048
	ds_read_b128 v[30:33], v188 offset:3072
	s_add_u32 s18, s12, 0x100
	s_addc_u32 s19, s13, 0
	s_add_u32 s16, s12, 0x180
	s_addc_u32 s17, s13, 0
	s_add_u32 s6, s14, 0x100
	s_addc_u32 s7, s15, 0
	ds_read_b128 v[34:37], v187
	ds_read_b128 v[38:41], v187 offset:1024
	ds_read_b128 v[42:45], v187 offset:2048
	ds_read_b128 v[46:49], v187 offset:3072
	ds_read_b128 v[50:53], v187 offset:4096
	ds_read_b128 v[54:57], v187 offset:5120
	ds_read_b128 v[58:61], v187 offset:6144
	ds_read_b128 v[62:65], v187 offset:7168
	s_waitcnt vmcnt(44)
	s_waitcnt lgkmcnt(0)
	s_barrier
	s_nop 0
	s_waitcnt lgkmcnt(0)
	v_mfma_f32_16x16x32_bf16 v[90:93], v[2:5], v[58:61], 0
	v_mfma_f32_16x16x32_bf16 v[66:69], v[2:5], v[34:37], 0
	v_mfma_f32_16x16x32_bf16 v[70:73], v[10:13], v[34:37], 0
	v_mfma_f32_16x16x32_bf16 v[74:77], v[2:5], v[42:45], 0
	v_mfma_f32_16x16x32_bf16 v[78:81], v[10:13], v[42:45], 0
	v_mfma_f32_16x16x32_bf16 v[82:85], v[2:5], v[50:53], 0
	v_mfma_f32_16x16x32_bf16 v[86:89], v[10:13], v[50:53], 0
	v_mfma_f32_16x16x32_bf16 v[100:103], v[6:9], v[62:65], v[90:93]
	v_mfma_f32_16x16x32_bf16 v[90:93], v[10:13], v[58:61], 0
	v_mfma_f32_16x16x32_bf16 v[66:69], v[6:9], v[38:41], v[66:69]
	v_mfma_f32_16x16x32_bf16 v[70:73], v[14:17], v[38:41], v[70:73]
	v_mfma_f32_16x16x32_bf16 v[74:77], v[6:9], v[46:49], v[74:77]
	v_mfma_f32_16x16x32_bf16 v[78:81], v[14:17], v[46:49], v[78:81]
	v_mfma_f32_16x16x32_bf16 v[82:85], v[6:9], v[54:57], v[82:85]
	v_mfma_f32_16x16x32_bf16 v[86:89], v[14:17], v[54:57], v[86:89]
	v_mfma_f32_16x16x32_bf16 v[104:107], v[14:17], v[62:65], v[90:93]
	s_nop 0
	s_nop 0
	v_mfma_f32_16x16x32_bf16 v[90:93], v[18:21], v[34:37], 0
	v_mfma_f32_16x16x32_bf16 v[34:37], v[26:29], v[34:37], 0
	v_mfma_f32_16x16x32_bf16 v[112:115], v[22:25], v[38:41], v[90:93]
	v_mfma_f32_16x16x32_bf16 v[34:37], v[30:33], v[38:41], v[34:37]
	v_mfma_f32_16x16x32_bf16 v[38:41], v[18:21], v[42:45], 0
	v_mfma_f32_16x16x32_bf16 v[42:45], v[26:29], v[42:45], 0
	v_mfma_f32_16x16x32_bf16 v[38:41], v[22:25], v[46:49], v[38:41]
	v_mfma_f32_16x16x32_bf16 v[42:45], v[30:33], v[46:49], v[42:45]
	v_mfma_f32_16x16x32_bf16 v[46:49], v[18:21], v[50:53], 0
	v_mfma_f32_16x16x32_bf16 v[50:53], v[26:29], v[50:53], 0
	v_mfma_f32_16x16x32_bf16 v[46:49], v[22:25], v[54:57], v[46:49]
	v_mfma_f32_16x16x32_bf16 v[50:53], v[30:33], v[54:57], v[50:53]
	v_mfma_f32_16x16x32_bf16 v[54:57], v[18:21], v[58:61], 0
	v_mfma_f32_16x16x32_bf16 v[58:61], v[26:29], v[58:61], 0
	v_mfma_f32_16x16x32_bf16 v[54:57], v[22:25], v[62:65], v[54:57]
	v_mfma_f32_16x16x32_bf16 v[58:61], v[30:33], v[62:65], v[58:61]
	s_nop 0
	s_barrier
	ds_read_b128 v[62:65], v187 offset:16384
	ds_read_b128 v[90:93], v187 offset:17408
	ds_read_b128 v[94:97], v187 offset:18432
	ds_read_b128 v[108:111], v187 offset:19456
	ds_read_b128 v[116:119], v187 offset:20480
	ds_read_b128 v[120:123], v187 offset:21504
	ds_read_b128 v[124:127], v187 offset:22528
	ds_read_b128 v[128:131], v187 offset:23552
	s_mov_b32 m0, s28
	s_nop 0
	global_load_lds_dwordx4 v175, s[6:7]
	s_nop 0
	s_mov_b32 m0, s29
	s_nop 0
	global_load_lds_dwordx4 v177, s[6:7]
	s_add_u32 s6, s14, 0x80100
	s_addc_u32 s7, s15, 0
	s_mov_b32 m0, s30
	s_nop 0
	global_load_lds_dwordx4 v175, s[6:7]
	s_nop 0
	s_mov_b32 m0, s31
	s_nop 0
	global_load_lds_dwordx4 v177, s[6:7]
	s_nop 0
	s_mov_b32 m0, s27
	s_nop 0
	global_load_lds_dwordx4 v174, s[18:19]
	s_nop 0
	s_mov_b32 m0, s35
	s_nop 0
	global_load_lds_dwordx4 v176, s[18:19]
	s_waitcnt vmcnt(44)
	s_waitcnt lgkmcnt(0)
	s_barrier
	s_nop 0
	s_waitcnt lgkmcnt(0)
	v_mfma_f32_16x16x32_bf16 v[132:135], v[2:5], v[62:65], 0
	v_mfma_f32_16x16x32_bf16 v[148:151], v[6:9], v[90:93], v[132:135]
	v_mfma_f32_16x16x32_bf16 v[132:135], v[10:13], v[62:65], 0
	v_mfma_f32_16x16x32_bf16 v[152:155], v[14:17], v[90:93], v[132:135]
	v_mfma_f32_16x16x32_bf16 v[132:135], v[2:5], v[94:97], 0
	v_mfma_f32_16x16x32_bf16 v[156:159], v[6:9], v[108:111], v[132:135]
	v_mfma_f32_16x16x32_bf16 v[132:135], v[10:13], v[94:97], 0
	v_mfma_f32_16x16x32_bf16 v[160:163], v[14:17], v[108:111], v[132:135]
	v_mfma_f32_16x16x32_bf16 v[132:135], v[2:5], v[116:119], 0
	v_mfma_f32_16x16x32_bf16 v[2:5], v[2:5], v[124:127], 0
	v_mfma_f32_16x16x32_bf16 v[164:167], v[6:9], v[120:123], v[132:135]
	v_mfma_f32_16x16x32_bf16 v[2:5], v[6:9], v[128:131], v[2:5]
	v_mfma_f32_16x16x32_bf16 v[6:9], v[10:13], v[124:127], 0
	v_mfma_f32_16x16x32_bf16 v[132:135], v[10:13], v[116:119], 0
	v_mfma_f32_16x16x32_bf16 v[6:9], v[14:17], v[128:131], v[6:9]
	v_mfma_f32_16x16x32_bf16 v[168:171], v[14:17], v[120:123], v[132:135]
	s_nop 0
	s_nop 0
	v_mfma_f32_16x16x32_bf16 v[10:13], v[18:21], v[62:65], 0
	v_mfma_f32_16x16x32_bf16 v[178:181], v[22:25], v[90:93], v[10:13]
	v_mfma_f32_16x16x32_bf16 v[10:13], v[26:29], v[62:65], 0
	v_mfma_f32_16x16x32_bf16 v[192:195], v[30:33], v[90:93], v[10:13]
	v_mfma_f32_16x16x32_bf16 v[10:13], v[18:21], v[94:97], 0
	v_mfma_f32_16x16x32_bf16 v[196:199], v[22:25], v[108:111], v[10:13]
	v_mfma_f32_16x16x32_bf16 v[10:13], v[26:29], v[94:97], 0
	v_mfma_f32_16x16x32_bf16 v[200:203], v[30:33], v[108:111], v[10:13]
	v_mfma_f32_16x16x32_bf16 v[10:13], v[18:21], v[116:119], 0
	v_mfma_f32_16x16x32_bf16 v[204:207], v[22:25], v[120:123], v[10:13]
	v_mfma_f32_16x16x32_bf16 v[10:13], v[26:29], v[116:119], 0
	v_mfma_f32_16x16x32_bf16 v[120:123], v[30:33], v[120:123], v[10:13]
	v_mfma_f32_16x16x32_bf16 v[10:13], v[18:21], v[124:127], 0
	v_mfma_f32_16x16x32_bf16 v[208:211], v[22:25], v[128:131], v[10:13]
	v_mfma_f32_16x16x32_bf16 v[10:13], v[26:29], v[124:127], 0
	v_mfma_f32_16x16x32_bf16 v[124:127], v[30:33], v[128:131], v[10:13]
	s_nop 0
	s_barrier
	s_nop 4
	ds_read_b128 v[10:13], v189
	ds_read_b128 v[14:17], v189 offset:1024
	ds_read_b128 v[20:23], v189 offset:2048
	ds_read_b128 v[24:27], v189 offset:3072
	ds_read_b128 v[128:131], v190
	ds_read_b128 v[212:215], v190 offset:1024
	ds_read_b128 v[216:219], v190 offset:2048
	ds_read_b128 v[188:191], v190 offset:3072
	ds_read_b128 v[28:31], v187 offset:32768
	ds_read_b128 v[62:65], v187 offset:33792
	ds_read_b128 v[220:223], v187 offset:34816
	ds_read_b128 v[224:227], v187 offset:35840
	ds_read_b128 v[228:231], v187 offset:36864
	ds_read_b128 v[232:235], v187 offset:37888
	ds_read_b128 v[236:239], v187 offset:38912
	ds_read_b128 v[240:243], v187 offset:39936
	s_add_u32 s6, s12, 0x80100
	s_addc_u32 s7, s13, 0
	s_mov_b32 m0, s36
	s_nop 0
	global_load_lds_dwordx4 v174, s[6:7]
	s_nop 0
	s_mov_b32 m0, s37
	s_nop 0
	global_load_lds_dwordx4 v176, s[6:7]
	s_waitcnt vmcnt(44)
	s_waitcnt lgkmcnt(0)
	s_barrier
	s_nop 0
	s_waitcnt lgkmcnt(0)
	v_mfma_f32_16x16x32_bf16 v[66:69], v[10:13], v[28:31], v[66:69]
	v_mfma_f32_16x16x32_bf16 v[144:147], v[14:17], v[62:65], v[66:69]
	v_mfma_f32_16x16x32_bf16 v[66:69], v[20:23], v[28:31], v[70:73]
	v_mfma_f32_16x16x32_bf16 v[140:143], v[24:27], v[62:65], v[66:69]
	v_mfma_f32_16x16x32_bf16 v[66:69], v[10:13], v[220:223], v[74:77]
	v_mfma_f32_16x16x32_bf16 v[116:119], v[14:17], v[224:227], v[66:69]
	v_mfma_f32_16x16x32_bf16 v[66:69], v[20:23], v[220:223], v[78:81]
	v_mfma_f32_16x16x32_bf16 v[108:111], v[24:27], v[224:227], v[66:69]
	v_mfma_f32_16x16x32_bf16 v[66:69], v[10:13], v[228:231], v[82:85]
	v_mfma_f32_16x16x32_bf16 v[96:99], v[14:17], v[232:235], v[66:69]
	v_mfma_f32_16x16x32_bf16 v[66:69], v[20:23], v[228:231], v[86:89]
	v_mfma_f32_16x16x32_bf16 v[92:95], v[24:27], v[232:235], v[66:69]
	v_mfma_f32_16x16x32_bf16 v[66:69], v[10:13], v[236:239], v[100:103]
	v_mfma_f32_16x16x32_bf16 v[80:83], v[14:17], v[240:243], v[66:69]
	v_mfma_f32_16x16x32_bf16 v[66:69], v[20:23], v[236:239], v[104:107]
	v_mfma_f32_16x16x32_bf16 v[76:79], v[24:27], v[240:243], v[66:69]
	s_nop 0
	s_nop 0
	v_mfma_f32_16x16x32_bf16 v[66:69], v[128:131], v[28:31], v[112:115]
	v_mfma_f32_16x16x32_bf16 v[28:31], v[216:219], v[28:31], v[34:37]
	v_mfma_f32_16x16x32_bf16 v[132:135], v[188:191], v[62:65], v[28:31]
	v_mfma_f32_16x16x32_bf16 v[28:31], v[128:131], v[220:223], v[38:41]
	v_mfma_f32_16x16x32_bf16 v[104:107], v[212:215], v[224:227], v[28:31]
	v_mfma_f32_16x16x32_bf16 v[28:31], v[216:219], v[220:223], v[42:45]
	v_mfma_f32_16x16x32_bf16 v[100:103], v[188:191], v[224:227], v[28:31]
	v_mfma_f32_16x16x32_bf16 v[28:31], v[128:131], v[228:231], v[46:49]
	v_mfma_f32_16x16x32_bf16 v[88:91], v[212:215], v[232:235], v[28:31]
	v_mfma_f32_16x16x32_bf16 v[28:31], v[216:219], v[228:231], v[50:53]
	v_mfma_f32_16x16x32_bf16 v[84:87], v[188:191], v[232:235], v[28:31]
	v_mfma_f32_16x16x32_bf16 v[28:31], v[128:131], v[236:239], v[54:57]
	v_mfma_f32_16x16x32_bf16 v[72:75], v[212:215], v[240:243], v[28:31]
	v_mfma_f32_16x16x32_bf16 v[28:31], v[216:219], v[236:239], v[58:61]
	v_mfma_f32_16x16x32_bf16 v[136:139], v[212:215], v[62:65], v[66:69]
	v_mfma_f32_16x16x32_bf16 v[68:71], v[188:191], v[240:243], v[28:31]
	s_nop 0
	s_barrier
	ds_read_b128 v[36:39], v187 offset:49152
	ds_read_b128 v[40:43], v187 offset:50176
	ds_read_b128 v[112:115], v187 offset:51200
	ds_read_b128 v[220:223], v187 offset:52224
	ds_read_b128 v[224:227], v187 offset:53248
	ds_read_b128 v[228:231], v187 offset:54272
	ds_read_b128 v[232:235], v187 offset:55296
	ds_read_b128 v[236:239], v187 offset:56320
	s_add_u32 s6, s14, 0x180
	s_addc_u32 s7, s15, 0
	s_mov_b32 m0, s44
	s_nop 0
	global_load_lds_dwordx4 v175, s[6:7]
	s_nop 0
	s_mov_b32 m0, s48
	s_nop 0
	global_load_lds_dwordx4 v177, s[6:7]
	s_add_u32 s6, s14, 0x80180
	s_addc_u32 s7, s15, 0
	s_mov_b32 m0, s52
	s_nop 0
	global_load_lds_dwordx4 v175, s[6:7]
	s_nop 0
	s_mov_b32 m0, s53
	s_nop 0
	global_load_lds_dwordx4 v177, s[6:7]
	s_nop 0
	s_mov_b32 m0, s49
	s_nop 0
	global_load_lds_dwordx4 v174, s[16:17]
	s_nop 0
	s_mov_b32 m0, s51
	s_nop 0
	global_load_lds_dwordx4 v176, s[16:17]
	s_waitcnt vmcnt(8)
	s_waitcnt lgkmcnt(0)
	s_barrier
	s_nop 0
	s_waitcnt lgkmcnt(0)
	v_mfma_f32_16x16x32_bf16 v[28:31], v[10:13], v[36:39], v[148:151]
	v_mfma_f32_16x16x32_bf16 v[64:67], v[14:17], v[40:43], v[28:31]
	v_mfma_f32_16x16x32_bf16 v[28:31], v[20:23], v[36:39], v[152:155]
	v_mfma_f32_16x16x32_bf16 v[60:63], v[24:27], v[40:43], v[28:31]
	v_mfma_f32_16x16x32_bf16 v[28:31], v[10:13], v[112:115], v[156:159]
	v_mfma_f32_16x16x32_bf16 v[48:51], v[14:17], v[220:223], v[28:31]
	v_mfma_f32_16x16x32_bf16 v[28:31], v[20:23], v[112:115], v[160:163]
	v_mfma_f32_16x16x32_bf16 v[44:47], v[24:27], v[220:223], v[28:31]
	v_mfma_f32_16x16x32_bf16 v[28:31], v[10:13], v[224:227], v[164:167]
	v_mfma_f32_16x16x32_bf16 v[2:5], v[10:13], v[232:235], v[2:5]
	v_mfma_f32_16x16x32_bf16 v[32:35], v[14:17], v[228:231], v[28:31]
	v_mfma_f32_16x16x32_bf16 v[28:31], v[20:23], v[224:227], v[168:171]
	v_mfma_f32_16x16x32_bf16 v[16:19], v[14:17], v[236:239], v[2:5]
	v_mfma_f32_16x16x32_bf16 v[2:5], v[20:23], v[232:235], v[6:9]
	v_mfma_f32_16x16x32_bf16 v[28:31], v[24:27], v[228:231], v[28:31]
	v_mfma_f32_16x16x32_bf16 v[12:15], v[24:27], v[236:239], v[2:5]
	s_nop 0
	s_nop 0
	v_mfma_f32_16x16x32_bf16 v[2:5], v[128:131], v[36:39], v[178:181]
	v_mfma_f32_16x16x32_bf16 v[56:59], v[212:215], v[40:43], v[2:5]
	v_mfma_f32_16x16x32_bf16 v[2:5], v[216:219], v[36:39], v[192:195]
	v_mfma_f32_16x16x32_bf16 v[52:55], v[188:191], v[40:43], v[2:5]
	v_mfma_f32_16x16x32_bf16 v[2:5], v[128:131], v[112:115], v[196:199]
	v_mfma_f32_16x16x32_bf16 v[40:43], v[212:215], v[220:223], v[2:5]
	v_mfma_f32_16x16x32_bf16 v[2:5], v[216:219], v[112:115], v[200:203]
	v_mfma_f32_16x16x32_bf16 v[36:39], v[188:191], v[220:223], v[2:5]
	v_mfma_f32_16x16x32_bf16 v[2:5], v[128:131], v[224:227], v[204:207]
	v_mfma_f32_16x16x32_bf16 v[24:27], v[212:215], v[228:231], v[2:5]
	v_mfma_f32_16x16x32_bf16 v[2:5], v[216:219], v[224:227], v[120:123]
	v_mfma_f32_16x16x32_bf16 v[20:23], v[188:191], v[228:231], v[2:5]
	v_mfma_f32_16x16x32_bf16 v[2:5], v[128:131], v[232:235], v[208:211]
	v_mfma_f32_16x16x32_bf16 v[8:11], v[212:215], v[236:239], v[2:5]
	v_mfma_f32_16x16x32_bf16 v[2:5], v[216:219], v[232:235], v[124:127]
	v_mfma_f32_16x16x32_bf16 v[4:7], v[188:191], v[236:239], v[2:5]
	s_nop 0
	s_barrier
	s_mov_b64 s[18:19], 0
	s_branch .LBB0_919

; #define MK_LAS __attribute__((address_space(3)))
; __device__ __forceinline__ unsigned mk_hwkey() { unsigned hw; asm volatile("s_getreg_b32 %0, hwreg(HW_REG_HW_ID, 0, 6)" : "=s"(hw)); return hw; }
; __device__ __forceinline__ int mk_wave() {
;     extern __shared__ __attribute__((aligned(16))) unsigned char lds[];
;     const unsigned hw = mk_hwkey();
;     return __builtin_amdgcn_readfirstlane((int)*(volatile MK_LAS unsigned*)((MK_LAS unsigned char*)lds + TIDTAB_OFF + 4 * hw));
; }
; template <class Epi, class Sched, bool ALIGN_EPI = false, bool SP2 = false>
; __device__ __forceinline__ void gemm_phase(PG8_LAS unsigned char* lds, const Gemm g, const Sched& S, const Epi& E) {
;     ...
;     for (int i = 0; i < 2; ++i) { int R, C; stage_rc(tid * 16 + i * 8192, R, C); const int Rb = Epi::PERM ? ((R & ~31) + perm32(R & 31)) : R;
;         voffA[i] = (unsigned)(R * g.lda + C) * 2u; voffB[i] = (unsigned)(Rb * g.ldb + C) * 2u; }
;     const size_t kstep = (size_t)(BK * 2);
;     const size_t hsA = (size_t)HALF * g.lda * 2, hsB = (size_t)HALF * g.ldb * 2;
;     const size_t tsA = 2 * hsA, tsB = 2 * hsB;
;     const unsigned ldsbase = (unsigned)(unsigned long long)lds;
;     const unsigned ldsw = (unsigned)wid * 1024u;
;     const int aoff = lds_byte(wr * 64 + fr, fq * 8), boff = lds_byte(wc * 32 + fr, fq * 8);
;     ...
;     Unit cur, nxt; int ui = 0; bool epi_ran = false;
;     if (!S.next(0, cur)) return;
;     f32x4 acc[2][2][4][2];
; #pragma unroll
;     for (int a = 0; a < 2; ++a)
; #pragma unroll
;         for (int b = 0; b < 2; ++b)
; #pragma unroll
;             for (int m = 0; m < 4; ++m)
; #pragma unroll
;                 for (int n = 0; n < 2; ++n) acc[a][b][m][n] = (f32x4){0.f, 0.f, 0.f, 0.f};
;     bf16x8 At[4][2], B0[2][2], B1[2][2];
;     const char* cA = (const char*)g.A + (size_t)cur.pm * tsA + (size_t)cur.k0 * 2; const char* cB = (const char*)g.Bt + (size_t)cur.pn * tsB + (size_t)cur.k0 * 2;
;     S.a_ready(cur);
;     if constexpr (SP2) {
;         PG8_STAGE(PG8_SB(0, 0), cB, voffB); PG8_STAGE(PG8_SB(0, 1), cB + hsB, voffB); PG8_STAGE(PG8_SA(0, 0), cA, voffA); PG8_STAGE(PG8_SA(0, 1), cA + hsA, voffA);
;         if (wr == 1) PG8_BAR;
;         PG8_WAIT_V(2); PG8_BAR;
;         PG8_STAGE(PG8_SB(1, 0), cB + kstep, voffB); PG8_STAGE(PG8_SA(1, 0), cA + kstep, voffA); PG8_STAGE(PG8_SB(1, 1), cB + hsB + kstep, voffB);
;         PG8_WAIT_V(6); PG8_BAR;
.LBB0_942:
	v_bfe_u32 v2, v0, 4, 2
	s_add_u32 s51, s72, 0x58400000
	v_and_b32_e32 v3, 15, v0
	v_lshlrev_b32_e32 v5, 4, v2
	v_lshlrev_b32_e32 v0, 2, v0
	s_addc_u32 s52, s73, 0
	v_lshl_or_b32 v4, s7, 6, v3
	v_lshl_or_b32 v3, v3, 6, v5
	s_lshl_b32 s7, s7, 13
	v_and_b32_e32 v0, 32, v0
	v_bitop3_b32 v5, v3, s7, v0 bitop3:0xde
	s_lshl_b32 s7, s8, 5
	s_and_b32 s14, s7, 0x60
	s_lshl_b32 s7, s14, 7
	s_add_i32 s53, s35, 0x18000
	s_add_u32 s8, s24, 0x80
	s_waitcnt vmcnt(2)
	s_barrier
	s_addc_u32 s9, s25, 0
	s_mov_b32 m0, s53
	s_nop 0
	global_load_lds_dwordx4 v130, s[8:9]
	s_add_i32 s57, s35, 0x1a000
	s_add_i32 s63, s35, 0x8000
	s_mov_b32 m0, s57
	s_nop 0
	global_load_lds_dwordx4 v131, s[8:9]
	s_add_u32 s8, s26, 0x80
	s_addc_u32 s9, s27, 0
	s_mov_b32 m0, s63
	s_nop 0
	global_load_lds_dwordx4 v130, s[8:9]
	s_add_i32 s64, s35, 0xa000
	s_add_i32 s67, s35, 0x1c000
	s_mov_b32 m0, s64
	s_nop 0
	global_load_lds_dwordx4 v131, s[8:9]
	s_add_u32 s8, s24, 0x80080
	s_addc_u32 s9, s25, 0
	s_mov_b32 m0, s67
	s_nop 0
	global_load_lds_dwordx4 v130, s[8:9]
	s_add_i32 s69, s35, 0x1e000
	s_mov_b32 m0, s69
	s_nop 0
	global_load_lds_dwordx4 v131, s[8:9]
	v_bitop3_b32 v3, v3, s7, v0 bitop3:0xde
	s_waitcnt vmcnt(6)
	s_add_i32 s78, s35, 0xc000
	v_mov_b32_e32 v82, v1
	v_mov_b32_e32 v83, v1
	v_mov_b32_e32 v84, v1
	v_mov_b32_e32 v85, v1
	s_cmpk_lt_u32 s6, 0x100
	v_lshlrev_b32_e32 v0, 2, v2
	v_add_u32_e32 v132, 0xffffc000, v4
	v_add_u32_e32 v133, 0, v3
	v_add_u32_e32 v134, 0, v5
	v_mov_b64_e32 v[96:97], v[84:85]
	v_mov_b64_e32 v[112:113], v[84:85]
	v_mov_b64_e32 v[108:109], v[84:85]
	v_mov_b64_e32 v[120:121], v[84:85]
	v_mov_b64_e32 v[116:117], v[84:85]
	v_mov_b64_e32 v[128:129], v[84:85]
	v_mov_b64_e32 v[124:125], v[84:85]
	v_mov_b64_e32 v[70:71], v[82:83]
	v_mov_b64_e32 v[66:67], v[82:83]
	v_mov_b64_e32 v[78:79], v[82:83]
	v_mov_b64_e32 v[74:75], v[82:83]
	v_mov_b64_e32 v[92:93], v[84:85]
	v_mov_b64_e32 v[88:89], v[84:85]
	v_mov_b64_e32 v[104:105], v[84:85]
	v_mov_b64_e32 v[100:101], v[84:85]
	v_mov_b64_e32 v[38:39], v[82:83]
	v_mov_b64_e32 v[34:35], v[82:83]
	v_mov_b64_e32 v[46:47], v[82:83]
	v_mov_b64_e32 v[42:43], v[82:83]
	v_mov_b64_e32 v[54:55], v[82:83]
	v_mov_b64_e32 v[50:51], v[82:83]
	v_mov_b64_e32 v[62:63], v[82:83]
	v_mov_b64_e32 v[58:59], v[82:83]
	v_mov_b64_e32 v[6:7], v[82:83]
	v_mov_b64_e32 v[2:3], v[82:83]
	v_mov_b64_e32 v[14:15], v[82:83]
	v_mov_b64_e32 v[10:11], v[82:83]
	v_mov_b64_e32 v[22:23], v[82:83]
	v_mov_b64_e32 v[18:19], v[82:83]
	v_mov_b64_e32 v[30:31], v[82:83]
	v_mov_b64_e32 v[26:27], v[82:83]
	v_readlane_b32 s8, v254, 33
	s_cselect_b64 s[12:13], -1, 0
	s_add_i32 s79, s35, 0xe000
	s_mov_b32 s7, 0
	s_lshl_b32 s84, s14, 2
	v_lshlrev_b32_e32 v0, 2, v0
	v_mov_b64_e32 v[94:95], v[82:83]
	v_mov_b64_e32 v[110:111], v[82:83]
	v_mov_b64_e32 v[106:107], v[82:83]
	v_mov_b64_e32 v[118:119], v[82:83]
	v_mov_b64_e32 v[114:115], v[82:83]
	v_mov_b64_e32 v[126:127], v[82:83]
	v_mov_b64_e32 v[122:123], v[82:83]
	v_mov_b64_e32 v[72:73], v[84:85]
	v_mov_b64_e32 v[68:69], v[84:85]
	v_mov_b64_e32 v[80:81], v[84:85]
	v_mov_b64_e32 v[76:77], v[84:85]
	v_mov_b64_e32 v[90:91], v[82:83]
	v_mov_b64_e32 v[86:87], v[82:83]
	v_mov_b64_e32 v[102:103], v[82:83]
	v_mov_b64_e32 v[98:99], v[82:83]
	v_mov_b64_e32 v[40:41], v[84:85]
	v_mov_b64_e32 v[36:37], v[84:85]
	v_mov_b64_e32 v[48:49], v[84:85]
	v_mov_b64_e32 v[44:45], v[84:85]
	v_mov_b64_e32 v[56:57], v[84:85]
	v_mov_b64_e32 v[52:53], v[84:85]
	v_mov_b64_e32 v[64:65], v[84:85]
	v_mov_b64_e32 v[60:61], v[84:85]
	v_mov_b64_e32 v[8:9], v[84:85]
	v_mov_b64_e32 v[4:5], v[84:85]
	v_mov_b64_e32 v[16:17], v[84:85]
	v_mov_b64_e32 v[12:13], v[84:85]
	v_mov_b64_e32 v[24:25], v[84:85]
	v_mov_b64_e32 v[20:21], v[84:85]
	v_mov_b64_e32 v[32:33], v[84:85]
	v_mov_b64_e32 v[28:29], v[84:85]
	v_readlane_b32 s6, v254, 31
	s_mov_b32 s83, s8
	v_readlane_b32 s91, v254, 29
	s_barrier
	v_readlane_b32 s9, v254, 34
	s_getreg_b32 s100, hwreg(HW_REG_HW_ID, 0, 6)
	s_lshl_b32 s100, s100, 2
	s_add_i32 s100, s100, 0x20540
	v_mov_b32_e32 v251, s100
	ds_read_b32 v251, v251
	s_waitcnt lgkmcnt(0)
	v_readfirstlane_b32 s100, v251
	s_cmp_ge_u32 s100, 4
	s_cbranch_scc0 statprio_skip3
	s_setprio 1
statprio_skip3:
	s_branch .LBB0_945
.LBB0_943:
	ds_read_b128 v[2:5], v135
	ds_read_b128 v[6:9], v135 offset:1024
	ds_read_b128 v[10:13], v135 offset:2048
	ds_read_b128 v[14:17], v135 offset:3072
	ds_read_b128 v[18:21], v136
	ds_read_b128 v[22:25], v136 offset:1024
	ds_read_b128 v[26:29], v136 offset:2048
	ds_read_b128 v[30:33], v136 offset:3072
	s_add_u32 s24, s20, 0x100
	s_addc_u32 s25, s21, 0
	s_add_u32 s8, s20, 0x180
	s_addc_u32 s9, s21, 0
	s_add_u32 s6, s22, 0x100
	s_addc_u32 s7, s23, 0
	ds_read_b128 v[34:37], v134
	ds_read_b128 v[38:41], v134 offset:1024
	ds_read_b128 v[42:45], v134 offset:2048
	ds_read_b128 v[46:49], v134 offset:3072
	ds_read_b128 v[50:53], v134 offset:4096
	ds_read_b128 v[54:57], v134 offset:5120
	ds_read_b128 v[58:61], v134 offset:6144
	ds_read_b128 v[62:65], v134 offset:7168
	s_waitcnt vmcnt(40)
	s_waitcnt lgkmcnt(0)
	s_barrier
	s_nop 0
	s_waitcnt lgkmcnt(7)
	v_mfma_f32_16x16x32_bf16 v[66:69], v[2:5], v[34:37], 0
	v_mfma_f32_16x16x32_bf16 v[70:73], v[10:13], v[34:37], 0
	s_waitcnt lgkmcnt(5)
	v_mfma_f32_16x16x32_bf16 v[74:77], v[2:5], v[42:45], 0
	v_mfma_f32_16x16x32_bf16 v[78:81], v[10:13], v[42:45], 0
	s_waitcnt lgkmcnt(3)
	v_mfma_f32_16x16x32_bf16 v[82:85], v[2:5], v[50:53], 0
	v_mfma_f32_16x16x32_bf16 v[86:89], v[10:13], v[50:53], 0
	s_waitcnt lgkmcnt(1)
	v_mfma_f32_16x16x32_bf16 v[90:93], v[2:5], v[58:61], 0
	v_mfma_f32_16x16x32_bf16 v[94:97], v[10:13], v[58:61], 0
	v_mfma_f32_16x16x32_bf16 v[66:69], v[6:9], v[38:41], v[66:69]
	v_mfma_f32_16x16x32_bf16 v[70:73], v[14:17], v[38:41], v[70:73]
	v_mfma_f32_16x16x32_bf16 v[74:77], v[6:9], v[46:49], v[74:77]
	v_mfma_f32_16x16x32_bf16 v[78:81], v[14:17], v[46:49], v[78:81]
	v_mfma_f32_16x16x32_bf16 v[82:85], v[6:9], v[54:57], v[82:85]
	v_mfma_f32_16x16x32_bf16 v[86:89], v[14:17], v[54:57], v[86:89]
	s_waitcnt lgkmcnt(0)
	v_mfma_f32_16x16x32_bf16 v[90:93], v[6:9], v[62:65], v[90:93]
	v_mfma_f32_16x16x32_bf16 v[94:97], v[14:17], v[62:65], v[94:97]
	s_nop 0
	s_nop 0
	v_mfma_f32_16x16x32_bf16 v[98:101], v[18:21], v[34:37], 0
	v_mfma_f32_16x16x32_bf16 v[34:37], v[26:29], v[34:37], 0
	v_mfma_f32_16x16x32_bf16 v[98:101], v[22:25], v[38:41], v[98:101]
	v_mfma_f32_16x16x32_bf16 v[34:37], v[30:33], v[38:41], v[34:37]
	v_mfma_f32_16x16x32_bf16 v[38:41], v[18:21], v[42:45], 0
	v_mfma_f32_16x16x32_bf16 v[42:45], v[26:29], v[42:45], 0
	v_mfma_f32_16x16x32_bf16 v[38:41], v[22:25], v[46:49], v[38:41]
	v_mfma_f32_16x16x32_bf16 v[42:45], v[30:33], v[46:49], v[42:45]
	v_mfma_f32_16x16x32_bf16 v[46:49], v[18:21], v[50:53], 0
	v_mfma_f32_16x16x32_bf16 v[50:53], v[26:29], v[50:53], 0
	v_mfma_f32_16x16x32_bf16 v[102:105], v[30:33], v[54:57], v[50:53]
	v_mfma_f32_16x16x32_bf16 v[50:53], v[18:21], v[58:61], 0
	v_mfma_f32_16x16x32_bf16 v[106:109], v[22:25], v[62:65], v[50:53]
	v_mfma_f32_16x16x32_bf16 v[50:53], v[26:29], v[58:61], 0
	v_mfma_f32_16x16x32_bf16 v[46:49], v[22:25], v[54:57], v[46:49]
	v_mfma_f32_16x16x32_bf16 v[110:113], v[30:33], v[62:65], v[50:53]
	s_nop 0
	s_barrier
	s_nop 3
	ds_read_b128 v[50:53], v134 offset:16384
	ds_read_b128 v[54:57], v134 offset:17408
	ds_read_b128 v[58:61], v134 offset:18432
	ds_read_b128 v[62:65], v134 offset:19456
	ds_read_b128 v[114:117], v134 offset:20480
	ds_read_b128 v[118:121], v134 offset:21504
	ds_read_b128 v[122:125], v134 offset:22528
	ds_read_b128 v[126:129], v134 offset:23552
	s_mov_b32 m0, s36
	s_nop 0
	global_load_lds_dwordx4 v130, s[6:7]
	s_nop 0
	s_mov_b32 m0, s37
	s_nop 0
	global_load_lds_dwordx4 v131, s[6:7]
	s_add_u32 s6, s22, 0x80100
	s_addc_u32 s7, s23, 0
	s_mov_b32 m0, s40
	s_nop 0
	global_load_lds_dwordx4 v130, s[6:7]
	s_nop 0
	s_mov_b32 m0, s41
	s_nop 0
	global_load_lds_dwordx4 v131, s[6:7]
	s_nop 0
	s_mov_b32 m0, s35
	s_nop 0
	global_load_lds_dwordx4 v130, s[24:25]
	s_nop 0
	s_mov_b32 m0, s44
	s_nop 0
	global_load_lds_dwordx4 v131, s[24:25]
	s_waitcnt vmcnt(40)
	s_waitcnt lgkmcnt(0)
	s_barrier
	s_nop 0
	s_waitcnt lgkmcnt(7)
	v_mfma_f32_16x16x32_bf16 v[140:143], v[2:5], v[50:53], 0
	s_waitcnt lgkmcnt(5)
	v_mfma_f32_16x16x32_bf16 v[148:151], v[2:5], v[58:61], 0
	s_waitcnt lgkmcnt(3)
	v_mfma_f32_16x16x32_bf16 v[156:159], v[2:5], v[114:117], 0
	s_waitcnt lgkmcnt(1)
	v_mfma_f32_16x16x32_bf16 v[2:5], v[2:5], v[122:125], 0
	v_mfma_f32_16x16x32_bf16 v[144:147], v[10:13], v[50:53], 0
	v_mfma_f32_16x16x32_bf16 v[152:155], v[10:13], v[58:61], 0
	v_mfma_f32_16x16x32_bf16 v[160:163], v[10:13], v[114:117], 0
	s_waitcnt lgkmcnt(0)
	v_mfma_f32_16x16x32_bf16 v[164:167], v[6:9], v[126:129], v[2:5]
	v_mfma_f32_16x16x32_bf16 v[2:5], v[10:13], v[122:125], 0
	v_mfma_f32_16x16x32_bf16 v[140:143], v[6:9], v[54:57], v[140:143]
	v_mfma_f32_16x16x32_bf16 v[144:147], v[14:17], v[54:57], v[144:147]
	v_mfma_f32_16x16x32_bf16 v[148:151], v[6:9], v[62:65], v[148:151]
	v_mfma_f32_16x16x32_bf16 v[152:155], v[14:17], v[62:65], v[152:155]
	v_mfma_f32_16x16x32_bf16 v[156:159], v[6:9], v[118:121], v[156:159]
	v_mfma_f32_16x16x32_bf16 v[160:163], v[14:17], v[118:121], v[160:163]
	v_mfma_f32_16x16x32_bf16 v[168:171], v[14:17], v[126:129], v[2:5]
	s_nop 0
	s_nop 0
	v_mfma_f32_16x16x32_bf16 v[2:5], v[18:21], v[50:53], 0
	v_mfma_f32_16x16x32_bf16 v[172:175], v[22:25], v[54:57], v[2:5]
	v_mfma_f32_16x16x32_bf16 v[2:5], v[26:29], v[50:53], 0
	v_mfma_f32_16x16x32_bf16 v[176:179], v[30:33], v[54:57], v[2:5]
	v_mfma_f32_16x16x32_bf16 v[2:5], v[18:21], v[58:61], 0
	v_mfma_f32_16x16x32_bf16 v[184:187], v[22:25], v[62:65], v[2:5]
	v_mfma_f32_16x16x32_bf16 v[2:5], v[26:29], v[58:61], 0
	v_mfma_f32_16x16x32_bf16 v[188:191], v[30:33], v[62:65], v[2:5]
	v_mfma_f32_16x16x32_bf16 v[2:5], v[18:21], v[114:117], 0
	v_mfma_f32_16x16x32_bf16 v[192:195], v[22:25], v[118:121], v[2:5]
	v_mfma_f32_16x16x32_bf16 v[2:5], v[26:29], v[114:117], 0
	v_mfma_f32_16x16x32_bf16 v[196:199], v[30:33], v[118:121], v[2:5]
	v_mfma_f32_16x16x32_bf16 v[2:5], v[18:21], v[122:125], 0
	v_mfma_f32_16x16x32_bf16 v[200:203], v[22:25], v[126:129], v[2:5]
	v_mfma_f32_16x16x32_bf16 v[2:5], v[26:29], v[122:125], 0
	v_mfma_f32_16x16x32_bf16 v[204:207], v[30:33], v[126:129], v[2:5]
	s_nop 0
	s_barrier
	ds_read_b128 v[114:117], v137
	ds_read_b128 v[118:121], v137 offset:1024
	ds_read_b128 v[122:125], v137 offset:2048
	ds_read_b128 v[126:129], v137 offset:3072
	ds_read_b128 v[208:211], v138
	ds_read_b128 v[212:215], v138 offset:1024
	ds_read_b128 v[216:219], v138 offset:2048
	ds_read_b128 v[136:139], v138 offset:3072
	ds_read_b128 v[50:53], v134 offset:32768
	ds_read_b128 v[54:57], v134 offset:33792
	ds_read_b128 v[220:223], v134 offset:34816
	ds_read_b128 v[224:227], v134 offset:35840
	ds_read_b128 v[228:231], v134 offset:36864
	ds_read_b128 v[232:235], v134 offset:37888
	ds_read_b128 v[236:239], v134 offset:38912
	ds_read_b128 v[240:243], v134 offset:39936
	s_add_u32 s6, s20, 0x80100
	s_addc_u32 s7, s21, 0
	s_mov_b32 m0, s48
	s_nop 0
	global_load_lds_dwordx4 v130, s[6:7]
	s_nop 0
	s_mov_b32 m0, s49
	s_nop 0
	global_load_lds_dwordx4 v131, s[6:7]
	s_waitcnt vmcnt(40)
	s_waitcnt lgkmcnt(0)
	s_barrier
	s_nop 0
	s_waitcnt lgkmcnt(7)
	v_mfma_f32_16x16x32_bf16 v[2:5], v[114:117], v[50:53], v[66:69]
	s_waitcnt lgkmcnt(6)
	v_mfma_f32_16x16x32_bf16 v[26:29], v[118:121], v[54:57], v[2:5]
	v_mfma_f32_16x16x32_bf16 v[2:5], v[122:125], v[50:53], v[70:73]
	v_mfma_f32_16x16x32_bf16 v[30:33], v[126:129], v[54:57], v[2:5]
	s_waitcnt lgkmcnt(5)
	v_mfma_f32_16x16x32_bf16 v[2:5], v[114:117], v[220:223], v[74:77]
	s_waitcnt lgkmcnt(4)
	v_mfma_f32_16x16x32_bf16 v[18:21], v[118:121], v[224:227], v[2:5]
	v_mfma_f32_16x16x32_bf16 v[2:5], v[122:125], v[220:223], v[78:81]
	v_mfma_f32_16x16x32_bf16 v[22:25], v[126:129], v[224:227], v[2:5]
	s_waitcnt lgkmcnt(3)
	v_mfma_f32_16x16x32_bf16 v[2:5], v[114:117], v[228:231], v[82:85]
	s_waitcnt lgkmcnt(2)
	v_mfma_f32_16x16x32_bf16 v[10:13], v[118:121], v[232:235], v[2:5]
	v_mfma_f32_16x16x32_bf16 v[2:5], v[122:125], v[228:231], v[86:89]
	v_mfma_f32_16x16x32_bf16 v[14:17], v[126:129], v[232:235], v[2:5]
	s_waitcnt lgkmcnt(1)
	v_mfma_f32_16x16x32_bf16 v[2:5], v[114:117], v[236:239], v[90:93]
	v_mfma_f32_16x16x32_bf16 v[6:9], v[122:125], v[236:239], v[94:97]
	s_waitcnt lgkmcnt(0)
	v_mfma_f32_16x16x32_bf16 v[2:5], v[118:121], v[240:243], v[2:5]
	v_mfma_f32_16x16x32_bf16 v[6:9], v[126:129], v[240:243], v[6:9]
	s_nop 0
	s_nop 0
	v_mfma_f32_16x16x32_bf16 v[34:37], v[216:219], v[50:53], v[34:37]
	v_mfma_f32_16x16x32_bf16 v[62:65], v[136:139], v[54:57], v[34:37]
	v_mfma_f32_16x16x32_bf16 v[34:37], v[208:211], v[220:223], v[38:41]
	v_mfma_f32_16x16x32_bf16 v[58:61], v[208:211], v[50:53], v[98:101]
	v_mfma_f32_16x16x32_bf16 v[50:53], v[212:215], v[224:227], v[34:37]
	v_mfma_f32_16x16x32_bf16 v[34:37], v[216:219], v[220:223], v[42:45]
	v_mfma_f32_16x16x32_bf16 v[58:61], v[212:215], v[54:57], v[58:61]
	v_mfma_f32_16x16x32_bf16 v[54:57], v[136:139], v[224:227], v[34:37]
	v_mfma_f32_16x16x32_bf16 v[34:37], v[208:211], v[228:231], v[46:49]
	v_mfma_f32_16x16x32_bf16 v[42:45], v[212:215], v[232:235], v[34:37]
	v_mfma_f32_16x16x32_bf16 v[34:37], v[216:219], v[228:231], v[102:105]
	v_mfma_f32_16x16x32_bf16 v[46:49], v[136:139], v[232:235], v[34:37]
	v_mfma_f32_16x16x32_bf16 v[34:37], v[208:211], v[236:239], v[106:109]
	v_mfma_f32_16x16x32_bf16 v[38:41], v[216:219], v[236:239], v[110:113]
	v_mfma_f32_16x16x32_bf16 v[34:37], v[212:215], v[240:243], v[34:37]
	v_mfma_f32_16x16x32_bf16 v[38:41], v[136:139], v[240:243], v[38:41]
	s_nop 0
	s_barrier
	ds_read_b128 v[82:85], v134 offset:49152
	ds_read_b128 v[94:97], v134 offset:50176
	ds_read_b128 v[106:109], v134 offset:51200
	ds_read_b128 v[110:113], v134 offset:52224
	ds_read_b128 v[220:223], v134 offset:53248
	ds_read_b128 v[224:227], v134 offset:54272
	ds_read_b128 v[228:231], v134 offset:55296
	ds_read_b128 v[232:235], v134 offset:56320
	s_add_u32 s6, s22, 0x180
	s_addc_u32 s7, s23, 0
	s_mov_b32 m0, s53
	s_nop 0
	global_load_lds_dwordx4 v130, s[6:7]
	s_nop 0
	s_mov_b32 m0, s57
	s_nop 0
	global_load_lds_dwordx4 v131, s[6:7]
	s_add_u32 s6, s22, 0x80180
	s_addc_u32 s7, s23, 0
	s_mov_b32 m0, s67
	s_nop 0
	global_load_lds_dwordx4 v130, s[6:7]
	s_nop 0
	s_mov_b32 m0, s69
	s_nop 0
	global_load_lds_dwordx4 v131, s[6:7]
	s_nop 0
	s_mov_b32 m0, s63
	s_nop 0
	global_load_lds_dwordx4 v130, s[8:9]
	s_nop 0
	s_mov_b32 m0, s64
	s_nop 0
	global_load_lds_dwordx4 v131, s[8:9]
	s_waitcnt vmcnt(8)
	s_waitcnt lgkmcnt(0)
	s_barrier
	s_nop 0
	s_waitcnt lgkmcnt(7)
	v_mfma_f32_16x16x32_bf16 v[66:69], v[114:117], v[82:85], v[140:143]
	s_waitcnt lgkmcnt(6)
	v_mfma_f32_16x16x32_bf16 v[98:101], v[118:121], v[94:97], v[66:69]
	v_mfma_f32_16x16x32_bf16 v[66:69], v[122:125], v[82:85], v[144:147]
	v_mfma_f32_16x16x32_bf16 v[102:105], v[126:129], v[94:97], v[66:69]
	s_waitcnt lgkmcnt(5)
	v_mfma_f32_16x16x32_bf16 v[66:69], v[114:117], v[106:109], v[148:151]
	s_waitcnt lgkmcnt(4)
	v_mfma_f32_16x16x32_bf16 v[86:89], v[118:121], v[110:113], v[66:69]
	v_mfma_f32_16x16x32_bf16 v[66:69], v[122:125], v[106:109], v[152:155]
	v_mfma_f32_16x16x32_bf16 v[90:93], v[126:129], v[110:113], v[66:69]
	s_waitcnt lgkmcnt(3)
	v_mfma_f32_16x16x32_bf16 v[66:69], v[114:117], v[220:223], v[156:159]
	s_waitcnt lgkmcnt(2)
	v_mfma_f32_16x16x32_bf16 v[74:77], v[118:121], v[224:227], v[66:69]
	v_mfma_f32_16x16x32_bf16 v[66:69], v[122:125], v[220:223], v[160:163]
	v_mfma_f32_16x16x32_bf16 v[78:81], v[126:129], v[224:227], v[66:69]
	s_waitcnt lgkmcnt(1)
	v_mfma_f32_16x16x32_bf16 v[66:69], v[114:117], v[228:231], v[164:167]
	v_mfma_f32_16x16x32_bf16 v[70:73], v[122:125], v[228:231], v[168:171]
	s_waitcnt lgkmcnt(0)
	v_mfma_f32_16x16x32_bf16 v[66:69], v[118:121], v[232:235], v[66:69]
	v_mfma_f32_16x16x32_bf16 v[70:73], v[126:129], v[232:235], v[70:73]
	s_nop 0
	s_nop 0
	v_mfma_f32_16x16x32_bf16 v[114:117], v[208:211], v[82:85], v[172:175]
	v_mfma_f32_16x16x32_bf16 v[82:85], v[216:219], v[82:85], v[176:179]
	v_mfma_f32_16x16x32_bf16 v[126:129], v[136:139], v[94:97], v[82:85]
	v_mfma_f32_16x16x32_bf16 v[82:85], v[208:211], v[106:109], v[184:187]
	v_mfma_f32_16x16x32_bf16 v[122:125], v[212:215], v[94:97], v[114:117]
	v_mfma_f32_16x16x32_bf16 v[114:117], v[212:215], v[110:113], v[82:85]
	v_mfma_f32_16x16x32_bf16 v[82:85], v[216:219], v[106:109], v[188:191]
	v_mfma_f32_16x16x32_bf16 v[118:121], v[136:139], v[110:113], v[82:85]
	v_mfma_f32_16x16x32_bf16 v[82:85], v[208:211], v[220:223], v[192:195]
	v_mfma_f32_16x16x32_bf16 v[106:109], v[212:215], v[224:227], v[82:85]
	v_mfma_f32_16x16x32_bf16 v[82:85], v[216:219], v[220:223], v[196:199]
	v_mfma_f32_16x16x32_bf16 v[110:113], v[136:139], v[224:227], v[82:85]
	v_mfma_f32_16x16x32_bf16 v[82:85], v[208:211], v[228:231], v[200:203]
	v_mfma_f32_16x16x32_bf16 v[94:97], v[212:215], v[232:235], v[82:85]
	v_mfma_f32_16x16x32_bf16 v[82:85], v[216:219], v[228:231], v[204:207]
	v_mfma_f32_16x16x32_bf16 v[82:85], v[136:139], v[232:235], v[82:85]
	s_nop 0
	s_barrier
	s_mov_b64 s[8:9], 0

.LBB0_952:
	v_add_u32_e32 v135, 0x10000, v133
	v_add_u32_e32 v136, 0x14000, v133
	ds_read_b128 v[138:141], v135
	ds_read_b128 v[142:145], v135 offset:1024
	ds_read_b128 v[146:149], v135 offset:2048
	ds_read_b128 v[150:153], v135 offset:3072
	ds_read_b128 v[154:157], v136
	ds_read_b128 v[158:161], v136 offset:1024
	ds_read_b128 v[162:165], v136 offset:2048
	ds_read_b128 v[166:169], v136 offset:3072
	s_add_u32 s19, s24, 0xfff80080
	s_addc_u32 s26, s25, -1
	s_cmp_eq_u32 s7, 4
	s_cselect_b32 s30, s20, s19
	s_cselect_b32 s31, s21, s26
	s_cselect_b32 s28, s22, s15
	s_cselect_b32 s29, s23, s17
	s_add_u32 s26, s30, 0x80
	s_addc_u32 s27, s31, 0
	ds_read_b128 v[170:173], v134
	ds_read_b128 v[174:177], v134 offset:1024
	ds_read_b128 v[178:181], v134 offset:2048
	ds_read_b128 v[184:187], v134 offset:3072
	ds_read_b128 v[188:191], v134 offset:4096
	ds_read_b128 v[192:195], v134 offset:5120
	ds_read_b128 v[196:199], v134 offset:6144
	ds_read_b128 v[200:203], v134 offset:7168
	s_mov_b32 m0, s78
	s_nop 0
	global_load_lds_dwordx4 v130, s[24:25]
	s_nop 0
	s_mov_b32 m0, s79
	s_nop 0
	global_load_lds_dwordx4 v131, s[24:25]
	s_waitcnt vmcnt(8)
	s_waitcnt lgkmcnt(0)
	s_barrier
	s_nop 0
	s_waitcnt lgkmcnt(7)
	v_mfma_f32_16x16x32_bf16 v[26:29], v[138:141], v[170:173], v[26:29]
	v_mfma_f32_16x16x32_bf16 v[30:33], v[146:149], v[170:173], v[30:33]
	s_waitcnt lgkmcnt(5)
	v_mfma_f32_16x16x32_bf16 v[18:21], v[138:141], v[178:181], v[18:21]
	v_mfma_f32_16x16x32_bf16 v[22:25], v[146:149], v[178:181], v[22:25]
	s_waitcnt lgkmcnt(3)
	v_mfma_f32_16x16x32_bf16 v[10:13], v[138:141], v[188:191], v[10:13]
	v_mfma_f32_16x16x32_bf16 v[14:17], v[146:149], v[188:191], v[14:17]
	s_waitcnt lgkmcnt(1)
	v_mfma_f32_16x16x32_bf16 v[2:5], v[138:141], v[196:199], v[2:5]
	v_mfma_f32_16x16x32_bf16 v[6:9], v[146:149], v[196:199], v[6:9]
	v_mfma_f32_16x16x32_bf16 v[26:29], v[142:145], v[174:177], v[26:29]
	v_mfma_f32_16x16x32_bf16 v[30:33], v[150:153], v[174:177], v[30:33]
	v_mfma_f32_16x16x32_bf16 v[18:21], v[142:145], v[184:187], v[18:21]
	v_mfma_f32_16x16x32_bf16 v[22:25], v[150:153], v[184:187], v[22:25]
	v_mfma_f32_16x16x32_bf16 v[10:13], v[142:145], v[192:195], v[10:13]
	v_mfma_f32_16x16x32_bf16 v[14:17], v[150:153], v[192:195], v[14:17]
	s_waitcnt lgkmcnt(0)
	v_mfma_f32_16x16x32_bf16 v[2:5], v[142:145], v[200:203], v[2:5]
	v_mfma_f32_16x16x32_bf16 v[6:9], v[150:153], v[200:203], v[6:9]
	s_nop 0
	s_nop 0
	v_mfma_f32_16x16x32_bf16 v[58:61], v[154:157], v[170:173], v[58:61]
	v_mfma_f32_16x16x32_bf16 v[62:65], v[162:165], v[170:173], v[62:65]
	v_mfma_f32_16x16x32_bf16 v[50:53], v[154:157], v[178:181], v[50:53]
	v_mfma_f32_16x16x32_bf16 v[54:57], v[162:165], v[178:181], v[54:57]
	v_mfma_f32_16x16x32_bf16 v[42:45], v[154:157], v[188:191], v[42:45]
	v_mfma_f32_16x16x32_bf16 v[46:49], v[162:165], v[188:191], v[46:49]
	v_mfma_f32_16x16x32_bf16 v[34:37], v[154:157], v[196:199], v[34:37]
	v_mfma_f32_16x16x32_bf16 v[38:41], v[162:165], v[196:199], v[38:41]
	v_mfma_f32_16x16x32_bf16 v[58:61], v[158:161], v[174:177], v[58:61]
	v_mfma_f32_16x16x32_bf16 v[62:65], v[166:169], v[174:177], v[62:65]
	v_mfma_f32_16x16x32_bf16 v[50:53], v[158:161], v[184:187], v[50:53]
	v_mfma_f32_16x16x32_bf16 v[54:57], v[166:169], v[184:187], v[54:57]
	v_mfma_f32_16x16x32_bf16 v[42:45], v[158:161], v[192:195], v[42:45]
	v_mfma_f32_16x16x32_bf16 v[46:49], v[166:169], v[192:195], v[46:49]
	v_mfma_f32_16x16x32_bf16 v[34:37], v[158:161], v[200:203], v[34:37]
	v_mfma_f32_16x16x32_bf16 v[38:41], v[166:169], v[200:203], v[38:41]
	s_nop 0
	s_barrier
	ds_read_b128 v[170:173], v134 offset:16384
	ds_read_b128 v[174:177], v134 offset:17408
	ds_read_b128 v[178:181], v134 offset:18432
	ds_read_b128 v[184:187], v134 offset:19456
	ds_read_b128 v[188:191], v134 offset:20480
	ds_read_b128 v[192:195], v134 offset:21504
	ds_read_b128 v[196:199], v134 offset:22528
	ds_read_b128 v[200:203], v134 offset:23552
	s_mov_b32 m0, s36
	s_nop 0
	global_load_lds_dwordx4 v130, s[28:29]
	s_add_u32 s88, s28, 0x80000
	s_mov_b32 m0, s37
	s_nop 0
	global_load_lds_dwordx4 v131, s[28:29]
	s_addc_u32 s89, s29, 0
	s_mov_b32 m0, s40
	s_nop 0
	global_load_lds_dwordx4 v130, s[88:89]
	s_nop 0
	s_mov_b32 m0, s41
	s_nop 0
	global_load_lds_dwordx4 v131, s[88:89]
	s_nop 0
	s_mov_b32 m0, s35
	s_nop 0
	global_load_lds_dwordx4 v130, s[30:31]
	s_nop 0
	s_mov_b32 m0, s44
	s_nop 0
	global_load_lds_dwordx4 v131, s[30:31]
	s_waitcnt vmcnt(8)
	s_waitcnt lgkmcnt(0)
	s_barrier
	s_nop 0
	s_waitcnt lgkmcnt(7)
	v_mfma_f32_16x16x32_bf16 v[98:101], v[138:141], v[170:173], v[98:101]
	v_mfma_f32_16x16x32_bf16 v[102:105], v[146:149], v[170:173], v[102:105]
	s_waitcnt lgkmcnt(5)
	v_mfma_f32_16x16x32_bf16 v[86:89], v[138:141], v[178:181], v[86:89]
	v_mfma_f32_16x16x32_bf16 v[90:93], v[146:149], v[178:181], v[90:93]
	s_waitcnt lgkmcnt(3)
	v_mfma_f32_16x16x32_bf16 v[74:77], v[138:141], v[188:191], v[74:77]
	v_mfma_f32_16x16x32_bf16 v[78:81], v[146:149], v[188:191], v[78:81]
	s_waitcnt lgkmcnt(1)
	v_mfma_f32_16x16x32_bf16 v[66:69], v[138:141], v[196:199], v[66:69]
	v_mfma_f32_16x16x32_bf16 v[70:73], v[146:149], v[196:199], v[70:73]
	v_mfma_f32_16x16x32_bf16 v[98:101], v[142:145], v[174:177], v[98:101]
	v_mfma_f32_16x16x32_bf16 v[102:105], v[150:153], v[174:177], v[102:105]
	v_mfma_f32_16x16x32_bf16 v[86:89], v[142:145], v[184:187], v[86:89]
	v_mfma_f32_16x16x32_bf16 v[90:93], v[150:153], v[184:187], v[90:93]
	v_mfma_f32_16x16x32_bf16 v[74:77], v[142:145], v[192:195], v[74:77]
	v_mfma_f32_16x16x32_bf16 v[78:81], v[150:153], v[192:195], v[78:81]
	s_waitcnt lgkmcnt(0)
	v_mfma_f32_16x16x32_bf16 v[66:69], v[142:145], v[200:203], v[66:69]
	v_mfma_f32_16x16x32_bf16 v[70:73], v[150:153], v[200:203], v[70:73]
	s_nop 0
	s_nop 0
	v_mfma_f32_16x16x32_bf16 v[122:125], v[154:157], v[170:173], v[122:125]
	v_mfma_f32_16x16x32_bf16 v[126:129], v[162:165], v[170:173], v[126:129]
	v_mfma_f32_16x16x32_bf16 v[114:117], v[154:157], v[178:181], v[114:117]
	v_mfma_f32_16x16x32_bf16 v[118:121], v[162:165], v[178:181], v[118:121]
	v_mfma_f32_16x16x32_bf16 v[106:109], v[154:157], v[188:191], v[106:109]
	v_mfma_f32_16x16x32_bf16 v[110:113], v[162:165], v[188:191], v[110:113]
	v_mfma_f32_16x16x32_bf16 v[94:97], v[154:157], v[196:199], v[94:97]
	v_mfma_f32_16x16x32_bf16 v[82:85], v[162:165], v[196:199], v[82:85]
	v_mfma_f32_16x16x32_bf16 v[122:125], v[158:161], v[174:177], v[122:125]
	v_mfma_f32_16x16x32_bf16 v[126:129], v[166:169], v[174:177], v[126:129]
	v_mfma_f32_16x16x32_bf16 v[114:117], v[158:161], v[184:187], v[114:117]
	v_mfma_f32_16x16x32_bf16 v[118:121], v[166:169], v[184:187], v[118:121]
	v_mfma_f32_16x16x32_bf16 v[106:109], v[158:161], v[192:195], v[106:109]
	v_mfma_f32_16x16x32_bf16 v[110:113], v[166:169], v[192:195], v[110:113]
	v_mfma_f32_16x16x32_bf16 v[94:97], v[158:161], v[200:203], v[94:97]
	v_mfma_f32_16x16x32_bf16 v[82:85], v[166:169], v[200:203], v[82:85]
	s_nop 0
	s_barrier
	v_add_u32_e32 v137, 0x18000, v133
	v_add_u32_e32 v138, 0x1c000, v133
	ds_read_b128 v[140:143], v137
	ds_read_b128 v[144:147], v137 offset:1024
	ds_read_b128 v[148:151], v137 offset:2048
	ds_read_b128 v[152:155], v137 offset:3072
	ds_read_b128 v[156:159], v138
	ds_read_b128 v[160:163], v138 offset:1024
	ds_read_b128 v[164:167], v138 offset:2048
	ds_read_b128 v[168:171], v138 offset:3072
	ds_read_b128 v[172:175], v134 offset:32768
	ds_read_b128 v[176:179], v134 offset:33792
	ds_read_b128 v[184:187], v134 offset:34816
	ds_read_b128 v[188:191], v134 offset:35840
	ds_read_b128 v[192:195], v134 offset:36864
	ds_read_b128 v[196:199], v134 offset:37888
	ds_read_b128 v[200:203], v134 offset:38912
	ds_read_b128 v[204:207], v134 offset:39936
	s_add_u32 s30, s30, 0x80000
	s_addc_u32 s31, s31, 0
	s_mov_b32 m0, s48
	s_nop 0
	global_load_lds_dwordx4 v130, s[30:31]
	s_nop 0
	s_mov_b32 m0, s49
	s_nop 0
	global_load_lds_dwordx4 v131, s[30:31]
	s_waitcnt vmcnt(8)
	s_waitcnt lgkmcnt(0)
	s_barrier
	s_nop 0
	s_waitcnt lgkmcnt(7)
	v_mfma_f32_16x16x32_bf16 v[26:29], v[140:143], v[172:175], v[26:29]
	v_mfma_f32_16x16x32_bf16 v[30:33], v[148:151], v[172:175], v[30:33]
	s_waitcnt lgkmcnt(5)
	v_mfma_f32_16x16x32_bf16 v[18:21], v[140:143], v[184:187], v[18:21]
	v_mfma_f32_16x16x32_bf16 v[22:25], v[148:151], v[184:187], v[22:25]
	s_waitcnt lgkmcnt(3)
	v_mfma_f32_16x16x32_bf16 v[10:13], v[140:143], v[192:195], v[10:13]
	v_mfma_f32_16x16x32_bf16 v[14:17], v[148:151], v[192:195], v[14:17]
	s_waitcnt lgkmcnt(1)
	v_mfma_f32_16x16x32_bf16 v[2:5], v[140:143], v[200:203], v[2:5]
	v_mfma_f32_16x16x32_bf16 v[6:9], v[148:151], v[200:203], v[6:9]
	v_mfma_f32_16x16x32_bf16 v[26:29], v[144:147], v[176:179], v[26:29]
	v_mfma_f32_16x16x32_bf16 v[30:33], v[152:155], v[176:179], v[30:33]
	v_mfma_f32_16x16x32_bf16 v[18:21], v[144:147], v[188:191], v[18:21]
	v_mfma_f32_16x16x32_bf16 v[22:25], v[152:155], v[188:191], v[22:25]
	v_mfma_f32_16x16x32_bf16 v[10:13], v[144:147], v[196:199], v[10:13]
	v_mfma_f32_16x16x32_bf16 v[14:17], v[152:155], v[196:199], v[14:17]
	s_waitcnt lgkmcnt(0)
	v_mfma_f32_16x16x32_bf16 v[2:5], v[144:147], v[204:207], v[2:5]
	v_mfma_f32_16x16x32_bf16 v[6:9], v[152:155], v[204:207], v[6:9]
	s_nop 0
	s_nop 0
	v_mfma_f32_16x16x32_bf16 v[58:61], v[156:159], v[172:175], v[58:61]
	v_mfma_f32_16x16x32_bf16 v[62:65], v[164:167], v[172:175], v[62:65]
	v_mfma_f32_16x16x32_bf16 v[50:53], v[156:159], v[184:187], v[50:53]
	v_mfma_f32_16x16x32_bf16 v[54:57], v[164:167], v[184:187], v[54:57]
	v_mfma_f32_16x16x32_bf16 v[42:45], v[156:159], v[192:195], v[42:45]
	v_mfma_f32_16x16x32_bf16 v[46:49], v[164:167], v[192:195], v[46:49]
	v_mfma_f32_16x16x32_bf16 v[34:37], v[156:159], v[200:203], v[34:37]
	v_mfma_f32_16x16x32_bf16 v[38:41], v[164:167], v[200:203], v[38:41]
	v_mfma_f32_16x16x32_bf16 v[58:61], v[160:163], v[176:179], v[58:61]
	v_mfma_f32_16x16x32_bf16 v[62:65], v[168:171], v[176:179], v[62:65]
	v_mfma_f32_16x16x32_bf16 v[50:53], v[160:163], v[188:191], v[50:53]
	v_mfma_f32_16x16x32_bf16 v[54:57], v[168:171], v[188:191], v[54:57]
	v_mfma_f32_16x16x32_bf16 v[42:45], v[160:163], v[196:199], v[42:45]
	v_mfma_f32_16x16x32_bf16 v[46:49], v[168:171], v[196:199], v[46:49]
	v_mfma_f32_16x16x32_bf16 v[34:37], v[160:163], v[204:207], v[34:37]
	v_mfma_f32_16x16x32_bf16 v[38:41], v[168:171], v[204:207], v[38:41]
	s_nop 0
	s_barrier
; #define PG8_STAGE(bufoff, gbase, voff) do { _Pragma("unroll") for (int _i = 0; _i < 2; ++_i) { \
;         const unsigned m0_ = ldsbase + (unsigned)(bufoff) + ldsw + (unsigned)_i * 8192u; \
;         asm volatile("s_mov_b32 m0, %2\n\ts_nop 0\n\tglobal_load_lds_dwordx4 %0, %1" :: "v"((voff)[_i]), "s"((const char*)(gbase)), "s"(m0_) : "memory", "m0"); } } while (0)
; template <class Epi, class Sched, bool ALIGN_EPI = false, bool SP2 = false>
; __device__ __forceinline__ void gemm_phase(PG8_LAS unsigned char* lds, const Gemm g, const Sched& S, const Epi& E) {
;     ...
;         if constexpr (DRO) { asm volatile("" ::: "memory"); PG8_STAGE(PG8_SA(1, 1), nA + kstep + hsA, voffA); asm volatile("" ::: "memory"); }
	ds_read_b128 v[172:175], v134 offset:49152
	ds_read_b128 v[176:179], v134 offset:50176
	ds_read_b128 v[184:187], v134 offset:51200
	ds_read_b128 v[188:191], v134 offset:52224
	ds_read_b128 v[192:195], v134 offset:53248
	ds_read_b128 v[196:199], v134 offset:54272
	ds_read_b128 v[200:203], v134 offset:55296
	ds_read_b128 v[204:207], v134 offset:56320
	s_add_u32 s30, s28, 0x80
	s_addc_u32 s31, s29, 0
	s_mov_b32 m0, s53
	s_nop 0
	global_load_lds_dwordx4 v130, s[30:31]
	s_add_u32 s28, s28, 0x80080
	s_mov_b32 m0, s57
	s_nop 0
	global_load_lds_dwordx4 v131, s[30:31]
	s_addc_u32 s29, s29, 0
	s_mov_b32 m0, s67
	s_nop 0
	global_load_lds_dwordx4 v130, s[28:29]
	s_nop 0
	s_mov_b32 m0, s69
	s_nop 0
	global_load_lds_dwordx4 v131, s[28:29]
	s_nop 0
	s_mov_b32 m0, s63
	s_nop 0
	global_load_lds_dwordx4 v130, s[26:27]
	s_nop 0
	s_mov_b32 m0, s64
	s_nop 0
	global_load_lds_dwordx4 v131, s[26:27]
	s_waitcnt vmcnt(8)
	s_waitcnt lgkmcnt(0)
	s_barrier
	s_nop 0
	s_waitcnt lgkmcnt(7)
	v_mfma_f32_16x16x32_bf16 v[98:101], v[140:143], v[172:175], v[98:101]
	v_mfma_f32_16x16x32_bf16 v[102:105], v[148:151], v[172:175], v[102:105]
	s_waitcnt lgkmcnt(5)
	v_mfma_f32_16x16x32_bf16 v[86:89], v[140:143], v[184:187], v[86:89]
	v_mfma_f32_16x16x32_bf16 v[90:93], v[148:151], v[184:187], v[90:93]
	s_waitcnt lgkmcnt(3)
	v_mfma_f32_16x16x32_bf16 v[74:77], v[140:143], v[192:195], v[74:77]
	v_mfma_f32_16x16x32_bf16 v[78:81], v[148:151], v[192:195], v[78:81]
	s_waitcnt lgkmcnt(1)
	v_mfma_f32_16x16x32_bf16 v[66:69], v[140:143], v[200:203], v[66:69]
	v_mfma_f32_16x16x32_bf16 v[70:73], v[148:151], v[200:203], v[70:73]
	v_mfma_f32_16x16x32_bf16 v[98:101], v[144:147], v[176:179], v[98:101]
	v_mfma_f32_16x16x32_bf16 v[102:105], v[152:155], v[176:179], v[102:105]
	v_mfma_f32_16x16x32_bf16 v[86:89], v[144:147], v[188:191], v[86:89]
	v_mfma_f32_16x16x32_bf16 v[90:93], v[152:155], v[188:191], v[90:93]
	v_mfma_f32_16x16x32_bf16 v[74:77], v[144:147], v[196:199], v[74:77]
	v_mfma_f32_16x16x32_bf16 v[78:81], v[152:155], v[196:199], v[78:81]
	s_waitcnt lgkmcnt(0)
	v_mfma_f32_16x16x32_bf16 v[66:69], v[144:147], v[204:207], v[66:69]
	v_mfma_f32_16x16x32_bf16 v[70:73], v[152:155], v[204:207], v[70:73]
	s_nop 0
	s_nop 0
	v_mfma_f32_16x16x32_bf16 v[122:125], v[156:159], v[172:175], v[122:125]
	v_mfma_f32_16x16x32_bf16 v[126:129], v[164:167], v[172:175], v[126:129]
	v_mfma_f32_16x16x32_bf16 v[114:117], v[156:159], v[184:187], v[114:117]
	v_mfma_f32_16x16x32_bf16 v[118:121], v[164:167], v[184:187], v[118:121]
	v_mfma_f32_16x16x32_bf16 v[106:109], v[156:159], v[192:195], v[106:109]
	v_mfma_f32_16x16x32_bf16 v[110:113], v[164:167], v[192:195], v[110:113]
	v_mfma_f32_16x16x32_bf16 v[94:97], v[156:159], v[200:203], v[94:97]
	v_mfma_f32_16x16x32_bf16 v[82:85], v[164:167], v[200:203], v[82:85]
	v_mfma_f32_16x16x32_bf16 v[122:125], v[160:163], v[176:179], v[122:125]
	v_mfma_f32_16x16x32_bf16 v[126:129], v[168:171], v[176:179], v[126:129]
	v_mfma_f32_16x16x32_bf16 v[114:117], v[160:163], v[188:191], v[114:117]
	v_mfma_f32_16x16x32_bf16 v[118:121], v[168:171], v[188:191], v[118:121]
	v_mfma_f32_16x16x32_bf16 v[106:109], v[160:163], v[196:199], v[106:109]
	v_mfma_f32_16x16x32_bf16 v[110:113], v[168:171], v[196:199], v[110:113]
	v_mfma_f32_16x16x32_bf16 v[94:97], v[160:163], v[204:207], v[94:97]
	v_mfma_f32_16x16x32_bf16 v[82:85], v[168:171], v[204:207], v[82:85]
	s_nop 0
	s_barrier
	s_add_i32 s7, s7, 2
	s_add_u32 s15, s15, 0x100
	s_addc_u32 s17, s17, 0
	s_add_u32 s24, s24, 0x100
	s_addc_u32 s25, s25, 0
	s_cmp_gt_u32 s7, 5
	s_cbranch_scc0 .LBB0_952
	s_add_u32 s24, s20, 0x80080
	s_addc_u32 s25, s21, 0
	s_mov_b32 m0, s78
	s_nop 0
	global_load_lds_dwordx4 v130, s[24:25]
	s_and_b64 vcc, exec, s[12:13]
	s_mov_b32 m0, s79
	s_nop 0
	global_load_lds_dwordx4 v131, s[24:25]
	s_cbranch_vccz .LBB0_955
	s_barrier

; #define MK_LAS __attribute__((address_space(3)))
; __device__ __forceinline__ unsigned mk_hwkey() { unsigned hw; asm volatile("s_getreg_b32 %0, hwreg(HW_REG_HW_ID, 0, 6)" : "=s"(hw)); return hw; }
; __device__ __forceinline__ int mk_wave() {
;     extern __shared__ __attribute__((aligned(16))) unsigned char lds[];
;     const unsigned hw = mk_hwkey();
;     return __builtin_amdgcn_readfirstlane((int)*(volatile MK_LAS unsigned*)((MK_LAS unsigned char*)lds + TIDTAB_OFF + 4 * hw));
; }
; template <class Epi, class Sched, bool ALIGN_EPI = false, bool SP2 = false>
; __device__ __forceinline__ void gemm_phase(PG8_LAS unsigned char* lds, const Gemm g, const Sched& S, const Epi& E) {
;     ...
;     for (int i = 0; i < 2; ++i) { int R, C; stage_rc(tid * 16 + i * 8192, R, C); const int Rb = Epi::PERM ? ((R & ~31) + perm32(R & 31)) : R;
;         voffA[i] = (unsigned)(R * g.lda + C) * 2u; voffB[i] = (unsigned)(Rb * g.ldb + C) * 2u; }
;     const size_t kstep = (size_t)(BK * 2);
;     const size_t hsA = (size_t)HALF * g.lda * 2, hsB = (size_t)HALF * g.ldb * 2;
;     const size_t tsA = 2 * hsA, tsB = 2 * hsB;
;     const unsigned ldsbase = (unsigned)(unsigned long long)lds;
;     const unsigned ldsw = (unsigned)wid * 1024u;
;     const int aoff = lds_byte(wr * 64 + fr, fq * 8), boff = lds_byte(wc * 32 + fr, fq * 8);
;     ...
;     Unit cur, nxt; int ui = 0; bool epi_ran = false;
;     if (!S.next(0, cur)) return;
;     f32x4 acc[2][2][4][2];
; #pragma unroll
;     for (int a = 0; a < 2; ++a)
; #pragma unroll
;         for (int b = 0; b < 2; ++b)
; #pragma unroll
;             for (int m = 0; m < 4; ++m)
; #pragma unroll
;                 for (int n = 0; n < 2; ++n) acc[a][b][m][n] = (f32x4){0.f, 0.f, 0.f, 0.f};
;     bf16x8 At[4][2], B0[2][2], B1[2][2];
;     const char* cA = (const char*)g.A + (size_t)cur.pm * tsA + (size_t)cur.k0 * 2; const char* cB = (const char*)g.Bt + (size_t)cur.pn * tsB + (size_t)cur.k0 * 2;
;     S.a_ready(cur);
;     if constexpr (SP2) {
;         PG8_STAGE(PG8_SB(0, 0), cB, voffB); PG8_STAGE(PG8_SB(0, 1), cB + hsB, voffB); PG8_STAGE(PG8_SA(0, 0), cA, voffA); PG8_STAGE(PG8_SA(0, 1), cA + hsA, voffA);
;         if (wr == 1) PG8_BAR;
;         PG8_WAIT_V(2); PG8_BAR;
;         PG8_STAGE(PG8_SB(1, 0), cB + kstep, voffB); PG8_STAGE(PG8_SA(1, 0), cA + kstep, voffA); PG8_STAGE(PG8_SB(1, 1), cB + hsB + kstep, voffB);
;         PG8_WAIT_V(6); PG8_BAR;
.LBB0_1108:
	v_lshrrev_b32_e32 v3, 1, v0
	v_and_b32_e32 v3, 24, v3
	v_and_b32_e32 v2, 15, v0
	v_lshlrev_b32_e32 v4, 1, v3
	v_lshlrev_b32_e32 v0, 2, v0
	v_lshl_or_b32 v136, s7, 6, v2
	v_lshl_or_b32 v2, v2, 6, v4
	s_lshl_b32 s7, s7, 13
	v_and_b32_e32 v0, 32, v0
	v_bitop3_b32 v4, v2, s7, v0 bitop3:0xde
	s_lshl_b32 s7, s10, 5
	s_and_b32 s7, s7, 0x60
	s_lshl_b32 s10, s7, 7
	s_add_i32 s53, s25, 0x18000
	v_bitop3_b32 v5, v2, s10, v0 bitop3:0xde
	s_add_u32 s10, s26, 0x80
	s_waitcnt vmcnt(2)
	s_barrier
	s_addc_u32 s11, s27, 0
	s_mov_b32 m0, s53
	s_nop 0
	global_load_lds_dwordx4 v133, s[10:11]
	s_add_i32 s57, s25, 0x1a000
	s_add_i32 s63, s25, 0x8000
	s_mov_b32 m0, s57
	s_nop 0
	global_load_lds_dwordx4 v135, s[10:11]
	s_add_u32 s10, s28, 0x80
	s_addc_u32 s11, s29, 0
	s_mov_b32 m0, s63
	s_nop 0
	global_load_lds_dwordx4 v132, s[10:11]
	s_add_i32 s64, s25, 0xa000
	s_add_i32 s67, s25, 0x1c000
	s_mov_b32 m0, s64
	s_nop 0
	global_load_lds_dwordx4 v134, s[10:11]
	s_add_u32 s10, s26, 0x80080
	s_addc_u32 s11, s27, 0
	s_mov_b32 m0, s67
	s_nop 0
	global_load_lds_dwordx4 v133, s[10:11]
	s_add_i32 s69, s25, 0x1e000
	s_mov_b32 m0, s69
	s_nop 0
	global_load_lds_dwordx4 v135, s[10:11]
	s_waitcnt vmcnt(6)
	s_add_i32 s77, s25, 0xc000
	v_or_b32_e32 v137, s7, v3
	v_mov_b32_e32 v2, v1
	v_mov_b32_e32 v3, v1
	s_cmpk_lt_u32 s6, 0x100
	v_mov_b32_e32 v0, v1
	v_add_u32_e32 v138, 0, v5
	v_add_u32_e32 v139, 0, v4
	v_mov_b64_e32 v[10:11], v[2:3]
	v_mov_b64_e32 v[18:19], v[2:3]
	v_mov_b64_e32 v[26:27], v[2:3]
	v_mov_b64_e32 v[34:35], v[2:3]
	v_mov_b64_e32 v[42:43], v[2:3]
	v_mov_b64_e32 v[50:51], v[2:3]
	v_mov_b64_e32 v[58:59], v[2:3]
	v_mov_b64_e32 v[74:75], v[2:3]
	v_mov_b64_e32 v[6:7], v[2:3]
	v_mov_b64_e32 v[14:15], v[2:3]
	v_mov_b64_e32 v[22:23], v[2:3]
	v_mov_b64_e32 v[30:31], v[2:3]
	v_mov_b64_e32 v[38:39], v[2:3]
	v_mov_b64_e32 v[46:47], v[2:3]
	v_mov_b64_e32 v[54:55], v[2:3]
	v_mov_b64_e32 v[66:67], v[2:3]
	v_mov_b64_e32 v[70:71], v[2:3]
	v_mov_b64_e32 v[82:83], v[2:3]
	v_mov_b64_e32 v[90:91], v[2:3]
	v_mov_b64_e32 v[98:99], v[2:3]
	v_mov_b64_e32 v[106:107], v[2:3]
	v_mov_b64_e32 v[114:115], v[2:3]
	v_mov_b64_e32 v[122:123], v[2:3]
	v_mov_b64_e32 v[130:131], v[2:3]
	v_mov_b64_e32 v[62:63], v[2:3]
	v_mov_b64_e32 v[78:79], v[2:3]
	v_mov_b64_e32 v[86:87], v[2:3]
	v_mov_b64_e32 v[94:95], v[2:3]
	v_mov_b64_e32 v[102:103], v[2:3]
	v_mov_b64_e32 v[110:111], v[2:3]
	v_mov_b64_e32 v[118:119], v[2:3]
	v_mov_b64_e32 v[126:127], v[2:3]
	s_cselect_b64 s[10:11], -1, 0
	s_add_i32 s78, s25, 0xe000
	s_mov_b32 s23, 0
	v_mov_b64_e32 v[8:9], v[0:1]
	v_mov_b64_e32 v[16:17], v[0:1]
	v_mov_b64_e32 v[24:25], v[0:1]
	v_mov_b64_e32 v[32:33], v[0:1]
	v_mov_b64_e32 v[40:41], v[0:1]
	v_mov_b64_e32 v[48:49], v[0:1]
	v_mov_b64_e32 v[56:57], v[0:1]
	v_mov_b64_e32 v[72:73], v[0:1]
	v_mov_b64_e32 v[4:5], v[0:1]
	v_mov_b64_e32 v[12:13], v[0:1]
	v_mov_b64_e32 v[20:21], v[0:1]
	v_mov_b64_e32 v[28:29], v[0:1]
	v_mov_b64_e32 v[36:37], v[0:1]
	v_mov_b64_e32 v[44:45], v[0:1]
	v_mov_b64_e32 v[52:53], v[0:1]
	v_mov_b64_e32 v[64:65], v[0:1]
	v_mov_b64_e32 v[68:69], v[0:1]
	v_mov_b64_e32 v[80:81], v[0:1]
	v_mov_b64_e32 v[88:89], v[0:1]
	v_mov_b64_e32 v[96:97], v[0:1]
	v_mov_b64_e32 v[104:105], v[0:1]
	v_mov_b64_e32 v[112:113], v[0:1]
	v_mov_b64_e32 v[120:121], v[0:1]
	v_mov_b64_e32 v[128:129], v[0:1]
	v_mov_b64_e32 v[60:61], v[0:1]
	v_mov_b64_e32 v[76:77], v[0:1]
	v_mov_b64_e32 v[84:85], v[0:1]
	v_mov_b64_e32 v[92:93], v[0:1]
	v_mov_b64_e32 v[100:101], v[0:1]
	v_mov_b64_e32 v[108:109], v[0:1]
	v_mov_b64_e32 v[116:117], v[0:1]
	v_mov_b64_e32 v[124:125], v[0:1]
	s_barrier
	s_getreg_b32 s100, hwreg(HW_REG_HW_ID, 0, 6)
	s_lshl_b32 s100, s100, 2
	s_add_i32 s100, s100, 0x20540
	v_mov_b32_e32 v251, s100
	ds_read_b32 v251, v251
	s_waitcnt lgkmcnt(0)
	v_readfirstlane_b32 s100, v251
	s_cmp_ge_u32 s100, 4
	s_cbranch_scc0 statprio_skip4
	s_setprio 1
statprio_skip4:
	s_branch .LBB0_1111
.LBB0_1109:
	ds_read_b128 v[4:7], v0
	ds_read_b128 v[8:11], v0 offset:1024
	ds_read_b128 v[12:15], v0 offset:2048
	ds_read_b128 v[16:19], v0 offset:3072
	ds_read_b128 v[20:23], v2
	ds_read_b128 v[24:27], v2 offset:1024
	ds_read_b128 v[28:31], v2 offset:2048
	ds_read_b128 v[32:35], v2 offset:3072
	s_add_u32 s22, s16, 0x100
	s_addc_u32 s23, s17, 0
	s_add_u32 s20, s16, 0x180
	s_addc_u32 s21, s17, 0
	s_add_u32 s6, s18, 0x100
	s_addc_u32 s7, s19, 0
	ds_read_b128 v[36:39], v139
	ds_read_b128 v[40:43], v139 offset:1024
	ds_read_b128 v[44:47], v139 offset:2048
	ds_read_b128 v[48:51], v139 offset:3072
	ds_read_b128 v[52:55], v139 offset:4096
	ds_read_b128 v[56:59], v139 offset:5120
	ds_read_b128 v[60:63], v139 offset:6144
	ds_read_b128 v[64:67], v139 offset:7168
	s_waitcnt vmcnt(16)
	s_waitcnt lgkmcnt(0)
	s_barrier
	s_nop 0
	s_waitcnt lgkmcnt(1)
	v_mfma_f32_16x16x32_bf16 v[92:95], v[4:7], v[60:63], 0
	v_mfma_f32_16x16x32_bf16 v[68:71], v[4:7], v[36:39], 0
	v_mfma_f32_16x16x32_bf16 v[72:75], v[12:15], v[36:39], 0
	v_mfma_f32_16x16x32_bf16 v[76:79], v[4:7], v[44:47], 0
	v_mfma_f32_16x16x32_bf16 v[80:83], v[12:15], v[44:47], 0
	v_mfma_f32_16x16x32_bf16 v[84:87], v[4:7], v[52:55], 0
	v_mfma_f32_16x16x32_bf16 v[88:91], v[12:15], v[52:55], 0
	s_waitcnt lgkmcnt(0)
	v_mfma_f32_16x16x32_bf16 v[96:99], v[8:11], v[64:67], v[92:95]
	v_mfma_f32_16x16x32_bf16 v[92:95], v[12:15], v[60:63], 0
	v_mfma_f32_16x16x32_bf16 v[68:71], v[8:11], v[40:43], v[68:71]
	v_mfma_f32_16x16x32_bf16 v[72:75], v[16:19], v[40:43], v[72:75]
	v_mfma_f32_16x16x32_bf16 v[76:79], v[8:11], v[48:51], v[76:79]
	v_mfma_f32_16x16x32_bf16 v[80:83], v[16:19], v[48:51], v[80:83]
	v_mfma_f32_16x16x32_bf16 v[84:87], v[8:11], v[56:59], v[84:87]
	v_mfma_f32_16x16x32_bf16 v[88:91], v[16:19], v[56:59], v[88:91]
	v_mfma_f32_16x16x32_bf16 v[104:107], v[16:19], v[64:67], v[92:95]
	s_nop 0
	s_nop 0
	v_mfma_f32_16x16x32_bf16 v[92:95], v[20:23], v[36:39], 0
	v_mfma_f32_16x16x32_bf16 v[36:39], v[28:31], v[36:39], 0
	v_mfma_f32_16x16x32_bf16 v[112:115], v[24:27], v[40:43], v[92:95]
	v_mfma_f32_16x16x32_bf16 v[36:39], v[32:35], v[40:43], v[36:39]
	v_mfma_f32_16x16x32_bf16 v[40:43], v[20:23], v[44:47], 0
	v_mfma_f32_16x16x32_bf16 v[44:47], v[28:31], v[44:47], 0
	v_mfma_f32_16x16x32_bf16 v[40:43], v[24:27], v[48:51], v[40:43]
	v_mfma_f32_16x16x32_bf16 v[44:47], v[32:35], v[48:51], v[44:47]
	v_mfma_f32_16x16x32_bf16 v[48:51], v[20:23], v[52:55], 0
	v_mfma_f32_16x16x32_bf16 v[52:55], v[28:31], v[52:55], 0
	v_mfma_f32_16x16x32_bf16 v[48:51], v[24:27], v[56:59], v[48:51]
	v_mfma_f32_16x16x32_bf16 v[52:55], v[32:35], v[56:59], v[52:55]
	v_mfma_f32_16x16x32_bf16 v[56:59], v[20:23], v[60:63], 0
	v_mfma_f32_16x16x32_bf16 v[60:63], v[28:31], v[60:63], 0
	v_mfma_f32_16x16x32_bf16 v[56:59], v[24:27], v[64:67], v[56:59]
	v_mfma_f32_16x16x32_bf16 v[64:67], v[32:35], v[64:67], v[60:63]
	s_nop 0
	s_barrier
	s_nop 3
	ds_read_b128 v[60:63], v139 offset:16384
	ds_read_b128 v[92:95], v139 offset:17408
	ds_read_b128 v[100:103], v139 offset:18432
	ds_read_b128 v[108:111], v139 offset:19456
	ds_read_b128 v[116:119], v139 offset:20480
	ds_read_b128 v[120:123], v139 offset:21504
	ds_read_b128 v[124:127], v139 offset:22528
	ds_read_b128 v[128:131], v139 offset:23552
	s_mov_b32 m0, s41
	s_nop 0
	global_load_lds_dwordx4 v133, s[6:7]
	s_nop 0
	s_mov_b32 m0, s44
	s_nop 0
	global_load_lds_dwordx4 v135, s[6:7]
	s_add_u32 s6, s18, 0x80100
	s_addc_u32 s7, s19, 0
	s_mov_b32 m0, s47
	s_nop 0
	global_load_lds_dwordx4 v133, s[6:7]
	s_nop 0
	s_mov_b32 m0, s48
	s_nop 0
	global_load_lds_dwordx4 v135, s[6:7]
	s_nop 0
	s_mov_b32 m0, s25
	s_nop 0
	global_load_lds_dwordx4 v132, s[22:23]
	s_nop 0
	s_mov_b32 m0, s49
	s_nop 0
	global_load_lds_dwordx4 v134, s[22:23]
	s_waitcnt vmcnt(16)
	s_waitcnt lgkmcnt(0)
	s_barrier
	s_nop 0
	s_waitcnt lgkmcnt(7)
	v_mfma_f32_16x16x32_bf16 v[142:145], v[4:7], v[60:63], 0
	s_waitcnt lgkmcnt(5)
	v_mfma_f32_16x16x32_bf16 v[150:153], v[4:7], v[100:103], 0
	s_waitcnt lgkmcnt(3)
	v_mfma_f32_16x16x32_bf16 v[158:161], v[4:7], v[116:119], 0
	s_waitcnt lgkmcnt(1)
	v_mfma_f32_16x16x32_bf16 v[4:7], v[4:7], v[124:127], 0
	v_mfma_f32_16x16x32_bf16 v[142:145], v[8:11], v[92:95], v[142:145]
	v_mfma_f32_16x16x32_bf16 v[150:153], v[8:11], v[108:111], v[150:153]
	v_mfma_f32_16x16x32_bf16 v[158:161], v[8:11], v[120:123], v[158:161]
	s_waitcnt lgkmcnt(0)
	v_mfma_f32_16x16x32_bf16 v[4:7], v[8:11], v[128:131], v[4:7]
	v_mfma_f32_16x16x32_bf16 v[8:11], v[12:15], v[124:127], 0
	v_mfma_f32_16x16x32_bf16 v[146:149], v[12:15], v[60:63], 0
	v_mfma_f32_16x16x32_bf16 v[154:157], v[12:15], v[100:103], 0
	v_mfma_f32_16x16x32_bf16 v[162:165], v[12:15], v[116:119], 0
	v_mfma_f32_16x16x32_bf16 v[8:11], v[16:19], v[128:131], v[8:11]
	v_mfma_f32_16x16x32_bf16 v[146:149], v[16:19], v[92:95], v[146:149]
	v_mfma_f32_16x16x32_bf16 v[154:157], v[16:19], v[108:111], v[154:157]
	v_mfma_f32_16x16x32_bf16 v[162:165], v[16:19], v[120:123], v[162:165]
	s_nop 0
	s_nop 0
	v_mfma_f32_16x16x32_bf16 v[12:15], v[20:23], v[60:63], 0
	v_mfma_f32_16x16x32_bf16 v[16:19], v[24:27], v[92:95], v[12:15]
	v_mfma_f32_16x16x32_bf16 v[12:15], v[28:31], v[60:63], 0
	v_mfma_f32_16x16x32_bf16 v[166:169], v[32:35], v[92:95], v[12:15]
	v_mfma_f32_16x16x32_bf16 v[12:15], v[20:23], v[100:103], 0
	v_mfma_f32_16x16x32_bf16 v[170:173], v[24:27], v[108:111], v[12:15]
	v_mfma_f32_16x16x32_bf16 v[12:15], v[28:31], v[100:103], 0
	v_mfma_f32_16x16x32_bf16 v[174:177], v[32:35], v[108:111], v[12:15]
	v_mfma_f32_16x16x32_bf16 v[12:15], v[20:23], v[116:119], 0
	v_mfma_f32_16x16x32_bf16 v[178:181], v[24:27], v[120:123], v[12:15]
	v_mfma_f32_16x16x32_bf16 v[12:15], v[28:31], v[116:119], 0
	v_mfma_f32_16x16x32_bf16 v[184:187], v[32:35], v[120:123], v[12:15]
	v_mfma_f32_16x16x32_bf16 v[12:15], v[20:23], v[124:127], 0
	v_mfma_f32_16x16x32_bf16 v[188:191], v[24:27], v[128:131], v[12:15]
	v_mfma_f32_16x16x32_bf16 v[12:15], v[28:31], v[124:127], 0
	v_mfma_f32_16x16x32_bf16 v[192:195], v[32:35], v[128:131], v[12:15]
	s_nop 0
	s_barrier
	s_nop 4
	ds_read_b128 v[12:15], v3
	ds_read_b128 v[24:27], v3 offset:1024
	ds_read_b128 v[32:35], v3 offset:2048
	ds_read_b128 v[196:199], v3 offset:3072
	ds_read_b128 v[200:203], v140
	ds_read_b128 v[204:207], v140 offset:1024
	ds_read_b128 v[208:211], v140 offset:2048
	ds_read_b128 v[212:215], v140 offset:3072
	ds_read_b128 v[20:23], v139 offset:32768
	ds_read_b128 v[28:31], v139 offset:33792
	ds_read_b128 v[216:219], v139 offset:34816
	ds_read_b128 v[220:223], v139 offset:35840
	ds_read_b128 v[224:227], v139 offset:36864
	ds_read_b128 v[228:231], v139 offset:37888
	ds_read_b128 v[232:235], v139 offset:38912
	ds_read_b128 v[236:239], v139 offset:39936
	s_add_u32 s6, s16, 0x80100
	s_addc_u32 s7, s17, 0
	s_mov_b32 m0, s51
	s_nop 0
	global_load_lds_dwordx4 v132, s[6:7]
	s_nop 0
	s_mov_b32 m0, s52
	s_nop 0
	global_load_lds_dwordx4 v134, s[6:7]
	s_waitcnt vmcnt(16)
	s_waitcnt lgkmcnt(0)
	s_barrier
	s_nop 0
	s_waitcnt lgkmcnt(7)
	v_mfma_f32_16x16x32_bf16 v[60:63], v[12:15], v[20:23], v[68:71]
	s_waitcnt lgkmcnt(6)
	v_mfma_f32_16x16x32_bf16 v[124:127], v[24:27], v[28:31], v[60:63]
	v_mfma_f32_16x16x32_bf16 v[60:63], v[32:35], v[20:23], v[72:75]
	v_mfma_f32_16x16x32_bf16 v[116:119], v[196:199], v[28:31], v[60:63]
	s_waitcnt lgkmcnt(5)
	v_mfma_f32_16x16x32_bf16 v[60:63], v[12:15], v[216:219], v[76:79]
	s_waitcnt lgkmcnt(4)
	v_mfma_f32_16x16x32_bf16 v[108:111], v[24:27], v[220:223], v[60:63]
	v_mfma_f32_16x16x32_bf16 v[60:63], v[32:35], v[216:219], v[80:83]
	v_mfma_f32_16x16x32_bf16 v[100:103], v[196:199], v[220:223], v[60:63]
	s_waitcnt lgkmcnt(3)
	v_mfma_f32_16x16x32_bf16 v[60:63], v[12:15], v[224:227], v[84:87]
	s_waitcnt lgkmcnt(2)
	v_mfma_f32_16x16x32_bf16 v[92:95], v[24:27], v[228:231], v[60:63]
	v_mfma_f32_16x16x32_bf16 v[60:63], v[32:35], v[224:227], v[88:91]
	v_mfma_f32_16x16x32_bf16 v[84:87], v[196:199], v[228:231], v[60:63]
	s_waitcnt lgkmcnt(1)
	v_mfma_f32_16x16x32_bf16 v[60:63], v[12:15], v[232:235], v[96:99]
	s_waitcnt lgkmcnt(0)
	v_mfma_f32_16x16x32_bf16 v[76:79], v[24:27], v[236:239], v[60:63]
	v_mfma_f32_16x16x32_bf16 v[60:63], v[32:35], v[232:235], v[104:107]
	v_mfma_f32_16x16x32_bf16 v[60:63], v[196:199], v[236:239], v[60:63]
	s_nop 0
	s_nop 0
	v_mfma_f32_16x16x32_bf16 v[68:71], v[200:203], v[20:23], v[112:115]
	v_mfma_f32_16x16x32_bf16 v[20:23], v[208:211], v[20:23], v[36:39]
	v_mfma_f32_16x16x32_bf16 v[120:123], v[212:215], v[28:31], v[20:23]
	v_mfma_f32_16x16x32_bf16 v[20:23], v[200:203], v[216:219], v[40:43]
	v_mfma_f32_16x16x32_bf16 v[112:115], v[204:207], v[220:223], v[20:23]
	v_mfma_f32_16x16x32_bf16 v[20:23], v[208:211], v[216:219], v[44:47]
	v_mfma_f32_16x16x32_bf16 v[104:107], v[212:215], v[220:223], v[20:23]
	v_mfma_f32_16x16x32_bf16 v[20:23], v[200:203], v[224:227], v[48:51]
	v_mfma_f32_16x16x32_bf16 v[96:99], v[204:207], v[228:231], v[20:23]
	v_mfma_f32_16x16x32_bf16 v[20:23], v[208:211], v[224:227], v[52:55]
	v_mfma_f32_16x16x32_bf16 v[88:91], v[212:215], v[228:231], v[20:23]
	v_mfma_f32_16x16x32_bf16 v[20:23], v[200:203], v[232:235], v[56:59]
	v_mfma_f32_16x16x32_bf16 v[80:83], v[204:207], v[236:239], v[20:23]
	v_mfma_f32_16x16x32_bf16 v[20:23], v[208:211], v[232:235], v[64:67]
	v_mfma_f32_16x16x32_bf16 v[128:131], v[204:207], v[28:31], v[68:71]
	v_mfma_f32_16x16x32_bf16 v[68:71], v[212:215], v[236:239], v[20:23]
	s_nop 0
	s_barrier
	ds_read_b128 v[40:43], v139 offset:49152
	ds_read_b128 v[48:51], v139 offset:50176
	ds_read_b128 v[216:219], v139 offset:51200
	ds_read_b128 v[220:223], v139 offset:52224
	ds_read_b128 v[224:227], v139 offset:53248
	ds_read_b128 v[228:231], v139 offset:54272
	ds_read_b128 v[232:235], v139 offset:55296
	ds_read_b128 v[236:239], v139 offset:56320
	s_add_u32 s6, s18, 0x180
	s_addc_u32 s7, s19, 0
	s_mov_b32 m0, s53
	s_nop 0
	global_load_lds_dwordx4 v133, s[6:7]
	s_nop 0
	s_mov_b32 m0, s57
	s_nop 0
	global_load_lds_dwordx4 v135, s[6:7]
	s_add_u32 s6, s18, 0x80180
	s_addc_u32 s7, s19, 0
	s_mov_b32 m0, s67
	s_nop 0
	global_load_lds_dwordx4 v133, s[6:7]
	s_nop 0
	s_mov_b32 m0, s69
	s_nop 0
	global_load_lds_dwordx4 v135, s[6:7]
	s_nop 0
	s_mov_b32 m0, s63
	s_nop 0
	global_load_lds_dwordx4 v132, s[20:21]
	s_nop 0
	s_mov_b32 m0, s64
	s_nop 0
	global_load_lds_dwordx4 v134, s[20:21]
	s_waitcnt vmcnt(8)
	s_waitcnt lgkmcnt(0)
	s_barrier
	s_nop 0
	s_waitcnt lgkmcnt(7)
	v_mfma_f32_16x16x32_bf16 v[20:23], v[12:15], v[40:43], v[142:145]
	s_waitcnt lgkmcnt(6)
	v_mfma_f32_16x16x32_bf16 v[64:67], v[24:27], v[48:51], v[20:23]
	v_mfma_f32_16x16x32_bf16 v[20:23], v[32:35], v[40:43], v[146:149]
	v_mfma_f32_16x16x32_bf16 v[52:55], v[196:199], v[48:51], v[20:23]
	s_waitcnt lgkmcnt(5)
	v_mfma_f32_16x16x32_bf16 v[20:23], v[12:15], v[216:219], v[150:153]
	s_waitcnt lgkmcnt(4)
	v_mfma_f32_16x16x32_bf16 v[44:47], v[24:27], v[220:223], v[20:23]
	v_mfma_f32_16x16x32_bf16 v[20:23], v[32:35], v[216:219], v[154:157]
	v_mfma_f32_16x16x32_bf16 v[36:39], v[196:199], v[220:223], v[20:23]
	s_waitcnt lgkmcnt(3)
	v_mfma_f32_16x16x32_bf16 v[20:23], v[12:15], v[224:227], v[158:161]
	s_waitcnt lgkmcnt(1)
	v_mfma_f32_16x16x32_bf16 v[2:5], v[12:15], v[232:235], v[4:7]
	v_mfma_f32_16x16x32_bf16 v[28:31], v[24:27], v[228:231], v[20:23]
	v_mfma_f32_16x16x32_bf16 v[20:23], v[32:35], v[224:227], v[162:165]
	s_waitcnt lgkmcnt(0)
	v_mfma_f32_16x16x32_bf16 v[12:15], v[24:27], v[236:239], v[2:5]
	v_mfma_f32_16x16x32_bf16 v[2:5], v[32:35], v[232:235], v[8:11]
	v_mfma_f32_16x16x32_bf16 v[20:23], v[196:199], v[228:231], v[20:23]
	v_mfma_f32_16x16x32_bf16 v[4:7], v[196:199], v[236:239], v[2:5]
	s_nop 0
	s_nop 0
	v_mfma_f32_16x16x32_bf16 v[8:11], v[200:203], v[40:43], v[16:19]
	v_mfma_f32_16x16x32_bf16 v[72:75], v[204:207], v[48:51], v[8:11]
	v_mfma_f32_16x16x32_bf16 v[8:11], v[208:211], v[40:43], v[166:169]
	v_mfma_f32_16x16x32_bf16 v[56:59], v[212:215], v[48:51], v[8:11]
	v_mfma_f32_16x16x32_bf16 v[8:11], v[200:203], v[216:219], v[170:173]
	v_mfma_f32_16x16x32_bf16 v[48:51], v[204:207], v[220:223], v[8:11]
	v_mfma_f32_16x16x32_bf16 v[8:11], v[208:211], v[216:219], v[174:177]
	v_mfma_f32_16x16x32_bf16 v[40:43], v[212:215], v[220:223], v[8:11]
	v_mfma_f32_16x16x32_bf16 v[8:11], v[200:203], v[224:227], v[178:181]
	v_mfma_f32_16x16x32_bf16 v[32:35], v[204:207], v[228:231], v[8:11]
	v_mfma_f32_16x16x32_bf16 v[8:11], v[208:211], v[224:227], v[184:187]
	v_mfma_f32_16x16x32_bf16 v[24:27], v[212:215], v[228:231], v[8:11]
	v_mfma_f32_16x16x32_bf16 v[8:11], v[200:203], v[232:235], v[188:191]
	v_mfma_f32_16x16x32_bf16 v[16:19], v[204:207], v[236:239], v[8:11]
	v_mfma_f32_16x16x32_bf16 v[8:11], v[208:211], v[232:235], v[192:195]
	v_mfma_f32_16x16x32_bf16 v[8:11], v[212:215], v[236:239], v[8:11]
	s_nop 0
	s_barrier
	s_mov_b64 s[22:23], 0

.LBB0_1119:
	v_add_u32_e32 v0, 0x10000, v138
	v_add_u32_e32 v2, 0x14000, v138
	ds_read_b128 v[140:143], v0
	ds_read_b128 v[144:147], v0 offset:1024
	ds_read_b128 v[148:151], v0 offset:2048
	ds_read_b128 v[152:155], v0 offset:3072
	ds_read_b128 v[156:159], v2
	ds_read_b128 v[160:163], v2 offset:1024
	ds_read_b128 v[164:167], v2 offset:2048
	ds_read_b128 v[168:171], v2 offset:3072
	s_add_u32 s28, s26, 0xfff80080
	s_addc_u32 s29, s27, -1
	s_cmp_eq_u32 s23, 28
	s_cselect_b32 s34, s7, s28
	s_cselect_b32 s35, s6, s29
	s_cselect_b32 s30, s15, s82
	s_cselect_b32 s31, s13, s83
	s_add_u32 s28, s34, 0x80
	s_addc_u32 s29, s35, 0
	ds_read_b128 v[172:175], v139
	ds_read_b128 v[176:179], v139 offset:1024
	ds_read_b128 v[184:187], v139 offset:2048
	ds_read_b128 v[188:191], v139 offset:3072
	ds_read_b128 v[192:195], v139 offset:4096
	ds_read_b128 v[196:199], v139 offset:5120
	ds_read_b128 v[200:203], v139 offset:6144
	ds_read_b128 v[204:207], v139 offset:7168
	s_mov_b32 m0, s77
	s_nop 0
	global_load_lds_dwordx4 v132, s[26:27]
	s_nop 0
	s_mov_b32 m0, s78
	s_nop 0
	global_load_lds_dwordx4 v134, s[26:27]
	s_waitcnt vmcnt(8)
	s_waitcnt lgkmcnt(0)
	s_barrier
	s_nop 0
	s_waitcnt lgkmcnt(7)
	v_mfma_f32_16x16x32_bf16 v[124:127], v[140:143], v[172:175], v[124:127]
	v_mfma_f32_16x16x32_bf16 v[116:119], v[148:151], v[172:175], v[116:119]
	s_waitcnt lgkmcnt(5)
	v_mfma_f32_16x16x32_bf16 v[108:111], v[140:143], v[184:187], v[108:111]
	v_mfma_f32_16x16x32_bf16 v[100:103], v[148:151], v[184:187], v[100:103]
	s_waitcnt lgkmcnt(3)
	v_mfma_f32_16x16x32_bf16 v[92:95], v[140:143], v[192:195], v[92:95]
	v_mfma_f32_16x16x32_bf16 v[84:87], v[148:151], v[192:195], v[84:87]
	s_waitcnt lgkmcnt(1)
	v_mfma_f32_16x16x32_bf16 v[76:79], v[140:143], v[200:203], v[76:79]
	v_mfma_f32_16x16x32_bf16 v[60:63], v[148:151], v[200:203], v[60:63]
	v_mfma_f32_16x16x32_bf16 v[124:127], v[144:147], v[176:179], v[124:127]
	v_mfma_f32_16x16x32_bf16 v[116:119], v[152:155], v[176:179], v[116:119]
	v_mfma_f32_16x16x32_bf16 v[108:111], v[144:147], v[188:191], v[108:111]
	v_mfma_f32_16x16x32_bf16 v[100:103], v[152:155], v[188:191], v[100:103]
	v_mfma_f32_16x16x32_bf16 v[92:95], v[144:147], v[196:199], v[92:95]
	v_mfma_f32_16x16x32_bf16 v[84:87], v[152:155], v[196:199], v[84:87]
	s_waitcnt lgkmcnt(0)
	v_mfma_f32_16x16x32_bf16 v[76:79], v[144:147], v[204:207], v[76:79]
	v_mfma_f32_16x16x32_bf16 v[60:63], v[152:155], v[204:207], v[60:63]
	s_nop 0
	s_nop 0
	v_mfma_f32_16x16x32_bf16 v[128:131], v[156:159], v[172:175], v[128:131]
	v_mfma_f32_16x16x32_bf16 v[120:123], v[164:167], v[172:175], v[120:123]
	v_mfma_f32_16x16x32_bf16 v[112:115], v[156:159], v[184:187], v[112:115]
	v_mfma_f32_16x16x32_bf16 v[104:107], v[164:167], v[184:187], v[104:107]
	v_mfma_f32_16x16x32_bf16 v[96:99], v[156:159], v[192:195], v[96:99]
	v_mfma_f32_16x16x32_bf16 v[88:91], v[164:167], v[192:195], v[88:91]
	v_mfma_f32_16x16x32_bf16 v[80:83], v[156:159], v[200:203], v[80:83]
	v_mfma_f32_16x16x32_bf16 v[68:71], v[164:167], v[200:203], v[68:71]
	v_mfma_f32_16x16x32_bf16 v[128:131], v[160:163], v[176:179], v[128:131]
	v_mfma_f32_16x16x32_bf16 v[120:123], v[168:171], v[176:179], v[120:123]
	v_mfma_f32_16x16x32_bf16 v[112:115], v[160:163], v[188:191], v[112:115]
	v_mfma_f32_16x16x32_bf16 v[104:107], v[168:171], v[188:191], v[104:107]
	v_mfma_f32_16x16x32_bf16 v[96:99], v[160:163], v[196:199], v[96:99]
	v_mfma_f32_16x16x32_bf16 v[88:91], v[168:171], v[196:199], v[88:91]
	v_mfma_f32_16x16x32_bf16 v[80:83], v[160:163], v[204:207], v[80:83]
	v_mfma_f32_16x16x32_bf16 v[68:71], v[168:171], v[204:207], v[68:71]
	s_nop 0
	s_barrier
	ds_read_b128 v[172:175], v139 offset:16384
	ds_read_b128 v[176:179], v139 offset:17408
	ds_read_b128 v[184:187], v139 offset:18432
	ds_read_b128 v[188:191], v139 offset:19456
	ds_read_b128 v[192:195], v139 offset:20480
	ds_read_b128 v[196:199], v139 offset:21504
	ds_read_b128 v[200:203], v139 offset:22528
	ds_read_b128 v[204:207], v139 offset:23552
	s_mov_b32 m0, s41
	s_nop 0
	global_load_lds_dwordx4 v133, s[30:31]
	s_add_u32 s88, s30, 0x80000
	s_mov_b32 m0, s44
	s_nop 0
	global_load_lds_dwordx4 v135, s[30:31]
	s_addc_u32 s89, s31, 0
	s_mov_b32 m0, s47
	s_nop 0
	global_load_lds_dwordx4 v133, s[88:89]
	s_nop 0
	s_mov_b32 m0, s48
	s_nop 0
	global_load_lds_dwordx4 v135, s[88:89]
	s_nop 0
	s_mov_b32 m0, s25
	s_nop 0
	global_load_lds_dwordx4 v132, s[34:35]
	s_nop 0
	s_mov_b32 m0, s49
	s_nop 0
	global_load_lds_dwordx4 v134, s[34:35]
	s_waitcnt vmcnt(8)
	s_waitcnt lgkmcnt(0)
	s_barrier
;     __host__ __device__ bool next(int i, Unit& u) const { return StaticOrder::next(i >> 1, u); }
;     __device__ __forceinline__ bool next(int i, Unit& u) const { const int s = i * G + c; if (s >= 128) return false; const int t = s >> 2; u.pm = pm0 + (t & 3); u.pn = t >> 2; u.k0 = (s & 3) * ksub; return true; }
; #define PG8_WAIT_V(n) asm volatile("s_waitcnt vmcnt(" #n ")" ::: "memory")
; template <class Epi, class Sched, bool ALIGN_EPI = false, bool SP2 = false>
; __device__ __forceinline__ void gemm_phase(PG8_LAS unsigned char* lds, const Gemm g, const Sched& S, const Epi& E) {
;     ...
;     for (;;) {
;         const bool has_next = S.next(ui + 1, nxt);
;         const char* nA = has_next ? (const char*)g.A + (size_t)nxt.pm * tsA + (size_t)nxt.k0 * 2 : cA; const char* nB = has_next ? (const char*)g.Bt + (size_t)nxt.pn * tsB + (size_t)nxt.k0 * 2 : cB;
;         for (int t = (DRO && ui > 0) ? 2 : 0; t < nt; t += 2) {
;             const bool last = (t == nt - 2);
;             const char* a1 = cA + (size_t)(t + 1) * kstep;
;             const char* a2 = last ? nA : cA + (size_t)(t + 2) * kstep; const char* b2 = last ? nB : cB + (size_t)(t + 2) * kstep;
;             const char* a3 = a2 + kstep; const char* b3 = b2 + kstep;
;             if (last && has_next) S.a_ready(nxt);
;             if constexpr (SP2) {
;             PG8_TRIP(true, PG8_WAIT_V(8));
	s_nop 0
	s_waitcnt lgkmcnt(7)
	v_mfma_f32_16x16x32_bf16 v[64:67], v[140:143], v[172:175], v[64:67]
	v_mfma_f32_16x16x32_bf16 v[52:55], v[148:151], v[172:175], v[52:55]
	s_waitcnt lgkmcnt(5)
	v_mfma_f32_16x16x32_bf16 v[44:47], v[140:143], v[184:187], v[44:47]
	v_mfma_f32_16x16x32_bf16 v[36:39], v[148:151], v[184:187], v[36:39]
	s_waitcnt lgkmcnt(3)
	v_mfma_f32_16x16x32_bf16 v[28:31], v[140:143], v[192:195], v[28:31]
	v_mfma_f32_16x16x32_bf16 v[20:23], v[148:151], v[192:195], v[20:23]
	s_waitcnt lgkmcnt(1)
	v_mfma_f32_16x16x32_bf16 v[12:15], v[140:143], v[200:203], v[12:15]
	v_mfma_f32_16x16x32_bf16 v[4:7], v[148:151], v[200:203], v[4:7]
	v_mfma_f32_16x16x32_bf16 v[64:67], v[144:147], v[176:179], v[64:67]
	v_mfma_f32_16x16x32_bf16 v[52:55], v[152:155], v[176:179], v[52:55]
	v_mfma_f32_16x16x32_bf16 v[44:47], v[144:147], v[188:191], v[44:47]
	v_mfma_f32_16x16x32_bf16 v[36:39], v[152:155], v[188:191], v[36:39]
	v_mfma_f32_16x16x32_bf16 v[28:31], v[144:147], v[196:199], v[28:31]
	v_mfma_f32_16x16x32_bf16 v[20:23], v[152:155], v[196:199], v[20:23]
	s_waitcnt lgkmcnt(0)
	v_mfma_f32_16x16x32_bf16 v[12:15], v[144:147], v[204:207], v[12:15]
	v_mfma_f32_16x16x32_bf16 v[4:7], v[152:155], v[204:207], v[4:7]
	s_nop 0
	s_nop 0
	v_mfma_f32_16x16x32_bf16 v[72:75], v[156:159], v[172:175], v[72:75]
	v_mfma_f32_16x16x32_bf16 v[56:59], v[164:167], v[172:175], v[56:59]
	v_mfma_f32_16x16x32_bf16 v[48:51], v[156:159], v[184:187], v[48:51]
	v_mfma_f32_16x16x32_bf16 v[40:43], v[164:167], v[184:187], v[40:43]
	v_mfma_f32_16x16x32_bf16 v[32:35], v[156:159], v[192:195], v[32:35]
	v_mfma_f32_16x16x32_bf16 v[24:27], v[164:167], v[192:195], v[24:27]
	v_mfma_f32_16x16x32_bf16 v[16:19], v[156:159], v[200:203], v[16:19]
	v_mfma_f32_16x16x32_bf16 v[8:11], v[164:167], v[200:203], v[8:11]
	v_mfma_f32_16x16x32_bf16 v[72:75], v[160:163], v[176:179], v[72:75]
	v_mfma_f32_16x16x32_bf16 v[56:59], v[168:171], v[176:179], v[56:59]
	v_mfma_f32_16x16x32_bf16 v[48:51], v[160:163], v[188:191], v[48:51]
	v_mfma_f32_16x16x32_bf16 v[40:43], v[168:171], v[188:191], v[40:43]
	v_mfma_f32_16x16x32_bf16 v[32:35], v[160:163], v[196:199], v[32:35]
	v_mfma_f32_16x16x32_bf16 v[24:27], v[168:171], v[196:199], v[24:27]
	v_mfma_f32_16x16x32_bf16 v[16:19], v[160:163], v[204:207], v[16:19]
	v_mfma_f32_16x16x32_bf16 v[8:11], v[168:171], v[204:207], v[8:11]
	s_nop 0
	s_barrier
	v_add_u32_e32 v3, 0x18000, v138
	v_add_u32_e32 v140, 0x1c000, v138
	ds_read_b128 v[142:145], v3
	ds_read_b128 v[146:149], v3 offset:1024
	ds_read_b128 v[150:153], v3 offset:2048
	ds_read_b128 v[154:157], v3 offset:3072
	ds_read_b128 v[158:161], v140
	ds_read_b128 v[162:165], v140 offset:1024
	ds_read_b128 v[166:169], v140 offset:2048
	ds_read_b128 v[170:173], v140 offset:3072
	ds_read_b128 v[174:177], v139 offset:32768
	ds_read_b128 v[178:181], v139 offset:33792
	ds_read_b128 v[184:187], v139 offset:34816
	ds_read_b128 v[188:191], v139 offset:35840
	ds_read_b128 v[192:195], v139 offset:36864
	ds_read_b128 v[196:199], v139 offset:37888
	ds_read_b128 v[200:203], v139 offset:38912
	ds_read_b128 v[204:207], v139 offset:39936
	s_add_u32 s34, s34, 0x80000
	s_addc_u32 s35, s35, 0
	s_mov_b32 m0, s51
	s_nop 0
	global_load_lds_dwordx4 v132, s[34:35]
	s_nop 0
	s_mov_b32 m0, s52
	s_nop 0
	global_load_lds_dwordx4 v134, s[34:35]
	s_waitcnt vmcnt(8)
	s_waitcnt lgkmcnt(0)
	s_barrier
	s_nop 0
	s_waitcnt lgkmcnt(7)
	v_mfma_f32_16x16x32_bf16 v[124:127], v[142:145], v[174:177], v[124:127]
	v_mfma_f32_16x16x32_bf16 v[116:119], v[150:153], v[174:177], v[116:119]
	s_waitcnt lgkmcnt(5)
	v_mfma_f32_16x16x32_bf16 v[108:111], v[142:145], v[184:187], v[108:111]
	v_mfma_f32_16x16x32_bf16 v[100:103], v[150:153], v[184:187], v[100:103]
	s_waitcnt lgkmcnt(3)
	v_mfma_f32_16x16x32_bf16 v[92:95], v[142:145], v[192:195], v[92:95]
	v_mfma_f32_16x16x32_bf16 v[84:87], v[150:153], v[192:195], v[84:87]
	s_waitcnt lgkmcnt(1)
	v_mfma_f32_16x16x32_bf16 v[76:79], v[142:145], v[200:203], v[76:79]
	v_mfma_f32_16x16x32_bf16 v[60:63], v[150:153], v[200:203], v[60:63]
	v_mfma_f32_16x16x32_bf16 v[124:127], v[146:149], v[178:181], v[124:127]
	v_mfma_f32_16x16x32_bf16 v[116:119], v[154:157], v[178:181], v[116:119]
	v_mfma_f32_16x16x32_bf16 v[108:111], v[146:149], v[188:191], v[108:111]
	v_mfma_f32_16x16x32_bf16 v[100:103], v[154:157], v[188:191], v[100:103]
	v_mfma_f32_16x16x32_bf16 v[92:95], v[146:149], v[196:199], v[92:95]
	v_mfma_f32_16x16x32_bf16 v[84:87], v[154:157], v[196:199], v[84:87]
	s_waitcnt lgkmcnt(0)
	v_mfma_f32_16x16x32_bf16 v[76:79], v[146:149], v[204:207], v[76:79]
	v_mfma_f32_16x16x32_bf16 v[60:63], v[154:157], v[204:207], v[60:63]
	s_nop 0
	s_nop 0
	v_mfma_f32_16x16x32_bf16 v[128:131], v[158:161], v[174:177], v[128:131]
	v_mfma_f32_16x16x32_bf16 v[120:123], v[166:169], v[174:177], v[120:123]
	v_mfma_f32_16x16x32_bf16 v[112:115], v[158:161], v[184:187], v[112:115]
	v_mfma_f32_16x16x32_bf16 v[104:107], v[166:169], v[184:187], v[104:107]
	v_mfma_f32_16x16x32_bf16 v[96:99], v[158:161], v[192:195], v[96:99]
	v_mfma_f32_16x16x32_bf16 v[88:91], v[166:169], v[192:195], v[88:91]
	v_mfma_f32_16x16x32_bf16 v[80:83], v[158:161], v[200:203], v[80:83]
	v_mfma_f32_16x16x32_bf16 v[68:71], v[166:169], v[200:203], v[68:71]
	v_mfma_f32_16x16x32_bf16 v[128:131], v[162:165], v[178:181], v[128:131]
	v_mfma_f32_16x16x32_bf16 v[120:123], v[170:173], v[178:181], v[120:123]
	v_mfma_f32_16x16x32_bf16 v[112:115], v[162:165], v[188:191], v[112:115]
	v_mfma_f32_16x16x32_bf16 v[104:107], v[170:173], v[188:191], v[104:107]
	v_mfma_f32_16x16x32_bf16 v[96:99], v[162:165], v[196:199], v[96:99]
	v_mfma_f32_16x16x32_bf16 v[88:91], v[170:173], v[196:199], v[88:91]
	v_mfma_f32_16x16x32_bf16 v[80:83], v[162:165], v[204:207], v[80:83]
	v_mfma_f32_16x16x32_bf16 v[68:71], v[170:173], v[204:207], v[68:71]
	s_nop 0
	s_barrier
;     __host__ __device__ bool next(int i, Unit& u) const { return StaticOrder::next(i >> 1, u); }
; template <class Epi, class Sched, bool ALIGN_EPI = false, bool SP2 = false>
; __device__ __forceinline__ void gemm_phase(PG8_LAS unsigned char* lds, const Gemm g, const Sched& S, const Epi& E) {
;     ...
;     for (;;) {
;         const bool has_next = S.next(ui + 1, nxt);
;         const char* nA = has_next ? (const char*)g.A + (size_t)nxt.pm * tsA + (size_t)nxt.k0 * 2 : cA; const char* nB = has_next ? (const char*)g.Bt + (size_t)nxt.pn * tsB + (size_t)nxt.k0 * 2 : cB;
;         for (int t = (DRO && ui > 0) ? 2 : 0; t < nt; t += 2) {
;             const bool last = (t == nt - 2);
;             const char* a1 = cA + (size_t)(t + 1) * kstep;
;             const char* a2 = last ? nA : cA + (size_t)(t + 2) * kstep; const char* b2 = last ? nB : cB + (size_t)(t + 2) * kstep;
;             const char* a3 = a2 + kstep; const char* b3 = b2 + kstep;
;             if (last && has_next) S.a_ready(nxt);
;             if constexpr (SP2) {
;             PG8_TRIP(true, PG8_WAIT_V(8));
;             } else {
;             PG8_LDB(B0, 0, 0); PG8_SCHED; PG8_LDA(At, 0, 0); PG8_STAGE(PG8_SA(1, 1), a1 + hsA, voffA);
;             PG8_WAIT_L(8); PG8_BAR; PG8_WAIT_L(0); PG8_MMA(0, 0, At, B0); PG8_BAR; PG8_SCHED;
;             PG8_LDB(B1, 0, 1); PG8_STAGE(PG8_SB(0, 0), b2, voffB);
;             PG8_BAR; PG8_WAIT_L(0); PG8_MMA(0, 1, At, B1); PG8_BAR;
;             PG8_LDA(At, 0, 1); PG8_STAGE(PG8_SA(0, 0), a2, voffA);
;             PG8_BAR; PG8_WAIT_L(0); PG8_MMA(1, 0, At, B0); PG8_BAR; PG8_SCHED;
;             PG8_STAGE(PG8_SB(0, 1), b2 + hsB, voffB);
;             PG8_WAIT_V(6); PG8_BAR; PG8_MMA(1, 1, At, B1); PG8_BAR;
;             PG8_LDB(B0, 1, 0); PG8_SCHED; PG8_LDA(At, 1, 0); PG8_STAGE(PG8_SA(0, 1), a2 + hsA, voffA);
;             PG8_WAIT_L(8); PG8_BAR; PG8_WAIT_L(0); PG8_MMA(0, 0, At, B0); PG8_BAR; PG8_SCHED;
;             PG8_LDB(B1, 1, 1); PG8_STAGE(PG8_SB(1, 0), b3, voffB);
;             PG8_BAR; PG8_WAIT_L(0); PG8_MMA(0, 1, At, B1); PG8_BAR;
;             PG8_LDA(At, 1, 1); PG8_STAGE(PG8_SA(1, 0), a3, voffA);
;             PG8_BAR; PG8_WAIT_L(0); PG8_MMA(1, 0, At, B0); PG8_BAR; PG8_SCHED;
;             PG8_STAGE(PG8_SB(1, 1), b3 + hsB, voffB);
;             PG8_WAIT_V(6); PG8_BAR; PG8_MMA(1, 1, At, B1); PG8_BAR;
;             }
;         }
	ds_read_b128 v[174:177], v139 offset:49152
	ds_read_b128 v[178:181], v139 offset:50176
	ds_read_b128 v[184:187], v139 offset:51200
	ds_read_b128 v[188:191], v139 offset:52224
	ds_read_b128 v[192:195], v139 offset:53248
	ds_read_b128 v[196:199], v139 offset:54272
	ds_read_b128 v[200:203], v139 offset:55296
	ds_read_b128 v[204:207], v139 offset:56320
	s_add_u32 s34, s30, 0x80
	s_addc_u32 s35, s31, 0
	s_mov_b32 m0, s53
	s_nop 0
	global_load_lds_dwordx4 v133, s[34:35]
	s_add_u32 s30, s30, 0x80080
	s_mov_b32 m0, s57
	s_nop 0
	global_load_lds_dwordx4 v135, s[34:35]
	s_addc_u32 s31, s31, 0
	s_mov_b32 m0, s67
	s_nop 0
	global_load_lds_dwordx4 v133, s[30:31]
	s_nop 0
	s_mov_b32 m0, s69
	s_nop 0
	global_load_lds_dwordx4 v135, s[30:31]
	s_nop 0
	s_mov_b32 m0, s63
	s_nop 0
	global_load_lds_dwordx4 v132, s[28:29]
	s_nop 0
	s_mov_b32 m0, s64
	s_nop 0
	global_load_lds_dwordx4 v134, s[28:29]
	s_waitcnt vmcnt(8)
	s_waitcnt lgkmcnt(0)
	s_barrier
	s_nop 0
	s_waitcnt lgkmcnt(7)
	v_mfma_f32_16x16x32_bf16 v[64:67], v[142:145], v[174:177], v[64:67]
	v_mfma_f32_16x16x32_bf16 v[52:55], v[150:153], v[174:177], v[52:55]
	s_waitcnt lgkmcnt(5)
	v_mfma_f32_16x16x32_bf16 v[44:47], v[142:145], v[184:187], v[44:47]
	v_mfma_f32_16x16x32_bf16 v[36:39], v[150:153], v[184:187], v[36:39]
	s_waitcnt lgkmcnt(3)
	v_mfma_f32_16x16x32_bf16 v[28:31], v[142:145], v[192:195], v[28:31]
	v_mfma_f32_16x16x32_bf16 v[20:23], v[150:153], v[192:195], v[20:23]
	s_waitcnt lgkmcnt(1)
	v_mfma_f32_16x16x32_bf16 v[12:15], v[142:145], v[200:203], v[12:15]
	v_mfma_f32_16x16x32_bf16 v[4:7], v[150:153], v[200:203], v[4:7]
	v_mfma_f32_16x16x32_bf16 v[64:67], v[146:149], v[178:181], v[64:67]
	v_mfma_f32_16x16x32_bf16 v[52:55], v[154:157], v[178:181], v[52:55]
	v_mfma_f32_16x16x32_bf16 v[44:47], v[146:149], v[188:191], v[44:47]
	v_mfma_f32_16x16x32_bf16 v[36:39], v[154:157], v[188:191], v[36:39]
	v_mfma_f32_16x16x32_bf16 v[28:31], v[146:149], v[196:199], v[28:31]
	v_mfma_f32_16x16x32_bf16 v[20:23], v[154:157], v[196:199], v[20:23]
	s_waitcnt lgkmcnt(0)
	v_mfma_f32_16x16x32_bf16 v[12:15], v[146:149], v[204:207], v[12:15]
	v_mfma_f32_16x16x32_bf16 v[4:7], v[154:157], v[204:207], v[4:7]
	s_nop 0
	s_nop 0
	v_mfma_f32_16x16x32_bf16 v[72:75], v[158:161], v[174:177], v[72:75]
	v_mfma_f32_16x16x32_bf16 v[56:59], v[166:169], v[174:177], v[56:59]
	v_mfma_f32_16x16x32_bf16 v[48:51], v[158:161], v[184:187], v[48:51]
	v_mfma_f32_16x16x32_bf16 v[40:43], v[166:169], v[184:187], v[40:43]
	v_mfma_f32_16x16x32_bf16 v[32:35], v[158:161], v[192:195], v[32:35]
	v_mfma_f32_16x16x32_bf16 v[24:27], v[166:169], v[192:195], v[24:27]
	v_mfma_f32_16x16x32_bf16 v[16:19], v[158:161], v[200:203], v[16:19]
	v_mfma_f32_16x16x32_bf16 v[8:11], v[166:169], v[200:203], v[8:11]
	v_mfma_f32_16x16x32_bf16 v[72:75], v[162:165], v[178:181], v[72:75]
	v_mfma_f32_16x16x32_bf16 v[56:59], v[170:173], v[178:181], v[56:59]
	v_mfma_f32_16x16x32_bf16 v[48:51], v[162:165], v[188:191], v[48:51]
	v_mfma_f32_16x16x32_bf16 v[40:43], v[170:173], v[188:191], v[40:43]
	v_mfma_f32_16x16x32_bf16 v[32:35], v[162:165], v[196:199], v[32:35]
	v_mfma_f32_16x16x32_bf16 v[24:27], v[170:173], v[196:199], v[24:27]
	v_mfma_f32_16x16x32_bf16 v[16:19], v[162:165], v[204:207], v[16:19]
	v_mfma_f32_16x16x32_bf16 v[8:11], v[170:173], v[204:207], v[8:11]
	s_nop 0
	s_barrier
	s_add_i32 s23, s23, 2
	s_add_u32 s82, s82, 0x100
	s_addc_u32 s83, s83, 0
	s_add_u32 s26, s26, 0x100
	s_addc_u32 s27, s27, 0
	s_cmp_gt_u32 s23, 29
	s_cbranch_scc0 .LBB0_1119
	s_add_u32 s26, s7, 0x80080
	s_addc_u32 s27, s6, 0
	s_mov_b32 m0, s77
	s_nop 0
	global_load_lds_dwordx4 v132, s[26:27]
	s_and_b64 vcc, exec, s[10:11]
	s_mov_b32 m0, s78
	s_nop 0
	global_load_lds_dwordx4 v134, s[26:27]
	s_mov_b32 s83, 0x80000
	s_cbranch_vccz .LBB0_1122
	s_barrier

; __device__ __forceinline__ int mk_tid() { return mk_wave() * 64 + mk_lane(); }
;     __host__ __device__ bool next(int i, Unit& u) const { return StaticOrder::next(i >> 1, u); }
; template <class Epi, class Sched, bool ALIGN_EPI = false, bool SP2 = false>
; __device__ __forceinline__ void gemm_phase(PG8_LAS unsigned char* lds, const Gemm g, const Sched& S, const Epi& E) {
;     int tid_ = mk_tid(); asm volatile("" : "+v"(tid_));
;     const int tid = tid_, wid = __builtin_amdgcn_readfirstlane(tid >> 6), lane = tid & 63, wr = wid >> 2, wc = wid & 3, fr = lane & 15, fq = lane >> 4;
;     const int K = g.K, nt = K / BK;
;     unsigned voffA[2], voffB[2];
; #pragma unroll
;     for (int i = 0; i < 2; ++i) { int R, C; stage_rc(tid * 16 + i * 8192, R, C); const int Rb = Epi::PERM ? ((R & ~31) + perm32(R & 31)) : R;
;         voffA[i] = (unsigned)(R * g.lda + C) * 2u; voffB[i] = (unsigned)(Rb * g.ldb + C) * 2u; }
;     const size_t kstep = (size_t)(BK * 2);
;     const size_t hsA = (size_t)HALF * g.lda * 2, hsB = (size_t)HALF * g.ldb * 2;
;     const size_t tsA = 2 * hsA, tsB = 2 * hsB;
;     const unsigned ldsbase = (unsigned)(unsigned long long)lds;
;     const unsigned ldsw = (unsigned)wid * 1024u;
;     const int aoff = lds_byte(wr * 64 + fr, fq * 8), boff = lds_byte(wc * 32 + fr, fq * 8);
;     ...
;     Unit cur, nxt; int ui = 0; bool epi_ran = false;
;     if (!S.next(0, cur)) return;
;     f32x4 acc[2][2][4][2];
; #pragma unroll
;     for (int a = 0; a < 2; ++a)
; #pragma unroll
;         for (int b = 0; b < 2; ++b)
; #pragma unroll
;             for (int m = 0; m < 4; ++m)
; #pragma unroll
;                 for (int n = 0; n < 2; ++n) acc[a][b][m][n] = (f32x4){0.f, 0.f, 0.f, 0.f};
;     bf16x8 At[4][2], B0[2][2], B1[2][2];
;     const char* cA = (const char*)g.A + (size_t)cur.pm * tsA + (size_t)cur.k0 * 2; const char* cB = (const char*)g.Bt + (size_t)cur.pn * tsB + (size_t)cur.k0 * 2;
;     S.a_ready(cur);
;     if constexpr (SP2) {
;         PG8_STAGE(PG8_SB(0, 0), cB, voffB); PG8_STAGE(PG8_SB(0, 1), cB + hsB, voffB); PG8_STAGE(PG8_SA(0, 0), cA, voffA); PG8_STAGE(PG8_SA(0, 1), cA + hsA, voffA);
;         if (wr == 1) PG8_BAR;
;         PG8_WAIT_V(2); PG8_BAR;
;         PG8_STAGE(PG8_SB(1, 0), cB + kstep, voffB); PG8_STAGE(PG8_SA(1, 0), cA + kstep, voffA); PG8_STAGE(PG8_SB(1, 1), cB + hsB + kstep, voffB);
;         PG8_WAIT_V(6); PG8_BAR;
.LBB0_1208:
	s_add_u32 s31, s86, 0xa000
	v_lshrrev_b32_e32 v3, 1, v0
	s_addc_u32 s33, s87, 0
	v_and_b32_e32 v3, 24, v3
	s_lshl_b32 s6, s6, 5
	v_and_b32_e32 v2, 15, v0
	v_lshlrev_b32_e32 v4, 1, v3
	v_lshlrev_b32_e32 v0, 2, v0
	s_and_b32 s8, s6, 0x60
	v_lshl_or_b32 v184, s7, 6, v2
	v_lshl_or_b32 v2, v2, 6, v4
	s_lshl_b32 s7, s7, 13
	v_and_b32_e32 v0, 32, v0
	s_lshl_b32 s6, s8, 7
	s_add_i32 s34, s21, 0x18000
	v_bitop3_b32 v5, v2, s6, v0 bitop3:0xde
	s_add_u32 s6, s12, 0x80
	v_bitop3_b32 v4, v2, s7, v0 bitop3:0xde
	s_waitcnt vmcnt(2)
	s_barrier
	s_addc_u32 s7, s13, 0
	s_mov_b32 m0, s34
	s_nop 0
	global_load_lds_dwordx4 v175, s[6:7]
	s_add_i32 s35, s21, 0x1a000
	s_add_i32 s36, s21, 0x8000
	s_mov_b32 m0, s35
	s_nop 0
	global_load_lds_dwordx4 v177, s[6:7]
	s_add_u32 s6, s14, 0x80
	s_addc_u32 s7, s15, 0
	s_mov_b32 m0, s36
	s_nop 0
	global_load_lds_dwordx4 v174, s[6:7]
	s_add_i32 s37, s21, 0xa000
	s_add_i32 s40, s21, 0x1c000
	s_mov_b32 m0, s37
	s_nop 0
	global_load_lds_dwordx4 v176, s[6:7]
	s_add_u32 s6, s12, 0x160080
	s_addc_u32 s7, s13, 0
	s_mov_b32 m0, s40
	s_nop 0
	global_load_lds_dwordx4 v175, s[6:7]
	s_add_i32 s41, s21, 0x1e000
	s_mov_b32 m0, s41
	s_nop 0
	global_load_lds_dwordx4 v177, s[6:7]
	v_readlane_b32 s6, v255, 8
	s_waitcnt vmcnt(6)
	v_or_b32_e32 v185, s8, v3
	v_mov_b32_e32 v2, v1
	v_mov_b32_e32 v3, v1
	v_readlane_b32 s7, v255, 9
	v_mov_b32_e32 v0, v1
	v_add_u32_e32 v186, 0, v5
	v_add_u32_e32 v187, 0, v4
	v_mov_b64_e32 v[6:7], v[2:3]
	v_mov_b64_e32 v[10:11], v[2:3]
	v_mov_b64_e32 v[22:23], v[2:3]
	v_mov_b64_e32 v[26:27], v[2:3]
	v_mov_b64_e32 v[38:39], v[2:3]
	v_mov_b64_e32 v[42:43], v[2:3]
	v_mov_b64_e32 v[54:55], v[2:3]
	v_mov_b64_e32 v[58:59], v[2:3]
	v_mov_b64_e32 v[14:15], v[2:3]
	v_mov_b64_e32 v[18:19], v[2:3]
	v_mov_b64_e32 v[30:31], v[2:3]
	v_mov_b64_e32 v[34:35], v[2:3]
	v_mov_b64_e32 v[46:47], v[2:3]
	v_mov_b64_e32 v[50:51], v[2:3]
	v_mov_b64_e32 v[62:63], v[2:3]
	v_mov_b64_e32 v[66:67], v[2:3]
	v_mov_b64_e32 v[70:71], v[2:3]
	v_mov_b64_e32 v[74:75], v[2:3]
	v_mov_b64_e32 v[86:87], v[2:3]
	v_mov_b64_e32 v[90:91], v[2:3]
	v_mov_b64_e32 v[102:103], v[2:3]
	v_mov_b64_e32 v[106:107], v[2:3]
	v_mov_b64_e32 v[130:131], v[2:3]
	v_mov_b64_e32 v[138:139], v[2:3]
	v_mov_b64_e32 v[78:79], v[2:3]
	v_mov_b64_e32 v[82:83], v[2:3]
	v_mov_b64_e32 v[94:95], v[2:3]
	v_mov_b64_e32 v[98:99], v[2:3]
	v_mov_b64_e32 v[110:111], v[2:3]
	v_mov_b64_e32 v[118:119], v[2:3]
	v_mov_b64_e32 v[142:143], v[2:3]
	v_mov_b64_e32 v[146:147], v[2:3]
	s_mov_b32 s49, s6
	v_readlane_b32 s6, v255, 4
	s_add_i32 s44, s21, 0xc000
	s_add_i32 s45, s21, 0xe000
	s_mov_b32 s16, 0
	v_mov_b64_e32 v[4:5], v[0:1]
	v_mov_b64_e32 v[8:9], v[0:1]
	v_mov_b64_e32 v[20:21], v[0:1]
	v_mov_b64_e32 v[24:25], v[0:1]
	v_mov_b64_e32 v[36:37], v[0:1]
	v_mov_b64_e32 v[40:41], v[0:1]
	v_mov_b64_e32 v[52:53], v[0:1]
	v_mov_b64_e32 v[56:57], v[0:1]
	v_mov_b64_e32 v[12:13], v[0:1]
	v_mov_b64_e32 v[16:17], v[0:1]
	v_mov_b64_e32 v[28:29], v[0:1]
	v_mov_b64_e32 v[32:33], v[0:1]
	v_mov_b64_e32 v[44:45], v[0:1]
	v_mov_b64_e32 v[48:49], v[0:1]
	v_mov_b64_e32 v[60:61], v[0:1]
	v_mov_b64_e32 v[64:65], v[0:1]
	v_mov_b64_e32 v[68:69], v[0:1]
	v_mov_b64_e32 v[72:73], v[0:1]
	v_mov_b64_e32 v[84:85], v[0:1]
	v_mov_b64_e32 v[88:89], v[0:1]
	v_mov_b64_e32 v[100:101], v[0:1]
	v_mov_b64_e32 v[104:105], v[0:1]
	v_mov_b64_e32 v[128:129], v[0:1]
	v_mov_b64_e32 v[136:137], v[0:1]
	v_mov_b64_e32 v[76:77], v[0:1]
	v_mov_b64_e32 v[80:81], v[0:1]
	v_mov_b64_e32 v[92:93], v[0:1]
	v_mov_b64_e32 v[96:97], v[0:1]
	v_mov_b64_e32 v[108:109], v[0:1]
	v_mov_b64_e32 v[116:117], v[0:1]
	v_mov_b64_e32 v[140:141], v[0:1]
	v_mov_b64_e32 v[144:145], v[0:1]
	s_mov_b32 s51, s6
	s_barrier
	v_readlane_b32 s7, v255, 5
	s_getreg_b32 s100, hwreg(HW_REG_HW_ID, 0, 6)
	s_lshl_b32 s100, s100, 2
	s_add_i32 s100, s100, 0x20540
	v_mov_b32_e32 v251, s100
	ds_read_b32 v251, v251
	s_waitcnt lgkmcnt(0)
	v_readfirstlane_b32 s100, v251
	s_cmp_ge_u32 s100, 4
	s_cbranch_scc0 statprio_skip5
	s_setprio 1
statprio_skip5:
	s_branch .LBB0_1210

;     __host__ __device__ bool next(int i, Unit& u) const { return StaticOrder::next(i >> 1, u); }
;     __device__ __forceinline__ bool next(int i, Unit& u) const { const int s = i * G + c; if (s >= 128) return false; const int t = s >> 2; u.pm = pm0 + (t & 3); u.pn = t >> 2; u.k0 = (s & 3) * ksub; return true; }
; #define PG8_WAIT_V(n) asm volatile("s_waitcnt vmcnt(" #n ")" ::: "memory")
; template <class Epi, class Sched, bool ALIGN_EPI = false, bool SP2 = false>
; __device__ __forceinline__ void gemm_phase(PG8_LAS unsigned char* lds, const Gemm g, const Sched& S, const Epi& E) {
;     ...
;     for (;;) {
;         const bool has_next = S.next(ui + 1, nxt);
;         const char* nA = has_next ? (const char*)g.A + (size_t)nxt.pm * tsA + (size_t)nxt.k0 * 2 : cA; const char* nB = has_next ? (const char*)g.Bt + (size_t)nxt.pn * tsB + (size_t)nxt.k0 * 2 : cB;
;         for (int t = (DRO && ui > 0) ? 2 : 0; t < nt; t += 2) {
;             const bool last = (t == nt - 2);
;             const char* a1 = cA + (size_t)(t + 1) * kstep;
;             const char* a2 = last ? nA : cA + (size_t)(t + 2) * kstep; const char* b2 = last ? nB : cB + (size_t)(t + 2) * kstep;
;             const char* a3 = a2 + kstep; const char* b3 = b2 + kstep;
;             if (last && has_next) S.a_ready(nxt);
;             if constexpr (SP2) {
;             PG8_TRIP(true, PG8_WAIT_V(8));
.LBB0_1226:
	v_add_u32_e32 v0, 0x10000, v186
	v_add_u32_e32 v188, 0x14000, v186
	ds_read_b128 v[112:115], v0
	ds_read_b128 v[120:123], v0 offset:1024
	ds_read_b128 v[124:127], v0 offset:2048
	ds_read_b128 v[132:135], v0 offset:3072
	ds_read_b128 v[148:151], v188
	ds_read_b128 v[152:155], v188 offset:1024
	ds_read_b128 v[156:159], v188 offset:2048
	ds_read_b128 v[160:163], v188 offset:3072
	s_add_u32 s14, s12, 0xffea0080
	s_addc_u32 s15, s13, -1
	s_cmpk_eq_i32 s52, 0x54
	s_cselect_b32 s18, s8, s14
	s_cselect_b32 s19, s9, s15
	s_cselect_b32 s16, s6, s53
	s_cselect_b32 s17, s7, s57
	s_add_u32 s14, s18, 0x80
	s_addc_u32 s15, s19, 0
	ds_read_b128 v[164:167], v187
	ds_read_b128 v[168:171], v187 offset:1024
	ds_read_b128 v[178:181], v187 offset:2048
	ds_read_b128 v[190:193], v187 offset:3072
	ds_read_b128 v[194:197], v187 offset:4096
	ds_read_b128 v[198:201], v187 offset:5120
	ds_read_b128 v[202:205], v187 offset:6144
	ds_read_b128 v[206:209], v187 offset:7168
	s_mov_b32 m0, s44
	s_nop 0
	global_load_lds_dwordx4 v174, s[12:13]
	s_nop 0
	s_mov_b32 m0, s45
	s_nop 0
	global_load_lds_dwordx4 v176, s[12:13]
	s_waitcnt vmcnt(8)
	s_waitcnt lgkmcnt(0)
	s_barrier
	s_nop 0
	s_waitcnt lgkmcnt(0)
	v_mfma_f32_16x16x32_bf16 v[144:147], v[112:115], v[164:167], v[144:147]
	v_mfma_f32_16x16x32_bf16 v[140:143], v[124:127], v[164:167], v[140:143]
	s_waitcnt lgkmcnt(5)
	v_mfma_f32_16x16x32_bf16 v[116:119], v[112:115], v[178:181], v[116:119]
	v_mfma_f32_16x16x32_bf16 v[108:111], v[124:127], v[178:181], v[108:111]
	s_waitcnt lgkmcnt(3)
	v_mfma_f32_16x16x32_bf16 v[96:99], v[112:115], v[194:197], v[96:99]
	v_mfma_f32_16x16x32_bf16 v[92:95], v[124:127], v[194:197], v[92:95]
	s_waitcnt lgkmcnt(1)
	v_mfma_f32_16x16x32_bf16 v[80:83], v[112:115], v[202:205], v[80:83]
	v_mfma_f32_16x16x32_bf16 v[76:79], v[124:127], v[202:205], v[76:79]
	v_mfma_f32_16x16x32_bf16 v[144:147], v[120:123], v[168:171], v[144:147]
	v_mfma_f32_16x16x32_bf16 v[140:143], v[132:135], v[168:171], v[140:143]
	v_mfma_f32_16x16x32_bf16 v[116:119], v[120:123], v[190:193], v[116:119]
	v_mfma_f32_16x16x32_bf16 v[108:111], v[132:135], v[190:193], v[108:111]
	v_mfma_f32_16x16x32_bf16 v[96:99], v[120:123], v[198:201], v[96:99]
	v_mfma_f32_16x16x32_bf16 v[92:95], v[132:135], v[198:201], v[92:95]
	s_waitcnt lgkmcnt(0)
	v_mfma_f32_16x16x32_bf16 v[80:83], v[120:123], v[206:209], v[80:83]
	v_mfma_f32_16x16x32_bf16 v[76:79], v[132:135], v[206:209], v[76:79]
	s_nop 0
	s_nop 0
	v_mfma_f32_16x16x32_bf16 v[136:139], v[148:151], v[164:167], v[136:139]
	v_mfma_f32_16x16x32_bf16 v[128:131], v[156:159], v[164:167], v[128:131]
	v_mfma_f32_16x16x32_bf16 v[104:107], v[148:151], v[178:181], v[104:107]
	v_mfma_f32_16x16x32_bf16 v[100:103], v[156:159], v[178:181], v[100:103]
	v_mfma_f32_16x16x32_bf16 v[88:91], v[148:151], v[194:197], v[88:91]
	v_mfma_f32_16x16x32_bf16 v[84:87], v[156:159], v[194:197], v[84:87]
	v_mfma_f32_16x16x32_bf16 v[72:75], v[148:151], v[202:205], v[72:75]
	v_mfma_f32_16x16x32_bf16 v[68:71], v[156:159], v[202:205], v[68:71]
	v_mfma_f32_16x16x32_bf16 v[136:139], v[152:155], v[168:171], v[136:139]
	v_mfma_f32_16x16x32_bf16 v[128:131], v[160:163], v[168:171], v[128:131]
	v_mfma_f32_16x16x32_bf16 v[104:107], v[152:155], v[190:193], v[104:107]
	v_mfma_f32_16x16x32_bf16 v[100:103], v[160:163], v[190:193], v[100:103]
	v_mfma_f32_16x16x32_bf16 v[88:91], v[152:155], v[198:201], v[88:91]
	v_mfma_f32_16x16x32_bf16 v[84:87], v[160:163], v[198:201], v[84:87]
	v_mfma_f32_16x16x32_bf16 v[72:75], v[152:155], v[206:209], v[72:75]
	v_mfma_f32_16x16x32_bf16 v[68:71], v[160:163], v[206:209], v[68:71]
	s_nop 0
	s_barrier
	ds_read_b128 v[164:167], v187 offset:16384
	ds_read_b128 v[168:171], v187 offset:17408
	ds_read_b128 v[178:181], v187 offset:18432
	ds_read_b128 v[190:193], v187 offset:19456
	ds_read_b128 v[194:197], v187 offset:20480
	ds_read_b128 v[198:201], v187 offset:21504
	ds_read_b128 v[202:205], v187 offset:22528
	ds_read_b128 v[206:209], v187 offset:23552
	s_mov_b32 m0, s22
	s_nop 0
	global_load_lds_dwordx4 v175, s[16:17]
	s_add_u32 s78, s16, 0x160000
	s_mov_b32 m0, s23
	s_nop 0
	global_load_lds_dwordx4 v177, s[16:17]
	s_addc_u32 s79, s17, 0
	s_mov_b32 m0, s26
	s_nop 0
	global_load_lds_dwordx4 v175, s[78:79]
	s_nop 0
	s_mov_b32 m0, s27
	s_nop 0
	global_load_lds_dwordx4 v177, s[78:79]
	s_nop 0
	s_mov_b32 m0, s21
	s_nop 0
	global_load_lds_dwordx4 v174, s[18:19]
	s_nop 0
	s_mov_b32 m0, s28
	s_nop 0
	global_load_lds_dwordx4 v176, s[18:19]
	s_waitcnt vmcnt(8)
	s_waitcnt lgkmcnt(0)
	s_barrier
;     __host__ __device__ bool next(int i, Unit& u) const { return StaticOrder::next(i >> 1, u); }
;     __device__ __forceinline__ bool next(int i, Unit& u) const { const int s = i * G + c; if (s >= 128) return false; const int t = s >> 2; u.pm = pm0 + (t & 3); u.pn = t >> 2; u.k0 = (s & 3) * ksub; return true; }
; #define PG8_WAIT_V(n) asm volatile("s_waitcnt vmcnt(" #n ")" ::: "memory")
; template <class Epi, class Sched, bool ALIGN_EPI = false, bool SP2 = false>
; __device__ __forceinline__ void gemm_phase(PG8_LAS unsigned char* lds, const Gemm g, const Sched& S, const Epi& E) {
;     ...
;     for (;;) {
;         const bool has_next = S.next(ui + 1, nxt);
;         const char* nA = has_next ? (const char*)g.A + (size_t)nxt.pm * tsA + (size_t)nxt.k0 * 2 : cA; const char* nB = has_next ? (const char*)g.Bt + (size_t)nxt.pn * tsB + (size_t)nxt.k0 * 2 : cB;
;         for (int t = (DRO && ui > 0) ? 2 : 0; t < nt; t += 2) {
;             const bool last = (t == nt - 2);
;             const char* a1 = cA + (size_t)(t + 1) * kstep;
;             const char* a2 = last ? nA : cA + (size_t)(t + 2) * kstep; const char* b2 = last ? nB : cB + (size_t)(t + 2) * kstep;
;             const char* a3 = a2 + kstep; const char* b3 = b2 + kstep;
;             if (last && has_next) S.a_ready(nxt);
;             if constexpr (SP2) {
;             PG8_TRIP(true, PG8_WAIT_V(8));
	s_nop 0
	s_waitcnt lgkmcnt(0)
	v_mfma_f32_16x16x32_bf16 v[64:67], v[112:115], v[164:167], v[64:67]
	v_mfma_f32_16x16x32_bf16 v[60:63], v[124:127], v[164:167], v[60:63]
	s_waitcnt lgkmcnt(5)
	v_mfma_f32_16x16x32_bf16 v[48:51], v[112:115], v[178:181], v[48:51]
	v_mfma_f32_16x16x32_bf16 v[44:47], v[124:127], v[178:181], v[44:47]
	s_waitcnt lgkmcnt(3)
	v_mfma_f32_16x16x32_bf16 v[32:35], v[112:115], v[194:197], v[32:35]
	v_mfma_f32_16x16x32_bf16 v[28:31], v[124:127], v[194:197], v[28:31]
	s_waitcnt lgkmcnt(1)
	v_mfma_f32_16x16x32_bf16 v[16:19], v[112:115], v[202:205], v[16:19]
	v_mfma_f32_16x16x32_bf16 v[12:15], v[124:127], v[202:205], v[12:15]
	v_mfma_f32_16x16x32_bf16 v[64:67], v[120:123], v[168:171], v[64:67]
	v_mfma_f32_16x16x32_bf16 v[60:63], v[132:135], v[168:171], v[60:63]
	v_mfma_f32_16x16x32_bf16 v[48:51], v[120:123], v[190:193], v[48:51]
	v_mfma_f32_16x16x32_bf16 v[44:47], v[132:135], v[190:193], v[44:47]
	v_mfma_f32_16x16x32_bf16 v[32:35], v[120:123], v[198:201], v[32:35]
	v_mfma_f32_16x16x32_bf16 v[28:31], v[132:135], v[198:201], v[28:31]
	s_waitcnt lgkmcnt(0)
	v_mfma_f32_16x16x32_bf16 v[16:19], v[120:123], v[206:209], v[16:19]
	v_mfma_f32_16x16x32_bf16 v[12:15], v[132:135], v[206:209], v[12:15]
	s_nop 0
	s_nop 0
	v_mfma_f32_16x16x32_bf16 v[56:59], v[148:151], v[164:167], v[56:59]
	v_mfma_f32_16x16x32_bf16 v[52:55], v[156:159], v[164:167], v[52:55]
	v_mfma_f32_16x16x32_bf16 v[40:43], v[148:151], v[178:181], v[40:43]
	v_mfma_f32_16x16x32_bf16 v[36:39], v[156:159], v[178:181], v[36:39]
	v_mfma_f32_16x16x32_bf16 v[24:27], v[148:151], v[194:197], v[24:27]
	v_mfma_f32_16x16x32_bf16 v[20:23], v[156:159], v[194:197], v[20:23]
	v_mfma_f32_16x16x32_bf16 v[8:11], v[148:151], v[202:205], v[8:11]
	v_mfma_f32_16x16x32_bf16 v[2:5], v[156:159], v[202:205], v[4:7]
	v_mfma_f32_16x16x32_bf16 v[56:59], v[152:155], v[168:171], v[56:59]
	v_mfma_f32_16x16x32_bf16 v[52:55], v[160:163], v[168:171], v[52:55]
	v_mfma_f32_16x16x32_bf16 v[40:43], v[152:155], v[190:193], v[40:43]
	v_mfma_f32_16x16x32_bf16 v[36:39], v[160:163], v[190:193], v[36:39]
	v_mfma_f32_16x16x32_bf16 v[24:27], v[152:155], v[198:201], v[24:27]
	v_mfma_f32_16x16x32_bf16 v[20:23], v[160:163], v[198:201], v[20:23]
	v_mfma_f32_16x16x32_bf16 v[8:11], v[152:155], v[206:209], v[8:11]
	v_mfma_f32_16x16x32_bf16 v[2:5], v[160:163], v[206:209], v[2:5]
	s_nop 0
	s_barrier
	v_add_u32_e32 v189, 0x18000, v186
	v_add_u32_e32 v190, 0x1c000, v186
	ds_read_b128 v[112:115], v189
	ds_read_b128 v[120:123], v189 offset:1024
	ds_read_b128 v[124:127], v189 offset:2048
	ds_read_b128 v[132:135], v189 offset:3072
	ds_read_b128 v[148:151], v190
	ds_read_b128 v[152:155], v190 offset:1024
	ds_read_b128 v[156:159], v190 offset:2048
	ds_read_b128 v[160:163], v190 offset:3072
	ds_read_b128 v[164:167], v187 offset:32768
	ds_read_b128 v[168:171], v187 offset:33792
	ds_read_b128 v[178:181], v187 offset:34816
	ds_read_b128 v[192:195], v187 offset:35840
	ds_read_b128 v[196:199], v187 offset:36864
	ds_read_b128 v[200:203], v187 offset:37888
	ds_read_b128 v[204:207], v187 offset:38912
	ds_read_b128 v[208:211], v187 offset:39936
	s_add_u32 s18, s18, 0x160000
	s_addc_u32 s19, s19, 0
	s_mov_b32 m0, s29
	s_nop 0
	global_load_lds_dwordx4 v174, s[18:19]
	s_nop 0
	s_mov_b32 m0, s30
	s_nop 0
	global_load_lds_dwordx4 v176, s[18:19]
	s_waitcnt vmcnt(8)
	s_waitcnt lgkmcnt(0)
	s_barrier
	s_nop 0
	s_waitcnt lgkmcnt(0)
	v_mfma_f32_16x16x32_bf16 v[144:147], v[112:115], v[164:167], v[144:147]
	v_mfma_f32_16x16x32_bf16 v[140:143], v[124:127], v[164:167], v[140:143]
	s_waitcnt lgkmcnt(5)
	v_mfma_f32_16x16x32_bf16 v[116:119], v[112:115], v[178:181], v[116:119]
	v_mfma_f32_16x16x32_bf16 v[108:111], v[124:127], v[178:181], v[108:111]
	s_waitcnt lgkmcnt(3)
	v_mfma_f32_16x16x32_bf16 v[96:99], v[112:115], v[196:199], v[96:99]
	v_mfma_f32_16x16x32_bf16 v[92:95], v[124:127], v[196:199], v[92:95]
	s_waitcnt lgkmcnt(1)
	v_mfma_f32_16x16x32_bf16 v[80:83], v[112:115], v[204:207], v[80:83]
	v_mfma_f32_16x16x32_bf16 v[76:79], v[124:127], v[204:207], v[76:79]
	v_mfma_f32_16x16x32_bf16 v[144:147], v[120:123], v[168:171], v[144:147]
	v_mfma_f32_16x16x32_bf16 v[140:143], v[132:135], v[168:171], v[140:143]
	v_mfma_f32_16x16x32_bf16 v[116:119], v[120:123], v[192:195], v[116:119]
	v_mfma_f32_16x16x32_bf16 v[108:111], v[132:135], v[192:195], v[108:111]
	v_mfma_f32_16x16x32_bf16 v[96:99], v[120:123], v[200:203], v[96:99]
	v_mfma_f32_16x16x32_bf16 v[92:95], v[132:135], v[200:203], v[92:95]
	s_waitcnt lgkmcnt(0)
	v_mfma_f32_16x16x32_bf16 v[80:83], v[120:123], v[208:211], v[80:83]
	v_mfma_f32_16x16x32_bf16 v[76:79], v[132:135], v[208:211], v[76:79]
	s_nop 0
	s_nop 0
	v_mfma_f32_16x16x32_bf16 v[136:139], v[148:151], v[164:167], v[136:139]
	v_mfma_f32_16x16x32_bf16 v[128:131], v[156:159], v[164:167], v[128:131]
	v_mfma_f32_16x16x32_bf16 v[104:107], v[148:151], v[178:181], v[104:107]
	v_mfma_f32_16x16x32_bf16 v[100:103], v[156:159], v[178:181], v[100:103]
	v_mfma_f32_16x16x32_bf16 v[88:91], v[148:151], v[196:199], v[88:91]
	v_mfma_f32_16x16x32_bf16 v[84:87], v[156:159], v[196:199], v[84:87]
	v_mfma_f32_16x16x32_bf16 v[72:75], v[148:151], v[204:207], v[72:75]
	v_mfma_f32_16x16x32_bf16 v[68:71], v[156:159], v[204:207], v[68:71]
	v_mfma_f32_16x16x32_bf16 v[136:139], v[152:155], v[168:171], v[136:139]
	v_mfma_f32_16x16x32_bf16 v[128:131], v[160:163], v[168:171], v[128:131]
	v_mfma_f32_16x16x32_bf16 v[104:107], v[152:155], v[192:195], v[104:107]
	v_mfma_f32_16x16x32_bf16 v[100:103], v[160:163], v[192:195], v[100:103]
	v_mfma_f32_16x16x32_bf16 v[88:91], v[152:155], v[200:203], v[88:91]
	v_mfma_f32_16x16x32_bf16 v[84:87], v[160:163], v[200:203], v[84:87]
	v_mfma_f32_16x16x32_bf16 v[72:75], v[152:155], v[208:211], v[72:75]
	v_mfma_f32_16x16x32_bf16 v[68:71], v[160:163], v[208:211], v[68:71]
	s_nop 0
	s_barrier
;     __host__ __device__ bool next(int i, Unit& u) const { return StaticOrder::next(i >> 1, u); }
; template <class Epi, class Sched, bool ALIGN_EPI = false, bool SP2 = false>
; __device__ __forceinline__ void gemm_phase(PG8_LAS unsigned char* lds, const Gemm g, const Sched& S, const Epi& E) {
;     ...
;     for (;;) {
;         const bool has_next = S.next(ui + 1, nxt);
;         const char* nA = has_next ? (const char*)g.A + (size_t)nxt.pm * tsA + (size_t)nxt.k0 * 2 : cA; const char* nB = has_next ? (const char*)g.Bt + (size_t)nxt.pn * tsB + (size_t)nxt.k0 * 2 : cB;
;         for (int t = (DRO && ui > 0) ? 2 : 0; t < nt; t += 2) {
;             const bool last = (t == nt - 2);
;             const char* a1 = cA + (size_t)(t + 1) * kstep;
;             const char* a2 = last ? nA : cA + (size_t)(t + 2) * kstep; const char* b2 = last ? nB : cB + (size_t)(t + 2) * kstep;
;             const char* a3 = a2 + kstep; const char* b3 = b2 + kstep;
;             if (last && has_next) S.a_ready(nxt);
;             if constexpr (SP2) {
;             PG8_TRIP(true, PG8_WAIT_V(8));
;             } else {
;             PG8_LDB(B0, 0, 0); PG8_SCHED; PG8_LDA(At, 0, 0); PG8_STAGE(PG8_SA(1, 1), a1 + hsA, voffA);
;             PG8_WAIT_L(8); PG8_BAR; PG8_WAIT_L(0); PG8_MMA(0, 0, At, B0); PG8_BAR; PG8_SCHED;
;             PG8_LDB(B1, 0, 1); PG8_STAGE(PG8_SB(0, 0), b2, voffB);
;             PG8_BAR; PG8_WAIT_L(0); PG8_MMA(0, 1, At, B1); PG8_BAR;
;             PG8_LDA(At, 0, 1); PG8_STAGE(PG8_SA(0, 0), a2, voffA);
;             PG8_BAR; PG8_WAIT_L(0); PG8_MMA(1, 0, At, B0); PG8_BAR; PG8_SCHED;
;             PG8_STAGE(PG8_SB(0, 1), b2 + hsB, voffB);
;             PG8_WAIT_V(6); PG8_BAR; PG8_MMA(1, 1, At, B1); PG8_BAR;
;             PG8_LDB(B0, 1, 0); PG8_SCHED; PG8_LDA(At, 1, 0); PG8_STAGE(PG8_SA(0, 1), a2 + hsA, voffA);
;             PG8_WAIT_L(8); PG8_BAR; PG8_WAIT_L(0); PG8_MMA(0, 0, At, B0); PG8_BAR; PG8_SCHED;
;             PG8_LDB(B1, 1, 1); PG8_STAGE(PG8_SB(1, 0), b3, voffB);
;             PG8_BAR; PG8_WAIT_L(0); PG8_MMA(0, 1, At, B1); PG8_BAR;
;             PG8_LDA(At, 1, 1); PG8_STAGE(PG8_SA(1, 0), a3, voffA);
;             PG8_BAR; PG8_WAIT_L(0); PG8_MMA(1, 0, At, B0); PG8_BAR; PG8_SCHED;
;             PG8_STAGE(PG8_SB(1, 1), b3 + hsB, voffB);
;             PG8_WAIT_V(6); PG8_BAR; PG8_MMA(1, 1, At, B1); PG8_BAR;
;             }
;         }
	ds_read_b128 v[164:167], v187 offset:49152
	ds_read_b128 v[168:171], v187 offset:50176
	ds_read_b128 v[178:181], v187 offset:51200
	ds_read_b128 v[192:195], v187 offset:52224
	ds_read_b128 v[196:199], v187 offset:53248
	ds_read_b128 v[200:203], v187 offset:54272
	ds_read_b128 v[204:207], v187 offset:55296
	ds_read_b128 v[208:211], v187 offset:56320
	s_add_u32 s18, s16, 0x80
	s_addc_u32 s19, s17, 0
	s_mov_b32 m0, s34
	s_nop 0
	global_load_lds_dwordx4 v175, s[18:19]
	s_add_u32 s16, s16, 0x160080
	s_mov_b32 m0, s35
	s_nop 0
	global_load_lds_dwordx4 v177, s[18:19]
	s_addc_u32 s17, s17, 0
	s_mov_b32 m0, s40
	s_nop 0
	global_load_lds_dwordx4 v175, s[16:17]
	s_nop 0
	s_mov_b32 m0, s41
	s_nop 0
	global_load_lds_dwordx4 v177, s[16:17]
	s_nop 0
	s_mov_b32 m0, s36
	s_nop 0
	global_load_lds_dwordx4 v174, s[14:15]
	s_nop 0
	s_mov_b32 m0, s37
	s_nop 0
	global_load_lds_dwordx4 v176, s[14:15]
	s_waitcnt vmcnt(8)
	s_waitcnt lgkmcnt(0)
	s_barrier
	s_nop 0
	s_waitcnt lgkmcnt(0)
	v_mfma_f32_16x16x32_bf16 v[64:67], v[112:115], v[164:167], v[64:67]
	v_mfma_f32_16x16x32_bf16 v[60:63], v[124:127], v[164:167], v[60:63]
	s_waitcnt lgkmcnt(5)
	v_mfma_f32_16x16x32_bf16 v[48:51], v[112:115], v[178:181], v[48:51]
	v_mfma_f32_16x16x32_bf16 v[44:47], v[124:127], v[178:181], v[44:47]
	s_waitcnt lgkmcnt(3)
	v_mfma_f32_16x16x32_bf16 v[32:35], v[112:115], v[196:199], v[32:35]
	v_mfma_f32_16x16x32_bf16 v[28:31], v[124:127], v[196:199], v[28:31]
	s_waitcnt lgkmcnt(1)
	v_mfma_f32_16x16x32_bf16 v[16:19], v[112:115], v[204:207], v[16:19]
	v_mfma_f32_16x16x32_bf16 v[12:15], v[124:127], v[204:207], v[12:15]
	v_mfma_f32_16x16x32_bf16 v[64:67], v[120:123], v[168:171], v[64:67]
	v_mfma_f32_16x16x32_bf16 v[60:63], v[132:135], v[168:171], v[60:63]
	v_mfma_f32_16x16x32_bf16 v[48:51], v[120:123], v[192:195], v[48:51]
	v_mfma_f32_16x16x32_bf16 v[44:47], v[132:135], v[192:195], v[44:47]
	v_mfma_f32_16x16x32_bf16 v[32:35], v[120:123], v[200:203], v[32:35]
	v_mfma_f32_16x16x32_bf16 v[28:31], v[132:135], v[200:203], v[28:31]
	s_waitcnt lgkmcnt(0)
	v_mfma_f32_16x16x32_bf16 v[16:19], v[120:123], v[208:211], v[16:19]
	v_mfma_f32_16x16x32_bf16 v[12:15], v[132:135], v[208:211], v[12:15]
	s_nop 0
	s_nop 0
	v_mfma_f32_16x16x32_bf16 v[56:59], v[148:151], v[164:167], v[56:59]
	v_mfma_f32_16x16x32_bf16 v[52:55], v[156:159], v[164:167], v[52:55]
	v_mfma_f32_16x16x32_bf16 v[40:43], v[148:151], v[178:181], v[40:43]
	v_mfma_f32_16x16x32_bf16 v[36:39], v[156:159], v[178:181], v[36:39]
	v_mfma_f32_16x16x32_bf16 v[24:27], v[148:151], v[196:199], v[24:27]
	v_mfma_f32_16x16x32_bf16 v[20:23], v[156:159], v[196:199], v[20:23]
	v_mfma_f32_16x16x32_bf16 v[6:9], v[148:151], v[204:207], v[8:11]
	v_mfma_f32_16x16x32_bf16 v[2:5], v[156:159], v[204:207], v[2:5]
	v_mfma_f32_16x16x32_bf16 v[56:59], v[152:155], v[168:171], v[56:59]
	v_mfma_f32_16x16x32_bf16 v[52:55], v[160:163], v[168:171], v[52:55]
	v_mfma_f32_16x16x32_bf16 v[40:43], v[152:155], v[192:195], v[40:43]
	v_mfma_f32_16x16x32_bf16 v[36:39], v[160:163], v[192:195], v[36:39]
	v_mfma_f32_16x16x32_bf16 v[24:27], v[152:155], v[200:203], v[24:27]
	v_mfma_f32_16x16x32_bf16 v[20:23], v[160:163], v[200:203], v[20:23]
	v_mfma_f32_16x16x32_bf16 v[8:11], v[152:155], v[208:211], v[6:9]
	v_mfma_f32_16x16x32_bf16 v[4:7], v[160:163], v[208:211], v[2:5]
	s_nop 0
	s_barrier
	s_add_i32 s52, s52, 2
	s_add_u32 s53, s53, 0x100
	s_addc_u32 s57, s57, 0
	s_add_u32 s12, s12, 0x100
	s_addc_u32 s13, s13, 0
	s_cmpk_gt_u32 s52, 0x55
	s_cbranch_scc0 .LBB0_1226
	s_add_u32 s12, s8, 0x160080
	s_addc_u32 s13, s9, 0
	s_mov_b32 m0, s44
	s_nop 0
	global_load_lds_dwordx4 v174, s[12:13]
	v_lshl_add_u32 v2, s51, 8, v184
	s_mov_b32 m0, s45
	s_nop 0
	global_load_lds_dwordx4 v176, s[12:13]
	s_min_i32 s12, s51, 64
	s_ashr_i32 s12, s12, 4
	s_mul_hi_i32 s13, s12, 0xc000
	s_mul_i32 s12, s12, 0xc000
	v_ashrrev_i32_e32 v3, 31, v2
	v_lshl_or_b32 v148, s49, 8, v185
	s_add_u32 s12, s31, s12
	v_lshlrev_b64 v[2:3], 12, v[2:3]
	s_addc_u32 s13, s33, s13
	v_ashrrev_i32_e32 v149, 31, v148
	v_lshl_add_u64 v[2:3], s[80:81], 0, v[2:3]
	v_lshl_add_u64 v[112:113], v[148:149], 2, s[12:13]
	v_lshl_add_u64 v[2:3], v[148:149], 1, v[2:3]
	global_load_dwordx4 v[132:135], v[112:113], off
	global_load_dwordx4 v[124:127], v[112:113], off offset:16
	global_load_dwordx4 v[120:123], v[112:113], off offset:512
	global_load_dwordx4 v[112:115], v[112:113], off offset:528
	global_load_dwordx4 v[178:181], v[2:3], off
	global_load_dwordx4 v[192:195], v[2:3], off offset:256
	v_add_co_u32_e32 v172, vcc, 0x10000, v2
	s_nop 1
	v_addc_co_u32_e32 v173, vcc, 0, v3, vcc
	global_load_dwordx4 v[196:199], v[172:173], off
	global_load_dwordx4 v[164:167], v[172:173], off offset:256
	v_add_co_u32_e32 v170, vcc, 0x20000, v2
	s_nop 1
	v_addc_co_u32_e32 v171, vcc, 0, v3, vcc
	global_load_dwordx4 v[160:163], v[170:171], off
	global_load_dwordx4 v[156:159], v[170:171], off offset:256
	v_add_co_u32_e32 v168, vcc, 0x30000, v2
	s_nop 1
	v_addc_co_u32_e32 v169, vcc, 0, v3, vcc
	global_load_dwordx4 v[152:155], v[168:169], off
	global_load_dwordx4 v[148:151], v[168:169], off offset:256
	v_add_co_u32_e32 v244, vcc, 0x80000, v2
	s_nop 1
	v_addc_co_u32_e32 v245, vcc, 0, v3, vcc
	global_load_dwordx4 v[212:215], v[244:245], off
	global_load_dwordx4 v[216:219], v[244:245], off offset:256
	v_add_co_u32_e32 v246, vcc, 0x90000, v2
	s_nop 1
	v_addc_co_u32_e32 v247, vcc, 0, v3, vcc
	global_load_dwordx4 v[220:223], v[246:247], off
	global_load_dwordx4 v[224:227], v[246:247], off offset:256
	v_add_co_u32_e32 v248, vcc, 0xa0000, v2
	s_nop 1
	v_addc_co_u32_e32 v249, vcc, 0, v3, vcc
	global_load_dwordx4 v[228:231], v[248:249], off
	global_load_dwordx4 v[232:235], v[248:249], off offset:256
	v_add_co_u32_e32 v250, vcc, 0xb0000, v2
	s_nop 1
	v_addc_co_u32_e32 v251, vcc, 0, v3, vcc
	global_load_dwordx4 v[236:239], v[250:251], off
	global_load_dwordx4 v[240:243], v[250:251], off offset:256
	s_nop 0
	s_nop 0
	s_mov_b32 s12, 0x10000
	s_mov_b32 s12, 0x90000
	s_nop 0
	s_waitcnt vmcnt(15)
; #define ER_LOAD(dst, ai, mp) do { _Pragma("unroll") for (int mm = 0; mm < 2; ++mm) _Pragma("unroll") for (int bj = 0; bj < 2; ++bj) \
;             dst[mm][bj] = *(const u32x4*)(xb + (size_t)((ai) * HALF + (2 * (mp) + mm) * 16) * 2048 + bj * HALF); } while (0)
;     __device__ __forceinline__ void operator()(const f32x4 (&acc)[2][2][4][2], const Unit& u, int wr, int wc, int fr, int fq) const {
;     ...
;         ER_LOAD(xa, 0, 0); ER_LOAD(xc, 0, 1);
;         ER_STORE(xa, 0, 0); ER_LOAD(xa, 1, 0);
;         ER_STORE(xc, 0, 1); ER_LOAD(xc, 1, 1);
;         ER_STORE(xa, 1, 0); ER_STORE(xc, 1, 1);
	v_cvt_f32_f16_e32 v200, v178
	v_cvt_f32_f16_sdwa v201, v178 dst_sel:DWORD dst_unused:UNUSED_PAD src0_sel:WORD_1
	s_nop 0
	v_cvt_f32_f16_e32 v178, v179
	v_cvt_f32_f16_sdwa v179, v179 dst_sel:DWORD dst_unused:UNUSED_PAD src0_sel:WORD_1
	v_pk_fma_f32 v[144:145], v[144:145], v[132:133], v[200:201]
	v_pk_fma_f32 v[146:147], v[146:147], v[134:135], v[178:179]
	v_cvt_f32_f16_e32 v178, v180
	v_cvt_f32_f16_sdwa v179, v180 dst_sel:DWORD dst_unused:UNUSED_PAD src0_sel:WORD_1
	v_cvt_f32_f16_e32 v180, v181
	v_cvt_f32_f16_sdwa v181, v181 dst_sel:DWORD dst_unused:UNUSED_PAD src0_sel:WORD_1
	v_pk_fma_f32 v[180:181], v[142:143], v[126:127], v[180:181]
	v_pk_fma_f32 v[142:143], v[140:141], v[124:125], v[178:179]
	v_cvt_pk_f16_f32 v140, v144, v145
	v_cvt_pk_f16_f32 v141, v146, v147
	v_cvt_pk_f16_f32 v142, v142, v143
	v_cvt_pk_f16_f32 v143, v180, v181
	global_store_dwordx4 v[2:3], v[140:143], off
	s_nop 1
	s_waitcnt vmcnt(15)
	v_cvt_f32_f16_e32 v140, v192
	v_cvt_f32_f16_sdwa v141, v192 dst_sel:DWORD dst_unused:UNUSED_PAD src0_sel:WORD_1
	v_cvt_f32_f16_e32 v142, v193
	v_cvt_f32_f16_sdwa v143, v193 dst_sel:DWORD dst_unused:UNUSED_PAD src0_sel:WORD_1
	v_pk_fma_f32 v[136:137], v[136:137], v[120:121], v[140:141]
	v_cvt_f32_f16_e32 v140, v194
	v_pk_fma_f32 v[138:139], v[138:139], v[122:123], v[142:143]
	v_cvt_f32_f16_sdwa v141, v194 dst_sel:DWORD dst_unused:UNUSED_PAD src0_sel:WORD_1
	v_cvt_f32_f16_e32 v142, v195
	v_cvt_f32_f16_sdwa v143, v195 dst_sel:DWORD dst_unused:UNUSED_PAD src0_sel:WORD_1
	v_pk_fma_f32 v[142:143], v[130:131], v[114:115], v[142:143]
	v_pk_fma_f32 v[130:131], v[128:129], v[112:113], v[140:141]
	v_cvt_pk_f16_f32 v128, v136, v137
	v_cvt_pk_f16_f32 v129, v138, v139
	v_cvt_pk_f16_f32 v130, v130, v131
	v_cvt_pk_f16_f32 v131, v142, v143
	global_store_dwordx4 v[2:3], v[128:131], off offset:256
	s_waitcnt vmcnt(13)
	v_cvt_f32_f16_e32 v136, v160
	v_cvt_f32_f16_e32 v128, v196
	v_cvt_f32_f16_sdwa v129, v196 dst_sel:DWORD dst_unused:UNUSED_PAD src0_sel:WORD_1
	v_cvt_f32_f16_e32 v130, v197
	v_cvt_f32_f16_sdwa v131, v197 dst_sel:DWORD dst_unused:UNUSED_PAD src0_sel:WORD_1
	v_cvt_f32_f16_sdwa v137, v160 dst_sel:DWORD dst_unused:UNUSED_PAD src0_sel:WORD_1
	v_pk_fma_f32 v[116:117], v[116:117], v[132:133], v[128:129]
	v_cvt_f32_f16_e32 v128, v198
	v_pk_fma_f32 v[118:119], v[118:119], v[134:135], v[130:131]
	v_cvt_f32_f16_sdwa v129, v198 dst_sel:DWORD dst_unused:UNUSED_PAD src0_sel:WORD_1
	v_cvt_f32_f16_e32 v130, v199
	v_cvt_f32_f16_sdwa v131, v199 dst_sel:DWORD dst_unused:UNUSED_PAD src0_sel:WORD_1
	v_cvt_f32_f16_e32 v138, v161
	v_cvt_f32_f16_sdwa v139, v161 dst_sel:DWORD dst_unused:UNUSED_PAD src0_sel:WORD_1
	v_pk_fma_f32 v[96:97], v[96:97], v[132:133], v[136:137]
	v_pk_fma_f32 v[130:131], v[110:111], v[126:127], v[130:131]
	v_pk_fma_f32 v[110:111], v[108:109], v[124:125], v[128:129]
	v_cvt_pk_f16_f32 v108, v116, v117
	v_cvt_pk_f16_f32 v109, v118, v119
	v_cvt_pk_f16_f32 v110, v110, v111
	v_cvt_pk_f16_f32 v111, v130, v131
	global_store_dwordx4 v[172:173], v[108:111], off
	v_add_co_u32_e32 v130, vcc, s83, v2
	s_nop 0
	v_cvt_f32_f16_e32 v108, v164
	v_cvt_f32_f16_sdwa v109, v164 dst_sel:DWORD dst_unused:UNUSED_PAD src0_sel:WORD_1
	v_cvt_f32_f16_e32 v110, v165
	v_cvt_f32_f16_sdwa v111, v165 dst_sel:DWORD dst_unused:UNUSED_PAD src0_sel:WORD_1
	v_addc_co_u32_e32 v131, vcc, 0, v3, vcc
	v_pk_fma_f32 v[104:105], v[104:105], v[120:121], v[108:109]
	v_pk_fma_f32 v[106:107], v[106:107], v[122:123], v[110:111]
	v_cvt_f32_f16_e32 v108, v166
	v_cvt_f32_f16_sdwa v109, v166 dst_sel:DWORD dst_unused:UNUSED_PAD src0_sel:WORD_1
	v_cvt_f32_f16_e32 v110, v167
	v_cvt_f32_f16_sdwa v111, v167 dst_sel:DWORD dst_unused:UNUSED_PAD src0_sel:WORD_1
	v_pk_fma_f32 v[98:99], v[98:99], v[134:135], v[138:139]
	v_cvt_f32_f16_e32 v136, v162
	v_cvt_f32_f16_sdwa v137, v162 dst_sel:DWORD dst_unused:UNUSED_PAD src0_sel:WORD_1
	v_pk_fma_f32 v[110:111], v[102:103], v[114:115], v[110:111]
	v_pk_fma_f32 v[102:103], v[100:101], v[112:113], v[108:109]
	v_cvt_pk_f16_f32 v100, v104, v105
	v_cvt_pk_f16_f32 v101, v106, v107
	v_cvt_pk_f16_f32 v102, v102, v103
	v_cvt_pk_f16_f32 v103, v110, v111
	global_store_dwordx4 v[172:173], v[100:103], off offset:256
	v_cvt_f32_f16_e32 v138, v163
	v_cvt_f32_f16_sdwa v139, v163 dst_sel:DWORD dst_unused:UNUSED_PAD src0_sel:WORD_1
	v_add_co_u32_e32 v128, vcc, s12, v2
	s_mov_b32 s12, 0xa0000
	v_pk_fma_f32 v[138:139], v[94:95], v[126:127], v[138:139]
	v_pk_fma_f32 v[94:95], v[92:93], v[124:125], v[136:137]
	v_addc_co_u32_e32 v129, vcc, 0, v3, vcc
	v_cvt_pk_f16_f32 v92, v96, v97
	v_cvt_pk_f16_f32 v93, v98, v99
	v_cvt_pk_f16_f32 v94, v94, v95
	v_cvt_pk_f16_f32 v95, v138, v139
	s_nop 0
	global_store_dwordx4 v[170:171], v[92:95], off
	s_nop 1
	s_waitcnt vmcnt(15)
	v_cvt_f32_f16_e32 v92, v156
	v_cvt_f32_f16_sdwa v93, v156 dst_sel:DWORD dst_unused:UNUSED_PAD src0_sel:WORD_1
	v_cvt_f32_f16_e32 v94, v157
	v_cvt_f32_f16_sdwa v95, v157 dst_sel:DWORD dst_unused:UNUSED_PAD src0_sel:WORD_1
	v_pk_fma_f32 v[88:89], v[88:89], v[120:121], v[92:93]
	v_cvt_f32_f16_e32 v92, v158
	v_pk_fma_f32 v[90:91], v[90:91], v[122:123], v[94:95]
	v_cvt_f32_f16_sdwa v93, v158 dst_sel:DWORD dst_unused:UNUSED_PAD src0_sel:WORD_1
	v_cvt_f32_f16_e32 v94, v159
	v_cvt_f32_f16_sdwa v95, v159 dst_sel:DWORD dst_unused:UNUSED_PAD src0_sel:WORD_1
	v_pk_fma_f32 v[94:95], v[86:87], v[114:115], v[94:95]
	v_pk_fma_f32 v[86:87], v[84:85], v[112:113], v[92:93]
	v_cvt_pk_f16_f32 v84, v88, v89
	v_cvt_pk_f16_f32 v85, v90, v91
	v_cvt_pk_f16_f32 v86, v86, v87
	v_cvt_pk_f16_f32 v87, v94, v95
	global_store_dwordx4 v[170:171], v[84:87], off offset:256
	s_waitcnt vmcnt(13)
; #define ER_LOAD(dst, ai, mp) do { _Pragma("unroll") for (int mm = 0; mm < 2; ++mm) _Pragma("unroll") for (int bj = 0; bj < 2; ++bj) \
;             dst[mm][bj] = *(const u32x4*)(xb + (size_t)((ai) * HALF + (2 * (mp) + mm) * 16) * 2048 + bj * HALF); } while (0)
;     __device__ __forceinline__ void operator()(const f32x4 (&acc)[2][2][4][2], const Unit& u, int wr, int wc, int fr, int fq) const {
;     ...
;         ER_LOAD(xa, 0, 0); ER_LOAD(xc, 0, 1);
;         ER_STORE(xa, 0, 0); ER_LOAD(xa, 1, 0);
;         ER_STORE(xc, 0, 1); ER_LOAD(xc, 1, 1);
;         ER_STORE(xa, 1, 0); ER_STORE(xc, 1, 1);
	v_cvt_f32_f16_e32 v88, v213
	v_cvt_f32_f16_e32 v84, v152
	v_cvt_f32_f16_sdwa v85, v152 dst_sel:DWORD dst_unused:UNUSED_PAD src0_sel:WORD_1
	v_cvt_f32_f16_e32 v86, v153
	v_cvt_f32_f16_sdwa v87, v153 dst_sel:DWORD dst_unused:UNUSED_PAD src0_sel:WORD_1
	v_cvt_f32_f16_sdwa v89, v213 dst_sel:DWORD dst_unused:UNUSED_PAD src0_sel:WORD_1
	v_pk_fma_f32 v[80:81], v[80:81], v[132:133], v[84:85]
	v_cvt_f32_f16_e32 v84, v154
	v_pk_fma_f32 v[82:83], v[82:83], v[134:135], v[86:87]
	v_cvt_f32_f16_sdwa v85, v154 dst_sel:DWORD dst_unused:UNUSED_PAD src0_sel:WORD_1
	v_cvt_f32_f16_e32 v86, v155
	v_cvt_f32_f16_sdwa v87, v155 dst_sel:DWORD dst_unused:UNUSED_PAD src0_sel:WORD_1
	v_pk_fma_f32 v[66:67], v[66:67], v[134:135], v[88:89]
	v_cvt_f32_f16_e32 v88, v215
	v_cvt_f32_f16_sdwa v89, v215 dst_sel:DWORD dst_unused:UNUSED_PAD src0_sel:WORD_1
	v_pk_fma_f32 v[86:87], v[78:79], v[126:127], v[86:87]
	v_pk_fma_f32 v[78:79], v[76:77], v[124:125], v[84:85]
	v_cvt_pk_f16_f32 v76, v80, v81
	v_cvt_pk_f16_f32 v77, v82, v83
	v_cvt_pk_f16_f32 v78, v78, v79
	v_cvt_pk_f16_f32 v79, v86, v87
	global_store_dwordx4 v[168:169], v[76:79], off
	v_add_co_u32_e32 v84, vcc, s12, v2
	s_nop 0
	v_cvt_f32_f16_e32 v76, v148
	v_cvt_f32_f16_sdwa v77, v148 dst_sel:DWORD dst_unused:UNUSED_PAD src0_sel:WORD_1
	v_cvt_f32_f16_e32 v78, v149
	v_cvt_f32_f16_sdwa v79, v149 dst_sel:DWORD dst_unused:UNUSED_PAD src0_sel:WORD_1
	v_addc_co_u32_e32 v85, vcc, 0, v3, vcc
	v_pk_fma_f32 v[72:73], v[72:73], v[120:121], v[76:77]
	v_pk_fma_f32 v[74:75], v[74:75], v[122:123], v[78:79]
	v_cvt_f32_f16_e32 v76, v150
	v_cvt_f32_f16_sdwa v77, v150 dst_sel:DWORD dst_unused:UNUSED_PAD src0_sel:WORD_1
	v_cvt_f32_f16_e32 v78, v151
	v_cvt_f32_f16_sdwa v79, v151 dst_sel:DWORD dst_unused:UNUSED_PAD src0_sel:WORD_1
	s_mov_b32 s12, 0xb0000
	v_add_co_u32_e32 v2, vcc, s12, v2
	v_pk_fma_f32 v[78:79], v[70:71], v[114:115], v[78:79]
	v_pk_fma_f32 v[70:71], v[68:69], v[112:113], v[76:77]
	v_cvt_pk_f16_f32 v68, v72, v73
	v_cvt_pk_f16_f32 v69, v74, v75
	v_cvt_pk_f16_f32 v70, v70, v71
	v_cvt_pk_f16_f32 v71, v78, v79
	global_store_dwordx4 v[168:169], v[68:71], off offset:256
	v_addc_co_u32_e32 v3, vcc, 0, v3, vcc
	v_cvt_f32_f16_e32 v86, v212
	v_cvt_f32_f16_sdwa v87, v212 dst_sel:DWORD dst_unused:UNUSED_PAD src0_sel:WORD_1
	v_pk_fma_f32 v[88:89], v[62:63], v[126:127], v[88:89]
	s_mov_b64 s[12:13], -1
	s_and_b64 vcc, exec, s[10:11]
	v_pk_fma_f32 v[64:65], v[64:65], v[132:133], v[86:87]
	v_cvt_f32_f16_e32 v86, v214
	v_cvt_f32_f16_sdwa v87, v214 dst_sel:DWORD dst_unused:UNUSED_PAD src0_sel:WORD_1
	v_pk_fma_f32 v[62:63], v[60:61], v[124:125], v[86:87]
	v_cvt_pk_f16_f32 v60, v64, v65
	v_cvt_pk_f16_f32 v61, v66, v67
	v_cvt_pk_f16_f32 v62, v62, v63
	v_cvt_pk_f16_f32 v63, v88, v89
	global_store_dwordx4 v[130:131], v[60:63], off
	s_nop 1
	s_waitcnt vmcnt(15)
	v_cvt_f32_f16_e32 v60, v216
	v_cvt_f32_f16_sdwa v61, v216 dst_sel:DWORD dst_unused:UNUSED_PAD src0_sel:WORD_1
	v_cvt_f32_f16_e32 v62, v217
	v_cvt_f32_f16_sdwa v63, v217 dst_sel:DWORD dst_unused:UNUSED_PAD src0_sel:WORD_1
	v_pk_fma_f32 v[56:57], v[56:57], v[120:121], v[60:61]
	v_cvt_f32_f16_e32 v60, v218
	v_pk_fma_f32 v[58:59], v[58:59], v[122:123], v[62:63]
	v_cvt_f32_f16_sdwa v61, v218 dst_sel:DWORD dst_unused:UNUSED_PAD src0_sel:WORD_1
	v_cvt_f32_f16_e32 v62, v219
	v_cvt_f32_f16_sdwa v63, v219 dst_sel:DWORD dst_unused:UNUSED_PAD src0_sel:WORD_1
	v_pk_fma_f32 v[62:63], v[54:55], v[114:115], v[62:63]
	v_pk_fma_f32 v[54:55], v[52:53], v[112:113], v[60:61]
	v_cvt_pk_f16_f32 v52, v56, v57
	v_cvt_pk_f16_f32 v53, v58, v59
	v_cvt_pk_f16_f32 v54, v54, v55
	v_cvt_pk_f16_f32 v55, v62, v63
	global_store_dwordx4 v[130:131], v[52:55], off offset:256
	s_nop 1
	s_waitcnt vmcnt(15)
	v_cvt_f32_f16_e32 v52, v220
	v_cvt_f32_f16_sdwa v53, v220 dst_sel:DWORD dst_unused:UNUSED_PAD src0_sel:WORD_1
	v_cvt_f32_f16_e32 v54, v221
	v_cvt_f32_f16_sdwa v55, v221 dst_sel:DWORD dst_unused:UNUSED_PAD src0_sel:WORD_1
	v_pk_fma_f32 v[48:49], v[48:49], v[132:133], v[52:53]
	v_cvt_f32_f16_e32 v52, v222
	v_pk_fma_f32 v[50:51], v[50:51], v[134:135], v[54:55]
	v_cvt_f32_f16_sdwa v53, v222 dst_sel:DWORD dst_unused:UNUSED_PAD src0_sel:WORD_1
	v_cvt_f32_f16_e32 v54, v223
	v_cvt_f32_f16_sdwa v55, v223 dst_sel:DWORD dst_unused:UNUSED_PAD src0_sel:WORD_1
	v_pk_fma_f32 v[54:55], v[46:47], v[126:127], v[54:55]
	v_pk_fma_f32 v[46:47], v[44:45], v[124:125], v[52:53]
	v_cvt_pk_f16_f32 v44, v48, v49
	v_cvt_pk_f16_f32 v45, v50, v51
	v_cvt_pk_f16_f32 v46, v46, v47
	v_cvt_pk_f16_f32 v47, v54, v55
	global_store_dwordx4 v[128:129], v[44:47], off
	s_nop 1
	s_waitcnt vmcnt(15)
	v_cvt_f32_f16_e32 v44, v224
	v_cvt_f32_f16_sdwa v45, v224 dst_sel:DWORD dst_unused:UNUSED_PAD src0_sel:WORD_1
	v_cvt_f32_f16_e32 v46, v225
	v_cvt_f32_f16_sdwa v47, v225 dst_sel:DWORD dst_unused:UNUSED_PAD src0_sel:WORD_1
	v_pk_fma_f32 v[40:41], v[40:41], v[120:121], v[44:45]
	v_cvt_f32_f16_e32 v44, v226
	v_pk_fma_f32 v[42:43], v[42:43], v[122:123], v[46:47]
	v_cvt_f32_f16_sdwa v45, v226 dst_sel:DWORD dst_unused:UNUSED_PAD src0_sel:WORD_1
	v_cvt_f32_f16_e32 v46, v227
	v_cvt_f32_f16_sdwa v47, v227 dst_sel:DWORD dst_unused:UNUSED_PAD src0_sel:WORD_1
	v_pk_fma_f32 v[46:47], v[38:39], v[114:115], v[46:47]
	v_pk_fma_f32 v[38:39], v[36:37], v[112:113], v[44:45]
	v_cvt_pk_f16_f32 v36, v40, v41
	v_cvt_pk_f16_f32 v37, v42, v43
	v_cvt_pk_f16_f32 v38, v38, v39
	v_cvt_pk_f16_f32 v39, v46, v47
	global_store_dwordx4 v[128:129], v[36:39], off offset:256
	s_nop 0
	s_waitcnt vmcnt(15)
; #define ER_LOAD(dst, ai, mp) do { _Pragma("unroll") for (int mm = 0; mm < 2; ++mm) _Pragma("unroll") for (int bj = 0; bj < 2; ++bj) \
;             dst[mm][bj] = *(const u32x4*)(xb + (size_t)((ai) * HALF + (2 * (mp) + mm) * 16) * 2048 + bj * HALF); } while (0)
;     __device__ __forceinline__ void operator()(const f32x4 (&acc)[2][2][4][2], const Unit& u, int wr, int wc, int fr, int fq) const {
;     ...
;         ER_LOAD(xa, 0, 0); ER_LOAD(xc, 0, 1);
;         ER_STORE(xa, 0, 0); ER_LOAD(xa, 1, 0);
;         ER_STORE(xc, 0, 1); ER_LOAD(xc, 1, 1);
;         ER_STORE(xa, 1, 0); ER_STORE(xc, 1, 1);
	v_cvt_f32_f16_e32 v36, v228
	v_cvt_f32_f16_sdwa v37, v228 dst_sel:DWORD dst_unused:UNUSED_PAD src0_sel:WORD_1
	v_cvt_f32_f16_e32 v38, v229
	v_cvt_f32_f16_sdwa v39, v229 dst_sel:DWORD dst_unused:UNUSED_PAD src0_sel:WORD_1
	v_pk_fma_f32 v[32:33], v[32:33], v[132:133], v[36:37]
	v_cvt_f32_f16_e32 v36, v230
	v_pk_fma_f32 v[34:35], v[34:35], v[134:135], v[38:39]
	v_cvt_f32_f16_sdwa v37, v230 dst_sel:DWORD dst_unused:UNUSED_PAD src0_sel:WORD_1
	v_cvt_f32_f16_e32 v38, v231
	v_cvt_f32_f16_sdwa v39, v231 dst_sel:DWORD dst_unused:UNUSED_PAD src0_sel:WORD_1
	v_pk_fma_f32 v[38:39], v[30:31], v[126:127], v[38:39]
	v_pk_fma_f32 v[30:31], v[28:29], v[124:125], v[36:37]
	v_cvt_pk_f16_f32 v28, v32, v33
	v_cvt_pk_f16_f32 v29, v34, v35
	v_cvt_pk_f16_f32 v30, v30, v31
	v_cvt_pk_f16_f32 v31, v38, v39
	global_store_dwordx4 v[84:85], v[28:31], off
	s_nop 1
	s_waitcnt vmcnt(15)
	v_cvt_f32_f16_e32 v28, v232
	v_cvt_f32_f16_sdwa v29, v232 dst_sel:DWORD dst_unused:UNUSED_PAD src0_sel:WORD_1
	v_cvt_f32_f16_e32 v30, v233
	v_cvt_f32_f16_sdwa v31, v233 dst_sel:DWORD dst_unused:UNUSED_PAD src0_sel:WORD_1
	v_pk_fma_f32 v[24:25], v[24:25], v[120:121], v[28:29]
	v_cvt_f32_f16_e32 v28, v234
	v_pk_fma_f32 v[26:27], v[26:27], v[122:123], v[30:31]
	v_cvt_f32_f16_sdwa v29, v234 dst_sel:DWORD dst_unused:UNUSED_PAD src0_sel:WORD_1
	v_cvt_f32_f16_e32 v30, v235
	v_cvt_f32_f16_sdwa v31, v235 dst_sel:DWORD dst_unused:UNUSED_PAD src0_sel:WORD_1
	v_pk_fma_f32 v[30:31], v[22:23], v[114:115], v[30:31]
	v_pk_fma_f32 v[22:23], v[20:21], v[112:113], v[28:29]
	v_cvt_pk_f16_f32 v20, v24, v25
	v_cvt_pk_f16_f32 v21, v26, v27
	v_cvt_pk_f16_f32 v22, v22, v23
	v_cvt_pk_f16_f32 v23, v30, v31
	global_store_dwordx4 v[84:85], v[20:23], off offset:256
	s_nop 1
	s_waitcnt vmcnt(15)
	v_cvt_f32_f16_e32 v20, v236
	v_cvt_f32_f16_sdwa v21, v236 dst_sel:DWORD dst_unused:UNUSED_PAD src0_sel:WORD_1
	v_cvt_f32_f16_e32 v22, v237
	v_cvt_f32_f16_sdwa v23, v237 dst_sel:DWORD dst_unused:UNUSED_PAD src0_sel:WORD_1
	v_pk_fma_f32 v[16:17], v[16:17], v[132:133], v[20:21]
	v_cvt_f32_f16_e32 v20, v238
	v_pk_fma_f32 v[18:19], v[18:19], v[134:135], v[22:23]
	v_cvt_f32_f16_sdwa v21, v238 dst_sel:DWORD dst_unused:UNUSED_PAD src0_sel:WORD_1
	v_cvt_f32_f16_e32 v22, v239
	v_cvt_f32_f16_sdwa v23, v239 dst_sel:DWORD dst_unused:UNUSED_PAD src0_sel:WORD_1
	v_pk_fma_f32 v[22:23], v[14:15], v[126:127], v[22:23]
	v_pk_fma_f32 v[14:15], v[12:13], v[124:125], v[20:21]
	v_cvt_pk_f16_f32 v12, v16, v17
	v_cvt_pk_f16_f32 v13, v18, v19
	v_cvt_pk_f16_f32 v14, v14, v15
	v_cvt_pk_f16_f32 v15, v22, v23
	global_store_dwordx4 v[2:3], v[12:15], off
	s_nop 1
	s_waitcnt vmcnt(15)
	v_cvt_f32_f16_e32 v12, v240
	v_cvt_f32_f16_sdwa v13, v240 dst_sel:DWORD dst_unused:UNUSED_PAD src0_sel:WORD_1
	v_cvt_f32_f16_e32 v14, v241
	v_cvt_f32_f16_sdwa v15, v241 dst_sel:DWORD dst_unused:UNUSED_PAD src0_sel:WORD_1
	v_pk_fma_f32 v[8:9], v[8:9], v[120:121], v[12:13]
	v_cvt_f32_f16_e32 v12, v242
	v_pk_fma_f32 v[10:11], v[10:11], v[122:123], v[14:15]
	v_cvt_f32_f16_sdwa v13, v242 dst_sel:DWORD dst_unused:UNUSED_PAD src0_sel:WORD_1
	v_cvt_f32_f16_e32 v14, v243
	v_cvt_f32_f16_sdwa v15, v243 dst_sel:DWORD dst_unused:UNUSED_PAD src0_sel:WORD_1
	v_pk_fma_f32 v[14:15], v[6:7], v[114:115], v[14:15]
	v_pk_fma_f32 v[6:7], v[4:5], v[112:113], v[12:13]
	v_cvt_pk_f16_f32 v4, v8, v9
	v_cvt_pk_f16_f32 v5, v10, v11
	v_cvt_pk_f16_f32 v6, v6, v7
	v_cvt_pk_f16_f32 v7, v14, v15
	global_store_dwordx4 v[2:3], v[4:7], off offset:256
	s_cbranch_vccz .LBB0_1209
	ds_read_b128 v[2:5], v0
	ds_read_b128 v[6:9], v0 offset:1024
	ds_read_b128 v[10:13], v0 offset:2048
	ds_read_b128 v[14:17], v0 offset:3072
	ds_read_b128 v[18:21], v188
	ds_read_b128 v[22:25], v188 offset:1024
	ds_read_b128 v[26:29], v188 offset:2048
	ds_read_b128 v[30:33], v188 offset:3072
	s_add_u32 s12, s8, 0x100
	s_addc_u32 s13, s9, 0
	s_add_u32 s10, s8, 0x180
	s_addc_u32 s11, s9, 0
	s_add_u32 s14, s6, 0x100
	s_addc_u32 s15, s7, 0
	ds_read_b128 v[34:37], v187
	ds_read_b128 v[38:41], v187 offset:1024
	ds_read_b128 v[42:45], v187 offset:2048
	ds_read_b128 v[46:49], v187 offset:3072
	ds_read_b128 v[50:53], v187 offset:4096
	ds_read_b128 v[54:57], v187 offset:5120
	ds_read_b128 v[58:61], v187 offset:6144
	ds_read_b128 v[62:65], v187 offset:7168
	s_waitcnt vmcnt(44)
	s_waitcnt lgkmcnt(0)
	s_barrier
	s_nop 0
	s_waitcnt lgkmcnt(0)
	v_mfma_f32_16x16x32_bf16 v[90:93], v[2:5], v[58:61], 0
	v_mfma_f32_16x16x32_bf16 v[66:69], v[2:5], v[34:37], 0
	v_mfma_f32_16x16x32_bf16 v[70:73], v[10:13], v[34:37], 0
	v_mfma_f32_16x16x32_bf16 v[74:77], v[2:5], v[42:45], 0
	v_mfma_f32_16x16x32_bf16 v[78:81], v[10:13], v[42:45], 0
	v_mfma_f32_16x16x32_bf16 v[82:85], v[2:5], v[50:53], 0
	v_mfma_f32_16x16x32_bf16 v[86:89], v[10:13], v[50:53], 0
	v_mfma_f32_16x16x32_bf16 v[100:103], v[6:9], v[62:65], v[90:93]
	v_mfma_f32_16x16x32_bf16 v[90:93], v[10:13], v[58:61], 0
	v_mfma_f32_16x16x32_bf16 v[66:69], v[6:9], v[38:41], v[66:69]
	v_mfma_f32_16x16x32_bf16 v[70:73], v[14:17], v[38:41], v[70:73]
	v_mfma_f32_16x16x32_bf16 v[74:77], v[6:9], v[46:49], v[74:77]
	v_mfma_f32_16x16x32_bf16 v[78:81], v[14:17], v[46:49], v[78:81]
	v_mfma_f32_16x16x32_bf16 v[82:85], v[6:9], v[54:57], v[82:85]
	v_mfma_f32_16x16x32_bf16 v[86:89], v[14:17], v[54:57], v[86:89]
	v_mfma_f32_16x16x32_bf16 v[104:107], v[14:17], v[62:65], v[90:93]
	s_nop 0
	s_nop 0
	v_mfma_f32_16x16x32_bf16 v[90:93], v[18:21], v[34:37], 0
	v_mfma_f32_16x16x32_bf16 v[34:37], v[26:29], v[34:37], 0
	v_mfma_f32_16x16x32_bf16 v[112:115], v[22:25], v[38:41], v[90:93]
	v_mfma_f32_16x16x32_bf16 v[34:37], v[30:33], v[38:41], v[34:37]
	v_mfma_f32_16x16x32_bf16 v[38:41], v[18:21], v[42:45], 0
	v_mfma_f32_16x16x32_bf16 v[42:45], v[26:29], v[42:45], 0
	v_mfma_f32_16x16x32_bf16 v[38:41], v[22:25], v[46:49], v[38:41]
	v_mfma_f32_16x16x32_bf16 v[42:45], v[30:33], v[46:49], v[42:45]
	v_mfma_f32_16x16x32_bf16 v[46:49], v[18:21], v[50:53], 0
	v_mfma_f32_16x16x32_bf16 v[50:53], v[26:29], v[50:53], 0
	v_mfma_f32_16x16x32_bf16 v[46:49], v[22:25], v[54:57], v[46:49]
	v_mfma_f32_16x16x32_bf16 v[50:53], v[30:33], v[54:57], v[50:53]
	v_mfma_f32_16x16x32_bf16 v[54:57], v[18:21], v[58:61], 0
	v_mfma_f32_16x16x32_bf16 v[58:61], v[26:29], v[58:61], 0
	v_mfma_f32_16x16x32_bf16 v[54:57], v[22:25], v[62:65], v[54:57]
	v_mfma_f32_16x16x32_bf16 v[58:61], v[30:33], v[62:65], v[58:61]
	s_nop 0
	s_barrier
	ds_read_b128 v[62:65], v187 offset:16384
	ds_read_b128 v[90:93], v187 offset:17408
	ds_read_b128 v[94:97], v187 offset:18432
	ds_read_b128 v[108:111], v187 offset:19456
	ds_read_b128 v[116:119], v187 offset:20480
	ds_read_b128 v[120:123], v187 offset:21504
	ds_read_b128 v[124:127], v187 offset:22528
	ds_read_b128 v[128:131], v187 offset:23552
	s_mov_b32 m0, s22
	s_nop 0
	global_load_lds_dwordx4 v175, s[14:15]
	s_nop 0
	s_mov_b32 m0, s23
	s_nop 0
	global_load_lds_dwordx4 v177, s[14:15]
	s_add_u32 s14, s6, 0x160100
	s_addc_u32 s15, s7, 0
	s_mov_b32 m0, s26
	s_nop 0
	global_load_lds_dwordx4 v175, s[14:15]
	s_nop 0
	s_mov_b32 m0, s27
	s_nop 0
	global_load_lds_dwordx4 v177, s[14:15]
	s_nop 0
	s_mov_b32 m0, s21
	s_nop 0
	global_load_lds_dwordx4 v174, s[12:13]
	s_nop 0
	s_mov_b32 m0, s28
	s_nop 0
	global_load_lds_dwordx4 v176, s[12:13]
	s_waitcnt vmcnt(44)
	s_waitcnt lgkmcnt(0)
	s_barrier
	s_nop 0
	s_waitcnt lgkmcnt(0)
	v_mfma_f32_16x16x32_bf16 v[136:139], v[10:13], v[62:65], 0
	v_mfma_f32_16x16x32_bf16 v[148:151], v[14:17], v[90:93], v[136:139]
	v_mfma_f32_16x16x32_bf16 v[136:139], v[2:5], v[94:97], 0
	v_mfma_f32_16x16x32_bf16 v[152:155], v[6:9], v[108:111], v[136:139]
	v_mfma_f32_16x16x32_bf16 v[136:139], v[10:13], v[94:97], 0
	v_mfma_f32_16x16x32_bf16 v[132:135], v[2:5], v[62:65], 0
	v_mfma_f32_16x16x32_bf16 v[156:159], v[14:17], v[108:111], v[136:139]
	v_mfma_f32_16x16x32_bf16 v[136:139], v[2:5], v[116:119], 0
	v_mfma_f32_16x16x32_bf16 v[2:5], v[2:5], v[124:127], 0
	v_mfma_f32_16x16x32_bf16 v[132:135], v[6:9], v[90:93], v[132:135]
	v_mfma_f32_16x16x32_bf16 v[160:163], v[6:9], v[120:123], v[136:139]
	v_mfma_f32_16x16x32_bf16 v[2:5], v[6:9], v[128:131], v[2:5]
	v_mfma_f32_16x16x32_bf16 v[6:9], v[10:13], v[124:127], 0
	v_mfma_f32_16x16x32_bf16 v[136:139], v[10:13], v[116:119], 0
	v_mfma_f32_16x16x32_bf16 v[6:9], v[14:17], v[128:131], v[6:9]
	v_mfma_f32_16x16x32_bf16 v[164:167], v[14:17], v[120:123], v[136:139]
	s_nop 0
	s_nop 0
	v_mfma_f32_16x16x32_bf16 v[10:13], v[18:21], v[62:65], 0
	v_mfma_f32_16x16x32_bf16 v[168:171], v[22:25], v[90:93], v[10:13]
	v_mfma_f32_16x16x32_bf16 v[10:13], v[26:29], v[62:65], 0
	v_mfma_f32_16x16x32_bf16 v[178:181], v[30:33], v[90:93], v[10:13]
	v_mfma_f32_16x16x32_bf16 v[10:13], v[18:21], v[94:97], 0
	v_mfma_f32_16x16x32_bf16 v[192:195], v[22:25], v[108:111], v[10:13]
	v_mfma_f32_16x16x32_bf16 v[10:13], v[26:29], v[94:97], 0
	v_mfma_f32_16x16x32_bf16 v[196:199], v[30:33], v[108:111], v[10:13]
	v_mfma_f32_16x16x32_bf16 v[10:13], v[18:21], v[116:119], 0
	v_mfma_f32_16x16x32_bf16 v[200:203], v[22:25], v[120:123], v[10:13]
	v_mfma_f32_16x16x32_bf16 v[10:13], v[26:29], v[116:119], 0
	v_mfma_f32_16x16x32_bf16 v[120:123], v[30:33], v[120:123], v[10:13]
	v_mfma_f32_16x16x32_bf16 v[10:13], v[18:21], v[124:127], 0
	v_mfma_f32_16x16x32_bf16 v[204:207], v[22:25], v[128:131], v[10:13]
	v_mfma_f32_16x16x32_bf16 v[10:13], v[26:29], v[124:127], 0
	v_mfma_f32_16x16x32_bf16 v[124:127], v[30:33], v[128:131], v[10:13]
	s_nop 0
	s_barrier
	s_nop 4
	ds_read_b128 v[10:13], v189
	ds_read_b128 v[14:17], v189 offset:1024
	ds_read_b128 v[20:23], v189 offset:2048
	ds_read_b128 v[24:27], v189 offset:3072
	ds_read_b128 v[208:211], v190
	ds_read_b128 v[212:215], v190 offset:1024
	ds_read_b128 v[216:219], v190 offset:2048
	ds_read_b128 v[188:191], v190 offset:3072
	ds_read_b128 v[28:31], v187 offset:32768
	ds_read_b128 v[62:65], v187 offset:33792
	ds_read_b128 v[220:223], v187 offset:34816
	ds_read_b128 v[224:227], v187 offset:35840
	ds_read_b128 v[228:231], v187 offset:36864
	ds_read_b128 v[232:235], v187 offset:37888
	ds_read_b128 v[236:239], v187 offset:38912
	ds_read_b128 v[240:243], v187 offset:39936
	s_add_u32 s12, s8, 0x160100
	s_addc_u32 s13, s9, 0
	s_mov_b32 m0, s29
	s_nop 0
	global_load_lds_dwordx4 v174, s[12:13]
	s_nop 0
	s_mov_b32 m0, s30
	s_nop 0
	global_load_lds_dwordx4 v176, s[12:13]
	s_waitcnt vmcnt(44)
	s_waitcnt lgkmcnt(0)
	s_barrier
; #define PG8_BAR __builtin_amdgcn_s_barrier()
; template <class Epi, class Sched, bool ALIGN_EPI = false, bool SP2 = false>
; __device__ __forceinline__ void gemm_phase(PG8_LAS unsigned char* lds, const Gemm g, const Sched& S, const Epi& E) {
;     ...
;         cur = nxt; cA = nA; cB = nB; ++ui;
;         if constexpr (ALIGN_EPI) { if (wr == 1) PG8_BAR; }
;         if constexpr (DRO) {
;             const char* a1 = cA + kstep; const char* a2 = cA + 2 * kstep; const char* b2 = cB + 2 * kstep; const char* a3 = a2 + kstep; const char* b3 = b2 + kstep;
;             PG8_TRIP(false, asm volatile("s_waitcnt vmcnt(%0)" :: "n"(8 + Epi::NVM) : "memory"));
;         }
	s_nop 0
	s_waitcnt lgkmcnt(0)
	v_mfma_f32_16x16x32_bf16 v[66:69], v[10:13], v[28:31], v[66:69]
	v_mfma_f32_16x16x32_bf16 v[144:147], v[14:17], v[62:65], v[66:69]
	v_mfma_f32_16x16x32_bf16 v[66:69], v[20:23], v[28:31], v[70:73]
	v_mfma_f32_16x16x32_bf16 v[140:143], v[24:27], v[62:65], v[66:69]
	v_mfma_f32_16x16x32_bf16 v[66:69], v[10:13], v[220:223], v[74:77]
	v_mfma_f32_16x16x32_bf16 v[116:119], v[14:17], v[224:227], v[66:69]
	v_mfma_f32_16x16x32_bf16 v[66:69], v[20:23], v[220:223], v[78:81]
	v_mfma_f32_16x16x32_bf16 v[108:111], v[24:27], v[224:227], v[66:69]
	v_mfma_f32_16x16x32_bf16 v[66:69], v[10:13], v[228:231], v[82:85]
	v_mfma_f32_16x16x32_bf16 v[96:99], v[14:17], v[232:235], v[66:69]
	v_mfma_f32_16x16x32_bf16 v[66:69], v[20:23], v[228:231], v[86:89]
	v_mfma_f32_16x16x32_bf16 v[92:95], v[24:27], v[232:235], v[66:69]
	v_mfma_f32_16x16x32_bf16 v[66:69], v[10:13], v[236:239], v[100:103]
	v_mfma_f32_16x16x32_bf16 v[80:83], v[14:17], v[240:243], v[66:69]
	v_mfma_f32_16x16x32_bf16 v[66:69], v[20:23], v[236:239], v[104:107]
	v_mfma_f32_16x16x32_bf16 v[76:79], v[24:27], v[240:243], v[66:69]
	s_nop 0
	s_nop 0
	v_mfma_f32_16x16x32_bf16 v[66:69], v[208:211], v[28:31], v[112:115]
	v_mfma_f32_16x16x32_bf16 v[28:31], v[216:219], v[28:31], v[34:37]
	v_mfma_f32_16x16x32_bf16 v[128:131], v[188:191], v[62:65], v[28:31]
	v_mfma_f32_16x16x32_bf16 v[28:31], v[208:211], v[220:223], v[38:41]
	v_mfma_f32_16x16x32_bf16 v[104:107], v[212:215], v[224:227], v[28:31]
	v_mfma_f32_16x16x32_bf16 v[28:31], v[216:219], v[220:223], v[42:45]
	v_mfma_f32_16x16x32_bf16 v[100:103], v[188:191], v[224:227], v[28:31]
	v_mfma_f32_16x16x32_bf16 v[28:31], v[208:211], v[228:231], v[46:49]
	v_mfma_f32_16x16x32_bf16 v[88:91], v[212:215], v[232:235], v[28:31]
	v_mfma_f32_16x16x32_bf16 v[28:31], v[216:219], v[228:231], v[50:53]
	v_mfma_f32_16x16x32_bf16 v[84:87], v[188:191], v[232:235], v[28:31]
	v_mfma_f32_16x16x32_bf16 v[28:31], v[208:211], v[236:239], v[54:57]
	v_mfma_f32_16x16x32_bf16 v[72:75], v[212:215], v[240:243], v[28:31]
	v_mfma_f32_16x16x32_bf16 v[28:31], v[216:219], v[236:239], v[58:61]
	v_mfma_f32_16x16x32_bf16 v[136:139], v[212:215], v[62:65], v[66:69]
	v_mfma_f32_16x16x32_bf16 v[68:71], v[188:191], v[240:243], v[28:31]
	s_nop 0
	s_barrier
	ds_read_b128 v[36:39], v187 offset:49152
	ds_read_b128 v[40:43], v187 offset:50176
	ds_read_b128 v[112:115], v187 offset:51200
	ds_read_b128 v[220:223], v187 offset:52224
	ds_read_b128 v[224:227], v187 offset:53248
	ds_read_b128 v[228:231], v187 offset:54272
	ds_read_b128 v[232:235], v187 offset:55296
	ds_read_b128 v[236:239], v187 offset:56320
	s_add_u32 s12, s6, 0x180
	s_addc_u32 s13, s7, 0
	s_mov_b32 m0, s34
	s_nop 0
	global_load_lds_dwordx4 v175, s[12:13]
	s_nop 0
	s_mov_b32 m0, s35
	s_nop 0
	global_load_lds_dwordx4 v177, s[12:13]
	s_add_u32 s12, s6, 0x160180
	s_addc_u32 s13, s7, 0
	s_mov_b32 m0, s40
	s_nop 0
	global_load_lds_dwordx4 v175, s[12:13]
	s_nop 0
	s_mov_b32 m0, s41
	s_nop 0
	global_load_lds_dwordx4 v177, s[12:13]
	s_nop 0
	s_mov_b32 m0, s36
	s_nop 0
	global_load_lds_dwordx4 v174, s[10:11]
	s_nop 0
	s_mov_b32 m0, s37
	s_nop 0
	global_load_lds_dwordx4 v176, s[10:11]
	s_waitcnt vmcnt(8)
	s_waitcnt lgkmcnt(0)
	s_barrier
	s_nop 0
	s_waitcnt lgkmcnt(0)
	v_mfma_f32_16x16x32_bf16 v[28:31], v[10:13], v[36:39], v[132:135]
	v_mfma_f32_16x16x32_bf16 v[64:67], v[14:17], v[40:43], v[28:31]
	v_mfma_f32_16x16x32_bf16 v[28:31], v[20:23], v[36:39], v[148:151]
	v_mfma_f32_16x16x32_bf16 v[60:63], v[24:27], v[40:43], v[28:31]
	v_mfma_f32_16x16x32_bf16 v[28:31], v[10:13], v[112:115], v[152:155]
	v_mfma_f32_16x16x32_bf16 v[48:51], v[14:17], v[220:223], v[28:31]
	v_mfma_f32_16x16x32_bf16 v[28:31], v[20:23], v[112:115], v[156:159]
	v_mfma_f32_16x16x32_bf16 v[44:47], v[24:27], v[220:223], v[28:31]
	v_mfma_f32_16x16x32_bf16 v[28:31], v[10:13], v[224:227], v[160:163]
	v_mfma_f32_16x16x32_bf16 v[2:5], v[10:13], v[232:235], v[2:5]
	v_mfma_f32_16x16x32_bf16 v[32:35], v[14:17], v[228:231], v[28:31]
	v_mfma_f32_16x16x32_bf16 v[28:31], v[20:23], v[224:227], v[164:167]
	v_mfma_f32_16x16x32_bf16 v[16:19], v[14:17], v[236:239], v[2:5]
	v_mfma_f32_16x16x32_bf16 v[2:5], v[20:23], v[232:235], v[6:9]
	v_mfma_f32_16x16x32_bf16 v[28:31], v[24:27], v[228:231], v[28:31]
	v_mfma_f32_16x16x32_bf16 v[12:15], v[24:27], v[236:239], v[2:5]
	s_nop 0
	s_nop 0
	v_mfma_f32_16x16x32_bf16 v[2:5], v[208:211], v[36:39], v[168:171]
	v_mfma_f32_16x16x32_bf16 v[56:59], v[212:215], v[40:43], v[2:5]
	v_mfma_f32_16x16x32_bf16 v[2:5], v[216:219], v[36:39], v[178:181]
	v_mfma_f32_16x16x32_bf16 v[52:55], v[188:191], v[40:43], v[2:5]
	v_mfma_f32_16x16x32_bf16 v[2:5], v[208:211], v[112:115], v[192:195]
	v_mfma_f32_16x16x32_bf16 v[40:43], v[212:215], v[220:223], v[2:5]
	v_mfma_f32_16x16x32_bf16 v[2:5], v[216:219], v[112:115], v[196:199]
	v_mfma_f32_16x16x32_bf16 v[36:39], v[188:191], v[220:223], v[2:5]
	v_mfma_f32_16x16x32_bf16 v[2:5], v[208:211], v[224:227], v[200:203]
	v_mfma_f32_16x16x32_bf16 v[24:27], v[212:215], v[228:231], v[2:5]
	v_mfma_f32_16x16x32_bf16 v[2:5], v[216:219], v[224:227], v[120:123]
	v_mfma_f32_16x16x32_bf16 v[20:23], v[188:191], v[228:231], v[2:5]
	v_mfma_f32_16x16x32_bf16 v[2:5], v[208:211], v[232:235], v[204:207]
	v_mfma_f32_16x16x32_bf16 v[8:11], v[212:215], v[236:239], v[2:5]
	v_mfma_f32_16x16x32_bf16 v[2:5], v[216:219], v[232:235], v[124:127]
	v_mfma_f32_16x16x32_bf16 v[4:7], v[188:191], v[236:239], v[2:5]
	s_nop 0
	s_barrier
	s_mov_b64 s[12:13], 0
	s_branch .LBB0_1209

; __device__ __forceinline__ int mk_tid() { return mk_wave() * 64 + mk_lane(); }
;     __host__ __device__ bool next(int i, Unit& u) const { return StaticOrder::next(i >> 1, u); }
; template <class Epi, class Sched, bool ALIGN_EPI = false, bool SP2 = false>
; __device__ __forceinline__ void gemm_phase(PG8_LAS unsigned char* lds, const Gemm g, const Sched& S, const Epi& E) {
;     int tid_ = mk_tid(); asm volatile("" : "+v"(tid_));
;     const int tid = tid_, wid = __builtin_amdgcn_readfirstlane(tid >> 6), lane = tid & 63, wr = wid >> 2, wc = wid & 3, fr = lane & 15, fq = lane >> 4;
;     const int K = g.K, nt = K / BK;
;     unsigned voffA[2], voffB[2];
; #pragma unroll
;     for (int i = 0; i < 2; ++i) { int R, C; stage_rc(tid * 16 + i * 8192, R, C); const int Rb = Epi::PERM ? ((R & ~31) + perm32(R & 31)) : R;
;         voffA[i] = (unsigned)(R * g.lda + C) * 2u; voffB[i] = (unsigned)(Rb * g.ldb + C) * 2u; }
;     const size_t kstep = (size_t)(BK * 2);
;     const size_t hsA = (size_t)HALF * g.lda * 2, hsB = (size_t)HALF * g.ldb * 2;
;     const size_t tsA = 2 * hsA, tsB = 2 * hsB;
;     const unsigned ldsbase = (unsigned)(unsigned long long)lds;
;     const unsigned ldsw = (unsigned)wid * 1024u;
;     const int aoff = lds_byte(wr * 64 + fr, fq * 8), boff = lds_byte(wc * 32 + fr, fq * 8);
;     ...
;     Unit cur, nxt; int ui = 0; bool epi_ran = false;
;     if (!S.next(0, cur)) return;
;     f32x4 acc[2][2][4][2];
; #pragma unroll
;     for (int a = 0; a < 2; ++a)
; #pragma unroll
;         for (int b = 0; b < 2; ++b)
; #pragma unroll
;             for (int m = 0; m < 4; ++m)
; #pragma unroll
;                 for (int n = 0; n < 2; ++n) acc[a][b][m][n] = (f32x4){0.f, 0.f, 0.f, 0.f};
;     bf16x8 At[4][2], B0[2][2], B1[2][2];
;     const char* cA = (const char*)g.A + (size_t)cur.pm * tsA + (size_t)cur.k0 * 2; const char* cB = (const char*)g.Bt + (size_t)cur.pn * tsB + (size_t)cur.k0 * 2;
;     S.a_ready(cur);
;     if constexpr (SP2) {
;         PG8_STAGE(PG8_SB(0, 0), cB, voffB); PG8_STAGE(PG8_SB(0, 1), cB + hsB, voffB); PG8_STAGE(PG8_SA(0, 0), cA, voffA); PG8_STAGE(PG8_SA(0, 1), cA + hsA, voffA);
;         if (wr == 1) PG8_BAR;
;         PG8_WAIT_V(2); PG8_BAR;
;         PG8_STAGE(PG8_SB(1, 0), cB + kstep, voffB); PG8_STAGE(PG8_SA(1, 0), cA + kstep, voffA); PG8_STAGE(PG8_SB(1, 1), cB + hsB + kstep, voffB);
;         PG8_WAIT_V(6); PG8_BAR;
.LBB0_1236:
	v_bfe_u32 v2, v0, 4, 2
	s_add_u32 s35, s72, 0x58400000
	v_and_b32_e32 v3, 15, v0
	v_lshlrev_b32_e32 v5, 4, v2
	v_lshlrev_b32_e32 v0, 2, v0
	s_addc_u32 s36, s73, 0
	v_lshl_or_b32 v4, s7, 6, v3
	v_lshl_or_b32 v3, v3, 6, v5
	s_lshl_b32 s7, s7, 13
	v_and_b32_e32 v0, 32, v0
	v_bitop3_b32 v5, v3, s7, v0 bitop3:0xde
	s_lshl_b32 s7, s8, 5
	s_and_b32 s7, s7, 0x60
	s_lshl_b32 s8, s7, 7
	s_add_i32 s37, s26, 0x18000
	v_bitop3_b32 v3, v3, s8, v0 bitop3:0xde
	s_add_u32 s8, s16, 0x80
	s_waitcnt vmcnt(2)
	s_barrier
	s_addc_u32 s9, s17, 0
	s_mov_b32 m0, s37
	s_nop 0
	global_load_lds_dwordx4 v130, s[8:9]
	s_add_i32 s40, s26, 0x1a000
	s_add_i32 s41, s26, 0x8000
	s_mov_b32 m0, s40
	s_nop 0
	global_load_lds_dwordx4 v131, s[8:9]
	s_add_u32 s8, s18, 0x80
	s_addc_u32 s9, s19, 0
	s_mov_b32 m0, s41
	s_nop 0
	global_load_lds_dwordx4 v130, s[8:9]
	s_add_i32 s44, s26, 0xa000
	s_add_i32 s45, s26, 0x1c000
	s_mov_b32 m0, s44
	s_nop 0
	global_load_lds_dwordx4 v131, s[8:9]
	s_add_u32 s8, s16, 0x160080
	s_addc_u32 s9, s17, 0
	s_mov_b32 m0, s45
	s_nop 0
	global_load_lds_dwordx4 v130, s[8:9]
	s_add_i32 s46, s26, 0x1e000
	s_mov_b32 m0, s46
	s_nop 0
	global_load_lds_dwordx4 v131, s[8:9]
	s_add_i32 s47, s26, 0xc000
	s_waitcnt vmcnt(6)
	s_cmpk_lt_u32 s6, 0x100
	v_mov_b32_e32 v82, v1
	v_mov_b32_e32 v83, v1
	v_mov_b32_e32 v84, v1
	v_mov_b32_e32 v85, v1
	s_cselect_b64 s[8:9], -1, 0
	v_lshlrev_b32_e32 v0, 2, v2
	v_add_u32_e32 v132, 0xffffc000, v4
	s_lshl_b32 s84, s7, 2
	v_add_u32_e32 v133, 0, v3
	v_add_u32_e32 v134, 0, v5
	v_mov_b64_e32 v[96:97], v[84:85]
	v_mov_b64_e32 v[112:113], v[84:85]
	v_mov_b64_e32 v[108:109], v[84:85]
	v_mov_b64_e32 v[120:121], v[84:85]
	v_mov_b64_e32 v[116:117], v[84:85]
	v_mov_b64_e32 v[128:129], v[84:85]
	v_mov_b64_e32 v[124:125], v[84:85]
	v_mov_b64_e32 v[70:71], v[82:83]
	v_mov_b64_e32 v[66:67], v[82:83]
	v_mov_b64_e32 v[78:79], v[82:83]
	v_mov_b64_e32 v[74:75], v[82:83]
	v_mov_b64_e32 v[92:93], v[84:85]
	v_mov_b64_e32 v[88:89], v[84:85]
	v_mov_b64_e32 v[104:105], v[84:85]
	v_mov_b64_e32 v[100:101], v[84:85]
	v_mov_b64_e32 v[38:39], v[82:83]
	v_mov_b64_e32 v[34:35], v[82:83]
	v_mov_b64_e32 v[46:47], v[82:83]
	v_mov_b64_e32 v[42:43], v[82:83]
	v_mov_b64_e32 v[54:55], v[82:83]
	v_mov_b64_e32 v[50:51], v[82:83]
	v_mov_b64_e32 v[62:63], v[82:83]
	v_mov_b64_e32 v[58:59], v[82:83]
	v_mov_b64_e32 v[6:7], v[82:83]
	v_mov_b64_e32 v[2:3], v[82:83]
	v_mov_b64_e32 v[14:15], v[82:83]
	v_mov_b64_e32 v[10:11], v[82:83]
	v_mov_b64_e32 v[22:23], v[82:83]
	v_mov_b64_e32 v[18:19], v[82:83]
	v_mov_b64_e32 v[30:31], v[82:83]
	v_mov_b64_e32 v[26:27], v[82:83]
	v_readlane_b32 s6, v254, 33
	s_add_i32 s48, s26, 0xe000
	s_mov_b32 s20, 0
	v_lshlrev_b32_e32 v0, 2, v0
	v_mov_b64_e32 v[94:95], v[82:83]
	v_mov_b64_e32 v[110:111], v[82:83]
	v_mov_b64_e32 v[106:107], v[82:83]
	v_mov_b64_e32 v[118:119], v[82:83]
	v_mov_b64_e32 v[114:115], v[82:83]
	v_mov_b64_e32 v[126:127], v[82:83]
	v_mov_b64_e32 v[122:123], v[82:83]
	v_mov_b64_e32 v[72:73], v[84:85]
	v_mov_b64_e32 v[68:69], v[84:85]
	v_mov_b64_e32 v[80:81], v[84:85]
	v_mov_b64_e32 v[76:77], v[84:85]
	v_mov_b64_e32 v[90:91], v[82:83]
	v_mov_b64_e32 v[86:87], v[82:83]
	v_mov_b64_e32 v[102:103], v[82:83]
	v_mov_b64_e32 v[98:99], v[82:83]
	v_mov_b64_e32 v[40:41], v[84:85]
	v_mov_b64_e32 v[36:37], v[84:85]
	v_mov_b64_e32 v[48:49], v[84:85]
	v_mov_b64_e32 v[44:45], v[84:85]
	v_mov_b64_e32 v[56:57], v[84:85]
	v_mov_b64_e32 v[52:53], v[84:85]
	v_mov_b64_e32 v[64:65], v[84:85]
	v_mov_b64_e32 v[60:61], v[84:85]
	v_mov_b64_e32 v[8:9], v[84:85]
	v_mov_b64_e32 v[4:5], v[84:85]
	v_mov_b64_e32 v[16:17], v[84:85]
	v_mov_b64_e32 v[12:13], v[84:85]
	v_mov_b64_e32 v[24:25], v[84:85]
	v_mov_b64_e32 v[20:21], v[84:85]
	v_mov_b64_e32 v[32:33], v[84:85]
	v_mov_b64_e32 v[28:29], v[84:85]
	v_readlane_b32 s63, v254, 45
	s_mov_b32 s53, s6
	v_readlane_b32 s57, v254, 29
	s_barrier
	v_readlane_b32 s7, v254, 34
	s_getreg_b32 s100, hwreg(HW_REG_HW_ID, 0, 6)
	s_lshl_b32 s100, s100, 2
	s_add_i32 s100, s100, 0x20540
	v_mov_b32_e32 v251, s100
	ds_read_b32 v251, v251
	s_waitcnt lgkmcnt(0)
	v_readfirstlane_b32 s100, v251
	s_cmp_ge_u32 s100, 4
	s_cbranch_scc0 statprio_skip6
	s_setprio 1
statprio_skip6:
	s_branch .LBB0_1239
.LBB0_1237:
	ds_read_b128 v[2:5], v135
	ds_read_b128 v[6:9], v135 offset:1024
	ds_read_b128 v[10:13], v135 offset:2048
	ds_read_b128 v[14:17], v135 offset:3072
	ds_read_b128 v[18:21], v136
	ds_read_b128 v[22:25], v136 offset:1024
	ds_read_b128 v[26:29], v136 offset:2048
	ds_read_b128 v[30:33], v136 offset:3072
	s_add_u32 s16, s12, 0x100
	s_addc_u32 s17, s13, 0
	s_add_u32 s6, s12, 0x180
	s_addc_u32 s7, s13, 0
	s_add_u32 s18, s14, 0x100
	s_addc_u32 s19, s15, 0
	ds_read_b128 v[34:37], v134
	ds_read_b128 v[38:41], v134 offset:1024
	ds_read_b128 v[42:45], v134 offset:2048
	ds_read_b128 v[46:49], v134 offset:3072
	ds_read_b128 v[50:53], v134 offset:4096
	ds_read_b128 v[54:57], v134 offset:5120
	ds_read_b128 v[58:61], v134 offset:6144
	ds_read_b128 v[62:65], v134 offset:7168
	s_waitcnt vmcnt(40)
	s_waitcnt lgkmcnt(0)
	s_barrier
	s_nop 0
	s_waitcnt lgkmcnt(7)
	v_mfma_f32_16x16x32_bf16 v[66:69], v[2:5], v[34:37], 0
	v_mfma_f32_16x16x32_bf16 v[70:73], v[10:13], v[34:37], 0
	s_waitcnt lgkmcnt(5)
	v_mfma_f32_16x16x32_bf16 v[74:77], v[2:5], v[42:45], 0
	v_mfma_f32_16x16x32_bf16 v[78:81], v[10:13], v[42:45], 0
	s_waitcnt lgkmcnt(3)
	v_mfma_f32_16x16x32_bf16 v[82:85], v[2:5], v[50:53], 0
	v_mfma_f32_16x16x32_bf16 v[86:89], v[10:13], v[50:53], 0
	s_waitcnt lgkmcnt(1)
	v_mfma_f32_16x16x32_bf16 v[90:93], v[2:5], v[58:61], 0
	v_mfma_f32_16x16x32_bf16 v[94:97], v[10:13], v[58:61], 0
	v_mfma_f32_16x16x32_bf16 v[66:69], v[6:9], v[38:41], v[66:69]
	v_mfma_f32_16x16x32_bf16 v[70:73], v[14:17], v[38:41], v[70:73]
	v_mfma_f32_16x16x32_bf16 v[74:77], v[6:9], v[46:49], v[74:77]
	v_mfma_f32_16x16x32_bf16 v[78:81], v[14:17], v[46:49], v[78:81]
	v_mfma_f32_16x16x32_bf16 v[82:85], v[6:9], v[54:57], v[82:85]
	v_mfma_f32_16x16x32_bf16 v[86:89], v[14:17], v[54:57], v[86:89]
	s_waitcnt lgkmcnt(0)
	v_mfma_f32_16x16x32_bf16 v[90:93], v[6:9], v[62:65], v[90:93]
	v_mfma_f32_16x16x32_bf16 v[94:97], v[14:17], v[62:65], v[94:97]
	s_nop 0
	s_nop 0
	v_mfma_f32_16x16x32_bf16 v[98:101], v[18:21], v[34:37], 0
	v_mfma_f32_16x16x32_bf16 v[34:37], v[26:29], v[34:37], 0
	v_mfma_f32_16x16x32_bf16 v[98:101], v[22:25], v[38:41], v[98:101]
	v_mfma_f32_16x16x32_bf16 v[34:37], v[30:33], v[38:41], v[34:37]
	v_mfma_f32_16x16x32_bf16 v[38:41], v[18:21], v[42:45], 0
	v_mfma_f32_16x16x32_bf16 v[42:45], v[26:29], v[42:45], 0
	v_mfma_f32_16x16x32_bf16 v[38:41], v[22:25], v[46:49], v[38:41]
	v_mfma_f32_16x16x32_bf16 v[42:45], v[30:33], v[46:49], v[42:45]
	v_mfma_f32_16x16x32_bf16 v[46:49], v[18:21], v[50:53], 0
	v_mfma_f32_16x16x32_bf16 v[50:53], v[26:29], v[50:53], 0
	v_mfma_f32_16x16x32_bf16 v[102:105], v[30:33], v[54:57], v[50:53]
	v_mfma_f32_16x16x32_bf16 v[50:53], v[18:21], v[58:61], 0
	v_mfma_f32_16x16x32_bf16 v[106:109], v[22:25], v[62:65], v[50:53]
	v_mfma_f32_16x16x32_bf16 v[50:53], v[26:29], v[58:61], 0
	v_mfma_f32_16x16x32_bf16 v[46:49], v[22:25], v[54:57], v[46:49]
	v_mfma_f32_16x16x32_bf16 v[110:113], v[30:33], v[62:65], v[50:53]
	s_nop 0
	s_barrier
	s_nop 3
	ds_read_b128 v[50:53], v134 offset:16384
	ds_read_b128 v[54:57], v134 offset:17408
	ds_read_b128 v[58:61], v134 offset:18432
	ds_read_b128 v[62:65], v134 offset:19456
	ds_read_b128 v[114:117], v134 offset:20480
	ds_read_b128 v[118:121], v134 offset:21504
	ds_read_b128 v[122:125], v134 offset:22528
	ds_read_b128 v[126:129], v134 offset:23552
	s_mov_b32 m0, s27
	s_nop 0
	global_load_lds_dwordx4 v130, s[18:19]
	s_nop 0
	s_mov_b32 m0, s28
	s_nop 0
	global_load_lds_dwordx4 v131, s[18:19]
	s_add_u32 s18, s14, 0x160100
	s_addc_u32 s19, s15, 0
	s_mov_b32 m0, s29
	s_nop 0
	global_load_lds_dwordx4 v130, s[18:19]
	s_nop 0
	s_mov_b32 m0, s30
	s_nop 0
	global_load_lds_dwordx4 v131, s[18:19]
	s_nop 0
	s_mov_b32 m0, s26
	s_nop 0
	global_load_lds_dwordx4 v130, s[16:17]
	s_nop 0
	s_mov_b32 m0, s31
	s_nop 0
	global_load_lds_dwordx4 v131, s[16:17]
	s_waitcnt vmcnt(40)
	s_waitcnt lgkmcnt(0)
	s_barrier
	s_nop 0
	s_waitcnt lgkmcnt(7)
	v_mfma_f32_16x16x32_bf16 v[140:143], v[2:5], v[50:53], 0
	s_waitcnt lgkmcnt(5)
	v_mfma_f32_16x16x32_bf16 v[148:151], v[2:5], v[58:61], 0
	s_waitcnt lgkmcnt(3)
	v_mfma_f32_16x16x32_bf16 v[156:159], v[2:5], v[114:117], 0
	s_waitcnt lgkmcnt(1)
	v_mfma_f32_16x16x32_bf16 v[2:5], v[2:5], v[122:125], 0
	v_mfma_f32_16x16x32_bf16 v[144:147], v[10:13], v[50:53], 0
	v_mfma_f32_16x16x32_bf16 v[152:155], v[10:13], v[58:61], 0
	v_mfma_f32_16x16x32_bf16 v[160:163], v[10:13], v[114:117], 0
	s_waitcnt lgkmcnt(0)
	v_mfma_f32_16x16x32_bf16 v[164:167], v[6:9], v[126:129], v[2:5]
	v_mfma_f32_16x16x32_bf16 v[2:5], v[10:13], v[122:125], 0
	v_mfma_f32_16x16x32_bf16 v[140:143], v[6:9], v[54:57], v[140:143]
	v_mfma_f32_16x16x32_bf16 v[144:147], v[14:17], v[54:57], v[144:147]
	v_mfma_f32_16x16x32_bf16 v[148:151], v[6:9], v[62:65], v[148:151]
	v_mfma_f32_16x16x32_bf16 v[152:155], v[14:17], v[62:65], v[152:155]
	v_mfma_f32_16x16x32_bf16 v[156:159], v[6:9], v[118:121], v[156:159]
	v_mfma_f32_16x16x32_bf16 v[160:163], v[14:17], v[118:121], v[160:163]
	v_mfma_f32_16x16x32_bf16 v[168:171], v[14:17], v[126:129], v[2:5]
	s_nop 0
	s_nop 0
	v_mfma_f32_16x16x32_bf16 v[2:5], v[18:21], v[50:53], 0
	v_mfma_f32_16x16x32_bf16 v[172:175], v[22:25], v[54:57], v[2:5]
	v_mfma_f32_16x16x32_bf16 v[2:5], v[26:29], v[50:53], 0
	v_mfma_f32_16x16x32_bf16 v[176:179], v[30:33], v[54:57], v[2:5]
	v_mfma_f32_16x16x32_bf16 v[2:5], v[18:21], v[58:61], 0
	v_mfma_f32_16x16x32_bf16 v[184:187], v[22:25], v[62:65], v[2:5]
	v_mfma_f32_16x16x32_bf16 v[2:5], v[26:29], v[58:61], 0
	v_mfma_f32_16x16x32_bf16 v[188:191], v[30:33], v[62:65], v[2:5]
	v_mfma_f32_16x16x32_bf16 v[2:5], v[18:21], v[114:117], 0
	v_mfma_f32_16x16x32_bf16 v[192:195], v[22:25], v[118:121], v[2:5]
	v_mfma_f32_16x16x32_bf16 v[2:5], v[26:29], v[114:117], 0
	v_mfma_f32_16x16x32_bf16 v[196:199], v[30:33], v[118:121], v[2:5]
	v_mfma_f32_16x16x32_bf16 v[2:5], v[18:21], v[122:125], 0
	v_mfma_f32_16x16x32_bf16 v[200:203], v[22:25], v[126:129], v[2:5]
	v_mfma_f32_16x16x32_bf16 v[2:5], v[26:29], v[122:125], 0
	v_mfma_f32_16x16x32_bf16 v[204:207], v[30:33], v[126:129], v[2:5]
	s_nop 0
	s_barrier
	ds_read_b128 v[114:117], v137
	ds_read_b128 v[118:121], v137 offset:1024
	ds_read_b128 v[122:125], v137 offset:2048
	ds_read_b128 v[126:129], v137 offset:3072
	ds_read_b128 v[208:211], v138
	ds_read_b128 v[212:215], v138 offset:1024
	ds_read_b128 v[216:219], v138 offset:2048
	ds_read_b128 v[136:139], v138 offset:3072
	ds_read_b128 v[50:53], v134 offset:32768
	ds_read_b128 v[54:57], v134 offset:33792
	ds_read_b128 v[220:223], v134 offset:34816
	ds_read_b128 v[224:227], v134 offset:35840
	ds_read_b128 v[228:231], v134 offset:36864
	ds_read_b128 v[232:235], v134 offset:37888
	ds_read_b128 v[236:239], v134 offset:38912
	ds_read_b128 v[240:243], v134 offset:39936
	s_add_u32 s16, s12, 0x160100
	s_addc_u32 s17, s13, 0
	s_mov_b32 m0, s33
	s_nop 0
	global_load_lds_dwordx4 v130, s[16:17]
	s_nop 0
	s_mov_b32 m0, s34
	s_nop 0
	global_load_lds_dwordx4 v131, s[16:17]
	s_waitcnt vmcnt(40)
	s_waitcnt lgkmcnt(0)
	s_barrier
	s_nop 0
	s_waitcnt lgkmcnt(7)
	v_mfma_f32_16x16x32_bf16 v[2:5], v[114:117], v[50:53], v[66:69]
	s_waitcnt lgkmcnt(6)
	v_mfma_f32_16x16x32_bf16 v[26:29], v[118:121], v[54:57], v[2:5]
	v_mfma_f32_16x16x32_bf16 v[2:5], v[122:125], v[50:53], v[70:73]
	v_mfma_f32_16x16x32_bf16 v[30:33], v[126:129], v[54:57], v[2:5]
	s_waitcnt lgkmcnt(5)
	v_mfma_f32_16x16x32_bf16 v[2:5], v[114:117], v[220:223], v[74:77]
	s_waitcnt lgkmcnt(4)
	v_mfma_f32_16x16x32_bf16 v[18:21], v[118:121], v[224:227], v[2:5]
	v_mfma_f32_16x16x32_bf16 v[2:5], v[122:125], v[220:223], v[78:81]
	v_mfma_f32_16x16x32_bf16 v[22:25], v[126:129], v[224:227], v[2:5]
	s_waitcnt lgkmcnt(3)
	v_mfma_f32_16x16x32_bf16 v[2:5], v[114:117], v[228:231], v[82:85]
	s_waitcnt lgkmcnt(2)
	v_mfma_f32_16x16x32_bf16 v[10:13], v[118:121], v[232:235], v[2:5]
	v_mfma_f32_16x16x32_bf16 v[2:5], v[122:125], v[228:231], v[86:89]
	v_mfma_f32_16x16x32_bf16 v[14:17], v[126:129], v[232:235], v[2:5]
	s_waitcnt lgkmcnt(1)
	v_mfma_f32_16x16x32_bf16 v[2:5], v[114:117], v[236:239], v[90:93]
	v_mfma_f32_16x16x32_bf16 v[6:9], v[122:125], v[236:239], v[94:97]
	s_waitcnt lgkmcnt(0)
	v_mfma_f32_16x16x32_bf16 v[2:5], v[118:121], v[240:243], v[2:5]
	v_mfma_f32_16x16x32_bf16 v[6:9], v[126:129], v[240:243], v[6:9]
	s_nop 0
	s_nop 0
	v_mfma_f32_16x16x32_bf16 v[34:37], v[216:219], v[50:53], v[34:37]
	v_mfma_f32_16x16x32_bf16 v[62:65], v[136:139], v[54:57], v[34:37]
	v_mfma_f32_16x16x32_bf16 v[34:37], v[208:211], v[220:223], v[38:41]
	v_mfma_f32_16x16x32_bf16 v[58:61], v[208:211], v[50:53], v[98:101]
	v_mfma_f32_16x16x32_bf16 v[50:53], v[212:215], v[224:227], v[34:37]
	v_mfma_f32_16x16x32_bf16 v[34:37], v[216:219], v[220:223], v[42:45]
	v_mfma_f32_16x16x32_bf16 v[58:61], v[212:215], v[54:57], v[58:61]
	v_mfma_f32_16x16x32_bf16 v[54:57], v[136:139], v[224:227], v[34:37]
	v_mfma_f32_16x16x32_bf16 v[34:37], v[208:211], v[228:231], v[46:49]
	v_mfma_f32_16x16x32_bf16 v[42:45], v[212:215], v[232:235], v[34:37]
	v_mfma_f32_16x16x32_bf16 v[34:37], v[216:219], v[228:231], v[102:105]
	v_mfma_f32_16x16x32_bf16 v[46:49], v[136:139], v[232:235], v[34:37]
	v_mfma_f32_16x16x32_bf16 v[34:37], v[208:211], v[236:239], v[106:109]
	v_mfma_f32_16x16x32_bf16 v[38:41], v[216:219], v[236:239], v[110:113]
	v_mfma_f32_16x16x32_bf16 v[34:37], v[212:215], v[240:243], v[34:37]
	v_mfma_f32_16x16x32_bf16 v[38:41], v[136:139], v[240:243], v[38:41]
	s_nop 0
	s_barrier
	ds_read_b128 v[82:85], v134 offset:49152
	ds_read_b128 v[94:97], v134 offset:50176
	ds_read_b128 v[106:109], v134 offset:51200
	ds_read_b128 v[110:113], v134 offset:52224
	ds_read_b128 v[220:223], v134 offset:53248
	ds_read_b128 v[224:227], v134 offset:54272
	ds_read_b128 v[228:231], v134 offset:55296
	ds_read_b128 v[232:235], v134 offset:56320
	s_add_u32 s16, s14, 0x180
	s_addc_u32 s17, s15, 0
	s_mov_b32 m0, s37
	s_nop 0
	global_load_lds_dwordx4 v130, s[16:17]
	s_nop 0
	s_mov_b32 m0, s40
	s_nop 0
	global_load_lds_dwordx4 v131, s[16:17]
	s_add_u32 s16, s14, 0x160180
	s_addc_u32 s17, s15, 0
	s_mov_b32 m0, s45
	s_nop 0
	global_load_lds_dwordx4 v130, s[16:17]
	s_nop 0
	s_mov_b32 m0, s46
	s_nop 0
	global_load_lds_dwordx4 v131, s[16:17]
	s_nop 0
	s_mov_b32 m0, s41
	s_nop 0
	global_load_lds_dwordx4 v130, s[6:7]
	s_nop 0
	s_mov_b32 m0, s44
	s_nop 0
	global_load_lds_dwordx4 v131, s[6:7]
	s_waitcnt vmcnt(8)
	s_waitcnt lgkmcnt(0)
	s_barrier
	s_nop 0
	s_waitcnt lgkmcnt(7)
	v_mfma_f32_16x16x32_bf16 v[66:69], v[114:117], v[82:85], v[140:143]
	s_waitcnt lgkmcnt(6)
	v_mfma_f32_16x16x32_bf16 v[98:101], v[118:121], v[94:97], v[66:69]
	v_mfma_f32_16x16x32_bf16 v[66:69], v[122:125], v[82:85], v[144:147]
	v_mfma_f32_16x16x32_bf16 v[102:105], v[126:129], v[94:97], v[66:69]
	s_waitcnt lgkmcnt(5)
	v_mfma_f32_16x16x32_bf16 v[66:69], v[114:117], v[106:109], v[148:151]
	s_waitcnt lgkmcnt(4)
	v_mfma_f32_16x16x32_bf16 v[86:89], v[118:121], v[110:113], v[66:69]
	v_mfma_f32_16x16x32_bf16 v[66:69], v[122:125], v[106:109], v[152:155]
	v_mfma_f32_16x16x32_bf16 v[90:93], v[126:129], v[110:113], v[66:69]
	s_waitcnt lgkmcnt(3)
	v_mfma_f32_16x16x32_bf16 v[66:69], v[114:117], v[220:223], v[156:159]
	s_waitcnt lgkmcnt(2)
	v_mfma_f32_16x16x32_bf16 v[74:77], v[118:121], v[224:227], v[66:69]
	v_mfma_f32_16x16x32_bf16 v[66:69], v[122:125], v[220:223], v[160:163]
	v_mfma_f32_16x16x32_bf16 v[78:81], v[126:129], v[224:227], v[66:69]
	s_waitcnt lgkmcnt(1)
	v_mfma_f32_16x16x32_bf16 v[66:69], v[114:117], v[228:231], v[164:167]
	v_mfma_f32_16x16x32_bf16 v[70:73], v[122:125], v[228:231], v[168:171]
	s_waitcnt lgkmcnt(0)
	v_mfma_f32_16x16x32_bf16 v[66:69], v[118:121], v[232:235], v[66:69]
	v_mfma_f32_16x16x32_bf16 v[70:73], v[126:129], v[232:235], v[70:73]
	s_nop 0
	s_nop 0
	v_mfma_f32_16x16x32_bf16 v[114:117], v[208:211], v[82:85], v[172:175]
	v_mfma_f32_16x16x32_bf16 v[82:85], v[216:219], v[82:85], v[176:179]
	v_mfma_f32_16x16x32_bf16 v[126:129], v[136:139], v[94:97], v[82:85]
	v_mfma_f32_16x16x32_bf16 v[82:85], v[208:211], v[106:109], v[184:187]
	v_mfma_f32_16x16x32_bf16 v[122:125], v[212:215], v[94:97], v[114:117]
	v_mfma_f32_16x16x32_bf16 v[114:117], v[212:215], v[110:113], v[82:85]
	v_mfma_f32_16x16x32_bf16 v[82:85], v[216:219], v[106:109], v[188:191]
	v_mfma_f32_16x16x32_bf16 v[118:121], v[136:139], v[110:113], v[82:85]
	v_mfma_f32_16x16x32_bf16 v[82:85], v[208:211], v[220:223], v[192:195]
	v_mfma_f32_16x16x32_bf16 v[106:109], v[212:215], v[224:227], v[82:85]
	v_mfma_f32_16x16x32_bf16 v[82:85], v[216:219], v[220:223], v[196:199]
	v_mfma_f32_16x16x32_bf16 v[110:113], v[136:139], v[224:227], v[82:85]
	v_mfma_f32_16x16x32_bf16 v[82:85], v[208:211], v[228:231], v[200:203]
	v_mfma_f32_16x16x32_bf16 v[94:97], v[212:215], v[232:235], v[82:85]
	v_mfma_f32_16x16x32_bf16 v[82:85], v[216:219], v[228:231], v[204:207]
	v_mfma_f32_16x16x32_bf16 v[82:85], v[136:139], v[232:235], v[82:85]
	s_nop 0
	s_barrier
	s_mov_b64 s[6:7], 0

;     __host__ __device__ bool next(int i, Unit& u) const { return StaticOrder::next(i >> 1, u); }
;     __device__ __forceinline__ bool next(int i, Unit& u) const { const int s = i * G + c; if (s >= 128) return false; const int t = s >> 2; u.pm = pm0 + (t & 3); u.pn = t >> 2; u.k0 = (s & 3) * ksub; return true; }
; #define PG8_WAIT_V(n) asm volatile("s_waitcnt vmcnt(" #n ")" ::: "memory")
; template <class Epi, class Sched, bool ALIGN_EPI = false, bool SP2 = false>
; __device__ __forceinline__ void gemm_phase(PG8_LAS unsigned char* lds, const Gemm g, const Sched& S, const Epi& E) {
;     ...
;     for (;;) {
;         const bool has_next = S.next(ui + 1, nxt);
;         const char* nA = has_next ? (const char*)g.A + (size_t)nxt.pm * tsA + (size_t)nxt.k0 * 2 : cA; const char* nB = has_next ? (const char*)g.Bt + (size_t)nxt.pn * tsB + (size_t)nxt.k0 * 2 : cB;
;         for (int t = (DRO && ui > 0) ? 2 : 0; t < nt; t += 2) {
;             const bool last = (t == nt - 2);
;             const char* a1 = cA + (size_t)(t + 1) * kstep;
;             const char* a2 = last ? nA : cA + (size_t)(t + 2) * kstep; const char* b2 = last ? nB : cB + (size_t)(t + 2) * kstep;
;             const char* a3 = a2 + kstep; const char* b3 = b2 + kstep;
;             if (last && has_next) S.a_ready(nxt);
;             if constexpr (SP2) {
;             PG8_TRIP(true, PG8_WAIT_V(8));
.LBB0_1246:
	v_add_u32_e32 v135, 0x10000, v133
	v_add_u32_e32 v136, 0x14000, v133
	ds_read_b128 v[138:141], v135
	ds_read_b128 v[142:145], v135 offset:1024
	ds_read_b128 v[146:149], v135 offset:2048
	ds_read_b128 v[150:153], v135 offset:3072
	ds_read_b128 v[154:157], v136
	ds_read_b128 v[158:161], v136 offset:1024
	ds_read_b128 v[162:165], v136 offset:2048
	ds_read_b128 v[166:169], v136 offset:3072
	s_add_u32 s18, s16, 0xffea0080
	s_addc_u32 s19, s17, -1
	s_cmp_eq_u32 s11, 18
	s_cselect_b32 s22, s12, s18
	s_cselect_b32 s23, s13, s19
	s_cselect_b32 s20, s14, s64
	s_cselect_b32 s21, s15, s67
	s_add_u32 s18, s22, 0x80
	s_addc_u32 s19, s23, 0
	ds_read_b128 v[170:173], v134
	ds_read_b128 v[174:177], v134 offset:1024
	ds_read_b128 v[178:181], v134 offset:2048
	ds_read_b128 v[184:187], v134 offset:3072
	ds_read_b128 v[188:191], v134 offset:4096
	ds_read_b128 v[192:195], v134 offset:5120
	ds_read_b128 v[196:199], v134 offset:6144
	ds_read_b128 v[200:203], v134 offset:7168
	s_mov_b32 m0, s47
	s_nop 0
	global_load_lds_dwordx4 v130, s[16:17]
	s_nop 0
	s_mov_b32 m0, s48
	s_nop 0
	global_load_lds_dwordx4 v131, s[16:17]
	s_waitcnt vmcnt(8)
	s_waitcnt lgkmcnt(0)
	s_barrier
	s_nop 0
	s_waitcnt lgkmcnt(7)
	v_mfma_f32_16x16x32_bf16 v[26:29], v[138:141], v[170:173], v[26:29]
	v_mfma_f32_16x16x32_bf16 v[30:33], v[146:149], v[170:173], v[30:33]
	s_waitcnt lgkmcnt(5)
	v_mfma_f32_16x16x32_bf16 v[18:21], v[138:141], v[178:181], v[18:21]
	v_mfma_f32_16x16x32_bf16 v[22:25], v[146:149], v[178:181], v[22:25]
	s_waitcnt lgkmcnt(3)
	v_mfma_f32_16x16x32_bf16 v[10:13], v[138:141], v[188:191], v[10:13]
	v_mfma_f32_16x16x32_bf16 v[14:17], v[146:149], v[188:191], v[14:17]
	s_waitcnt lgkmcnt(1)
	v_mfma_f32_16x16x32_bf16 v[2:5], v[138:141], v[196:199], v[2:5]
	v_mfma_f32_16x16x32_bf16 v[6:9], v[146:149], v[196:199], v[6:9]
	v_mfma_f32_16x16x32_bf16 v[26:29], v[142:145], v[174:177], v[26:29]
	v_mfma_f32_16x16x32_bf16 v[30:33], v[150:153], v[174:177], v[30:33]
	v_mfma_f32_16x16x32_bf16 v[18:21], v[142:145], v[184:187], v[18:21]
	v_mfma_f32_16x16x32_bf16 v[22:25], v[150:153], v[184:187], v[22:25]
	v_mfma_f32_16x16x32_bf16 v[10:13], v[142:145], v[192:195], v[10:13]
	v_mfma_f32_16x16x32_bf16 v[14:17], v[150:153], v[192:195], v[14:17]
	s_waitcnt lgkmcnt(0)
	v_mfma_f32_16x16x32_bf16 v[2:5], v[142:145], v[200:203], v[2:5]
	v_mfma_f32_16x16x32_bf16 v[6:9], v[150:153], v[200:203], v[6:9]
	s_nop 0
	s_nop 0
	v_mfma_f32_16x16x32_bf16 v[58:61], v[154:157], v[170:173], v[58:61]
	v_mfma_f32_16x16x32_bf16 v[62:65], v[162:165], v[170:173], v[62:65]
	v_mfma_f32_16x16x32_bf16 v[50:53], v[154:157], v[178:181], v[50:53]
	v_mfma_f32_16x16x32_bf16 v[54:57], v[162:165], v[178:181], v[54:57]
	v_mfma_f32_16x16x32_bf16 v[42:45], v[154:157], v[188:191], v[42:45]
	v_mfma_f32_16x16x32_bf16 v[46:49], v[162:165], v[188:191], v[46:49]
	v_mfma_f32_16x16x32_bf16 v[34:37], v[154:157], v[196:199], v[34:37]
	v_mfma_f32_16x16x32_bf16 v[38:41], v[162:165], v[196:199], v[38:41]
	v_mfma_f32_16x16x32_bf16 v[58:61], v[158:161], v[174:177], v[58:61]
	v_mfma_f32_16x16x32_bf16 v[62:65], v[166:169], v[174:177], v[62:65]
	v_mfma_f32_16x16x32_bf16 v[50:53], v[158:161], v[184:187], v[50:53]
	v_mfma_f32_16x16x32_bf16 v[54:57], v[166:169], v[184:187], v[54:57]
	v_mfma_f32_16x16x32_bf16 v[42:45], v[158:161], v[192:195], v[42:45]
	v_mfma_f32_16x16x32_bf16 v[46:49], v[166:169], v[192:195], v[46:49]
	v_mfma_f32_16x16x32_bf16 v[34:37], v[158:161], v[200:203], v[34:37]
	v_mfma_f32_16x16x32_bf16 v[38:41], v[166:169], v[200:203], v[38:41]
	s_nop 0
	s_barrier
	ds_read_b128 v[170:173], v134 offset:16384
	ds_read_b128 v[174:177], v134 offset:17408
	ds_read_b128 v[178:181], v134 offset:18432
	ds_read_b128 v[184:187], v134 offset:19456
	ds_read_b128 v[188:191], v134 offset:20480
	ds_read_b128 v[192:195], v134 offset:21504
	ds_read_b128 v[196:199], v134 offset:22528
	ds_read_b128 v[200:203], v134 offset:23552
	s_mov_b32 m0, s27
	s_nop 0
	global_load_lds_dwordx4 v130, s[20:21]
	s_add_u32 s78, s20, 0x160000
	s_mov_b32 m0, s28
	s_nop 0
	global_load_lds_dwordx4 v131, s[20:21]
	s_addc_u32 s79, s21, 0
	s_mov_b32 m0, s29
	s_nop 0
	global_load_lds_dwordx4 v130, s[78:79]
	s_nop 0
	s_mov_b32 m0, s30
	s_nop 0
	global_load_lds_dwordx4 v131, s[78:79]
	s_nop 0
	s_mov_b32 m0, s26
	s_nop 0
	global_load_lds_dwordx4 v130, s[22:23]
	s_nop 0
	s_mov_b32 m0, s31
	s_nop 0
	global_load_lds_dwordx4 v131, s[22:23]
	s_waitcnt vmcnt(8)
	s_waitcnt lgkmcnt(0)
	s_barrier
	s_nop 0
	s_waitcnt lgkmcnt(7)
	v_mfma_f32_16x16x32_bf16 v[98:101], v[138:141], v[170:173], v[98:101]
	v_mfma_f32_16x16x32_bf16 v[102:105], v[146:149], v[170:173], v[102:105]
	s_waitcnt lgkmcnt(5)
	v_mfma_f32_16x16x32_bf16 v[86:89], v[138:141], v[178:181], v[86:89]
	v_mfma_f32_16x16x32_bf16 v[90:93], v[146:149], v[178:181], v[90:93]
	s_waitcnt lgkmcnt(3)
	v_mfma_f32_16x16x32_bf16 v[74:77], v[138:141], v[188:191], v[74:77]
	v_mfma_f32_16x16x32_bf16 v[78:81], v[146:149], v[188:191], v[78:81]
	s_waitcnt lgkmcnt(1)
	v_mfma_f32_16x16x32_bf16 v[66:69], v[138:141], v[196:199], v[66:69]
	v_mfma_f32_16x16x32_bf16 v[70:73], v[146:149], v[196:199], v[70:73]
	v_mfma_f32_16x16x32_bf16 v[98:101], v[142:145], v[174:177], v[98:101]
	v_mfma_f32_16x16x32_bf16 v[102:105], v[150:153], v[174:177], v[102:105]
	v_mfma_f32_16x16x32_bf16 v[86:89], v[142:145], v[184:187], v[86:89]
	v_mfma_f32_16x16x32_bf16 v[90:93], v[150:153], v[184:187], v[90:93]
	v_mfma_f32_16x16x32_bf16 v[74:77], v[142:145], v[192:195], v[74:77]
	v_mfma_f32_16x16x32_bf16 v[78:81], v[150:153], v[192:195], v[78:81]
	s_waitcnt lgkmcnt(0)
	v_mfma_f32_16x16x32_bf16 v[66:69], v[142:145], v[200:203], v[66:69]
	v_mfma_f32_16x16x32_bf16 v[70:73], v[150:153], v[200:203], v[70:73]
	s_nop 0
	s_nop 0
	v_mfma_f32_16x16x32_bf16 v[122:125], v[154:157], v[170:173], v[122:125]
	v_mfma_f32_16x16x32_bf16 v[126:129], v[162:165], v[170:173], v[126:129]
	v_mfma_f32_16x16x32_bf16 v[114:117], v[154:157], v[178:181], v[114:117]
	v_mfma_f32_16x16x32_bf16 v[118:121], v[162:165], v[178:181], v[118:121]
	v_mfma_f32_16x16x32_bf16 v[106:109], v[154:157], v[188:191], v[106:109]
	v_mfma_f32_16x16x32_bf16 v[110:113], v[162:165], v[188:191], v[110:113]
	v_mfma_f32_16x16x32_bf16 v[94:97], v[154:157], v[196:199], v[94:97]
	v_mfma_f32_16x16x32_bf16 v[82:85], v[162:165], v[196:199], v[82:85]
	v_mfma_f32_16x16x32_bf16 v[122:125], v[158:161], v[174:177], v[122:125]
	v_mfma_f32_16x16x32_bf16 v[126:129], v[166:169], v[174:177], v[126:129]
	v_mfma_f32_16x16x32_bf16 v[114:117], v[158:161], v[184:187], v[114:117]
	v_mfma_f32_16x16x32_bf16 v[118:121], v[166:169], v[184:187], v[118:121]
	v_mfma_f32_16x16x32_bf16 v[106:109], v[158:161], v[192:195], v[106:109]
	v_mfma_f32_16x16x32_bf16 v[110:113], v[166:169], v[192:195], v[110:113]
	v_mfma_f32_16x16x32_bf16 v[94:97], v[158:161], v[200:203], v[94:97]
	v_mfma_f32_16x16x32_bf16 v[82:85], v[166:169], v[200:203], v[82:85]
	s_nop 0
	s_barrier
;     __host__ __device__ bool next(int i, Unit& u) const { return StaticOrder::next(i >> 1, u); }
;     __device__ __forceinline__ bool next(int i, Unit& u) const { const int s = i * G + c; if (s >= 128) return false; const int t = s >> 2; u.pm = pm0 + (t & 3); u.pn = t >> 2; u.k0 = (s & 3) * ksub; return true; }
; #define PG8_WAIT_V(n) asm volatile("s_waitcnt vmcnt(" #n ")" ::: "memory")
; template <class Epi, class Sched, bool ALIGN_EPI = false, bool SP2 = false>
; __device__ __forceinline__ void gemm_phase(PG8_LAS unsigned char* lds, const Gemm g, const Sched& S, const Epi& E) {
;     ...
;     for (;;) {
;         const bool has_next = S.next(ui + 1, nxt);
;         const char* nA = has_next ? (const char*)g.A + (size_t)nxt.pm * tsA + (size_t)nxt.k0 * 2 : cA; const char* nB = has_next ? (const char*)g.Bt + (size_t)nxt.pn * tsB + (size_t)nxt.k0 * 2 : cB;
;         for (int t = (DRO && ui > 0) ? 2 : 0; t < nt; t += 2) {
;             const bool last = (t == nt - 2);
;             const char* a1 = cA + (size_t)(t + 1) * kstep;
;             const char* a2 = last ? nA : cA + (size_t)(t + 2) * kstep; const char* b2 = last ? nB : cB + (size_t)(t + 2) * kstep;
;             const char* a3 = a2 + kstep; const char* b3 = b2 + kstep;
;             if (last && has_next) S.a_ready(nxt);
;             if constexpr (SP2) {
;             PG8_TRIP(true, PG8_WAIT_V(8));
	v_add_u32_e32 v137, 0x18000, v133
	v_add_u32_e32 v138, 0x1c000, v133
	ds_read_b128 v[140:143], v137
	ds_read_b128 v[144:147], v137 offset:1024
	ds_read_b128 v[148:151], v137 offset:2048
	ds_read_b128 v[152:155], v137 offset:3072
	ds_read_b128 v[156:159], v138
	ds_read_b128 v[160:163], v138 offset:1024
	ds_read_b128 v[164:167], v138 offset:2048
	ds_read_b128 v[168:171], v138 offset:3072
	ds_read_b128 v[172:175], v134 offset:32768
	ds_read_b128 v[176:179], v134 offset:33792
	ds_read_b128 v[184:187], v134 offset:34816
	ds_read_b128 v[188:191], v134 offset:35840
	ds_read_b128 v[192:195], v134 offset:36864
	ds_read_b128 v[196:199], v134 offset:37888
	ds_read_b128 v[200:203], v134 offset:38912
	ds_read_b128 v[204:207], v134 offset:39936
	s_add_u32 s22, s22, 0x160000
	s_addc_u32 s23, s23, 0
	s_mov_b32 m0, s33
	s_nop 0
	global_load_lds_dwordx4 v130, s[22:23]
	s_nop 0
	s_mov_b32 m0, s34
	s_nop 0
	global_load_lds_dwordx4 v131, s[22:23]
	s_waitcnt vmcnt(8)
	s_waitcnt lgkmcnt(0)
	s_barrier
	s_nop 0
	s_waitcnt lgkmcnt(7)
	v_mfma_f32_16x16x32_bf16 v[26:29], v[140:143], v[172:175], v[26:29]
	v_mfma_f32_16x16x32_bf16 v[30:33], v[148:151], v[172:175], v[30:33]
	s_waitcnt lgkmcnt(5)
	v_mfma_f32_16x16x32_bf16 v[18:21], v[140:143], v[184:187], v[18:21]
	v_mfma_f32_16x16x32_bf16 v[22:25], v[148:151], v[184:187], v[22:25]
	s_waitcnt lgkmcnt(3)
	v_mfma_f32_16x16x32_bf16 v[10:13], v[140:143], v[192:195], v[10:13]
	v_mfma_f32_16x16x32_bf16 v[14:17], v[148:151], v[192:195], v[14:17]
	s_waitcnt lgkmcnt(1)
	v_mfma_f32_16x16x32_bf16 v[2:5], v[140:143], v[200:203], v[2:5]
	v_mfma_f32_16x16x32_bf16 v[6:9], v[148:151], v[200:203], v[6:9]
	v_mfma_f32_16x16x32_bf16 v[26:29], v[144:147], v[176:179], v[26:29]
	v_mfma_f32_16x16x32_bf16 v[30:33], v[152:155], v[176:179], v[30:33]
	v_mfma_f32_16x16x32_bf16 v[18:21], v[144:147], v[188:191], v[18:21]
	v_mfma_f32_16x16x32_bf16 v[22:25], v[152:155], v[188:191], v[22:25]
	v_mfma_f32_16x16x32_bf16 v[10:13], v[144:147], v[196:199], v[10:13]
	v_mfma_f32_16x16x32_bf16 v[14:17], v[152:155], v[196:199], v[14:17]
	s_waitcnt lgkmcnt(0)
	v_mfma_f32_16x16x32_bf16 v[2:5], v[144:147], v[204:207], v[2:5]
	v_mfma_f32_16x16x32_bf16 v[6:9], v[152:155], v[204:207], v[6:9]
	s_nop 0
	s_nop 0
	v_mfma_f32_16x16x32_bf16 v[58:61], v[156:159], v[172:175], v[58:61]
	v_mfma_f32_16x16x32_bf16 v[62:65], v[164:167], v[172:175], v[62:65]
	v_mfma_f32_16x16x32_bf16 v[50:53], v[156:159], v[184:187], v[50:53]
	v_mfma_f32_16x16x32_bf16 v[54:57], v[164:167], v[184:187], v[54:57]
	v_mfma_f32_16x16x32_bf16 v[42:45], v[156:159], v[192:195], v[42:45]
	v_mfma_f32_16x16x32_bf16 v[46:49], v[164:167], v[192:195], v[46:49]
	v_mfma_f32_16x16x32_bf16 v[34:37], v[156:159], v[200:203], v[34:37]
	v_mfma_f32_16x16x32_bf16 v[38:41], v[164:167], v[200:203], v[38:41]
	v_mfma_f32_16x16x32_bf16 v[58:61], v[160:163], v[176:179], v[58:61]
	v_mfma_f32_16x16x32_bf16 v[62:65], v[168:171], v[176:179], v[62:65]
	v_mfma_f32_16x16x32_bf16 v[50:53], v[160:163], v[188:191], v[50:53]
	v_mfma_f32_16x16x32_bf16 v[54:57], v[168:171], v[188:191], v[54:57]
	v_mfma_f32_16x16x32_bf16 v[42:45], v[160:163], v[196:199], v[42:45]
	v_mfma_f32_16x16x32_bf16 v[46:49], v[168:171], v[196:199], v[46:49]
	v_mfma_f32_16x16x32_bf16 v[34:37], v[160:163], v[204:207], v[34:37]
	v_mfma_f32_16x16x32_bf16 v[38:41], v[168:171], v[204:207], v[38:41]
	s_nop 0
	s_barrier
;     __host__ __device__ bool next(int i, Unit& u) const { return StaticOrder::next(i >> 1, u); }
; template <class Epi, class Sched, bool ALIGN_EPI = false, bool SP2 = false>
; __device__ __forceinline__ void gemm_phase(PG8_LAS unsigned char* lds, const Gemm g, const Sched& S, const Epi& E) {
;     ...
;     for (;;) {
;         const bool has_next = S.next(ui + 1, nxt);
;         const char* nA = has_next ? (const char*)g.A + (size_t)nxt.pm * tsA + (size_t)nxt.k0 * 2 : cA; const char* nB = has_next ? (const char*)g.Bt + (size_t)nxt.pn * tsB + (size_t)nxt.k0 * 2 : cB;
;         for (int t = (DRO && ui > 0) ? 2 : 0; t < nt; t += 2) {
;             const bool last = (t == nt - 2);
;             const char* a1 = cA + (size_t)(t + 1) * kstep;
;             const char* a2 = last ? nA : cA + (size_t)(t + 2) * kstep; const char* b2 = last ? nB : cB + (size_t)(t + 2) * kstep;
;             const char* a3 = a2 + kstep; const char* b3 = b2 + kstep;
;             if (last && has_next) S.a_ready(nxt);
;             if constexpr (SP2) {
;             PG8_TRIP(true, PG8_WAIT_V(8));
;             } else {
;             PG8_LDB(B0, 0, 0); PG8_SCHED; PG8_LDA(At, 0, 0); PG8_STAGE(PG8_SA(1, 1), a1 + hsA, voffA);
;             PG8_WAIT_L(8); PG8_BAR; PG8_WAIT_L(0); PG8_MMA(0, 0, At, B0); PG8_BAR; PG8_SCHED;
;             PG8_LDB(B1, 0, 1); PG8_STAGE(PG8_SB(0, 0), b2, voffB);
;             PG8_BAR; PG8_WAIT_L(0); PG8_MMA(0, 1, At, B1); PG8_BAR;
;             PG8_LDA(At, 0, 1); PG8_STAGE(PG8_SA(0, 0), a2, voffA);
;             PG8_BAR; PG8_WAIT_L(0); PG8_MMA(1, 0, At, B0); PG8_BAR; PG8_SCHED;
;             PG8_STAGE(PG8_SB(0, 1), b2 + hsB, voffB);
;             PG8_WAIT_V(6); PG8_BAR; PG8_MMA(1, 1, At, B1); PG8_BAR;
;             PG8_LDB(B0, 1, 0); PG8_SCHED; PG8_LDA(At, 1, 0); PG8_STAGE(PG8_SA(0, 1), a2 + hsA, voffA);
;             PG8_WAIT_L(8); PG8_BAR; PG8_WAIT_L(0); PG8_MMA(0, 0, At, B0); PG8_BAR; PG8_SCHED;
;             PG8_LDB(B1, 1, 1); PG8_STAGE(PG8_SB(1, 0), b3, voffB);
;             PG8_BAR; PG8_WAIT_L(0); PG8_MMA(0, 1, At, B1); PG8_BAR;
;             PG8_LDA(At, 1, 1); PG8_STAGE(PG8_SA(1, 0), a3, voffA);
;             PG8_BAR; PG8_WAIT_L(0); PG8_MMA(1, 0, At, B0); PG8_BAR; PG8_SCHED;
;             PG8_STAGE(PG8_SB(1, 1), b3 + hsB, voffB);
;             PG8_WAIT_V(6); PG8_BAR; PG8_MMA(1, 1, At, B1); PG8_BAR;
;             }
;         }
	ds_read_b128 v[172:175], v134 offset:49152
	ds_read_b128 v[176:179], v134 offset:50176
	ds_read_b128 v[184:187], v134 offset:51200
	ds_read_b128 v[188:191], v134 offset:52224
	ds_read_b128 v[192:195], v134 offset:53248
	ds_read_b128 v[196:199], v134 offset:54272
	ds_read_b128 v[200:203], v134 offset:55296
	ds_read_b128 v[204:207], v134 offset:56320
	s_add_u32 s22, s20, 0x80
	s_addc_u32 s23, s21, 0
	s_mov_b32 m0, s37
	s_nop 0
	global_load_lds_dwordx4 v130, s[22:23]
	s_add_u32 s20, s20, 0x160080
	s_mov_b32 m0, s40
	s_nop 0
	global_load_lds_dwordx4 v131, s[22:23]
	s_addc_u32 s21, s21, 0
	s_mov_b32 m0, s45
	s_nop 0
	global_load_lds_dwordx4 v130, s[20:21]
	s_nop 0
	s_mov_b32 m0, s46
	s_nop 0
	global_load_lds_dwordx4 v131, s[20:21]
	s_nop 0
	s_mov_b32 m0, s41
	s_nop 0
	global_load_lds_dwordx4 v130, s[18:19]
	s_nop 0
	s_mov_b32 m0, s44
	s_nop 0
	global_load_lds_dwordx4 v131, s[18:19]
	s_waitcnt vmcnt(8)
	s_waitcnt lgkmcnt(0)
	s_barrier
	s_nop 0
	s_waitcnt lgkmcnt(7)
	v_mfma_f32_16x16x32_bf16 v[98:101], v[140:143], v[172:175], v[98:101]
	v_mfma_f32_16x16x32_bf16 v[102:105], v[148:151], v[172:175], v[102:105]
	s_waitcnt lgkmcnt(5)
	v_mfma_f32_16x16x32_bf16 v[86:89], v[140:143], v[184:187], v[86:89]
	v_mfma_f32_16x16x32_bf16 v[90:93], v[148:151], v[184:187], v[90:93]
	s_waitcnt lgkmcnt(3)
	v_mfma_f32_16x16x32_bf16 v[74:77], v[140:143], v[192:195], v[74:77]
	v_mfma_f32_16x16x32_bf16 v[78:81], v[148:151], v[192:195], v[78:81]
	s_waitcnt lgkmcnt(1)
	v_mfma_f32_16x16x32_bf16 v[66:69], v[140:143], v[200:203], v[66:69]
	v_mfma_f32_16x16x32_bf16 v[70:73], v[148:151], v[200:203], v[70:73]
	v_mfma_f32_16x16x32_bf16 v[98:101], v[144:147], v[176:179], v[98:101]
	v_mfma_f32_16x16x32_bf16 v[102:105], v[152:155], v[176:179], v[102:105]
	v_mfma_f32_16x16x32_bf16 v[86:89], v[144:147], v[188:191], v[86:89]
	v_mfma_f32_16x16x32_bf16 v[90:93], v[152:155], v[188:191], v[90:93]
	v_mfma_f32_16x16x32_bf16 v[74:77], v[144:147], v[196:199], v[74:77]
	v_mfma_f32_16x16x32_bf16 v[78:81], v[152:155], v[196:199], v[78:81]
	s_waitcnt lgkmcnt(0)
	v_mfma_f32_16x16x32_bf16 v[66:69], v[144:147], v[204:207], v[66:69]
	v_mfma_f32_16x16x32_bf16 v[70:73], v[152:155], v[204:207], v[70:73]
	s_nop 0
	s_nop 0
	v_mfma_f32_16x16x32_bf16 v[122:125], v[156:159], v[172:175], v[122:125]
	v_mfma_f32_16x16x32_bf16 v[126:129], v[164:167], v[172:175], v[126:129]
	v_mfma_f32_16x16x32_bf16 v[114:117], v[156:159], v[184:187], v[114:117]
	v_mfma_f32_16x16x32_bf16 v[118:121], v[164:167], v[184:187], v[118:121]
	v_mfma_f32_16x16x32_bf16 v[106:109], v[156:159], v[192:195], v[106:109]
	v_mfma_f32_16x16x32_bf16 v[110:113], v[164:167], v[192:195], v[110:113]
	v_mfma_f32_16x16x32_bf16 v[94:97], v[156:159], v[200:203], v[94:97]
	v_mfma_f32_16x16x32_bf16 v[82:85], v[164:167], v[200:203], v[82:85]
	v_mfma_f32_16x16x32_bf16 v[122:125], v[160:163], v[176:179], v[122:125]
	v_mfma_f32_16x16x32_bf16 v[126:129], v[168:171], v[176:179], v[126:129]
	v_mfma_f32_16x16x32_bf16 v[114:117], v[160:163], v[188:191], v[114:117]
	v_mfma_f32_16x16x32_bf16 v[118:121], v[168:171], v[188:191], v[118:121]
	v_mfma_f32_16x16x32_bf16 v[106:109], v[160:163], v[196:199], v[106:109]
	v_mfma_f32_16x16x32_bf16 v[110:113], v[168:171], v[196:199], v[110:113]
	v_mfma_f32_16x16x32_bf16 v[94:97], v[160:163], v[204:207], v[94:97]
	v_mfma_f32_16x16x32_bf16 v[82:85], v[168:171], v[204:207], v[82:85]
	s_nop 0
	s_barrier
	s_add_i32 s11, s11, 2
	s_add_u32 s64, s64, 0x100
	s_addc_u32 s67, s67, 0
	s_add_u32 s16, s16, 0x100
	s_addc_u32 s17, s17, 0
	s_cmp_gt_u32 s11, 19
	s_cbranch_scc0 .LBB0_1246
	s_add_u32 s16, s12, 0x160080
	s_addc_u32 s17, s13, 0
	s_mov_b32 m0, s47
	s_nop 0
	global_load_lds_dwordx4 v130, s[16:17]
	s_and_b64 vcc, exec, s[8:9]
	s_mov_b32 m0, s48
	s_nop 0
	global_load_lds_dwordx4 v131, s[16:17]
	s_cbranch_vccz .LBB0_1249
	s_barrier
